# sigmoid divisions in the expert-1 and gate epilogues: guarded short division (drops v_div_scale and v_div_fixup when all arguments are in the range where they are the identity; original code kept as t
# speedup vs baseline: 1.0128x; 1.0047x over previous
; DI unsigned pack2(float a, float b) { fl2_t f = {a, b}; bf2_t r = __builtin_convertvector(f, bf2_t); return __builtin_bit_cast(unsigned, r); }
; DI float sigmoidf_(float x) { return 1.f / (1.f + __expf(-x)); }
; DI void g1_phase(const P& p, int l, unsigned char* lds) {
;     ...
;     if (tn_ >= 10) {
;       const int br = (tn_ - 10) >> 2, tn2 = ((tn_ - 10) & 3) * 2 + (wn >> 1), wn2 = wn & 1;
;       u16* gf = (u16*)(p.ws + O_GF) + (size_t)br * TA * 1024;
; #pragma unroll
;       for (int mt = 0; mt < 4; ++mt) {
;         const int wave2 = (2 * wm + (mt >> 1)) * 2 + wn2, mt2 = mt & 1;
; #pragma unroll
;         for (int nt = 0; nt < 2; ++nt)
; #pragma unroll
;           for (int g4 = 0; g4 < 4; ++g4) {
;             size_t idx = ((((((size_t)tm_ * 8 + tn2) * 8 + wave2) * 2 + mt2) * 2 + nt) * 4 + g4) * 64 + lane;
;             *(uint2*)(gf + idx * 4) = make_uint2(pack2(sigmoidf_(acc[mt][nt][4 * g4]), sigmoidf_(acc[mt][nt][4 * g4 + 1])),
;                                                  pack2(sigmoidf_(acc[mt][nt][4 * g4 + 2]), sigmoidf_(acc[mt][nt][4 * g4 + 3])));
;           }
;       }
.LBB0_228:
	s_andn2_b64 vcc, exec, s[0:1]
	s_cbranch_vccnz .LBB0_230
	s_nop 7
	s_nop 7
	v_min_f32_e32 v150, v2, v3
	v_min3_f32 v150, v150, v4, v5
	v_min3_f32 v150, v150, v6, v7
	v_min3_f32 v150, v150, v8, v9
	v_min3_f32 v150, v150, v10, v11
	v_min3_f32 v150, v150, v12, v13
	v_min3_f32 v150, v150, v14, v15
	v_min3_f32 v150, v150, v16, v17
	v_min3_f32 v150, v150, v18, v19
	v_min3_f32 v150, v150, v20, v21
	v_min3_f32 v150, v150, v22, v23
	v_min3_f32 v150, v150, v24, v25
	v_min3_f32 v150, v150, v26, v27
	v_min3_f32 v150, v150, v28, v29
	v_min3_f32 v150, v150, v30, v31
	v_min3_f32 v150, v150, v32, v33
	v_min3_f32 v150, v150, v34, v35
	v_min3_f32 v150, v150, v36, v37
	v_min3_f32 v150, v150, v38, v39
	v_min3_f32 v150, v150, v40, v41
	v_min3_f32 v150, v150, v42, v43
	v_min3_f32 v150, v150, v44, v45
	v_min3_f32 v150, v150, v46, v47
	v_min3_f32 v150, v150, v48, v49
	v_min3_f32 v150, v150, v50, v51
	v_min3_f32 v150, v150, v52, v53
	v_min3_f32 v150, v150, v54, v55
	v_min3_f32 v150, v150, v56, v57
	v_min3_f32 v150, v150, v58, v59
	v_min3_f32 v150, v150, v60, v61
	v_min3_f32 v150, v150, v62, v63
	v_min3_f32 v150, v150, v64, v65
	v_min3_f32 v150, v150, v66, v67
	v_min3_f32 v150, v150, v68, v69
	v_min3_f32 v150, v150, v70, v71
	v_min3_f32 v150, v150, v72, v73
	v_min3_f32 v150, v150, v74, v75
	v_min3_f32 v150, v150, v76, v77
	v_min3_f32 v150, v150, v78, v79
	v_min3_f32 v150, v150, v80, v81
	v_min3_f32 v150, v150, v82, v83
	v_min3_f32 v150, v150, v84, v85
	v_min3_f32 v150, v150, v86, v87
	v_min3_f32 v150, v150, v88, v89
	v_min3_f32 v150, v150, v90, v91
	v_min3_f32 v150, v150, v92, v93
	v_min3_f32 v150, v150, v94, v95
	v_min3_f32 v150, v150, v96, v97
	v_min3_f32 v150, v150, v98, v99
	v_min3_f32 v150, v150, v100, v101
	v_min3_f32 v150, v150, v102, v103
	v_min3_f32 v150, v150, v104, v105
	v_min3_f32 v150, v150, v106, v107
	v_min3_f32 v150, v150, v108, v109
	v_min3_f32 v150, v150, v110, v111
	v_min3_f32 v150, v150, v112, v113
	v_min3_f32 v150, v150, v114, v115
	v_min3_f32 v150, v150, v116, v117
	v_min3_f32 v150, v150, v118, v119
	v_min3_f32 v150, v150, v120, v121
	v_min3_f32 v150, v150, v122, v123
	v_min3_f32 v150, v150, v124, v125
	v_min3_f32 v150, v150, v126, v127
	v_min3_f32 v150, v150, v128, v129
	v_mov_b32_e32 v151, 0xc2700000
	s_nop 0
	v_cmp_nlt_f32_e32 vcc, v151, v150
	s_cbranch_vccnz .Lg1_gate_slow
	s_add_i32 s0, s10, -10
	s_lshr_b32 s1, s0, 2
	s_lshl_b32 s0, s0, 1
	v_lshrrev_b32_e32 v130, 1, v139
	s_mul_hi_u32 s5, s1, 0x4200000
	s_mul_i32 s1, s1, 0x4200000
	v_and_or_b32 v131, s0, 6, v130
	v_bfe_u32 v130, v137, 6, 1
	s_add_u32 s0, s95, s1
	s_addc_u32 s1, s33, s5
	v_lshl_or_b32 v130, v140, 2, v130
	s_lshl_b32 s5, s25, 6
	v_lshl_or_b32 v178, v131, 3, s5
	v_ashrrev_i32_e32 v131, 31, v130
	v_lshl_add_u64 v[132:133], v[178:179], 0, v[130:131]
	v_mul_f32_e32 v131, 0xbfb8aa3b, v2
	v_exp_f32_e32 v134, v131
	v_mul_f32_e32 v131, 0xbfb8aa3b, v3
	v_exp_f32_e32 v135, v131
	v_or_b32_e32 v130, 2, v130
	v_pk_add_f32 v[134:135], v[134:135], 1.0 op_sel_hi:[1,0]
	s_nop 0
	v_rcp_f32_e32 v141, v135
	s_waitcnt vmcnt(4)
	v_fma_f32 v142, -v135, v141, 1.0
	v_fmac_f32_e32 v141, v142, v141
	v_fma_f32 v144, -v135, v141, 1.0
	v_fma_f32 v143, v144, v141, v141
	v_fma_f32 v131, -v135, v143, 1.0
	v_fma_f32 v131, v131, v141, v143
	v_rcp_f32_e32 v141, v134
	s_nop 0
	v_fma_f32 v142, -v134, v141, 1.0
	v_fmac_f32_e32 v141, v142, v141
	v_fma_f32 v144, -v134, v141, 1.0
	v_fma_f32 v143, v144, v141, v141
	v_fma_f32 v135, -v134, v143, 1.0
	v_fma_f32 v135, v135, v141, v143
	v_mov_b32_e32 v134, v135
	v_cvt_pk_bf16_f32 v142, v134, v131
	v_mul_f32_e32 v131, 0xbfb8aa3b, v4
	v_exp_f32_e32 v134, v131
	v_mul_f32_e32 v131, 0xbfb8aa3b, v5
	v_exp_f32_e32 v135, v131
	s_nop 0
	v_pk_add_f32 v[134:135], v[134:135], 1.0 op_sel_hi:[1,0]
	s_nop 0
	v_rcp_f32_e32 v141, v135
	s_nop 0
	v_fma_f32 v143, -v135, v141, 1.0
	v_fmac_f32_e32 v141, v143, v141
	v_fma_f32 v145, -v135, v141, 1.0
	v_fma_f32 v144, v145, v141, v141
	v_fma_f32 v131, -v135, v144, 1.0
	v_fma_f32 v131, v131, v141, v144
	v_rcp_f32_e32 v141, v134
	s_nop 0
	v_fma_f32 v143, -v134, v141, 1.0
	v_fmac_f32_e32 v141, v143, v141
	v_fma_f32 v145, -v134, v141, 1.0
	v_fma_f32 v144, v145, v141, v141
	v_fma_f32 v135, -v134, v144, 1.0
	v_fma_f32 v135, v135, v141, v144
	v_mov_b32_e32 v134, v135
	v_cvt_pk_bf16_f32 v143, v134, v131
	v_lshlrev_b64 v[134:135], 13, v[132:133]
	v_lshlrev_b32_e32 v132, 3, v1
	v_mov_b32_e32 v133, v179
	v_lshl_add_u64 v[134:135], s[0:1], 0, v[134:135]
	v_lshl_add_u64 v[134:135], v[134:135], 0, v[132:133]
	v_mul_f32_e32 v131, 0xbfb8aa3b, v6
	global_store_dwordx2 v[134:135], v[142:143], off
	v_exp_f32_e32 v142, v131
	v_mul_f32_e32 v131, 0xbfb8aa3b, v7
	v_exp_f32_e32 v143, v131
	s_nop 0
	v_pk_add_f32 v[142:143], v[142:143], 1.0 op_sel_hi:[1,0]
	s_nop 0
	v_rcp_f32_e32 v141, v143
	s_nop 0
	v_fma_f32 v144, -v143, v141, 1.0
	v_fmac_f32_e32 v141, v144, v141
	s_waitcnt vmcnt(4)
; DI unsigned pack2(float a, float b) { fl2_t f = {a, b}; bf2_t r = __builtin_convertvector(f, bf2_t); return __builtin_bit_cast(unsigned, r); }
; DI float sigmoidf_(float x) { return 1.f / (1.f + __expf(-x)); }
; DI void g1_phase(const P& p, int l, unsigned char* lds) {
;     ...
;       for (int mt = 0; mt < 4; ++mt) {
;         const int wave2 = (2 * wm + (mt >> 1)) * 2 + wn2, mt2 = mt & 1;
; #pragma unroll
;         for (int nt = 0; nt < 2; ++nt)
; #pragma unroll
;           for (int g4 = 0; g4 < 4; ++g4) {
;             size_t idx = ((((((size_t)tm_ * 8 + tn2) * 8 + wave2) * 2 + mt2) * 2 + nt) * 4 + g4) * 64 + lane;
;             *(uint2*)(gf + idx * 4) = make_uint2(pack2(sigmoidf_(acc[mt][nt][4 * g4]), sigmoidf_(acc[mt][nt][4 * g4 + 1])),
;                                                  pack2(sigmoidf_(acc[mt][nt][4 * g4 + 2]), sigmoidf_(acc[mt][nt][4 * g4 + 3])));
	v_fma_f32 v146, -v143, v141, 1.0
	v_fma_f32 v145, v146, v141, v141
	v_fma_f32 v131, -v143, v145, 1.0
	v_fma_f32 v131, v131, v141, v145
	v_rcp_f32_e32 v143, v142
	s_nop 0
	v_fma_f32 v144, -v142, v143, 1.0
	v_fmac_f32_e32 v143, v144, v143
	v_fma_f32 v146, -v142, v143, 1.0
	v_fma_f32 v145, v146, v143, v143
	v_fma_f32 v141, -v142, v145, 1.0
	v_fma_f32 v141, v141, v143, v145
	v_cvt_pk_bf16_f32 v142, v141, v131
	v_mul_f32_e32 v131, 0xbfb8aa3b, v8
	v_exp_f32_e32 v144, v131
	v_mul_f32_e32 v131, 0xbfb8aa3b, v9
	v_exp_f32_e32 v145, v131
	s_nop 0
	v_pk_add_f32 v[144:145], v[144:145], 1.0 op_sel_hi:[1,0]
	s_nop 0
	v_rcp_f32_e32 v141, v145
	s_nop 0
	v_fma_f32 v143, -v145, v141, 1.0
	v_fmac_f32_e32 v141, v143, v141
	v_fma_f32 v147, -v145, v141, 1.0
	v_fma_f32 v146, v147, v141, v141
	v_fma_f32 v131, -v145, v146, 1.0
	v_fma_f32 v131, v131, v141, v146
	v_rcp_f32_e32 v143, v144
	s_nop 0
	v_fma_f32 v145, -v144, v143, 1.0
	v_fmac_f32_e32 v143, v145, v143
	v_fma_f32 v147, -v144, v143, 1.0
	v_fma_f32 v146, v147, v143, v143
	v_fma_f32 v141, -v144, v146, 1.0
	v_fma_f32 v141, v141, v143, v146
	v_cvt_pk_bf16_f32 v143, v141, v131
	v_mul_f32_e32 v131, 0xbfb8aa3b, v10
	global_store_dwordx2 v[134:135], v[142:143], off offset:512
	v_exp_f32_e32 v142, v131
	v_mul_f32_e32 v131, 0xbfb8aa3b, v11
	v_exp_f32_e32 v143, v131
	s_nop 0
	v_pk_add_f32 v[142:143], v[142:143], 1.0 op_sel_hi:[1,0]
	s_nop 0
	v_rcp_f32_e32 v141, v143
	s_nop 0
	v_fma_f32 v144, -v143, v141, 1.0
	v_fmac_f32_e32 v141, v144, v141
	v_fma_f32 v146, -v143, v141, 1.0
	v_fma_f32 v145, v146, v141, v141
	v_fma_f32 v131, -v143, v145, 1.0
	v_fma_f32 v131, v131, v141, v145
	v_rcp_f32_e32 v143, v142
	s_nop 0
	v_fma_f32 v144, -v142, v143, 1.0
	v_fmac_f32_e32 v143, v144, v143
	v_fma_f32 v146, -v142, v143, 1.0
	v_fma_f32 v145, v146, v143, v143
	v_fma_f32 v141, -v142, v145, 1.0
	v_fma_f32 v141, v141, v143, v145
	v_cvt_pk_bf16_f32 v142, v141, v131
	v_mul_f32_e32 v131, 0xbfb8aa3b, v12
	v_exp_f32_e32 v144, v131
	v_mul_f32_e32 v131, 0xbfb8aa3b, v13
	v_exp_f32_e32 v145, v131
	s_nop 0
	v_pk_add_f32 v[144:145], v[144:145], 1.0 op_sel_hi:[1,0]
	s_nop 0
	v_rcp_f32_e32 v141, v145
	s_nop 0
	v_fma_f32 v143, -v145, v141, 1.0
	v_fmac_f32_e32 v141, v143, v141
	v_fma_f32 v147, -v145, v141, 1.0
	v_fma_f32 v146, v147, v141, v141
	v_fma_f32 v131, -v145, v146, 1.0
	v_fma_f32 v131, v131, v141, v146
	v_rcp_f32_e32 v143, v144
	s_nop 0
	v_fma_f32 v145, -v144, v143, 1.0
	v_fmac_f32_e32 v143, v145, v143
	v_fma_f32 v147, -v144, v143, 1.0
	v_fma_f32 v146, v147, v143, v143
	v_fma_f32 v141, -v144, v146, 1.0
	v_fma_f32 v141, v141, v143, v146
	v_cvt_pk_bf16_f32 v143, v141, v131
	v_mul_f32_e32 v131, 0xbfb8aa3b, v14
	global_store_dwordx2 v[134:135], v[142:143], off offset:1024
	v_exp_f32_e32 v142, v131
	v_mul_f32_e32 v131, 0xbfb8aa3b, v15
	v_exp_f32_e32 v143, v131
	s_nop 0
	v_pk_add_f32 v[142:143], v[142:143], 1.0 op_sel_hi:[1,0]
	s_nop 0
	v_rcp_f32_e32 v141, v143
	s_nop 0
	v_fma_f32 v144, -v143, v141, 1.0
	v_fmac_f32_e32 v141, v144, v141
	v_fma_f32 v146, -v143, v141, 1.0
	v_fma_f32 v145, v146, v141, v141
	v_fma_f32 v131, -v143, v145, 1.0
	v_fma_f32 v131, v131, v141, v145
	v_rcp_f32_e32 v143, v142
	s_nop 0
	v_fma_f32 v144, -v142, v143, 1.0
	v_fmac_f32_e32 v143, v144, v143
	v_fma_f32 v146, -v142, v143, 1.0
	v_fma_f32 v145, v146, v143, v143
	v_fma_f32 v141, -v142, v145, 1.0
	v_fma_f32 v141, v141, v143, v145
	v_cvt_pk_bf16_f32 v142, v141, v131
	v_mul_f32_e32 v131, 0xbfb8aa3b, v16
	v_exp_f32_e32 v144, v131
	v_mul_f32_e32 v131, 0xbfb8aa3b, v17
	v_exp_f32_e32 v145, v131
	s_nop 0
	v_pk_add_f32 v[144:145], v[144:145], 1.0 op_sel_hi:[1,0]
	s_nop 0
	v_rcp_f32_e32 v141, v145
	s_nop 0
	v_fma_f32 v143, -v145, v141, 1.0
	v_fmac_f32_e32 v141, v143, v141
	v_fma_f32 v147, -v145, v141, 1.0
	v_fma_f32 v146, v147, v141, v141
	v_fma_f32 v131, -v145, v146, 1.0
	v_fma_f32 v131, v131, v141, v146
	v_rcp_f32_e32 v143, v144
	s_nop 0
	v_fma_f32 v145, -v144, v143, 1.0
	v_fmac_f32_e32 v143, v145, v143
	v_fma_f32 v147, -v144, v143, 1.0
	v_fma_f32 v146, v147, v143, v143
	v_fma_f32 v141, -v144, v146, 1.0
	v_fma_f32 v141, v141, v143, v146
	v_cvt_pk_bf16_f32 v143, v141, v131
	v_mul_f32_e32 v131, 0xbfb8aa3b, v18
	global_store_dwordx2 v[134:135], v[142:143], off offset:1536
	v_exp_f32_e32 v142, v131
	v_mul_f32_e32 v131, 0xbfb8aa3b, v19
	v_exp_f32_e32 v143, v131
	s_nop 0
	v_pk_add_f32 v[142:143], v[142:143], 1.0 op_sel_hi:[1,0]
	s_nop 0
	v_rcp_f32_e32 v141, v143
	s_nop 0
	v_fma_f32 v144, -v143, v141, 1.0
	v_fmac_f32_e32 v141, v144, v141
	v_fma_f32 v146, -v143, v141, 1.0
	v_fma_f32 v145, v146, v141, v141
	v_fma_f32 v131, -v143, v145, 1.0
	v_fma_f32 v131, v131, v141, v145
	v_rcp_f32_e32 v143, v142
	s_nop 0
	v_fma_f32 v144, -v142, v143, 1.0
	v_fmac_f32_e32 v143, v144, v143
	v_fma_f32 v146, -v142, v143, 1.0
	v_fma_f32 v145, v146, v143, v143
	v_fma_f32 v141, -v142, v145, 1.0
	v_fma_f32 v141, v141, v143, v145
	v_cvt_pk_bf16_f32 v142, v141, v131
	v_mul_f32_e32 v131, 0xbfb8aa3b, v20
	v_exp_f32_e32 v144, v131
	v_mul_f32_e32 v131, 0xbfb8aa3b, v21
	v_exp_f32_e32 v145, v131
	s_nop 0
	v_pk_add_f32 v[144:145], v[144:145], 1.0 op_sel_hi:[1,0]
	s_nop 0
	v_rcp_f32_e32 v141, v145
	s_nop 0
	v_fma_f32 v143, -v145, v141, 1.0
	v_fmac_f32_e32 v141, v143, v141
	v_fma_f32 v147, -v145, v141, 1.0
	v_fma_f32 v146, v147, v141, v141
	v_fma_f32 v131, -v145, v146, 1.0
	v_fma_f32 v131, v131, v141, v146
	v_rcp_f32_e32 v143, v144
	s_nop 0
	v_fma_f32 v145, -v144, v143, 1.0
	v_fmac_f32_e32 v143, v145, v143
	v_fma_f32 v147, -v144, v143, 1.0
	v_fma_f32 v146, v147, v143, v143
	v_fma_f32 v141, -v144, v146, 1.0
	v_fma_f32 v141, v141, v143, v146
	v_cvt_pk_bf16_f32 v143, v141, v131
	v_mul_f32_e32 v131, 0xbfb8aa3b, v22
; DI unsigned pack2(float a, float b) { fl2_t f = {a, b}; bf2_t r = __builtin_convertvector(f, bf2_t); return __builtin_bit_cast(unsigned, r); }
; DI float sigmoidf_(float x) { return 1.f / (1.f + __expf(-x)); }
; DI void g1_phase(const P& p, int l, unsigned char* lds) {
;     ...
;       for (int mt = 0; mt < 4; ++mt) {
;         const int wave2 = (2 * wm + (mt >> 1)) * 2 + wn2, mt2 = mt & 1;
; #pragma unroll
;         for (int nt = 0; nt < 2; ++nt)
; #pragma unroll
;           for (int g4 = 0; g4 < 4; ++g4) {
;             size_t idx = ((((((size_t)tm_ * 8 + tn2) * 8 + wave2) * 2 + mt2) * 2 + nt) * 4 + g4) * 64 + lane;
;             *(uint2*)(gf + idx * 4) = make_uint2(pack2(sigmoidf_(acc[mt][nt][4 * g4]), sigmoidf_(acc[mt][nt][4 * g4 + 1])),
;                                                  pack2(sigmoidf_(acc[mt][nt][4 * g4 + 2]), sigmoidf_(acc[mt][nt][4 * g4 + 3])));
	global_store_dwordx2 v[134:135], v[142:143], off offset:2048
	v_exp_f32_e32 v142, v131
	v_mul_f32_e32 v131, 0xbfb8aa3b, v23
	v_exp_f32_e32 v143, v131
	s_nop 0
	v_pk_add_f32 v[142:143], v[142:143], 1.0 op_sel_hi:[1,0]
	s_nop 0
	v_rcp_f32_e32 v141, v143
	s_nop 0
	v_fma_f32 v144, -v143, v141, 1.0
	v_fmac_f32_e32 v141, v144, v141
	v_fma_f32 v146, -v143, v141, 1.0
	v_fma_f32 v145, v146, v141, v141
	v_fma_f32 v131, -v143, v145, 1.0
	v_fma_f32 v131, v131, v141, v145
	v_rcp_f32_e32 v143, v142
	s_nop 0
	v_fma_f32 v144, -v142, v143, 1.0
	v_fmac_f32_e32 v143, v144, v143
	v_fma_f32 v146, -v142, v143, 1.0
	v_fma_f32 v145, v146, v143, v143
	v_fma_f32 v141, -v142, v145, 1.0
	v_fma_f32 v141, v141, v143, v145
	v_cvt_pk_bf16_f32 v142, v141, v131
	v_mul_f32_e32 v131, 0xbfb8aa3b, v24
	v_exp_f32_e32 v144, v131
	v_mul_f32_e32 v131, 0xbfb8aa3b, v25
	v_exp_f32_e32 v145, v131
	s_nop 0
	v_pk_add_f32 v[144:145], v[144:145], 1.0 op_sel_hi:[1,0]
	s_nop 0
	v_rcp_f32_e32 v141, v145
	s_nop 0
	v_fma_f32 v143, -v145, v141, 1.0
	v_fmac_f32_e32 v141, v143, v141
	v_fma_f32 v147, -v145, v141, 1.0
	v_fma_f32 v146, v147, v141, v141
	v_fma_f32 v131, -v145, v146, 1.0
	v_fma_f32 v131, v131, v141, v146
	v_rcp_f32_e32 v143, v144
	s_nop 0
	v_fma_f32 v145, -v144, v143, 1.0
	v_fmac_f32_e32 v143, v145, v143
	v_fma_f32 v147, -v144, v143, 1.0
	v_fma_f32 v146, v147, v143, v143
	v_fma_f32 v141, -v144, v146, 1.0
	v_fma_f32 v141, v141, v143, v146
	v_cvt_pk_bf16_f32 v143, v141, v131
	v_mul_f32_e32 v131, 0xbfb8aa3b, v26
	global_store_dwordx2 v[134:135], v[142:143], off offset:2560
	v_exp_f32_e32 v142, v131
	v_mul_f32_e32 v131, 0xbfb8aa3b, v27
	v_exp_f32_e32 v143, v131
	s_nop 0
	v_pk_add_f32 v[142:143], v[142:143], 1.0 op_sel_hi:[1,0]
	s_nop 0
	v_rcp_f32_e32 v141, v143
	s_nop 0
	v_fma_f32 v144, -v143, v141, 1.0
	v_fmac_f32_e32 v141, v144, v141
	v_fma_f32 v146, -v143, v141, 1.0
	v_fma_f32 v145, v146, v141, v141
	v_fma_f32 v131, -v143, v145, 1.0
	v_fma_f32 v131, v131, v141, v145
	v_rcp_f32_e32 v143, v142
	s_nop 0
	v_fma_f32 v144, -v142, v143, 1.0
	v_fmac_f32_e32 v143, v144, v143
	v_fma_f32 v146, -v142, v143, 1.0
	v_fma_f32 v145, v146, v143, v143
	v_fma_f32 v141, -v142, v145, 1.0
	v_fma_f32 v141, v141, v143, v145
	v_cvt_pk_bf16_f32 v142, v141, v131
	v_mul_f32_e32 v131, 0xbfb8aa3b, v28
	v_exp_f32_e32 v144, v131
	v_mul_f32_e32 v131, 0xbfb8aa3b, v29
	v_exp_f32_e32 v145, v131
	s_nop 0
	v_pk_add_f32 v[144:145], v[144:145], 1.0 op_sel_hi:[1,0]
	s_nop 0
	v_rcp_f32_e32 v141, v145
	s_nop 0
	v_fma_f32 v143, -v145, v141, 1.0
	v_fmac_f32_e32 v141, v143, v141
	v_fma_f32 v147, -v145, v141, 1.0
	v_fma_f32 v146, v147, v141, v141
	v_fma_f32 v131, -v145, v146, 1.0
	v_fma_f32 v131, v131, v141, v146
	v_rcp_f32_e32 v143, v144
	s_nop 0
	v_fma_f32 v145, -v144, v143, 1.0
	v_fmac_f32_e32 v143, v145, v143
	v_fma_f32 v147, -v144, v143, 1.0
	v_fma_f32 v146, v147, v143, v143
	v_fma_f32 v141, -v144, v146, 1.0
	v_fma_f32 v141, v141, v143, v146
	v_cvt_pk_bf16_f32 v143, v141, v131
	v_mul_f32_e32 v131, 0xbfb8aa3b, v30
	global_store_dwordx2 v[134:135], v[142:143], off offset:3072
	v_exp_f32_e32 v142, v131
	v_mul_f32_e32 v131, 0xbfb8aa3b, v31
	v_exp_f32_e32 v143, v131
	s_nop 0
	v_pk_add_f32 v[142:143], v[142:143], 1.0 op_sel_hi:[1,0]
	s_nop 0
	v_rcp_f32_e32 v141, v143
	s_nop 0
	v_fma_f32 v144, -v143, v141, 1.0
	v_fmac_f32_e32 v141, v144, v141
	v_fma_f32 v146, -v143, v141, 1.0
	v_fma_f32 v145, v146, v141, v141
	v_fma_f32 v131, -v143, v145, 1.0
	v_fma_f32 v131, v131, v141, v145
	v_rcp_f32_e32 v143, v142
	s_nop 0
	v_fma_f32 v144, -v142, v143, 1.0
	v_fmac_f32_e32 v143, v144, v143
	v_fma_f32 v146, -v142, v143, 1.0
	v_fma_f32 v145, v146, v143, v143
	v_fma_f32 v141, -v142, v145, 1.0
	v_fma_f32 v141, v141, v143, v145
	v_cvt_pk_bf16_f32 v142, v141, v131
	v_mul_f32_e32 v131, 0xbfb8aa3b, v32
	v_exp_f32_e32 v144, v131
	v_mul_f32_e32 v131, 0xbfb8aa3b, v33
	v_exp_f32_e32 v145, v131
	s_nop 0
	v_pk_add_f32 v[144:145], v[144:145], 1.0 op_sel_hi:[1,0]
	s_nop 0
	v_rcp_f32_e32 v141, v145
	s_nop 0
	v_fma_f32 v143, -v145, v141, 1.0
	v_fmac_f32_e32 v141, v143, v141
	v_fma_f32 v147, -v145, v141, 1.0
	v_fma_f32 v146, v147, v141, v141
	v_fma_f32 v131, -v145, v146, 1.0
	v_fma_f32 v131, v131, v141, v146
	v_rcp_f32_e32 v143, v144
	s_nop 0
	v_fma_f32 v145, -v144, v143, 1.0
	v_fmac_f32_e32 v143, v145, v143
	v_fma_f32 v147, -v144, v143, 1.0
	v_fma_f32 v146, v147, v143, v143
	v_fma_f32 v141, -v144, v146, 1.0
	v_fma_f32 v141, v141, v143, v146
	v_cvt_pk_bf16_f32 v143, v141, v131
	v_mul_f32_e32 v131, 0xbfb8aa3b, v34
	global_store_dwordx2 v[134:135], v[142:143], off offset:3584
	v_exp_f32_e32 v142, v131
	v_mul_f32_e32 v131, 0xbfb8aa3b, v35
	v_exp_f32_e32 v143, v131
	s_nop 0
	v_pk_add_f32 v[142:143], v[142:143], 1.0 op_sel_hi:[1,0]
	s_nop 0
	v_rcp_f32_e32 v141, v143
	s_nop 0
	v_fma_f32 v144, -v143, v141, 1.0
	v_fmac_f32_e32 v141, v144, v141
	v_fma_f32 v146, -v143, v141, 1.0
	v_fma_f32 v145, v146, v141, v141
	v_fma_f32 v131, -v143, v145, 1.0
	v_fma_f32 v131, v131, v141, v145
	v_rcp_f32_e32 v143, v142
	s_nop 0
	v_fma_f32 v144, -v142, v143, 1.0
	v_fmac_f32_e32 v143, v144, v143
	v_fma_f32 v146, -v142, v143, 1.0
	v_fma_f32 v145, v146, v143, v143
	v_fma_f32 v141, -v142, v145, 1.0
	v_fma_f32 v141, v141, v143, v145
	v_cvt_pk_bf16_f32 v142, v141, v131
	v_mul_f32_e32 v131, 0xbfb8aa3b, v36
	v_exp_f32_e32 v144, v131
	v_mul_f32_e32 v131, 0xbfb8aa3b, v37
	v_exp_f32_e32 v145, v131
	s_nop 0
	v_pk_add_f32 v[144:145], v[144:145], 1.0 op_sel_hi:[1,0]
	s_nop 0
	v_rcp_f32_e32 v141, v145
	s_nop 0
	v_fma_f32 v143, -v145, v141, 1.0
	v_fmac_f32_e32 v141, v143, v141
	v_fma_f32 v147, -v145, v141, 1.0
	v_fma_f32 v146, v147, v141, v141
	v_fma_f32 v131, -v145, v146, 1.0
	v_fma_f32 v131, v131, v141, v146
; DI unsigned pack2(float a, float b) { fl2_t f = {a, b}; bf2_t r = __builtin_convertvector(f, bf2_t); return __builtin_bit_cast(unsigned, r); }
; DI float sigmoidf_(float x) { return 1.f / (1.f + __expf(-x)); }
; DI void g1_phase(const P& p, int l, unsigned char* lds) {
;     ...
;       for (int mt = 0; mt < 4; ++mt) {
;         const int wave2 = (2 * wm + (mt >> 1)) * 2 + wn2, mt2 = mt & 1;
; #pragma unroll
;         for (int nt = 0; nt < 2; ++nt)
; #pragma unroll
;           for (int g4 = 0; g4 < 4; ++g4) {
;             size_t idx = ((((((size_t)tm_ * 8 + tn2) * 8 + wave2) * 2 + mt2) * 2 + nt) * 4 + g4) * 64 + lane;
;             *(uint2*)(gf + idx * 4) = make_uint2(pack2(sigmoidf_(acc[mt][nt][4 * g4]), sigmoidf_(acc[mt][nt][4 * g4 + 1])),
;                                                  pack2(sigmoidf_(acc[mt][nt][4 * g4 + 2]), sigmoidf_(acc[mt][nt][4 * g4 + 3])));
	v_rcp_f32_e32 v143, v144
	s_nop 0
	v_fma_f32 v145, -v144, v143, 1.0
	v_fmac_f32_e32 v143, v145, v143
	v_fma_f32 v147, -v144, v143, 1.0
	v_fma_f32 v146, v147, v143, v143
	v_fma_f32 v141, -v144, v146, 1.0
	v_fma_f32 v141, v141, v143, v146
	v_add_co_u32_e32 v134, vcc, s46, v134
	v_cvt_pk_bf16_f32 v143, v141, v131
	s_nop 0
	v_addc_co_u32_e32 v135, vcc, 0, v135, vcc
	v_mul_f32_e32 v131, 0xbfb8aa3b, v38
	global_store_dwordx2 v[134:135], v[142:143], off
	v_exp_f32_e32 v142, v131
	v_mul_f32_e32 v131, 0xbfb8aa3b, v39
	v_exp_f32_e32 v143, v131
	s_nop 0
	v_pk_add_f32 v[142:143], v[142:143], 1.0 op_sel_hi:[1,0]
	s_nop 0
	v_rcp_f32_e32 v141, v143
	s_nop 0
	v_fma_f32 v144, -v143, v141, 1.0
	v_fmac_f32_e32 v141, v144, v141
	v_fma_f32 v146, -v143, v141, 1.0
	v_fma_f32 v145, v146, v141, v141
	v_fma_f32 v131, -v143, v145, 1.0
	v_fma_f32 v131, v131, v141, v145
	v_rcp_f32_e32 v143, v142
	s_nop 0
	v_fma_f32 v144, -v142, v143, 1.0
	v_fmac_f32_e32 v143, v144, v143
	v_fma_f32 v146, -v142, v143, 1.0
	v_fma_f32 v145, v146, v143, v143
	v_fma_f32 v141, -v142, v145, 1.0
	v_fma_f32 v141, v141, v143, v145
	v_cvt_pk_bf16_f32 v142, v141, v131
	v_mul_f32_e32 v131, 0xbfb8aa3b, v40
	v_exp_f32_e32 v144, v131
	v_mul_f32_e32 v131, 0xbfb8aa3b, v41
	v_exp_f32_e32 v145, v131
	s_nop 0
	v_pk_add_f32 v[144:145], v[144:145], 1.0 op_sel_hi:[1,0]
	s_nop 0
	v_rcp_f32_e32 v141, v145
	s_nop 0
	v_fma_f32 v143, -v145, v141, 1.0
	v_fmac_f32_e32 v141, v143, v141
	v_fma_f32 v147, -v145, v141, 1.0
	v_fma_f32 v146, v147, v141, v141
	v_fma_f32 v131, -v145, v146, 1.0
	v_fma_f32 v131, v131, v141, v146
	v_rcp_f32_e32 v143, v144
	s_nop 0
	v_fma_f32 v145, -v144, v143, 1.0
	v_fmac_f32_e32 v143, v145, v143
	v_fma_f32 v147, -v144, v143, 1.0
	v_fma_f32 v146, v147, v143, v143
	v_fma_f32 v141, -v144, v146, 1.0
	v_fma_f32 v141, v141, v143, v146
	v_cvt_pk_bf16_f32 v143, v141, v131
	v_mul_f32_e32 v131, 0xbfb8aa3b, v42
	global_store_dwordx2 v[134:135], v[142:143], off offset:512
	v_exp_f32_e32 v142, v131
	v_mul_f32_e32 v131, 0xbfb8aa3b, v43
	v_exp_f32_e32 v143, v131
	s_nop 0
	v_pk_add_f32 v[142:143], v[142:143], 1.0 op_sel_hi:[1,0]
	s_nop 0
	v_rcp_f32_e32 v141, v143
	s_nop 0
	v_fma_f32 v144, -v143, v141, 1.0
	v_fmac_f32_e32 v141, v144, v141
	v_fma_f32 v146, -v143, v141, 1.0
	v_fma_f32 v145, v146, v141, v141
	v_fma_f32 v131, -v143, v145, 1.0
	v_fma_f32 v131, v131, v141, v145
	v_rcp_f32_e32 v143, v142
	s_nop 0
	v_fma_f32 v144, -v142, v143, 1.0
	v_fmac_f32_e32 v143, v144, v143
	v_fma_f32 v146, -v142, v143, 1.0
	v_fma_f32 v145, v146, v143, v143
	v_fma_f32 v141, -v142, v145, 1.0
	v_fma_f32 v141, v141, v143, v145
	v_cvt_pk_bf16_f32 v142, v141, v131
	v_mul_f32_e32 v131, 0xbfb8aa3b, v44
	v_exp_f32_e32 v144, v131
	v_mul_f32_e32 v131, 0xbfb8aa3b, v45
	v_exp_f32_e32 v145, v131
	s_nop 0
	v_pk_add_f32 v[144:145], v[144:145], 1.0 op_sel_hi:[1,0]
	s_nop 0
	v_rcp_f32_e32 v141, v145
	s_nop 0
	v_fma_f32 v143, -v145, v141, 1.0
	v_fmac_f32_e32 v141, v143, v141
	v_fma_f32 v147, -v145, v141, 1.0
	v_fma_f32 v146, v147, v141, v141
	v_fma_f32 v131, -v145, v146, 1.0
	v_fma_f32 v131, v131, v141, v146
	v_rcp_f32_e32 v143, v144
	s_nop 0
	v_fma_f32 v145, -v144, v143, 1.0
	v_fmac_f32_e32 v143, v145, v143
	v_fma_f32 v147, -v144, v143, 1.0
	v_fma_f32 v146, v147, v143, v143
	v_fma_f32 v141, -v144, v146, 1.0
	v_fma_f32 v141, v141, v143, v146
	v_cvt_pk_bf16_f32 v143, v141, v131
	v_mul_f32_e32 v131, 0xbfb8aa3b, v46
	global_store_dwordx2 v[134:135], v[142:143], off offset:1024
	v_exp_f32_e32 v142, v131
	v_mul_f32_e32 v131, 0xbfb8aa3b, v47
	v_exp_f32_e32 v143, v131
	s_nop 0
	v_pk_add_f32 v[142:143], v[142:143], 1.0 op_sel_hi:[1,0]
	s_nop 0
	v_rcp_f32_e32 v141, v143
	s_nop 0
	v_fma_f32 v144, -v143, v141, 1.0
	v_fmac_f32_e32 v141, v144, v141
	v_fma_f32 v146, -v143, v141, 1.0
	v_fma_f32 v145, v146, v141, v141
	v_fma_f32 v131, -v143, v145, 1.0
	v_fma_f32 v131, v131, v141, v145
	v_rcp_f32_e32 v143, v142
	s_nop 0
	v_fma_f32 v144, -v142, v143, 1.0
	v_fmac_f32_e32 v143, v144, v143
	v_fma_f32 v146, -v142, v143, 1.0
	v_fma_f32 v145, v146, v143, v143
	v_fma_f32 v141, -v142, v145, 1.0
	v_fma_f32 v141, v141, v143, v145
	v_cvt_pk_bf16_f32 v142, v141, v131
	v_mul_f32_e32 v131, 0xbfb8aa3b, v48
	v_exp_f32_e32 v144, v131
	v_mul_f32_e32 v131, 0xbfb8aa3b, v49
	v_exp_f32_e32 v145, v131
	s_nop 0
	v_pk_add_f32 v[144:145], v[144:145], 1.0 op_sel_hi:[1,0]
	s_nop 0
	v_rcp_f32_e32 v141, v145
	s_nop 0
	v_fma_f32 v143, -v145, v141, 1.0
	v_fmac_f32_e32 v141, v143, v141
	v_fma_f32 v147, -v145, v141, 1.0
	v_fma_f32 v146, v147, v141, v141
	v_fma_f32 v131, -v145, v146, 1.0
	v_fma_f32 v131, v131, v141, v146
	v_rcp_f32_e32 v143, v144
	s_nop 0
	v_fma_f32 v145, -v144, v143, 1.0
	v_fmac_f32_e32 v143, v145, v143
	v_fma_f32 v147, -v144, v143, 1.0
	v_fma_f32 v146, v147, v143, v143
	v_fma_f32 v141, -v144, v146, 1.0
	v_fma_f32 v141, v141, v143, v146
	v_cvt_pk_bf16_f32 v143, v141, v131
	v_mul_f32_e32 v131, 0xbfb8aa3b, v50
	global_store_dwordx2 v[134:135], v[142:143], off offset:1536
	v_exp_f32_e32 v142, v131
	v_mul_f32_e32 v131, 0xbfb8aa3b, v51
	v_exp_f32_e32 v143, v131
	s_nop 0
	v_pk_add_f32 v[142:143], v[142:143], 1.0 op_sel_hi:[1,0]
	s_nop 0
	v_rcp_f32_e32 v141, v143
	s_nop 0
	v_fma_f32 v144, -v143, v141, 1.0
	v_fmac_f32_e32 v141, v144, v141
	v_fma_f32 v146, -v143, v141, 1.0
	v_fma_f32 v145, v146, v141, v141
	v_fma_f32 v131, -v143, v145, 1.0
	v_fma_f32 v131, v131, v141, v145
	v_rcp_f32_e32 v143, v142
	s_nop 0
	v_fma_f32 v144, -v142, v143, 1.0
	v_fmac_f32_e32 v143, v144, v143
	v_fma_f32 v146, -v142, v143, 1.0
	v_fma_f32 v145, v146, v143, v143
	v_fma_f32 v141, -v142, v145, 1.0
	v_fma_f32 v141, v141, v143, v145
	v_cvt_pk_bf16_f32 v142, v141, v131
	v_mul_f32_e32 v131, 0xbfb8aa3b, v52
; DI unsigned pack2(float a, float b) { fl2_t f = {a, b}; bf2_t r = __builtin_convertvector(f, bf2_t); return __builtin_bit_cast(unsigned, r); }
; DI float sigmoidf_(float x) { return 1.f / (1.f + __expf(-x)); }
; DI void g1_phase(const P& p, int l, unsigned char* lds) {
;     ...
;       for (int mt = 0; mt < 4; ++mt) {
;         const int wave2 = (2 * wm + (mt >> 1)) * 2 + wn2, mt2 = mt & 1;
; #pragma unroll
;         for (int nt = 0; nt < 2; ++nt)
; #pragma unroll
;           for (int g4 = 0; g4 < 4; ++g4) {
;             size_t idx = ((((((size_t)tm_ * 8 + tn2) * 8 + wave2) * 2 + mt2) * 2 + nt) * 4 + g4) * 64 + lane;
;             *(uint2*)(gf + idx * 4) = make_uint2(pack2(sigmoidf_(acc[mt][nt][4 * g4]), sigmoidf_(acc[mt][nt][4 * g4 + 1])),
;                                                  pack2(sigmoidf_(acc[mt][nt][4 * g4 + 2]), sigmoidf_(acc[mt][nt][4 * g4 + 3])));
	v_exp_f32_e32 v144, v131
	v_mul_f32_e32 v131, 0xbfb8aa3b, v53
	v_exp_f32_e32 v145, v131
	s_nop 0
	v_pk_add_f32 v[144:145], v[144:145], 1.0 op_sel_hi:[1,0]
	s_nop 0
	v_rcp_f32_e32 v141, v145
	s_nop 0
	v_fma_f32 v143, -v145, v141, 1.0
	v_fmac_f32_e32 v141, v143, v141
	v_fma_f32 v147, -v145, v141, 1.0
	v_fma_f32 v146, v147, v141, v141
	v_fma_f32 v131, -v145, v146, 1.0
	v_fma_f32 v131, v131, v141, v146
	v_rcp_f32_e32 v143, v144
	s_nop 0
	v_fma_f32 v145, -v144, v143, 1.0
	v_fmac_f32_e32 v143, v145, v143
	v_fma_f32 v147, -v144, v143, 1.0
	v_fma_f32 v146, v147, v143, v143
	v_fma_f32 v141, -v144, v146, 1.0
	v_fma_f32 v141, v141, v143, v146
	v_cvt_pk_bf16_f32 v143, v141, v131
	v_mul_f32_e32 v131, 0xbfb8aa3b, v54
	global_store_dwordx2 v[134:135], v[142:143], off offset:2048
	v_exp_f32_e32 v142, v131
	v_mul_f32_e32 v131, 0xbfb8aa3b, v55
	v_exp_f32_e32 v143, v131
	s_nop 0
	v_pk_add_f32 v[142:143], v[142:143], 1.0 op_sel_hi:[1,0]
	s_nop 0
	v_rcp_f32_e32 v141, v143
	s_nop 0
	v_fma_f32 v144, -v143, v141, 1.0
	v_fmac_f32_e32 v141, v144, v141
	v_fma_f32 v146, -v143, v141, 1.0
	v_fma_f32 v145, v146, v141, v141
	v_fma_f32 v131, -v143, v145, 1.0
	v_fma_f32 v131, v131, v141, v145
	v_rcp_f32_e32 v143, v142
	s_nop 0
	v_fma_f32 v144, -v142, v143, 1.0
	v_fmac_f32_e32 v143, v144, v143
	v_fma_f32 v146, -v142, v143, 1.0
	v_fma_f32 v145, v146, v143, v143
	v_fma_f32 v141, -v142, v145, 1.0
	v_fma_f32 v141, v141, v143, v145
	v_cvt_pk_bf16_f32 v142, v141, v131
	v_mul_f32_e32 v131, 0xbfb8aa3b, v56
	v_exp_f32_e32 v144, v131
	v_mul_f32_e32 v131, 0xbfb8aa3b, v57
	v_exp_f32_e32 v145, v131
	s_nop 0
	v_pk_add_f32 v[144:145], v[144:145], 1.0 op_sel_hi:[1,0]
	s_nop 0
	v_rcp_f32_e32 v141, v145
	s_nop 0
	v_fma_f32 v143, -v145, v141, 1.0
	v_fmac_f32_e32 v141, v143, v141
	v_fma_f32 v147, -v145, v141, 1.0
	v_fma_f32 v146, v147, v141, v141
	v_fma_f32 v131, -v145, v146, 1.0
	v_fma_f32 v131, v131, v141, v146
	v_rcp_f32_e32 v143, v144
	s_nop 0
	v_fma_f32 v145, -v144, v143, 1.0
	v_fmac_f32_e32 v143, v145, v143
	v_fma_f32 v147, -v144, v143, 1.0
	v_fma_f32 v146, v147, v143, v143
	v_fma_f32 v141, -v144, v146, 1.0
	v_fma_f32 v141, v141, v143, v146
	v_cvt_pk_bf16_f32 v143, v141, v131
	v_mul_f32_e32 v131, 0xbfb8aa3b, v58
	global_store_dwordx2 v[134:135], v[142:143], off offset:2560
	v_exp_f32_e32 v142, v131
	v_mul_f32_e32 v131, 0xbfb8aa3b, v59
	v_exp_f32_e32 v143, v131
	s_nop 0
	v_pk_add_f32 v[142:143], v[142:143], 1.0 op_sel_hi:[1,0]
	s_nop 0
	v_rcp_f32_e32 v141, v143
	s_nop 0
	v_fma_f32 v144, -v143, v141, 1.0
	v_fmac_f32_e32 v141, v144, v141
	v_fma_f32 v146, -v143, v141, 1.0
	v_fma_f32 v145, v146, v141, v141
	v_fma_f32 v131, -v143, v145, 1.0
	v_fma_f32 v131, v131, v141, v145
	v_rcp_f32_e32 v143, v142
	s_nop 0
	v_fma_f32 v144, -v142, v143, 1.0
	v_fmac_f32_e32 v143, v144, v143
	v_fma_f32 v146, -v142, v143, 1.0
	v_fma_f32 v145, v146, v143, v143
	v_fma_f32 v141, -v142, v145, 1.0
	v_fma_f32 v141, v141, v143, v145
	v_cvt_pk_bf16_f32 v142, v141, v131
	v_mul_f32_e32 v131, 0xbfb8aa3b, v60
	v_exp_f32_e32 v144, v131
	v_mul_f32_e32 v131, 0xbfb8aa3b, v61
	v_exp_f32_e32 v145, v131
	s_nop 0
	v_pk_add_f32 v[144:145], v[144:145], 1.0 op_sel_hi:[1,0]
	s_nop 0
	v_rcp_f32_e32 v141, v145
	s_nop 0
	v_fma_f32 v143, -v145, v141, 1.0
	v_fmac_f32_e32 v141, v143, v141
	v_fma_f32 v147, -v145, v141, 1.0
	v_fma_f32 v146, v147, v141, v141
	v_fma_f32 v131, -v145, v146, 1.0
	v_fma_f32 v131, v131, v141, v146
	v_rcp_f32_e32 v143, v144
	s_nop 0
	v_fma_f32 v145, -v144, v143, 1.0
	v_fmac_f32_e32 v143, v145, v143
	v_fma_f32 v147, -v144, v143, 1.0
	v_fma_f32 v146, v147, v143, v143
	v_fma_f32 v141, -v144, v146, 1.0
	v_fma_f32 v141, v141, v143, v146
	v_cvt_pk_bf16_f32 v143, v141, v131
	v_mul_f32_e32 v131, 0xbfb8aa3b, v62
	global_store_dwordx2 v[134:135], v[142:143], off offset:3072
	v_exp_f32_e32 v142, v131
	v_mul_f32_e32 v131, 0xbfb8aa3b, v63
	v_exp_f32_e32 v143, v131
	s_nop 0
	v_pk_add_f32 v[142:143], v[142:143], 1.0 op_sel_hi:[1,0]
	s_nop 0
	v_rcp_f32_e32 v141, v143
	s_nop 0
	v_fma_f32 v144, -v143, v141, 1.0
	v_fmac_f32_e32 v141, v144, v141
	v_fma_f32 v146, -v143, v141, 1.0
	v_fma_f32 v145, v146, v141, v141
	v_fma_f32 v131, -v143, v145, 1.0
	v_fma_f32 v131, v131, v141, v145
	v_rcp_f32_e32 v143, v142
	s_nop 0
	v_fma_f32 v144, -v142, v143, 1.0
	v_fmac_f32_e32 v143, v144, v143
	v_fma_f32 v146, -v142, v143, 1.0
	v_fma_f32 v145, v146, v143, v143
	v_fma_f32 v141, -v142, v145, 1.0
	v_fma_f32 v141, v141, v143, v145
	v_cvt_pk_bf16_f32 v142, v141, v131
	v_mul_f32_e32 v131, 0xbfb8aa3b, v64
	v_exp_f32_e32 v144, v131
	v_mul_f32_e32 v131, 0xbfb8aa3b, v65
	v_exp_f32_e32 v145, v131
	s_nop 0
	v_pk_add_f32 v[144:145], v[144:145], 1.0 op_sel_hi:[1,0]
	s_nop 0
	v_rcp_f32_e32 v141, v145
	s_nop 0
	v_fma_f32 v143, -v145, v141, 1.0
	v_fmac_f32_e32 v141, v143, v141
	v_fma_f32 v147, -v145, v141, 1.0
	v_fma_f32 v146, v147, v141, v141
	v_fma_f32 v131, -v145, v146, 1.0
	v_fma_f32 v131, v131, v141, v146
	v_rcp_f32_e32 v143, v144
	s_nop 0
	v_fma_f32 v145, -v144, v143, 1.0
	v_fmac_f32_e32 v143, v145, v143
	v_fma_f32 v147, -v144, v143, 1.0
	v_fma_f32 v146, v147, v143, v143
	v_fma_f32 v141, -v144, v146, 1.0
	v_fma_f32 v141, v141, v143, v146
	v_cvt_pk_bf16_f32 v143, v141, v131
	global_store_dwordx2 v[134:135], v[142:143], off offset:3584
	v_mul_f32_e32 v134, 0xbfb8aa3b, v66
	v_mul_f32_e32 v135, 0xbfb8aa3b, v67
	v_exp_f32_e32 v134, v134
	v_exp_f32_e32 v135, v135
	v_ashrrev_i32_e32 v131, 31, v130
	v_lshl_add_u64 v[130:131], v[178:179], 0, v[130:131]
	v_lshlrev_b64 v[130:131], 13, v[130:131]
	v_pk_add_f32 v[134:135], v[134:135], 1.0 op_sel_hi:[1,0]
	v_lshl_add_u64 v[130:131], s[0:1], 0, v[130:131]
	v_rcp_f32_e32 v142, v135
	v_lshl_add_u64 v[130:131], v[130:131], 0, v[132:133]
; DI unsigned pack2(float a, float b) { fl2_t f = {a, b}; bf2_t r = __builtin_convertvector(f, bf2_t); return __builtin_bit_cast(unsigned, r); }
; DI float sigmoidf_(float x) { return 1.f / (1.f + __expf(-x)); }
; DI void g1_phase(const P& p, int l, unsigned char* lds) {
;     ...
;       for (int mt = 0; mt < 4; ++mt) {
;         const int wave2 = (2 * wm + (mt >> 1)) * 2 + wn2, mt2 = mt & 1;
; #pragma unroll
;         for (int nt = 0; nt < 2; ++nt)
; #pragma unroll
;           for (int g4 = 0; g4 < 4; ++g4) {
;             size_t idx = ((((((size_t)tm_ * 8 + tn2) * 8 + wave2) * 2 + mt2) * 2 + nt) * 4 + g4) * 64 + lane;
;             *(uint2*)(gf + idx * 4) = make_uint2(pack2(sigmoidf_(acc[mt][nt][4 * g4]), sigmoidf_(acc[mt][nt][4 * g4 + 1])),
;                                                  pack2(sigmoidf_(acc[mt][nt][4 * g4 + 2]), sigmoidf_(acc[mt][nt][4 * g4 + 3])));
	v_mul_f32_e32 v132, 0xbfb8aa3b, v70
	v_mul_f32_e32 v133, 0xbfb8aa3b, v71
	v_fma_f32 v143, -v135, v142, 1.0
	v_fmac_f32_e32 v142, v143, v142
	v_fma_f32 v145, -v135, v142, 1.0
	v_fma_f32 v144, v145, v142, v142
	v_fma_f32 v141, -v135, v144, 1.0
	v_fma_f32 v141, v141, v142, v144
	v_mov_b32_e32 v135, v141
	v_rcp_f32_e32 v142, v134
	v_exp_f32_e32 v132, v132
	v_exp_f32_e32 v133, v133
	v_fma_f32 v143, -v134, v142, 1.0
	v_fmac_f32_e32 v142, v143, v142
	v_fma_f32 v145, -v134, v142, 1.0
	v_fma_f32 v144, v145, v142, v142
	v_fma_f32 v141, -v134, v144, 1.0
	v_fma_f32 v141, v141, v142, v144
	v_mov_b32_e32 v134, v141
	v_cvt_pk_bf16_f32 v134, v134, v135
	v_mul_f32_e32 v135, 0xbfb8aa3b, v68
	v_exp_f32_e32 v142, v135
	v_mul_f32_e32 v135, 0xbfb8aa3b, v69
	v_exp_f32_e32 v143, v135
	v_pk_add_f32 v[132:133], v[132:133], 1.0 op_sel_hi:[1,0]
	v_pk_add_f32 v[142:143], v[142:143], 1.0 op_sel_hi:[1,0]
	s_nop 0
	v_rcp_f32_e32 v141, v143
	s_nop 0
	v_fma_f32 v144, -v143, v141, 1.0
	v_fmac_f32_e32 v141, v144, v141
	v_fma_f32 v146, -v143, v141, 1.0
	v_fma_f32 v145, v146, v141, v141
	v_fma_f32 v135, -v143, v145, 1.0
	v_fma_f32 v135, v135, v141, v145
	v_rcp_f32_e32 v143, v142
	s_nop 0
	v_fma_f32 v144, -v142, v143, 1.0
	v_fmac_f32_e32 v143, v144, v143
	v_fma_f32 v146, -v142, v143, 1.0
	v_fma_f32 v145, v146, v143, v143
	v_fma_f32 v141, -v142, v145, 1.0
	v_fma_f32 v141, v141, v143, v145
	v_cvt_pk_bf16_f32 v135, v141, v135
	global_store_dwordx2 v[130:131], v[134:135], off
	v_rcp_f32_e32 v135, v133
	s_nop 0
	v_fma_f32 v141, -v133, v135, 1.0
	v_fmac_f32_e32 v135, v141, v135
	v_fma_f32 v143, -v133, v135, 1.0
	v_fma_f32 v142, v143, v135, v135
	v_fma_f32 v134, -v133, v142, 1.0
	v_fma_f32 v134, v134, v135, v142
	v_mov_b32_e32 v133, v134
	v_rcp_f32_e32 v135, v132
	s_nop 0
	v_fma_f32 v141, -v132, v135, 1.0
	v_fmac_f32_e32 v135, v141, v135
	v_fma_f32 v143, -v132, v135, 1.0
	v_fma_f32 v142, v143, v135, v135
	v_fma_f32 v134, -v132, v142, 1.0
	v_fma_f32 v134, v134, v135, v142
	v_mov_b32_e32 v132, v134
	v_cvt_pk_bf16_f32 v132, v132, v133
	v_mul_f32_e32 v133, 0xbfb8aa3b, v72
	v_exp_f32_e32 v134, v133
	v_mul_f32_e32 v133, 0xbfb8aa3b, v73
	v_exp_f32_e32 v135, v133
	s_nop 0
	v_pk_add_f32 v[134:135], v[134:135], 1.0 op_sel_hi:[1,0]
	s_nop 0
	v_rcp_f32_e32 v141, v135
	s_nop 0
	v_fma_f32 v142, -v135, v141, 1.0
	v_fmac_f32_e32 v141, v142, v141
	v_fma_f32 v144, -v135, v141, 1.0
	v_fma_f32 v143, v144, v141, v141
	v_fma_f32 v133, -v135, v143, 1.0
	v_fma_f32 v133, v133, v141, v143
	v_rcp_f32_e32 v141, v134
	s_nop 0
	v_fma_f32 v142, -v134, v141, 1.0
	v_fmac_f32_e32 v141, v142, v141
	v_fma_f32 v144, -v134, v141, 1.0
	v_fma_f32 v143, v144, v141, v141
	v_fma_f32 v135, -v134, v143, 1.0
	v_fma_f32 v135, v135, v141, v143
	v_mov_b32_e32 v134, v135
	v_cvt_pk_bf16_f32 v133, v134, v133
	global_store_dwordx2 v[130:131], v[132:133], off offset:512
	v_mul_f32_e32 v132, 0xbfb8aa3b, v74
	v_mul_f32_e32 v133, 0xbfb8aa3b, v75
	v_exp_f32_e32 v132, v132
	v_exp_f32_e32 v133, v133
	s_nop 0
	v_pk_add_f32 v[132:133], v[132:133], 1.0 op_sel_hi:[1,0]
	s_nop 0
	v_rcp_f32_e32 v135, v133
	s_nop 0
	v_fma_f32 v141, -v133, v135, 1.0
	v_fmac_f32_e32 v135, v141, v135
	v_fma_f32 v143, -v133, v135, 1.0
	v_fma_f32 v142, v143, v135, v135
	v_fma_f32 v134, -v133, v142, 1.0
	v_fma_f32 v134, v134, v135, v142
	v_mov_b32_e32 v133, v134
	v_rcp_f32_e32 v135, v132
	s_nop 0
	v_fma_f32 v141, -v132, v135, 1.0
	v_fmac_f32_e32 v135, v141, v135
	v_fma_f32 v143, -v132, v135, 1.0
	v_fma_f32 v142, v143, v135, v135
	v_fma_f32 v134, -v132, v142, 1.0
	v_fma_f32 v134, v134, v135, v142
	v_mov_b32_e32 v132, v134
	v_cvt_pk_bf16_f32 v132, v132, v133
	v_mul_f32_e32 v133, 0xbfb8aa3b, v76
	v_exp_f32_e32 v134, v133
	v_mul_f32_e32 v133, 0xbfb8aa3b, v77
	v_exp_f32_e32 v135, v133
	s_nop 0
	v_pk_add_f32 v[134:135], v[134:135], 1.0 op_sel_hi:[1,0]
	s_nop 0
	v_rcp_f32_e32 v141, v135
	s_nop 0
	v_fma_f32 v142, -v135, v141, 1.0
	v_fmac_f32_e32 v141, v142, v141
	v_fma_f32 v144, -v135, v141, 1.0
	v_fma_f32 v143, v144, v141, v141
	v_fma_f32 v133, -v135, v143, 1.0
	v_fma_f32 v133, v133, v141, v143
	v_rcp_f32_e32 v141, v134
	s_nop 0
	v_fma_f32 v142, -v134, v141, 1.0
	v_fmac_f32_e32 v141, v142, v141
	v_fma_f32 v144, -v134, v141, 1.0
	v_fma_f32 v143, v144, v141, v141
	v_fma_f32 v135, -v134, v143, 1.0
	v_fma_f32 v135, v135, v141, v143
	v_mov_b32_e32 v134, v135
	v_cvt_pk_bf16_f32 v133, v134, v133
	global_store_dwordx2 v[130:131], v[132:133], off offset:1024
	v_mul_f32_e32 v132, 0xbfb8aa3b, v78
	v_mul_f32_e32 v133, 0xbfb8aa3b, v79
	v_exp_f32_e32 v132, v132
	v_exp_f32_e32 v133, v133
	s_nop 0
	v_pk_add_f32 v[132:133], v[132:133], 1.0 op_sel_hi:[1,0]
	s_nop 0
	v_rcp_f32_e32 v135, v133
	s_nop 0
	v_fma_f32 v141, -v133, v135, 1.0
	v_fmac_f32_e32 v135, v141, v135
	v_fma_f32 v143, -v133, v135, 1.0
	v_fma_f32 v142, v143, v135, v135
	v_fma_f32 v134, -v133, v142, 1.0
	v_fma_f32 v134, v134, v135, v142
	v_mov_b32_e32 v133, v134
	v_rcp_f32_e32 v135, v132
	s_nop 0
	v_fma_f32 v141, -v132, v135, 1.0
	v_fmac_f32_e32 v135, v141, v135
	v_fma_f32 v143, -v132, v135, 1.0
	v_fma_f32 v142, v143, v135, v135
	v_fma_f32 v134, -v132, v142, 1.0
	v_fma_f32 v134, v134, v135, v142
	v_mov_b32_e32 v132, v134
	v_cvt_pk_bf16_f32 v132, v132, v133
	v_mul_f32_e32 v133, 0xbfb8aa3b, v80
	v_exp_f32_e32 v134, v133
	v_mul_f32_e32 v133, 0xbfb8aa3b, v81
	v_exp_f32_e32 v135, v133
	s_nop 0
	v_pk_add_f32 v[134:135], v[134:135], 1.0 op_sel_hi:[1,0]
	s_nop 0
	v_rcp_f32_e32 v141, v135
	s_nop 0
	v_fma_f32 v142, -v135, v141, 1.0
	v_fmac_f32_e32 v141, v142, v141
	v_fma_f32 v144, -v135, v141, 1.0
	v_fma_f32 v143, v144, v141, v141
	v_fma_f32 v133, -v135, v143, 1.0
	v_fma_f32 v133, v133, v141, v143
	v_rcp_f32_e32 v141, v134
	s_nop 0
; DI unsigned pack2(float a, float b) { fl2_t f = {a, b}; bf2_t r = __builtin_convertvector(f, bf2_t); return __builtin_bit_cast(unsigned, r); }
; DI float sigmoidf_(float x) { return 1.f / (1.f + __expf(-x)); }
; DI void g1_phase(const P& p, int l, unsigned char* lds) {
;     ...
;       for (int mt = 0; mt < 4; ++mt) {
;         const int wave2 = (2 * wm + (mt >> 1)) * 2 + wn2, mt2 = mt & 1;
; #pragma unroll
;         for (int nt = 0; nt < 2; ++nt)
; #pragma unroll
;           for (int g4 = 0; g4 < 4; ++g4) {
;             size_t idx = ((((((size_t)tm_ * 8 + tn2) * 8 + wave2) * 2 + mt2) * 2 + nt) * 4 + g4) * 64 + lane;
;             *(uint2*)(gf + idx * 4) = make_uint2(pack2(sigmoidf_(acc[mt][nt][4 * g4]), sigmoidf_(acc[mt][nt][4 * g4 + 1])),
;                                                  pack2(sigmoidf_(acc[mt][nt][4 * g4 + 2]), sigmoidf_(acc[mt][nt][4 * g4 + 3])));
	v_fma_f32 v142, -v134, v141, 1.0
	v_fmac_f32_e32 v141, v142, v141
	v_fma_f32 v144, -v134, v141, 1.0
	v_fma_f32 v143, v144, v141, v141
	v_fma_f32 v135, -v134, v143, 1.0
	v_fma_f32 v135, v135, v141, v143
	v_mov_b32_e32 v134, v135
	v_cvt_pk_bf16_f32 v133, v134, v133
	global_store_dwordx2 v[130:131], v[132:133], off offset:1536
	v_mul_f32_e32 v132, 0xbfb8aa3b, v82
	v_mul_f32_e32 v133, 0xbfb8aa3b, v83
	v_exp_f32_e32 v132, v132
	v_exp_f32_e32 v133, v133
	s_nop 0
	v_pk_add_f32 v[132:133], v[132:133], 1.0 op_sel_hi:[1,0]
	s_nop 0
	v_rcp_f32_e32 v135, v133
	s_nop 0
	v_fma_f32 v141, -v133, v135, 1.0
	v_fmac_f32_e32 v135, v141, v135
	v_fma_f32 v143, -v133, v135, 1.0
	v_fma_f32 v142, v143, v135, v135
	v_fma_f32 v134, -v133, v142, 1.0
	v_fma_f32 v134, v134, v135, v142
	v_mov_b32_e32 v133, v134
	v_rcp_f32_e32 v135, v132
	s_nop 0
	v_fma_f32 v141, -v132, v135, 1.0
	v_fmac_f32_e32 v135, v141, v135
	v_fma_f32 v143, -v132, v135, 1.0
	v_fma_f32 v142, v143, v135, v135
	v_fma_f32 v134, -v132, v142, 1.0
	v_fma_f32 v134, v134, v135, v142
	v_mov_b32_e32 v132, v134
	v_cvt_pk_bf16_f32 v132, v132, v133
	v_mul_f32_e32 v133, 0xbfb8aa3b, v84
	v_exp_f32_e32 v134, v133
	v_mul_f32_e32 v133, 0xbfb8aa3b, v85
	v_exp_f32_e32 v135, v133
	s_nop 0
	v_pk_add_f32 v[134:135], v[134:135], 1.0 op_sel_hi:[1,0]
	s_nop 0
	v_rcp_f32_e32 v141, v135
	s_nop 0
	v_fma_f32 v142, -v135, v141, 1.0
	v_fmac_f32_e32 v141, v142, v141
	v_fma_f32 v144, -v135, v141, 1.0
	v_fma_f32 v143, v144, v141, v141
	v_fma_f32 v133, -v135, v143, 1.0
	v_fma_f32 v133, v133, v141, v143
	v_rcp_f32_e32 v141, v134
	s_nop 0
	v_fma_f32 v142, -v134, v141, 1.0
	v_fmac_f32_e32 v141, v142, v141
	v_fma_f32 v144, -v134, v141, 1.0
	v_fma_f32 v143, v144, v141, v141
	v_fma_f32 v135, -v134, v143, 1.0
	v_fma_f32 v135, v135, v141, v143
	v_mov_b32_e32 v134, v135
	v_cvt_pk_bf16_f32 v133, v134, v133
	global_store_dwordx2 v[130:131], v[132:133], off offset:2048
	v_mul_f32_e32 v132, 0xbfb8aa3b, v86
	v_mul_f32_e32 v133, 0xbfb8aa3b, v87
	v_exp_f32_e32 v132, v132
	v_exp_f32_e32 v133, v133
	s_nop 0
	v_pk_add_f32 v[132:133], v[132:133], 1.0 op_sel_hi:[1,0]
	s_nop 0
	v_rcp_f32_e32 v135, v133
	s_nop 0
	v_fma_f32 v141, -v133, v135, 1.0
	v_fmac_f32_e32 v135, v141, v135
	v_fma_f32 v143, -v133, v135, 1.0
	v_fma_f32 v142, v143, v135, v135
	v_fma_f32 v134, -v133, v142, 1.0
	v_fma_f32 v134, v134, v135, v142
	v_mov_b32_e32 v133, v134
	v_rcp_f32_e32 v135, v132
	s_nop 0
	v_fma_f32 v141, -v132, v135, 1.0
	v_fmac_f32_e32 v135, v141, v135
	v_fma_f32 v143, -v132, v135, 1.0
	v_fma_f32 v142, v143, v135, v135
	v_fma_f32 v134, -v132, v142, 1.0
	v_fma_f32 v134, v134, v135, v142
	v_mov_b32_e32 v132, v134
	v_cvt_pk_bf16_f32 v132, v132, v133
	v_mul_f32_e32 v133, 0xbfb8aa3b, v88
	v_exp_f32_e32 v134, v133
	v_mul_f32_e32 v133, 0xbfb8aa3b, v89
	v_exp_f32_e32 v135, v133
	s_nop 0
	v_pk_add_f32 v[134:135], v[134:135], 1.0 op_sel_hi:[1,0]
	s_nop 0
	v_rcp_f32_e32 v141, v135
	s_nop 0
	v_fma_f32 v142, -v135, v141, 1.0
	v_fmac_f32_e32 v141, v142, v141
	v_fma_f32 v144, -v135, v141, 1.0
	v_fma_f32 v143, v144, v141, v141
	v_fma_f32 v133, -v135, v143, 1.0
	v_fma_f32 v133, v133, v141, v143
	v_rcp_f32_e32 v141, v134
	s_nop 0
	v_fma_f32 v142, -v134, v141, 1.0
	v_fmac_f32_e32 v141, v142, v141
	v_fma_f32 v144, -v134, v141, 1.0
	v_fma_f32 v143, v144, v141, v141
	v_fma_f32 v135, -v134, v143, 1.0
	v_fma_f32 v135, v135, v141, v143
	v_mov_b32_e32 v134, v135
	v_cvt_pk_bf16_f32 v133, v134, v133
	global_store_dwordx2 v[130:131], v[132:133], off offset:2560
	v_mul_f32_e32 v132, 0xbfb8aa3b, v90
	v_mul_f32_e32 v133, 0xbfb8aa3b, v91
	v_exp_f32_e32 v132, v132
	v_exp_f32_e32 v133, v133
	s_nop 0
	v_pk_add_f32 v[132:133], v[132:133], 1.0 op_sel_hi:[1,0]
	s_nop 0
	v_rcp_f32_e32 v135, v133
	s_nop 0
	v_fma_f32 v141, -v133, v135, 1.0
	v_fmac_f32_e32 v135, v141, v135
	v_fma_f32 v143, -v133, v135, 1.0
	v_fma_f32 v142, v143, v135, v135
	v_fma_f32 v134, -v133, v142, 1.0
	v_fma_f32 v134, v134, v135, v142
	v_mov_b32_e32 v133, v134
	v_rcp_f32_e32 v135, v132
	s_nop 0
	v_fma_f32 v141, -v132, v135, 1.0
	v_fmac_f32_e32 v135, v141, v135
	v_fma_f32 v143, -v132, v135, 1.0
	v_fma_f32 v142, v143, v135, v135
	v_fma_f32 v134, -v132, v142, 1.0
	v_fma_f32 v134, v134, v135, v142
	v_mov_b32_e32 v132, v134
	v_cvt_pk_bf16_f32 v132, v132, v133
	v_mul_f32_e32 v133, 0xbfb8aa3b, v92
	v_exp_f32_e32 v134, v133
	v_mul_f32_e32 v133, 0xbfb8aa3b, v93
	v_exp_f32_e32 v135, v133
	s_nop 0
	v_pk_add_f32 v[134:135], v[134:135], 1.0 op_sel_hi:[1,0]
	s_nop 0
	v_rcp_f32_e32 v141, v135
	s_nop 0
	v_fma_f32 v142, -v135, v141, 1.0
	v_fmac_f32_e32 v141, v142, v141
	v_fma_f32 v144, -v135, v141, 1.0
	v_fma_f32 v143, v144, v141, v141
	v_fma_f32 v133, -v135, v143, 1.0
	v_fma_f32 v133, v133, v141, v143
	v_rcp_f32_e32 v141, v134
	s_nop 0
	v_fma_f32 v142, -v134, v141, 1.0
	v_fmac_f32_e32 v141, v142, v141
	v_fma_f32 v144, -v134, v141, 1.0
	v_fma_f32 v143, v144, v141, v141
	v_fma_f32 v135, -v134, v143, 1.0
	v_fma_f32 v135, v135, v141, v143
	v_mov_b32_e32 v134, v135
	v_cvt_pk_bf16_f32 v133, v134, v133
	global_store_dwordx2 v[130:131], v[132:133], off offset:3072
	v_mul_f32_e32 v132, 0xbfb8aa3b, v94
	v_mul_f32_e32 v133, 0xbfb8aa3b, v95
	v_exp_f32_e32 v132, v132
	v_exp_f32_e32 v133, v133
	s_nop 0
	v_pk_add_f32 v[132:133], v[132:133], 1.0 op_sel_hi:[1,0]
	s_nop 0
	v_rcp_f32_e32 v135, v133
	s_nop 0
	v_fma_f32 v141, -v133, v135, 1.0
	v_fmac_f32_e32 v135, v141, v135
	v_fma_f32 v143, -v133, v135, 1.0
	v_fma_f32 v142, v143, v135, v135
	v_fma_f32 v134, -v133, v142, 1.0
	v_fma_f32 v134, v134, v135, v142
	v_mov_b32_e32 v133, v134
	v_rcp_f32_e32 v135, v132
	s_nop 0
	v_fma_f32 v141, -v132, v135, 1.0
	v_fmac_f32_e32 v135, v141, v135
	v_fma_f32 v143, -v132, v135, 1.0
; DI unsigned pack2(float a, float b) { fl2_t f = {a, b}; bf2_t r = __builtin_convertvector(f, bf2_t); return __builtin_bit_cast(unsigned, r); }
; DI float sigmoidf_(float x) { return 1.f / (1.f + __expf(-x)); }
; DI void g1_phase(const P& p, int l, unsigned char* lds) {
;     ...
;       for (int mt = 0; mt < 4; ++mt) {
;         const int wave2 = (2 * wm + (mt >> 1)) * 2 + wn2, mt2 = mt & 1;
; #pragma unroll
;         for (int nt = 0; nt < 2; ++nt)
; #pragma unroll
;           for (int g4 = 0; g4 < 4; ++g4) {
;             size_t idx = ((((((size_t)tm_ * 8 + tn2) * 8 + wave2) * 2 + mt2) * 2 + nt) * 4 + g4) * 64 + lane;
;             *(uint2*)(gf + idx * 4) = make_uint2(pack2(sigmoidf_(acc[mt][nt][4 * g4]), sigmoidf_(acc[mt][nt][4 * g4 + 1])),
;                                                  pack2(sigmoidf_(acc[mt][nt][4 * g4 + 2]), sigmoidf_(acc[mt][nt][4 * g4 + 3])));
	v_fma_f32 v142, v143, v135, v135
	v_fma_f32 v134, -v132, v142, 1.0
	v_fma_f32 v134, v134, v135, v142
	v_mov_b32_e32 v132, v134
	v_cvt_pk_bf16_f32 v132, v132, v133
	v_mul_f32_e32 v133, 0xbfb8aa3b, v96
	v_exp_f32_e32 v134, v133
	v_mul_f32_e32 v133, 0xbfb8aa3b, v97
	v_exp_f32_e32 v135, v133
	s_nop 0
	v_pk_add_f32 v[134:135], v[134:135], 1.0 op_sel_hi:[1,0]
	s_nop 0
	v_rcp_f32_e32 v141, v135
	s_nop 0
	v_fma_f32 v142, -v135, v141, 1.0
	v_fmac_f32_e32 v141, v142, v141
	v_fma_f32 v144, -v135, v141, 1.0
	v_fma_f32 v143, v144, v141, v141
	v_fma_f32 v133, -v135, v143, 1.0
	v_fma_f32 v133, v133, v141, v143
	v_rcp_f32_e32 v141, v134
	s_nop 0
	v_fma_f32 v142, -v134, v141, 1.0
	v_fmac_f32_e32 v141, v142, v141
	v_fma_f32 v144, -v134, v141, 1.0
	v_fma_f32 v143, v144, v141, v141
	v_fma_f32 v135, -v134, v143, 1.0
	v_fma_f32 v135, v135, v141, v143
	v_mov_b32_e32 v134, v135
	v_cvt_pk_bf16_f32 v133, v134, v133
	global_store_dwordx2 v[130:131], v[132:133], off offset:3584
	v_mul_f32_e32 v132, 0xbfb8aa3b, v98
	v_mul_f32_e32 v133, 0xbfb8aa3b, v99
	v_exp_f32_e32 v132, v132
	v_exp_f32_e32 v133, v133
	s_nop 0
	v_pk_add_f32 v[132:133], v[132:133], 1.0 op_sel_hi:[1,0]
	s_nop 0
	v_rcp_f32_e32 v135, v133
	s_nop 0
	v_fma_f32 v141, -v133, v135, 1.0
	v_fmac_f32_e32 v135, v141, v135
	v_fma_f32 v143, -v133, v135, 1.0
	v_fma_f32 v142, v143, v135, v135
	v_fma_f32 v134, -v133, v142, 1.0
	v_fma_f32 v134, v134, v135, v142
	v_mov_b32_e32 v133, v134
	v_rcp_f32_e32 v135, v132
	s_nop 0
	v_fma_f32 v141, -v132, v135, 1.0
	v_fmac_f32_e32 v135, v141, v135
	v_fma_f32 v143, -v132, v135, 1.0
	v_fma_f32 v142, v143, v135, v135
	v_fma_f32 v134, -v132, v142, 1.0
	v_fma_f32 v134, v134, v135, v142
	v_mov_b32_e32 v132, v134
	v_cvt_pk_bf16_f32 v132, v132, v133
	v_mul_f32_e32 v133, 0xbfb8aa3b, v100
	v_exp_f32_e32 v134, v133
	v_mul_f32_e32 v133, 0xbfb8aa3b, v101
	v_exp_f32_e32 v135, v133
	s_nop 0
	v_pk_add_f32 v[134:135], v[134:135], 1.0 op_sel_hi:[1,0]
	s_nop 0
	v_rcp_f32_e32 v141, v135
	s_nop 0
	v_fma_f32 v142, -v135, v141, 1.0
	v_fmac_f32_e32 v141, v142, v141
	v_fma_f32 v144, -v135, v141, 1.0
	v_fma_f32 v143, v144, v141, v141
	v_fma_f32 v133, -v135, v143, 1.0
	v_fma_f32 v133, v133, v141, v143
	v_rcp_f32_e32 v141, v134
	s_nop 0
	v_fma_f32 v142, -v134, v141, 1.0
	v_fmac_f32_e32 v141, v142, v141
	v_fma_f32 v144, -v134, v141, 1.0
	v_fma_f32 v143, v144, v141, v141
	v_fma_f32 v135, -v134, v143, 1.0
	v_fma_f32 v135, v135, v141, v143
	v_mov_b32_e32 v134, v135
	v_add_co_u32_e32 v130, vcc, s46, v130
	v_cvt_pk_bf16_f32 v133, v134, v133
	s_nop 0
	v_addc_co_u32_e32 v131, vcc, 0, v131, vcc
	global_store_dwordx2 v[130:131], v[132:133], off
	v_mul_f32_e32 v132, 0xbfb8aa3b, v102
	v_mul_f32_e32 v133, 0xbfb8aa3b, v103
	v_exp_f32_e32 v132, v132
	v_exp_f32_e32 v133, v133
	s_nop 0
	v_pk_add_f32 v[132:133], v[132:133], 1.0 op_sel_hi:[1,0]
	s_nop 0
	v_rcp_f32_e32 v135, v133
	s_nop 0
	v_fma_f32 v141, -v133, v135, 1.0
	v_fmac_f32_e32 v135, v141, v135
	v_fma_f32 v143, -v133, v135, 1.0
	v_fma_f32 v142, v143, v135, v135
	v_fma_f32 v134, -v133, v142, 1.0
	v_fma_f32 v134, v134, v135, v142
	v_mov_b32_e32 v133, v134
	v_rcp_f32_e32 v135, v132
	s_nop 0
	v_fma_f32 v141, -v132, v135, 1.0
	v_fmac_f32_e32 v135, v141, v135
	v_fma_f32 v143, -v132, v135, 1.0
	v_fma_f32 v142, v143, v135, v135
	v_fma_f32 v134, -v132, v142, 1.0
	v_fma_f32 v134, v134, v135, v142
	v_mov_b32_e32 v132, v134
	v_cvt_pk_bf16_f32 v132, v132, v133
	v_mul_f32_e32 v133, 0xbfb8aa3b, v104
	v_exp_f32_e32 v134, v133
	v_mul_f32_e32 v133, 0xbfb8aa3b, v105
	v_exp_f32_e32 v135, v133
	s_nop 0
	v_pk_add_f32 v[134:135], v[134:135], 1.0 op_sel_hi:[1,0]
	s_nop 0
	v_rcp_f32_e32 v141, v135
	s_nop 0
	v_fma_f32 v142, -v135, v141, 1.0
	v_fmac_f32_e32 v141, v142, v141
	v_fma_f32 v144, -v135, v141, 1.0
	v_fma_f32 v143, v144, v141, v141
	v_fma_f32 v133, -v135, v143, 1.0
	v_fma_f32 v133, v133, v141, v143
	v_rcp_f32_e32 v141, v134
	s_nop 0
	v_fma_f32 v142, -v134, v141, 1.0
	v_fmac_f32_e32 v141, v142, v141
	v_fma_f32 v144, -v134, v141, 1.0
	v_fma_f32 v143, v144, v141, v141
	v_fma_f32 v135, -v134, v143, 1.0
	v_fma_f32 v135, v135, v141, v143
	v_mov_b32_e32 v134, v135
	v_cvt_pk_bf16_f32 v133, v134, v133
	global_store_dwordx2 v[130:131], v[132:133], off offset:512
	v_mul_f32_e32 v132, 0xbfb8aa3b, v106
	v_mul_f32_e32 v133, 0xbfb8aa3b, v107
	v_exp_f32_e32 v132, v132
	v_exp_f32_e32 v133, v133
	s_nop 0
	v_pk_add_f32 v[132:133], v[132:133], 1.0 op_sel_hi:[1,0]
	s_nop 0
	v_rcp_f32_e32 v135, v133
	s_nop 0
	v_fma_f32 v141, -v133, v135, 1.0
	v_fmac_f32_e32 v135, v141, v135
	v_fma_f32 v143, -v133, v135, 1.0
	v_fma_f32 v142, v143, v135, v135
	v_fma_f32 v134, -v133, v142, 1.0
	v_fma_f32 v134, v134, v135, v142
	v_mov_b32_e32 v133, v134
	v_rcp_f32_e32 v135, v132
	s_nop 0
	v_fma_f32 v141, -v132, v135, 1.0
	v_fmac_f32_e32 v135, v141, v135
	v_fma_f32 v143, -v132, v135, 1.0
	v_fma_f32 v142, v143, v135, v135
	v_fma_f32 v134, -v132, v142, 1.0
	v_fma_f32 v134, v134, v135, v142
	v_mov_b32_e32 v132, v134
	v_cvt_pk_bf16_f32 v132, v132, v133
	v_mul_f32_e32 v133, 0xbfb8aa3b, v108
	v_exp_f32_e32 v134, v133
	v_mul_f32_e32 v133, 0xbfb8aa3b, v109
	v_exp_f32_e32 v135, v133
	s_nop 0
	v_pk_add_f32 v[134:135], v[134:135], 1.0 op_sel_hi:[1,0]
	s_nop 0
	v_rcp_f32_e32 v141, v135
	s_nop 0
	v_fma_f32 v142, -v135, v141, 1.0
	v_fmac_f32_e32 v141, v142, v141
	v_fma_f32 v144, -v135, v141, 1.0
	v_fma_f32 v143, v144, v141, v141
	v_fma_f32 v133, -v135, v143, 1.0
	v_fma_f32 v133, v133, v141, v143
	v_rcp_f32_e32 v141, v134
	s_nop 0
	v_fma_f32 v142, -v134, v141, 1.0
	v_fmac_f32_e32 v141, v142, v141
	v_fma_f32 v144, -v134, v141, 1.0
	v_fma_f32 v143, v144, v141, v141
	v_fma_f32 v135, -v134, v143, 1.0
	v_fma_f32 v135, v135, v141, v143
; DI unsigned pack2(float a, float b) { fl2_t f = {a, b}; bf2_t r = __builtin_convertvector(f, bf2_t); return __builtin_bit_cast(unsigned, r); }
; DI float sigmoidf_(float x) { return 1.f / (1.f + __expf(-x)); }
; DI void g1_phase(const P& p, int l, unsigned char* lds) {
;     ...
;       for (int mt = 0; mt < 4; ++mt) {
;         const int wave2 = (2 * wm + (mt >> 1)) * 2 + wn2, mt2 = mt & 1;
; #pragma unroll
;         for (int nt = 0; nt < 2; ++nt)
; #pragma unroll
;           for (int g4 = 0; g4 < 4; ++g4) {
;             size_t idx = ((((((size_t)tm_ * 8 + tn2) * 8 + wave2) * 2 + mt2) * 2 + nt) * 4 + g4) * 64 + lane;
;             *(uint2*)(gf + idx * 4) = make_uint2(pack2(sigmoidf_(acc[mt][nt][4 * g4]), sigmoidf_(acc[mt][nt][4 * g4 + 1])),
;                                                  pack2(sigmoidf_(acc[mt][nt][4 * g4 + 2]), sigmoidf_(acc[mt][nt][4 * g4 + 3])));
	v_mov_b32_e32 v134, v135
	v_cvt_pk_bf16_f32 v133, v134, v133
	global_store_dwordx2 v[130:131], v[132:133], off offset:1024
	v_mul_f32_e32 v132, 0xbfb8aa3b, v110
	v_mul_f32_e32 v133, 0xbfb8aa3b, v111
	v_exp_f32_e32 v132, v132
	v_exp_f32_e32 v133, v133
	s_nop 0
	v_pk_add_f32 v[132:133], v[132:133], 1.0 op_sel_hi:[1,0]
	s_nop 0
	v_rcp_f32_e32 v135, v133
	s_nop 0
	v_fma_f32 v141, -v133, v135, 1.0
	v_fmac_f32_e32 v135, v141, v135
	v_fma_f32 v143, -v133, v135, 1.0
	v_fma_f32 v142, v143, v135, v135
	v_fma_f32 v134, -v133, v142, 1.0
	v_fma_f32 v134, v134, v135, v142
	v_mov_b32_e32 v133, v134
	v_rcp_f32_e32 v135, v132
	s_nop 0
	v_fma_f32 v141, -v132, v135, 1.0
	v_fmac_f32_e32 v135, v141, v135
	v_fma_f32 v143, -v132, v135, 1.0
	v_fma_f32 v142, v143, v135, v135
	v_fma_f32 v134, -v132, v142, 1.0
	v_fma_f32 v134, v134, v135, v142
	v_mov_b32_e32 v132, v134
	v_cvt_pk_bf16_f32 v132, v132, v133
	v_mul_f32_e32 v133, 0xbfb8aa3b, v112
	v_exp_f32_e32 v134, v133
	v_mul_f32_e32 v133, 0xbfb8aa3b, v113
	v_exp_f32_e32 v135, v133
	s_nop 0
	v_pk_add_f32 v[134:135], v[134:135], 1.0 op_sel_hi:[1,0]
	s_nop 0
	v_rcp_f32_e32 v141, v135
	s_nop 0
	v_fma_f32 v142, -v135, v141, 1.0
	v_fmac_f32_e32 v141, v142, v141
	v_fma_f32 v144, -v135, v141, 1.0
	v_fma_f32 v143, v144, v141, v141
	v_fma_f32 v133, -v135, v143, 1.0
	v_fma_f32 v133, v133, v141, v143
	v_rcp_f32_e32 v141, v134
	s_nop 0
	v_fma_f32 v142, -v134, v141, 1.0
	v_fmac_f32_e32 v141, v142, v141
	v_fma_f32 v144, -v134, v141, 1.0
	v_fma_f32 v143, v144, v141, v141
	v_fma_f32 v135, -v134, v143, 1.0
	v_fma_f32 v135, v135, v141, v143
	v_mov_b32_e32 v134, v135
	v_cvt_pk_bf16_f32 v133, v134, v133
	global_store_dwordx2 v[130:131], v[132:133], off offset:1536
	v_mul_f32_e32 v132, 0xbfb8aa3b, v114
	v_mul_f32_e32 v133, 0xbfb8aa3b, v115
	v_exp_f32_e32 v132, v132
	v_exp_f32_e32 v133, v133
	s_nop 0
	v_pk_add_f32 v[132:133], v[132:133], 1.0 op_sel_hi:[1,0]
	s_nop 0
	v_rcp_f32_e32 v135, v133
	s_nop 0
	v_fma_f32 v141, -v133, v135, 1.0
	v_fmac_f32_e32 v135, v141, v135
	v_fma_f32 v143, -v133, v135, 1.0
	v_fma_f32 v142, v143, v135, v135
	v_fma_f32 v134, -v133, v142, 1.0
	v_fma_f32 v134, v134, v135, v142
	v_mov_b32_e32 v133, v134
	v_rcp_f32_e32 v135, v132
	s_nop 0
	v_fma_f32 v141, -v132, v135, 1.0
	v_fmac_f32_e32 v135, v141, v135
	v_fma_f32 v143, -v132, v135, 1.0
	v_fma_f32 v142, v143, v135, v135
	v_fma_f32 v134, -v132, v142, 1.0
	v_fma_f32 v134, v134, v135, v142
	v_mov_b32_e32 v132, v134
	v_cvt_pk_bf16_f32 v132, v132, v133
	v_mul_f32_e32 v133, 0xbfb8aa3b, v116
	v_exp_f32_e32 v134, v133
	v_mul_f32_e32 v133, 0xbfb8aa3b, v117
	v_exp_f32_e32 v135, v133
	s_nop 0
	v_pk_add_f32 v[134:135], v[134:135], 1.0 op_sel_hi:[1,0]
	s_nop 0
	v_rcp_f32_e32 v141, v135
	s_nop 0
	v_fma_f32 v142, -v135, v141, 1.0
	v_fmac_f32_e32 v141, v142, v141
	v_fma_f32 v144, -v135, v141, 1.0
	v_fma_f32 v143, v144, v141, v141
	v_fma_f32 v133, -v135, v143, 1.0
	v_fma_f32 v133, v133, v141, v143
	v_rcp_f32_e32 v141, v134
	s_nop 0
	v_fma_f32 v142, -v134, v141, 1.0
	v_fmac_f32_e32 v141, v142, v141
	v_fma_f32 v144, -v134, v141, 1.0
	v_fma_f32 v143, v144, v141, v141
	v_fma_f32 v135, -v134, v143, 1.0
	v_fma_f32 v135, v135, v141, v143
	v_mov_b32_e32 v134, v135
	v_cvt_pk_bf16_f32 v133, v134, v133
	global_store_dwordx2 v[130:131], v[132:133], off offset:2048
	v_mul_f32_e32 v132, 0xbfb8aa3b, v118
	v_mul_f32_e32 v133, 0xbfb8aa3b, v119
	v_exp_f32_e32 v132, v132
	v_exp_f32_e32 v133, v133
	s_nop 0
	v_pk_add_f32 v[132:133], v[132:133], 1.0 op_sel_hi:[1,0]
	s_nop 0
	v_rcp_f32_e32 v135, v133
	s_nop 0
	v_fma_f32 v141, -v133, v135, 1.0
	v_fmac_f32_e32 v135, v141, v135
	v_fma_f32 v143, -v133, v135, 1.0
	v_fma_f32 v142, v143, v135, v135
	v_fma_f32 v134, -v133, v142, 1.0
	v_fma_f32 v134, v134, v135, v142
	v_mov_b32_e32 v133, v134
	v_rcp_f32_e32 v135, v132
	s_nop 0
	v_fma_f32 v141, -v132, v135, 1.0
	v_fmac_f32_e32 v135, v141, v135
	v_fma_f32 v143, -v132, v135, 1.0
	v_fma_f32 v142, v143, v135, v135
	v_fma_f32 v134, -v132, v142, 1.0
	v_fma_f32 v134, v134, v135, v142
	v_mov_b32_e32 v132, v134
	v_cvt_pk_bf16_f32 v132, v132, v133
	v_mul_f32_e32 v133, 0xbfb8aa3b, v120
	v_exp_f32_e32 v134, v133
	v_mul_f32_e32 v133, 0xbfb8aa3b, v121
	v_exp_f32_e32 v135, v133
	s_nop 0
	v_pk_add_f32 v[134:135], v[134:135], 1.0 op_sel_hi:[1,0]
	s_nop 0
	v_rcp_f32_e32 v141, v135
	s_nop 0
	v_fma_f32 v142, -v135, v141, 1.0
	v_fmac_f32_e32 v141, v142, v141
	v_fma_f32 v144, -v135, v141, 1.0
	v_fma_f32 v143, v144, v141, v141
	v_fma_f32 v133, -v135, v143, 1.0
	v_fma_f32 v133, v133, v141, v143
	v_rcp_f32_e32 v141, v134
	s_nop 0
	v_fma_f32 v142, -v134, v141, 1.0
	v_fmac_f32_e32 v141, v142, v141
	v_fma_f32 v144, -v134, v141, 1.0
	v_fma_f32 v143, v144, v141, v141
	v_fma_f32 v135, -v134, v143, 1.0
	v_fma_f32 v135, v135, v141, v143
	v_mov_b32_e32 v134, v135
	v_cvt_pk_bf16_f32 v133, v134, v133
	global_store_dwordx2 v[130:131], v[132:133], off offset:2560
	v_mul_f32_e32 v132, 0xbfb8aa3b, v122
	v_mul_f32_e32 v133, 0xbfb8aa3b, v123
	v_exp_f32_e32 v132, v132
	v_exp_f32_e32 v133, v133
	s_nop 0
	v_pk_add_f32 v[132:133], v[132:133], 1.0 op_sel_hi:[1,0]
	s_nop 0
	v_rcp_f32_e32 v135, v133
	s_nop 0
	v_fma_f32 v141, -v133, v135, 1.0
	v_fmac_f32_e32 v135, v141, v135
	v_fma_f32 v143, -v133, v135, 1.0
	v_fma_f32 v142, v143, v135, v135
	v_fma_f32 v134, -v133, v142, 1.0
	v_fma_f32 v134, v134, v135, v142
	v_mov_b32_e32 v133, v134
	v_rcp_f32_e32 v135, v132
	s_nop 0
	v_fma_f32 v141, -v132, v135, 1.0
	v_fmac_f32_e32 v135, v141, v135
	v_fma_f32 v143, -v132, v135, 1.0
	v_fma_f32 v142, v143, v135, v135
	v_fma_f32 v134, -v132, v142, 1.0
	v_fma_f32 v134, v134, v135, v142
	v_mov_b32_e32 v132, v134
	v_cvt_pk_bf16_f32 v132, v132, v133
	v_mul_f32_e32 v133, 0xbfb8aa3b, v124
; DI unsigned pack2(float a, float b) { fl2_t f = {a, b}; bf2_t r = __builtin_convertvector(f, bf2_t); return __builtin_bit_cast(unsigned, r); }
; DI float sigmoidf_(float x) { return 1.f / (1.f + __expf(-x)); }
; DI void g1_phase(const P& p, int l, unsigned char* lds) {
;     ...
;     if (tn_ >= 10) {
;       const int br = (tn_ - 10) >> 2, tn2 = ((tn_ - 10) & 3) * 2 + (wn >> 1), wn2 = wn & 1;
;       u16* gf = (u16*)(p.ws + O_GF) + (size_t)br * TA * 1024;
; #pragma unroll
;       for (int mt = 0; mt < 4; ++mt) {
;         const int wave2 = (2 * wm + (mt >> 1)) * 2 + wn2, mt2 = mt & 1;
; #pragma unroll
;         for (int nt = 0; nt < 2; ++nt)
; #pragma unroll
;           for (int g4 = 0; g4 < 4; ++g4) {
;             size_t idx = ((((((size_t)tm_ * 8 + tn2) * 8 + wave2) * 2 + mt2) * 2 + nt) * 4 + g4) * 64 + lane;
;             *(uint2*)(gf + idx * 4) = make_uint2(pack2(sigmoidf_(acc[mt][nt][4 * g4]), sigmoidf_(acc[mt][nt][4 * g4 + 1])),
;                                                  pack2(sigmoidf_(acc[mt][nt][4 * g4 + 2]), sigmoidf_(acc[mt][nt][4 * g4 + 3])));
	v_exp_f32_e32 v134, v133
	v_mul_f32_e32 v133, 0xbfb8aa3b, v125
	v_exp_f32_e32 v135, v133
	s_nop 0
	v_pk_add_f32 v[134:135], v[134:135], 1.0 op_sel_hi:[1,0]
	s_nop 0
	v_rcp_f32_e32 v141, v135
	s_nop 0
	v_fma_f32 v142, -v135, v141, 1.0
	v_fmac_f32_e32 v141, v142, v141
	v_fma_f32 v144, -v135, v141, 1.0
	v_fma_f32 v143, v144, v141, v141
	v_fma_f32 v133, -v135, v143, 1.0
	v_fma_f32 v133, v133, v141, v143
	v_rcp_f32_e32 v141, v134
	s_nop 0
	v_fma_f32 v142, -v134, v141, 1.0
	v_fmac_f32_e32 v141, v142, v141
	v_fma_f32 v144, -v134, v141, 1.0
	v_fma_f32 v143, v144, v141, v141
	v_fma_f32 v135, -v134, v143, 1.0
	v_fma_f32 v135, v135, v141, v143
	v_mov_b32_e32 v134, v135
	v_cvt_pk_bf16_f32 v133, v134, v133
	global_store_dwordx2 v[130:131], v[132:133], off offset:3072
	v_mul_f32_e32 v132, 0xbfb8aa3b, v126
	v_mul_f32_e32 v133, 0xbfb8aa3b, v127
	v_exp_f32_e32 v132, v132
	v_exp_f32_e32 v133, v133
	s_nop 0
	v_pk_add_f32 v[132:133], v[132:133], 1.0 op_sel_hi:[1,0]
	s_nop 0
	v_rcp_f32_e32 v135, v133
	s_nop 0
	v_fma_f32 v141, -v133, v135, 1.0
	v_fmac_f32_e32 v135, v141, v135
	v_fma_f32 v143, -v133, v135, 1.0
	v_fma_f32 v142, v143, v135, v135
	v_fma_f32 v134, -v133, v142, 1.0
	v_fma_f32 v134, v134, v135, v142
	v_mov_b32_e32 v133, v134
	v_rcp_f32_e32 v135, v132
	s_nop 0
	v_fma_f32 v141, -v132, v135, 1.0
	v_fmac_f32_e32 v135, v141, v135
	v_fma_f32 v143, -v132, v135, 1.0
	v_fma_f32 v142, v143, v135, v135
	v_fma_f32 v134, -v132, v142, 1.0
	v_fma_f32 v134, v134, v135, v142
	v_mov_b32_e32 v132, v134
	v_cvt_pk_bf16_f32 v132, v132, v133
	v_mul_f32_e32 v133, 0xbfb8aa3b, v128
	v_exp_f32_e32 v134, v133
	v_mul_f32_e32 v133, 0xbfb8aa3b, v129
	v_exp_f32_e32 v135, v133
	s_nop 0
	v_pk_add_f32 v[134:135], v[134:135], 1.0 op_sel_hi:[1,0]
	s_nop 0
	v_rcp_f32_e32 v141, v135
	s_nop 0
	v_fma_f32 v142, -v135, v141, 1.0
	v_fmac_f32_e32 v141, v142, v141
	v_fma_f32 v144, -v135, v141, 1.0
	v_fma_f32 v143, v144, v141, v141
	v_fma_f32 v133, -v135, v143, 1.0
	v_fma_f32 v133, v133, v141, v143
	v_rcp_f32_e32 v141, v134
	s_nop 0
	v_fma_f32 v142, -v134, v141, 1.0
	v_fmac_f32_e32 v141, v142, v141
	v_fma_f32 v144, -v134, v141, 1.0
	v_fma_f32 v143, v144, v141, v141
	v_fma_f32 v135, -v134, v143, 1.0
	v_fma_f32 v135, v135, v141, v143
	v_mov_b32_e32 v134, v135
	v_cvt_pk_bf16_f32 v133, v134, v133
	global_store_dwordx2 v[130:131], v[132:133], off offset:3584
	s_branch .LBB0_230
.Lg1_gate_slow:
	s_add_i32 s0, s10, -10
	s_lshr_b32 s1, s0, 2
	s_lshl_b32 s0, s0, 1
	v_lshrrev_b32_e32 v130, 1, v139
	s_mul_hi_u32 s5, s1, 0x4200000
	s_mul_i32 s1, s1, 0x4200000
	v_and_or_b32 v131, s0, 6, v130
	v_bfe_u32 v130, v137, 6, 1
	s_add_u32 s0, s95, s1
	s_addc_u32 s1, s33, s5
	v_lshl_or_b32 v130, v140, 2, v130
	s_lshl_b32 s5, s25, 6
	v_lshl_or_b32 v178, v131, 3, s5
	v_ashrrev_i32_e32 v131, 31, v130
	v_lshl_add_u64 v[132:133], v[178:179], 0, v[130:131]
	v_mul_f32_e32 v131, 0xbfb8aa3b, v2
	v_exp_f32_e32 v134, v131
	v_mul_f32_e32 v131, 0xbfb8aa3b, v3
	v_exp_f32_e32 v135, v131
	v_or_b32_e32 v130, 2, v130
	v_pk_add_f32 v[134:135], v[134:135], 1.0 op_sel_hi:[1,0]
	s_nop 0
	v_div_scale_f32 v131, s[10:11], v135, v135, 1.0
	v_rcp_f32_e32 v141, v131
	s_waitcnt vmcnt(4)
	v_fma_f32 v142, -v131, v141, 1.0
	v_fmac_f32_e32 v141, v142, v141
	v_div_scale_f32 v142, vcc, 1.0, v135, 1.0
	v_mul_f32_e32 v143, v142, v141
	v_fma_f32 v144, -v131, v143, v142
	v_fmac_f32_e32 v143, v144, v141
	v_fma_f32 v131, -v131, v143, v142
	v_div_fmas_f32 v131, v131, v141, v143
	v_div_fixup_f32 v131, v131, v135, 1.0
	v_div_scale_f32 v135, s[10:11], v134, v134, 1.0
	v_rcp_f32_e32 v141, v135
	s_nop 0
	v_fma_f32 v142, -v135, v141, 1.0
	v_fmac_f32_e32 v141, v142, v141
	v_div_scale_f32 v142, vcc, 1.0, v134, 1.0
	v_mul_f32_e32 v143, v142, v141
	v_fma_f32 v144, -v135, v143, v142
	v_fmac_f32_e32 v143, v144, v141
	v_fma_f32 v135, -v135, v143, v142
	v_div_fmas_f32 v135, v135, v141, v143
	v_div_fixup_f32 v134, v135, v134, 1.0
	v_cvt_pk_bf16_f32 v142, v134, v131
	v_mul_f32_e32 v131, 0xbfb8aa3b, v4
	v_exp_f32_e32 v134, v131
	v_mul_f32_e32 v131, 0xbfb8aa3b, v5
	v_exp_f32_e32 v135, v131
	s_nop 0
	v_pk_add_f32 v[134:135], v[134:135], 1.0 op_sel_hi:[1,0]
	s_nop 0
	v_div_scale_f32 v131, s[10:11], v135, v135, 1.0
	v_rcp_f32_e32 v141, v131
	s_nop 0
	v_fma_f32 v143, -v131, v141, 1.0
	v_fmac_f32_e32 v141, v143, v141
	v_div_scale_f32 v143, vcc, 1.0, v135, 1.0
	v_mul_f32_e32 v144, v143, v141
	v_fma_f32 v145, -v131, v144, v143
	v_fmac_f32_e32 v144, v145, v141
	v_fma_f32 v131, -v131, v144, v143
	v_div_fmas_f32 v131, v131, v141, v144
	v_div_fixup_f32 v131, v131, v135, 1.0
	v_div_scale_f32 v135, s[10:11], v134, v134, 1.0
	v_rcp_f32_e32 v141, v135
	s_nop 0
	v_fma_f32 v143, -v135, v141, 1.0
	v_fmac_f32_e32 v141, v143, v141
	v_div_scale_f32 v143, vcc, 1.0, v134, 1.0
	v_mul_f32_e32 v144, v143, v141
	v_fma_f32 v145, -v135, v144, v143
	v_fmac_f32_e32 v144, v145, v141
	v_fma_f32 v135, -v135, v144, v143
	v_div_fmas_f32 v135, v135, v141, v144
	v_div_fixup_f32 v134, v135, v134, 1.0
	v_cvt_pk_bf16_f32 v143, v134, v131
	v_lshlrev_b64 v[134:135], 13, v[132:133]
	v_lshlrev_b32_e32 v132, 3, v1
	v_mov_b32_e32 v133, v179
	v_lshl_add_u64 v[134:135], s[0:1], 0, v[134:135]
	v_lshl_add_u64 v[134:135], v[134:135], 0, v[132:133]
	v_mul_f32_e32 v131, 0xbfb8aa3b, v6
	global_store_dwordx2 v[134:135], v[142:143], off
	v_exp_f32_e32 v142, v131
	v_mul_f32_e32 v131, 0xbfb8aa3b, v7
	v_exp_f32_e32 v143, v131
	s_nop 0
	v_pk_add_f32 v[142:143], v[142:143], 1.0 op_sel_hi:[1,0]
	s_nop 0
	v_div_scale_f32 v131, s[10:11], v143, v143, 1.0
	v_rcp_f32_e32 v141, v131
	s_nop 0
	v_fma_f32 v144, -v131, v141, 1.0
	v_fmac_f32_e32 v141, v144, v141
	v_div_scale_f32 v144, vcc, 1.0, v143, 1.0
	v_mul_f32_e32 v145, v144, v141
	s_waitcnt vmcnt(4)
; DI unsigned pack2(float a, float b) { fl2_t f = {a, b}; bf2_t r = __builtin_convertvector(f, bf2_t); return __builtin_bit_cast(unsigned, r); }
; DI float sigmoidf_(float x) { return 1.f / (1.f + __expf(-x)); }
; DI void g1_phase(const P& p, int l, unsigned char* lds) {
;     ...
;       for (int mt = 0; mt < 4; ++mt) {
;         const int wave2 = (2 * wm + (mt >> 1)) * 2 + wn2, mt2 = mt & 1;
; #pragma unroll
;         for (int nt = 0; nt < 2; ++nt)
; #pragma unroll
;           for (int g4 = 0; g4 < 4; ++g4) {
;             size_t idx = ((((((size_t)tm_ * 8 + tn2) * 8 + wave2) * 2 + mt2) * 2 + nt) * 4 + g4) * 64 + lane;
;             *(uint2*)(gf + idx * 4) = make_uint2(pack2(sigmoidf_(acc[mt][nt][4 * g4]), sigmoidf_(acc[mt][nt][4 * g4 + 1])),
;                                                  pack2(sigmoidf_(acc[mt][nt][4 * g4 + 2]), sigmoidf_(acc[mt][nt][4 * g4 + 3])));
	v_fma_f32 v146, -v131, v145, v144
	v_fmac_f32_e32 v145, v146, v141
	v_fma_f32 v131, -v131, v145, v144
	v_div_fmas_f32 v131, v131, v141, v145
	v_div_scale_f32 v141, s[10:11], v142, v142, 1.0
	v_div_fixup_f32 v131, v131, v143, 1.0
	v_rcp_f32_e32 v143, v141
	s_nop 0
	v_fma_f32 v144, -v141, v143, 1.0
	v_fmac_f32_e32 v143, v144, v143
	v_div_scale_f32 v144, vcc, 1.0, v142, 1.0
	v_mul_f32_e32 v145, v144, v143
	v_fma_f32 v146, -v141, v145, v144
	v_fmac_f32_e32 v145, v146, v143
	v_fma_f32 v141, -v141, v145, v144
	v_div_fmas_f32 v141, v141, v143, v145
	v_div_fixup_f32 v141, v141, v142, 1.0
	v_cvt_pk_bf16_f32 v142, v141, v131
	v_mul_f32_e32 v131, 0xbfb8aa3b, v8
	v_exp_f32_e32 v144, v131
	v_mul_f32_e32 v131, 0xbfb8aa3b, v9
	v_exp_f32_e32 v145, v131
	s_nop 0
	v_pk_add_f32 v[144:145], v[144:145], 1.0 op_sel_hi:[1,0]
	s_nop 0
	v_div_scale_f32 v131, s[10:11], v145, v145, 1.0
	v_rcp_f32_e32 v141, v131
	s_nop 0
	v_fma_f32 v143, -v131, v141, 1.0
	v_fmac_f32_e32 v141, v143, v141
	v_div_scale_f32 v143, vcc, 1.0, v145, 1.0
	v_mul_f32_e32 v146, v143, v141
	v_fma_f32 v147, -v131, v146, v143
	v_fmac_f32_e32 v146, v147, v141
	v_fma_f32 v131, -v131, v146, v143
	v_div_fmas_f32 v131, v131, v141, v146
	v_div_scale_f32 v141, s[10:11], v144, v144, 1.0
	v_rcp_f32_e32 v143, v141
	v_div_fixup_f32 v131, v131, v145, 1.0
	v_fma_f32 v145, -v141, v143, 1.0
	v_fmac_f32_e32 v143, v145, v143
	v_div_scale_f32 v145, vcc, 1.0, v144, 1.0
	v_mul_f32_e32 v146, v145, v143
	v_fma_f32 v147, -v141, v146, v145
	v_fmac_f32_e32 v146, v147, v143
	v_fma_f32 v141, -v141, v146, v145
	v_div_fmas_f32 v141, v141, v143, v146
	v_div_fixup_f32 v141, v141, v144, 1.0
	v_cvt_pk_bf16_f32 v143, v141, v131
	v_mul_f32_e32 v131, 0xbfb8aa3b, v10
	global_store_dwordx2 v[134:135], v[142:143], off offset:512
	v_exp_f32_e32 v142, v131
	v_mul_f32_e32 v131, 0xbfb8aa3b, v11
	v_exp_f32_e32 v143, v131
	s_nop 0
	v_pk_add_f32 v[142:143], v[142:143], 1.0 op_sel_hi:[1,0]
	s_nop 0
	v_div_scale_f32 v131, s[10:11], v143, v143, 1.0
	v_rcp_f32_e32 v141, v131
	s_nop 0
	v_fma_f32 v144, -v131, v141, 1.0
	v_fmac_f32_e32 v141, v144, v141
	v_div_scale_f32 v144, vcc, 1.0, v143, 1.0
	v_mul_f32_e32 v145, v144, v141
	v_fma_f32 v146, -v131, v145, v144
	v_fmac_f32_e32 v145, v146, v141
	v_fma_f32 v131, -v131, v145, v144
	v_div_fmas_f32 v131, v131, v141, v145
	v_div_scale_f32 v141, s[10:11], v142, v142, 1.0
	v_div_fixup_f32 v131, v131, v143, 1.0
	v_rcp_f32_e32 v143, v141
	s_nop 0
	v_fma_f32 v144, -v141, v143, 1.0
	v_fmac_f32_e32 v143, v144, v143
	v_div_scale_f32 v144, vcc, 1.0, v142, 1.0
	v_mul_f32_e32 v145, v144, v143
	v_fma_f32 v146, -v141, v145, v144
	v_fmac_f32_e32 v145, v146, v143
	v_fma_f32 v141, -v141, v145, v144
	v_div_fmas_f32 v141, v141, v143, v145
	v_div_fixup_f32 v141, v141, v142, 1.0
	v_cvt_pk_bf16_f32 v142, v141, v131
	v_mul_f32_e32 v131, 0xbfb8aa3b, v12
	v_exp_f32_e32 v144, v131
	v_mul_f32_e32 v131, 0xbfb8aa3b, v13
	v_exp_f32_e32 v145, v131
	s_nop 0
	v_pk_add_f32 v[144:145], v[144:145], 1.0 op_sel_hi:[1,0]
	s_nop 0
	v_div_scale_f32 v131, s[10:11], v145, v145, 1.0
	v_rcp_f32_e32 v141, v131
	s_nop 0
	v_fma_f32 v143, -v131, v141, 1.0
	v_fmac_f32_e32 v141, v143, v141
	v_div_scale_f32 v143, vcc, 1.0, v145, 1.0
	v_mul_f32_e32 v146, v143, v141
	v_fma_f32 v147, -v131, v146, v143
	v_fmac_f32_e32 v146, v147, v141
	v_fma_f32 v131, -v131, v146, v143
	v_div_fmas_f32 v131, v131, v141, v146
	v_div_scale_f32 v141, s[10:11], v144, v144, 1.0
	v_rcp_f32_e32 v143, v141
	v_div_fixup_f32 v131, v131, v145, 1.0
	v_fma_f32 v145, -v141, v143, 1.0
	v_fmac_f32_e32 v143, v145, v143
	v_div_scale_f32 v145, vcc, 1.0, v144, 1.0
	v_mul_f32_e32 v146, v145, v143
	v_fma_f32 v147, -v141, v146, v145
	v_fmac_f32_e32 v146, v147, v143
	v_fma_f32 v141, -v141, v146, v145
	v_div_fmas_f32 v141, v141, v143, v146
	v_div_fixup_f32 v141, v141, v144, 1.0
	v_cvt_pk_bf16_f32 v143, v141, v131
	v_mul_f32_e32 v131, 0xbfb8aa3b, v14
	global_store_dwordx2 v[134:135], v[142:143], off offset:1024
	v_exp_f32_e32 v142, v131
	v_mul_f32_e32 v131, 0xbfb8aa3b, v15
	v_exp_f32_e32 v143, v131
	s_nop 0
	v_pk_add_f32 v[142:143], v[142:143], 1.0 op_sel_hi:[1,0]
	s_nop 0
	v_div_scale_f32 v131, s[10:11], v143, v143, 1.0
	v_rcp_f32_e32 v141, v131
	s_nop 0
	v_fma_f32 v144, -v131, v141, 1.0
	v_fmac_f32_e32 v141, v144, v141
	v_div_scale_f32 v144, vcc, 1.0, v143, 1.0
	v_mul_f32_e32 v145, v144, v141
	v_fma_f32 v146, -v131, v145, v144
	v_fmac_f32_e32 v145, v146, v141
	v_fma_f32 v131, -v131, v145, v144
	v_div_fmas_f32 v131, v131, v141, v145
	v_div_scale_f32 v141, s[10:11], v142, v142, 1.0
	v_div_fixup_f32 v131, v131, v143, 1.0
	v_rcp_f32_e32 v143, v141
	s_nop 0
	v_fma_f32 v144, -v141, v143, 1.0
	v_fmac_f32_e32 v143, v144, v143
	v_div_scale_f32 v144, vcc, 1.0, v142, 1.0
	v_mul_f32_e32 v145, v144, v143
	v_fma_f32 v146, -v141, v145, v144
	v_fmac_f32_e32 v145, v146, v143
	v_fma_f32 v141, -v141, v145, v144
	v_div_fmas_f32 v141, v141, v143, v145
	v_div_fixup_f32 v141, v141, v142, 1.0
	v_cvt_pk_bf16_f32 v142, v141, v131
	v_mul_f32_e32 v131, 0xbfb8aa3b, v16
	v_exp_f32_e32 v144, v131
	v_mul_f32_e32 v131, 0xbfb8aa3b, v17
	v_exp_f32_e32 v145, v131
	s_nop 0
	v_pk_add_f32 v[144:145], v[144:145], 1.0 op_sel_hi:[1,0]
	s_nop 0
	v_div_scale_f32 v131, s[10:11], v145, v145, 1.0
	v_rcp_f32_e32 v141, v131
	s_nop 0
	v_fma_f32 v143, -v131, v141, 1.0
	v_fmac_f32_e32 v141, v143, v141
	v_div_scale_f32 v143, vcc, 1.0, v145, 1.0
	v_mul_f32_e32 v146, v143, v141
	v_fma_f32 v147, -v131, v146, v143
	v_fmac_f32_e32 v146, v147, v141
	v_fma_f32 v131, -v131, v146, v143
	v_div_fmas_f32 v131, v131, v141, v146
	v_div_scale_f32 v141, s[10:11], v144, v144, 1.0
	v_rcp_f32_e32 v143, v141
	v_div_fixup_f32 v131, v131, v145, 1.0
	v_fma_f32 v145, -v141, v143, 1.0
; DI unsigned pack2(float a, float b) { fl2_t f = {a, b}; bf2_t r = __builtin_convertvector(f, bf2_t); return __builtin_bit_cast(unsigned, r); }
; DI float sigmoidf_(float x) { return 1.f / (1.f + __expf(-x)); }
; DI void g1_phase(const P& p, int l, unsigned char* lds) {
;     ...
;       for (int mt = 0; mt < 4; ++mt) {
;         const int wave2 = (2 * wm + (mt >> 1)) * 2 + wn2, mt2 = mt & 1;
; #pragma unroll
;         for (int nt = 0; nt < 2; ++nt)
; #pragma unroll
;           for (int g4 = 0; g4 < 4; ++g4) {
;             size_t idx = ((((((size_t)tm_ * 8 + tn2) * 8 + wave2) * 2 + mt2) * 2 + nt) * 4 + g4) * 64 + lane;
;             *(uint2*)(gf + idx * 4) = make_uint2(pack2(sigmoidf_(acc[mt][nt][4 * g4]), sigmoidf_(acc[mt][nt][4 * g4 + 1])),
;                                                  pack2(sigmoidf_(acc[mt][nt][4 * g4 + 2]), sigmoidf_(acc[mt][nt][4 * g4 + 3])));
	v_fmac_f32_e32 v143, v145, v143
	v_div_scale_f32 v145, vcc, 1.0, v144, 1.0
	v_mul_f32_e32 v146, v145, v143
	v_fma_f32 v147, -v141, v146, v145
	v_fmac_f32_e32 v146, v147, v143
	v_fma_f32 v141, -v141, v146, v145
	v_div_fmas_f32 v141, v141, v143, v146
	v_div_fixup_f32 v141, v141, v144, 1.0
	v_cvt_pk_bf16_f32 v143, v141, v131
	v_mul_f32_e32 v131, 0xbfb8aa3b, v18
	global_store_dwordx2 v[134:135], v[142:143], off offset:1536
	v_exp_f32_e32 v142, v131
	v_mul_f32_e32 v131, 0xbfb8aa3b, v19
	v_exp_f32_e32 v143, v131
	s_nop 0
	v_pk_add_f32 v[142:143], v[142:143], 1.0 op_sel_hi:[1,0]
	s_nop 0
	v_div_scale_f32 v131, s[10:11], v143, v143, 1.0
	v_rcp_f32_e32 v141, v131
	s_nop 0
	v_fma_f32 v144, -v131, v141, 1.0
	v_fmac_f32_e32 v141, v144, v141
	v_div_scale_f32 v144, vcc, 1.0, v143, 1.0
	v_mul_f32_e32 v145, v144, v141
	v_fma_f32 v146, -v131, v145, v144
	v_fmac_f32_e32 v145, v146, v141
	v_fma_f32 v131, -v131, v145, v144
	v_div_fmas_f32 v131, v131, v141, v145
	v_div_scale_f32 v141, s[10:11], v142, v142, 1.0
	v_div_fixup_f32 v131, v131, v143, 1.0
	v_rcp_f32_e32 v143, v141
	s_nop 0
	v_fma_f32 v144, -v141, v143, 1.0
	v_fmac_f32_e32 v143, v144, v143
	v_div_scale_f32 v144, vcc, 1.0, v142, 1.0
	v_mul_f32_e32 v145, v144, v143
	v_fma_f32 v146, -v141, v145, v144
	v_fmac_f32_e32 v145, v146, v143
	v_fma_f32 v141, -v141, v145, v144
	v_div_fmas_f32 v141, v141, v143, v145
	v_div_fixup_f32 v141, v141, v142, 1.0
	v_cvt_pk_bf16_f32 v142, v141, v131
	v_mul_f32_e32 v131, 0xbfb8aa3b, v20
	v_exp_f32_e32 v144, v131
	v_mul_f32_e32 v131, 0xbfb8aa3b, v21
	v_exp_f32_e32 v145, v131
	s_nop 0
	v_pk_add_f32 v[144:145], v[144:145], 1.0 op_sel_hi:[1,0]
	s_nop 0
	v_div_scale_f32 v131, s[10:11], v145, v145, 1.0
	v_rcp_f32_e32 v141, v131
	s_nop 0
	v_fma_f32 v143, -v131, v141, 1.0
	v_fmac_f32_e32 v141, v143, v141
	v_div_scale_f32 v143, vcc, 1.0, v145, 1.0
	v_mul_f32_e32 v146, v143, v141
	v_fma_f32 v147, -v131, v146, v143
	v_fmac_f32_e32 v146, v147, v141
	v_fma_f32 v131, -v131, v146, v143
	v_div_fmas_f32 v131, v131, v141, v146
	v_div_scale_f32 v141, s[10:11], v144, v144, 1.0
	v_rcp_f32_e32 v143, v141
	v_div_fixup_f32 v131, v131, v145, 1.0
	v_fma_f32 v145, -v141, v143, 1.0
	v_fmac_f32_e32 v143, v145, v143
	v_div_scale_f32 v145, vcc, 1.0, v144, 1.0
	v_mul_f32_e32 v146, v145, v143
	v_fma_f32 v147, -v141, v146, v145
	v_fmac_f32_e32 v146, v147, v143
	v_fma_f32 v141, -v141, v146, v145
	v_div_fmas_f32 v141, v141, v143, v146
	v_div_fixup_f32 v141, v141, v144, 1.0
	v_cvt_pk_bf16_f32 v143, v141, v131
	v_mul_f32_e32 v131, 0xbfb8aa3b, v22
	global_store_dwordx2 v[134:135], v[142:143], off offset:2048
	v_exp_f32_e32 v142, v131
	v_mul_f32_e32 v131, 0xbfb8aa3b, v23
	v_exp_f32_e32 v143, v131
	s_nop 0
	v_pk_add_f32 v[142:143], v[142:143], 1.0 op_sel_hi:[1,0]
	s_nop 0
	v_div_scale_f32 v131, s[10:11], v143, v143, 1.0
	v_rcp_f32_e32 v141, v131
	s_nop 0
	v_fma_f32 v144, -v131, v141, 1.0
	v_fmac_f32_e32 v141, v144, v141
	v_div_scale_f32 v144, vcc, 1.0, v143, 1.0
	v_mul_f32_e32 v145, v144, v141
	v_fma_f32 v146, -v131, v145, v144
	v_fmac_f32_e32 v145, v146, v141
	v_fma_f32 v131, -v131, v145, v144
	v_div_fmas_f32 v131, v131, v141, v145
	v_div_scale_f32 v141, s[10:11], v142, v142, 1.0
	v_div_fixup_f32 v131, v131, v143, 1.0
	v_rcp_f32_e32 v143, v141
	s_nop 0
	v_fma_f32 v144, -v141, v143, 1.0
	v_fmac_f32_e32 v143, v144, v143
	v_div_scale_f32 v144, vcc, 1.0, v142, 1.0
	v_mul_f32_e32 v145, v144, v143
	v_fma_f32 v146, -v141, v145, v144
	v_fmac_f32_e32 v145, v146, v143
	v_fma_f32 v141, -v141, v145, v144
	v_div_fmas_f32 v141, v141, v143, v145
	v_div_fixup_f32 v141, v141, v142, 1.0
	v_cvt_pk_bf16_f32 v142, v141, v131
	v_mul_f32_e32 v131, 0xbfb8aa3b, v24
	v_exp_f32_e32 v144, v131
	v_mul_f32_e32 v131, 0xbfb8aa3b, v25
	v_exp_f32_e32 v145, v131
	s_nop 0
	v_pk_add_f32 v[144:145], v[144:145], 1.0 op_sel_hi:[1,0]
	s_nop 0
	v_div_scale_f32 v131, s[10:11], v145, v145, 1.0
	v_rcp_f32_e32 v141, v131
	s_nop 0
	v_fma_f32 v143, -v131, v141, 1.0
	v_fmac_f32_e32 v141, v143, v141
	v_div_scale_f32 v143, vcc, 1.0, v145, 1.0
	v_mul_f32_e32 v146, v143, v141
	v_fma_f32 v147, -v131, v146, v143
	v_fmac_f32_e32 v146, v147, v141
	v_fma_f32 v131, -v131, v146, v143
	v_div_fmas_f32 v131, v131, v141, v146
	v_div_scale_f32 v141, s[10:11], v144, v144, 1.0
	v_rcp_f32_e32 v143, v141
	v_div_fixup_f32 v131, v131, v145, 1.0
	v_fma_f32 v145, -v141, v143, 1.0
	v_fmac_f32_e32 v143, v145, v143
	v_div_scale_f32 v145, vcc, 1.0, v144, 1.0
	v_mul_f32_e32 v146, v145, v143
	v_fma_f32 v147, -v141, v146, v145
	v_fmac_f32_e32 v146, v147, v143
	v_fma_f32 v141, -v141, v146, v145
	v_div_fmas_f32 v141, v141, v143, v146
	v_div_fixup_f32 v141, v141, v144, 1.0
	v_cvt_pk_bf16_f32 v143, v141, v131
	v_mul_f32_e32 v131, 0xbfb8aa3b, v26
	global_store_dwordx2 v[134:135], v[142:143], off offset:2560
	v_exp_f32_e32 v142, v131
	v_mul_f32_e32 v131, 0xbfb8aa3b, v27
	v_exp_f32_e32 v143, v131
	s_nop 0
	v_pk_add_f32 v[142:143], v[142:143], 1.0 op_sel_hi:[1,0]
	s_nop 0
	v_div_scale_f32 v131, s[10:11], v143, v143, 1.0
	v_rcp_f32_e32 v141, v131
	s_nop 0
	v_fma_f32 v144, -v131, v141, 1.0
	v_fmac_f32_e32 v141, v144, v141
	v_div_scale_f32 v144, vcc, 1.0, v143, 1.0
	v_mul_f32_e32 v145, v144, v141
	v_fma_f32 v146, -v131, v145, v144
	v_fmac_f32_e32 v145, v146, v141
	v_fma_f32 v131, -v131, v145, v144
	v_div_fmas_f32 v131, v131, v141, v145
	v_div_scale_f32 v141, s[10:11], v142, v142, 1.0
	v_div_fixup_f32 v131, v131, v143, 1.0
	v_rcp_f32_e32 v143, v141
	s_nop 0
	v_fma_f32 v144, -v141, v143, 1.0
	v_fmac_f32_e32 v143, v144, v143
	v_div_scale_f32 v144, vcc, 1.0, v142, 1.0
	v_mul_f32_e32 v145, v144, v143
	v_fma_f32 v146, -v141, v145, v144
	v_fmac_f32_e32 v145, v146, v143
	v_fma_f32 v141, -v141, v145, v144
; DI unsigned pack2(float a, float b) { fl2_t f = {a, b}; bf2_t r = __builtin_convertvector(f, bf2_t); return __builtin_bit_cast(unsigned, r); }
; DI float sigmoidf_(float x) { return 1.f / (1.f + __expf(-x)); }
; DI void g1_phase(const P& p, int l, unsigned char* lds) {
;     ...
;       for (int mt = 0; mt < 4; ++mt) {
;         const int wave2 = (2 * wm + (mt >> 1)) * 2 + wn2, mt2 = mt & 1;
; #pragma unroll
;         for (int nt = 0; nt < 2; ++nt)
; #pragma unroll
;           for (int g4 = 0; g4 < 4; ++g4) {
;             size_t idx = ((((((size_t)tm_ * 8 + tn2) * 8 + wave2) * 2 + mt2) * 2 + nt) * 4 + g4) * 64 + lane;
;             *(uint2*)(gf + idx * 4) = make_uint2(pack2(sigmoidf_(acc[mt][nt][4 * g4]), sigmoidf_(acc[mt][nt][4 * g4 + 1])),
;                                                  pack2(sigmoidf_(acc[mt][nt][4 * g4 + 2]), sigmoidf_(acc[mt][nt][4 * g4 + 3])));
	v_div_fmas_f32 v141, v141, v143, v145
	v_div_fixup_f32 v141, v141, v142, 1.0
	v_cvt_pk_bf16_f32 v142, v141, v131
	v_mul_f32_e32 v131, 0xbfb8aa3b, v28
	v_exp_f32_e32 v144, v131
	v_mul_f32_e32 v131, 0xbfb8aa3b, v29
	v_exp_f32_e32 v145, v131
	s_nop 0
	v_pk_add_f32 v[144:145], v[144:145], 1.0 op_sel_hi:[1,0]
	s_nop 0
	v_div_scale_f32 v131, s[10:11], v145, v145, 1.0
	v_rcp_f32_e32 v141, v131
	s_nop 0
	v_fma_f32 v143, -v131, v141, 1.0
	v_fmac_f32_e32 v141, v143, v141
	v_div_scale_f32 v143, vcc, 1.0, v145, 1.0
	v_mul_f32_e32 v146, v143, v141
	v_fma_f32 v147, -v131, v146, v143
	v_fmac_f32_e32 v146, v147, v141
	v_fma_f32 v131, -v131, v146, v143
	v_div_fmas_f32 v131, v131, v141, v146
	v_div_scale_f32 v141, s[10:11], v144, v144, 1.0
	v_rcp_f32_e32 v143, v141
	v_div_fixup_f32 v131, v131, v145, 1.0
	v_fma_f32 v145, -v141, v143, 1.0
	v_fmac_f32_e32 v143, v145, v143
	v_div_scale_f32 v145, vcc, 1.0, v144, 1.0
	v_mul_f32_e32 v146, v145, v143
	v_fma_f32 v147, -v141, v146, v145
	v_fmac_f32_e32 v146, v147, v143
	v_fma_f32 v141, -v141, v146, v145
	v_div_fmas_f32 v141, v141, v143, v146
	v_div_fixup_f32 v141, v141, v144, 1.0
	v_cvt_pk_bf16_f32 v143, v141, v131
	v_mul_f32_e32 v131, 0xbfb8aa3b, v30
	global_store_dwordx2 v[134:135], v[142:143], off offset:3072
	v_exp_f32_e32 v142, v131
	v_mul_f32_e32 v131, 0xbfb8aa3b, v31
	v_exp_f32_e32 v143, v131
	s_nop 0
	v_pk_add_f32 v[142:143], v[142:143], 1.0 op_sel_hi:[1,0]
	s_nop 0
	v_div_scale_f32 v131, s[10:11], v143, v143, 1.0
	v_rcp_f32_e32 v141, v131
	s_nop 0
	v_fma_f32 v144, -v131, v141, 1.0
	v_fmac_f32_e32 v141, v144, v141
	v_div_scale_f32 v144, vcc, 1.0, v143, 1.0
	v_mul_f32_e32 v145, v144, v141
	v_fma_f32 v146, -v131, v145, v144
	v_fmac_f32_e32 v145, v146, v141
	v_fma_f32 v131, -v131, v145, v144
	v_div_fmas_f32 v131, v131, v141, v145
	v_div_scale_f32 v141, s[10:11], v142, v142, 1.0
	v_div_fixup_f32 v131, v131, v143, 1.0
	v_rcp_f32_e32 v143, v141
	s_nop 0
	v_fma_f32 v144, -v141, v143, 1.0
	v_fmac_f32_e32 v143, v144, v143
	v_div_scale_f32 v144, vcc, 1.0, v142, 1.0
	v_mul_f32_e32 v145, v144, v143
	v_fma_f32 v146, -v141, v145, v144
	v_fmac_f32_e32 v145, v146, v143
	v_fma_f32 v141, -v141, v145, v144
	v_div_fmas_f32 v141, v141, v143, v145
	v_div_fixup_f32 v141, v141, v142, 1.0
	v_cvt_pk_bf16_f32 v142, v141, v131
	v_mul_f32_e32 v131, 0xbfb8aa3b, v32
	v_exp_f32_e32 v144, v131
	v_mul_f32_e32 v131, 0xbfb8aa3b, v33
	v_exp_f32_e32 v145, v131
	s_nop 0
	v_pk_add_f32 v[144:145], v[144:145], 1.0 op_sel_hi:[1,0]
	s_nop 0
	v_div_scale_f32 v131, s[10:11], v145, v145, 1.0
	v_rcp_f32_e32 v141, v131
	s_nop 0
	v_fma_f32 v143, -v131, v141, 1.0
	v_fmac_f32_e32 v141, v143, v141
	v_div_scale_f32 v143, vcc, 1.0, v145, 1.0
	v_mul_f32_e32 v146, v143, v141
	v_fma_f32 v147, -v131, v146, v143
	v_fmac_f32_e32 v146, v147, v141
	v_fma_f32 v131, -v131, v146, v143
	v_div_fmas_f32 v131, v131, v141, v146
	v_div_scale_f32 v141, s[10:11], v144, v144, 1.0
	v_rcp_f32_e32 v143, v141
	v_div_fixup_f32 v131, v131, v145, 1.0
	v_fma_f32 v145, -v141, v143, 1.0
	v_fmac_f32_e32 v143, v145, v143
	v_div_scale_f32 v145, vcc, 1.0, v144, 1.0
	v_mul_f32_e32 v146, v145, v143
	v_fma_f32 v147, -v141, v146, v145
	v_fmac_f32_e32 v146, v147, v143
	v_fma_f32 v141, -v141, v146, v145
	v_div_fmas_f32 v141, v141, v143, v146
	v_div_fixup_f32 v141, v141, v144, 1.0
	v_cvt_pk_bf16_f32 v143, v141, v131
	v_mul_f32_e32 v131, 0xbfb8aa3b, v34
	global_store_dwordx2 v[134:135], v[142:143], off offset:3584
	v_exp_f32_e32 v142, v131
	v_mul_f32_e32 v131, 0xbfb8aa3b, v35
	v_exp_f32_e32 v143, v131
	s_nop 0
	v_pk_add_f32 v[142:143], v[142:143], 1.0 op_sel_hi:[1,0]
	s_nop 0
	v_div_scale_f32 v131, s[10:11], v143, v143, 1.0
	v_rcp_f32_e32 v141, v131
	s_nop 0
	v_fma_f32 v144, -v131, v141, 1.0
	v_fmac_f32_e32 v141, v144, v141
	v_div_scale_f32 v144, vcc, 1.0, v143, 1.0
	v_mul_f32_e32 v145, v144, v141
	v_fma_f32 v146, -v131, v145, v144
	v_fmac_f32_e32 v145, v146, v141
	v_fma_f32 v131, -v131, v145, v144
	v_div_fmas_f32 v131, v131, v141, v145
	v_div_scale_f32 v141, s[10:11], v142, v142, 1.0
	v_div_fixup_f32 v131, v131, v143, 1.0
	v_rcp_f32_e32 v143, v141
	s_nop 0
	v_fma_f32 v144, -v141, v143, 1.0
	v_fmac_f32_e32 v143, v144, v143
	v_div_scale_f32 v144, vcc, 1.0, v142, 1.0
	v_mul_f32_e32 v145, v144, v143
	v_fma_f32 v146, -v141, v145, v144
	v_fmac_f32_e32 v145, v146, v143
	v_fma_f32 v141, -v141, v145, v144
	v_div_fmas_f32 v141, v141, v143, v145
	v_div_fixup_f32 v141, v141, v142, 1.0
	v_cvt_pk_bf16_f32 v142, v141, v131
	v_mul_f32_e32 v131, 0xbfb8aa3b, v36
	v_exp_f32_e32 v144, v131
	v_mul_f32_e32 v131, 0xbfb8aa3b, v37
	v_exp_f32_e32 v145, v131
	s_nop 0
	v_pk_add_f32 v[144:145], v[144:145], 1.0 op_sel_hi:[1,0]
	s_nop 0
	v_div_scale_f32 v131, s[10:11], v145, v145, 1.0
	v_rcp_f32_e32 v141, v131
	s_nop 0
	v_fma_f32 v143, -v131, v141, 1.0
	v_fmac_f32_e32 v141, v143, v141
	v_div_scale_f32 v143, vcc, 1.0, v145, 1.0
	v_mul_f32_e32 v146, v143, v141
	v_fma_f32 v147, -v131, v146, v143
	v_fmac_f32_e32 v146, v147, v141
	v_fma_f32 v131, -v131, v146, v143
	v_div_fmas_f32 v131, v131, v141, v146
	v_div_scale_f32 v141, s[10:11], v144, v144, 1.0
	v_rcp_f32_e32 v143, v141
	v_div_fixup_f32 v131, v131, v145, 1.0
	v_fma_f32 v145, -v141, v143, 1.0
	v_fmac_f32_e32 v143, v145, v143
	v_div_scale_f32 v145, vcc, 1.0, v144, 1.0
	v_mul_f32_e32 v146, v145, v143
	v_fma_f32 v147, -v141, v146, v145
	v_fmac_f32_e32 v146, v147, v143
	v_fma_f32 v141, -v141, v146, v145
	v_div_fmas_f32 v141, v141, v143, v146
	v_div_fixup_f32 v141, v141, v144, 1.0
	v_add_co_u32_e32 v134, vcc, s46, v134
	v_cvt_pk_bf16_f32 v143, v141, v131
	s_nop 0
	v_addc_co_u32_e32 v135, vcc, 0, v135, vcc
	v_mul_f32_e32 v131, 0xbfb8aa3b, v38
	global_store_dwordx2 v[134:135], v[142:143], off
; DI unsigned pack2(float a, float b) { fl2_t f = {a, b}; bf2_t r = __builtin_convertvector(f, bf2_t); return __builtin_bit_cast(unsigned, r); }
; DI float sigmoidf_(float x) { return 1.f / (1.f + __expf(-x)); }
; DI void g1_phase(const P& p, int l, unsigned char* lds) {
;     ...
;       for (int mt = 0; mt < 4; ++mt) {
;         const int wave2 = (2 * wm + (mt >> 1)) * 2 + wn2, mt2 = mt & 1;
; #pragma unroll
;         for (int nt = 0; nt < 2; ++nt)
; #pragma unroll
;           for (int g4 = 0; g4 < 4; ++g4) {
;             size_t idx = ((((((size_t)tm_ * 8 + tn2) * 8 + wave2) * 2 + mt2) * 2 + nt) * 4 + g4) * 64 + lane;
;             *(uint2*)(gf + idx * 4) = make_uint2(pack2(sigmoidf_(acc[mt][nt][4 * g4]), sigmoidf_(acc[mt][nt][4 * g4 + 1])),
;                                                  pack2(sigmoidf_(acc[mt][nt][4 * g4 + 2]), sigmoidf_(acc[mt][nt][4 * g4 + 3])));
	v_exp_f32_e32 v142, v131
	v_mul_f32_e32 v131, 0xbfb8aa3b, v39
	v_exp_f32_e32 v143, v131
	s_nop 0
	v_pk_add_f32 v[142:143], v[142:143], 1.0 op_sel_hi:[1,0]
	s_nop 0
	v_div_scale_f32 v131, s[10:11], v143, v143, 1.0
	v_rcp_f32_e32 v141, v131
	s_nop 0
	v_fma_f32 v144, -v131, v141, 1.0
	v_fmac_f32_e32 v141, v144, v141
	v_div_scale_f32 v144, vcc, 1.0, v143, 1.0
	v_mul_f32_e32 v145, v144, v141
	v_fma_f32 v146, -v131, v145, v144
	v_fmac_f32_e32 v145, v146, v141
	v_fma_f32 v131, -v131, v145, v144
	v_div_fmas_f32 v131, v131, v141, v145
	v_div_scale_f32 v141, s[10:11], v142, v142, 1.0
	v_div_fixup_f32 v131, v131, v143, 1.0
	v_rcp_f32_e32 v143, v141
	s_nop 0
	v_fma_f32 v144, -v141, v143, 1.0
	v_fmac_f32_e32 v143, v144, v143
	v_div_scale_f32 v144, vcc, 1.0, v142, 1.0
	v_mul_f32_e32 v145, v144, v143
	v_fma_f32 v146, -v141, v145, v144
	v_fmac_f32_e32 v145, v146, v143
	v_fma_f32 v141, -v141, v145, v144
	v_div_fmas_f32 v141, v141, v143, v145
	v_div_fixup_f32 v141, v141, v142, 1.0
	v_cvt_pk_bf16_f32 v142, v141, v131
	v_mul_f32_e32 v131, 0xbfb8aa3b, v40
	v_exp_f32_e32 v144, v131
	v_mul_f32_e32 v131, 0xbfb8aa3b, v41
	v_exp_f32_e32 v145, v131
	s_nop 0
	v_pk_add_f32 v[144:145], v[144:145], 1.0 op_sel_hi:[1,0]
	s_nop 0
	v_div_scale_f32 v131, s[10:11], v145, v145, 1.0
	v_rcp_f32_e32 v141, v131
	s_nop 0
	v_fma_f32 v143, -v131, v141, 1.0
	v_fmac_f32_e32 v141, v143, v141
	v_div_scale_f32 v143, vcc, 1.0, v145, 1.0
	v_mul_f32_e32 v146, v143, v141
	v_fma_f32 v147, -v131, v146, v143
	v_fmac_f32_e32 v146, v147, v141
	v_fma_f32 v131, -v131, v146, v143
	v_div_fmas_f32 v131, v131, v141, v146
	v_div_scale_f32 v141, s[10:11], v144, v144, 1.0
	v_rcp_f32_e32 v143, v141
	v_div_fixup_f32 v131, v131, v145, 1.0
	v_fma_f32 v145, -v141, v143, 1.0
	v_fmac_f32_e32 v143, v145, v143
	v_div_scale_f32 v145, vcc, 1.0, v144, 1.0
	v_mul_f32_e32 v146, v145, v143
	v_fma_f32 v147, -v141, v146, v145
	v_fmac_f32_e32 v146, v147, v143
	v_fma_f32 v141, -v141, v146, v145
	v_div_fmas_f32 v141, v141, v143, v146
	v_div_fixup_f32 v141, v141, v144, 1.0
	v_cvt_pk_bf16_f32 v143, v141, v131
	v_mul_f32_e32 v131, 0xbfb8aa3b, v42
	global_store_dwordx2 v[134:135], v[142:143], off offset:512
	v_exp_f32_e32 v142, v131
	v_mul_f32_e32 v131, 0xbfb8aa3b, v43
	v_exp_f32_e32 v143, v131
	s_nop 0
	v_pk_add_f32 v[142:143], v[142:143], 1.0 op_sel_hi:[1,0]
	s_nop 0
	v_div_scale_f32 v131, s[10:11], v143, v143, 1.0
	v_rcp_f32_e32 v141, v131
	s_nop 0
	v_fma_f32 v144, -v131, v141, 1.0
	v_fmac_f32_e32 v141, v144, v141
	v_div_scale_f32 v144, vcc, 1.0, v143, 1.0
	v_mul_f32_e32 v145, v144, v141
	v_fma_f32 v146, -v131, v145, v144
	v_fmac_f32_e32 v145, v146, v141
	v_fma_f32 v131, -v131, v145, v144
	v_div_fmas_f32 v131, v131, v141, v145
	v_div_scale_f32 v141, s[10:11], v142, v142, 1.0
	v_div_fixup_f32 v131, v131, v143, 1.0
	v_rcp_f32_e32 v143, v141
	s_nop 0
	v_fma_f32 v144, -v141, v143, 1.0
	v_fmac_f32_e32 v143, v144, v143
	v_div_scale_f32 v144, vcc, 1.0, v142, 1.0
	v_mul_f32_e32 v145, v144, v143
	v_fma_f32 v146, -v141, v145, v144
	v_fmac_f32_e32 v145, v146, v143
	v_fma_f32 v141, -v141, v145, v144
	v_div_fmas_f32 v141, v141, v143, v145
	v_div_fixup_f32 v141, v141, v142, 1.0
	v_cvt_pk_bf16_f32 v142, v141, v131
	v_mul_f32_e32 v131, 0xbfb8aa3b, v44
	v_exp_f32_e32 v144, v131
	v_mul_f32_e32 v131, 0xbfb8aa3b, v45
	v_exp_f32_e32 v145, v131
	s_nop 0
	v_pk_add_f32 v[144:145], v[144:145], 1.0 op_sel_hi:[1,0]
	s_nop 0
	v_div_scale_f32 v131, s[10:11], v145, v145, 1.0
	v_rcp_f32_e32 v141, v131
	s_nop 0
	v_fma_f32 v143, -v131, v141, 1.0
	v_fmac_f32_e32 v141, v143, v141
	v_div_scale_f32 v143, vcc, 1.0, v145, 1.0
	v_mul_f32_e32 v146, v143, v141
	v_fma_f32 v147, -v131, v146, v143
	v_fmac_f32_e32 v146, v147, v141
	v_fma_f32 v131, -v131, v146, v143
	v_div_fmas_f32 v131, v131, v141, v146
	v_div_scale_f32 v141, s[10:11], v144, v144, 1.0
	v_rcp_f32_e32 v143, v141
	v_div_fixup_f32 v131, v131, v145, 1.0
	v_fma_f32 v145, -v141, v143, 1.0
	v_fmac_f32_e32 v143, v145, v143
	v_div_scale_f32 v145, vcc, 1.0, v144, 1.0
	v_mul_f32_e32 v146, v145, v143
	v_fma_f32 v147, -v141, v146, v145
	v_fmac_f32_e32 v146, v147, v143
	v_fma_f32 v141, -v141, v146, v145
	v_div_fmas_f32 v141, v141, v143, v146
	v_div_fixup_f32 v141, v141, v144, 1.0
	v_cvt_pk_bf16_f32 v143, v141, v131
	v_mul_f32_e32 v131, 0xbfb8aa3b, v46
	global_store_dwordx2 v[134:135], v[142:143], off offset:1024
	v_exp_f32_e32 v142, v131
	v_mul_f32_e32 v131, 0xbfb8aa3b, v47
	v_exp_f32_e32 v143, v131
	s_nop 0
	v_pk_add_f32 v[142:143], v[142:143], 1.0 op_sel_hi:[1,0]
	s_nop 0
	v_div_scale_f32 v131, s[10:11], v143, v143, 1.0
	v_rcp_f32_e32 v141, v131
	s_nop 0
	v_fma_f32 v144, -v131, v141, 1.0
	v_fmac_f32_e32 v141, v144, v141
	v_div_scale_f32 v144, vcc, 1.0, v143, 1.0
	v_mul_f32_e32 v145, v144, v141
	v_fma_f32 v146, -v131, v145, v144
	v_fmac_f32_e32 v145, v146, v141
	v_fma_f32 v131, -v131, v145, v144
	v_div_fmas_f32 v131, v131, v141, v145
	v_div_scale_f32 v141, s[10:11], v142, v142, 1.0
	v_div_fixup_f32 v131, v131, v143, 1.0
	v_rcp_f32_e32 v143, v141
	s_nop 0
	v_fma_f32 v144, -v141, v143, 1.0
	v_fmac_f32_e32 v143, v144, v143
	v_div_scale_f32 v144, vcc, 1.0, v142, 1.0
	v_mul_f32_e32 v145, v144, v143
	v_fma_f32 v146, -v141, v145, v144
	v_fmac_f32_e32 v145, v146, v143
	v_fma_f32 v141, -v141, v145, v144
	v_div_fmas_f32 v141, v141, v143, v145
	v_div_fixup_f32 v141, v141, v142, 1.0
	v_cvt_pk_bf16_f32 v142, v141, v131
	v_mul_f32_e32 v131, 0xbfb8aa3b, v48
	v_exp_f32_e32 v144, v131
	v_mul_f32_e32 v131, 0xbfb8aa3b, v49
	v_exp_f32_e32 v145, v131
	s_nop 0
	v_pk_add_f32 v[144:145], v[144:145], 1.0 op_sel_hi:[1,0]
	s_nop 0
	v_div_scale_f32 v131, s[10:11], v145, v145, 1.0
	v_rcp_f32_e32 v141, v131
	s_nop 0
	v_fma_f32 v143, -v131, v141, 1.0
; DI unsigned pack2(float a, float b) { fl2_t f = {a, b}; bf2_t r = __builtin_convertvector(f, bf2_t); return __builtin_bit_cast(unsigned, r); }
; DI float sigmoidf_(float x) { return 1.f / (1.f + __expf(-x)); }
; DI void g1_phase(const P& p, int l, unsigned char* lds) {
;     ...
;       for (int mt = 0; mt < 4; ++mt) {
;         const int wave2 = (2 * wm + (mt >> 1)) * 2 + wn2, mt2 = mt & 1;
; #pragma unroll
;         for (int nt = 0; nt < 2; ++nt)
; #pragma unroll
;           for (int g4 = 0; g4 < 4; ++g4) {
;             size_t idx = ((((((size_t)tm_ * 8 + tn2) * 8 + wave2) * 2 + mt2) * 2 + nt) * 4 + g4) * 64 + lane;
;             *(uint2*)(gf + idx * 4) = make_uint2(pack2(sigmoidf_(acc[mt][nt][4 * g4]), sigmoidf_(acc[mt][nt][4 * g4 + 1])),
;                                                  pack2(sigmoidf_(acc[mt][nt][4 * g4 + 2]), sigmoidf_(acc[mt][nt][4 * g4 + 3])));
	v_fmac_f32_e32 v141, v143, v141
	v_div_scale_f32 v143, vcc, 1.0, v145, 1.0
	v_mul_f32_e32 v146, v143, v141
	v_fma_f32 v147, -v131, v146, v143
	v_fmac_f32_e32 v146, v147, v141
	v_fma_f32 v131, -v131, v146, v143
	v_div_fmas_f32 v131, v131, v141, v146
	v_div_scale_f32 v141, s[10:11], v144, v144, 1.0
	v_rcp_f32_e32 v143, v141
	v_div_fixup_f32 v131, v131, v145, 1.0
	v_fma_f32 v145, -v141, v143, 1.0
	v_fmac_f32_e32 v143, v145, v143
	v_div_scale_f32 v145, vcc, 1.0, v144, 1.0
	v_mul_f32_e32 v146, v145, v143
	v_fma_f32 v147, -v141, v146, v145
	v_fmac_f32_e32 v146, v147, v143
	v_fma_f32 v141, -v141, v146, v145
	v_div_fmas_f32 v141, v141, v143, v146
	v_div_fixup_f32 v141, v141, v144, 1.0
	v_cvt_pk_bf16_f32 v143, v141, v131
	v_mul_f32_e32 v131, 0xbfb8aa3b, v50
	global_store_dwordx2 v[134:135], v[142:143], off offset:1536
	v_exp_f32_e32 v142, v131
	v_mul_f32_e32 v131, 0xbfb8aa3b, v51
	v_exp_f32_e32 v143, v131
	s_nop 0
	v_pk_add_f32 v[142:143], v[142:143], 1.0 op_sel_hi:[1,0]
	s_nop 0
	v_div_scale_f32 v131, s[10:11], v143, v143, 1.0
	v_rcp_f32_e32 v141, v131
	s_nop 0
	v_fma_f32 v144, -v131, v141, 1.0
	v_fmac_f32_e32 v141, v144, v141
	v_div_scale_f32 v144, vcc, 1.0, v143, 1.0
	v_mul_f32_e32 v145, v144, v141
	v_fma_f32 v146, -v131, v145, v144
	v_fmac_f32_e32 v145, v146, v141
	v_fma_f32 v131, -v131, v145, v144
	v_div_fmas_f32 v131, v131, v141, v145
	v_div_scale_f32 v141, s[10:11], v142, v142, 1.0
	v_div_fixup_f32 v131, v131, v143, 1.0
	v_rcp_f32_e32 v143, v141
	s_nop 0
	v_fma_f32 v144, -v141, v143, 1.0
	v_fmac_f32_e32 v143, v144, v143
	v_div_scale_f32 v144, vcc, 1.0, v142, 1.0
	v_mul_f32_e32 v145, v144, v143
	v_fma_f32 v146, -v141, v145, v144
	v_fmac_f32_e32 v145, v146, v143
	v_fma_f32 v141, -v141, v145, v144
	v_div_fmas_f32 v141, v141, v143, v145
	v_div_fixup_f32 v141, v141, v142, 1.0
	v_cvt_pk_bf16_f32 v142, v141, v131
	v_mul_f32_e32 v131, 0xbfb8aa3b, v52
	v_exp_f32_e32 v144, v131
	v_mul_f32_e32 v131, 0xbfb8aa3b, v53
	v_exp_f32_e32 v145, v131
	s_nop 0
	v_pk_add_f32 v[144:145], v[144:145], 1.0 op_sel_hi:[1,0]
	s_nop 0
	v_div_scale_f32 v131, s[10:11], v145, v145, 1.0
	v_rcp_f32_e32 v141, v131
	s_nop 0
	v_fma_f32 v143, -v131, v141, 1.0
	v_fmac_f32_e32 v141, v143, v141
	v_div_scale_f32 v143, vcc, 1.0, v145, 1.0
	v_mul_f32_e32 v146, v143, v141
	v_fma_f32 v147, -v131, v146, v143
	v_fmac_f32_e32 v146, v147, v141
	v_fma_f32 v131, -v131, v146, v143
	v_div_fmas_f32 v131, v131, v141, v146
	v_div_scale_f32 v141, s[10:11], v144, v144, 1.0
	v_rcp_f32_e32 v143, v141
	v_div_fixup_f32 v131, v131, v145, 1.0
	v_fma_f32 v145, -v141, v143, 1.0
	v_fmac_f32_e32 v143, v145, v143
	v_div_scale_f32 v145, vcc, 1.0, v144, 1.0
	v_mul_f32_e32 v146, v145, v143
	v_fma_f32 v147, -v141, v146, v145
	v_fmac_f32_e32 v146, v147, v143
	v_fma_f32 v141, -v141, v146, v145
	v_div_fmas_f32 v141, v141, v143, v146
	v_div_fixup_f32 v141, v141, v144, 1.0
	v_cvt_pk_bf16_f32 v143, v141, v131
	v_mul_f32_e32 v131, 0xbfb8aa3b, v54
	global_store_dwordx2 v[134:135], v[142:143], off offset:2048
	v_exp_f32_e32 v142, v131
	v_mul_f32_e32 v131, 0xbfb8aa3b, v55
	v_exp_f32_e32 v143, v131
	s_nop 0
	v_pk_add_f32 v[142:143], v[142:143], 1.0 op_sel_hi:[1,0]
	s_nop 0
	v_div_scale_f32 v131, s[10:11], v143, v143, 1.0
	v_rcp_f32_e32 v141, v131
	s_nop 0
	v_fma_f32 v144, -v131, v141, 1.0
	v_fmac_f32_e32 v141, v144, v141
	v_div_scale_f32 v144, vcc, 1.0, v143, 1.0
	v_mul_f32_e32 v145, v144, v141
	v_fma_f32 v146, -v131, v145, v144
	v_fmac_f32_e32 v145, v146, v141
	v_fma_f32 v131, -v131, v145, v144
	v_div_fmas_f32 v131, v131, v141, v145
	v_div_scale_f32 v141, s[10:11], v142, v142, 1.0
	v_div_fixup_f32 v131, v131, v143, 1.0
	v_rcp_f32_e32 v143, v141
	s_nop 0
	v_fma_f32 v144, -v141, v143, 1.0
	v_fmac_f32_e32 v143, v144, v143
	v_div_scale_f32 v144, vcc, 1.0, v142, 1.0
	v_mul_f32_e32 v145, v144, v143
	v_fma_f32 v146, -v141, v145, v144
	v_fmac_f32_e32 v145, v146, v143
	v_fma_f32 v141, -v141, v145, v144
	v_div_fmas_f32 v141, v141, v143, v145
	v_div_fixup_f32 v141, v141, v142, 1.0
	v_cvt_pk_bf16_f32 v142, v141, v131
	v_mul_f32_e32 v131, 0xbfb8aa3b, v56
	v_exp_f32_e32 v144, v131
	v_mul_f32_e32 v131, 0xbfb8aa3b, v57
	v_exp_f32_e32 v145, v131
	s_nop 0
	v_pk_add_f32 v[144:145], v[144:145], 1.0 op_sel_hi:[1,0]
	s_nop 0
	v_div_scale_f32 v131, s[10:11], v145, v145, 1.0
	v_rcp_f32_e32 v141, v131
	s_nop 0
	v_fma_f32 v143, -v131, v141, 1.0
	v_fmac_f32_e32 v141, v143, v141
	v_div_scale_f32 v143, vcc, 1.0, v145, 1.0
	v_mul_f32_e32 v146, v143, v141
	v_fma_f32 v147, -v131, v146, v143
	v_fmac_f32_e32 v146, v147, v141
	v_fma_f32 v131, -v131, v146, v143
	v_div_fmas_f32 v131, v131, v141, v146
	v_div_scale_f32 v141, s[10:11], v144, v144, 1.0
	v_rcp_f32_e32 v143, v141
	v_div_fixup_f32 v131, v131, v145, 1.0
	v_fma_f32 v145, -v141, v143, 1.0
	v_fmac_f32_e32 v143, v145, v143
	v_div_scale_f32 v145, vcc, 1.0, v144, 1.0
	v_mul_f32_e32 v146, v145, v143
	v_fma_f32 v147, -v141, v146, v145
	v_fmac_f32_e32 v146, v147, v143
	v_fma_f32 v141, -v141, v146, v145
	v_div_fmas_f32 v141, v141, v143, v146
	v_div_fixup_f32 v141, v141, v144, 1.0
	v_cvt_pk_bf16_f32 v143, v141, v131
	v_mul_f32_e32 v131, 0xbfb8aa3b, v58
	global_store_dwordx2 v[134:135], v[142:143], off offset:2560
	v_exp_f32_e32 v142, v131
	v_mul_f32_e32 v131, 0xbfb8aa3b, v59
	v_exp_f32_e32 v143, v131
	s_nop 0
	v_pk_add_f32 v[142:143], v[142:143], 1.0 op_sel_hi:[1,0]
	s_nop 0
	v_div_scale_f32 v131, s[10:11], v143, v143, 1.0
	v_rcp_f32_e32 v141, v131
	s_nop 0
	v_fma_f32 v144, -v131, v141, 1.0
	v_fmac_f32_e32 v141, v144, v141
	v_div_scale_f32 v144, vcc, 1.0, v143, 1.0
	v_mul_f32_e32 v145, v144, v141
	v_fma_f32 v146, -v131, v145, v144
	v_fmac_f32_e32 v145, v146, v141
	v_fma_f32 v131, -v131, v145, v144
; DI unsigned pack2(float a, float b) { fl2_t f = {a, b}; bf2_t r = __builtin_convertvector(f, bf2_t); return __builtin_bit_cast(unsigned, r); }
; DI float sigmoidf_(float x) { return 1.f / (1.f + __expf(-x)); }
; DI void g1_phase(const P& p, int l, unsigned char* lds) {
;     ...
;       for (int mt = 0; mt < 4; ++mt) {
;         const int wave2 = (2 * wm + (mt >> 1)) * 2 + wn2, mt2 = mt & 1;
; #pragma unroll
;         for (int nt = 0; nt < 2; ++nt)
; #pragma unroll
;           for (int g4 = 0; g4 < 4; ++g4) {
;             size_t idx = ((((((size_t)tm_ * 8 + tn2) * 8 + wave2) * 2 + mt2) * 2 + nt) * 4 + g4) * 64 + lane;
;             *(uint2*)(gf + idx * 4) = make_uint2(pack2(sigmoidf_(acc[mt][nt][4 * g4]), sigmoidf_(acc[mt][nt][4 * g4 + 1])),
;                                                  pack2(sigmoidf_(acc[mt][nt][4 * g4 + 2]), sigmoidf_(acc[mt][nt][4 * g4 + 3])));
	v_div_fmas_f32 v131, v131, v141, v145
	v_div_scale_f32 v141, s[10:11], v142, v142, 1.0
	v_div_fixup_f32 v131, v131, v143, 1.0
	v_rcp_f32_e32 v143, v141
	s_nop 0
	v_fma_f32 v144, -v141, v143, 1.0
	v_fmac_f32_e32 v143, v144, v143
	v_div_scale_f32 v144, vcc, 1.0, v142, 1.0
	v_mul_f32_e32 v145, v144, v143
	v_fma_f32 v146, -v141, v145, v144
	v_fmac_f32_e32 v145, v146, v143
	v_fma_f32 v141, -v141, v145, v144
	v_div_fmas_f32 v141, v141, v143, v145
	v_div_fixup_f32 v141, v141, v142, 1.0
	v_cvt_pk_bf16_f32 v142, v141, v131
	v_mul_f32_e32 v131, 0xbfb8aa3b, v60
	v_exp_f32_e32 v144, v131
	v_mul_f32_e32 v131, 0xbfb8aa3b, v61
	v_exp_f32_e32 v145, v131
	s_nop 0
	v_pk_add_f32 v[144:145], v[144:145], 1.0 op_sel_hi:[1,0]
	s_nop 0
	v_div_scale_f32 v131, s[10:11], v145, v145, 1.0
	v_rcp_f32_e32 v141, v131
	s_nop 0
	v_fma_f32 v143, -v131, v141, 1.0
	v_fmac_f32_e32 v141, v143, v141
	v_div_scale_f32 v143, vcc, 1.0, v145, 1.0
	v_mul_f32_e32 v146, v143, v141
	v_fma_f32 v147, -v131, v146, v143
	v_fmac_f32_e32 v146, v147, v141
	v_fma_f32 v131, -v131, v146, v143
	v_div_fmas_f32 v131, v131, v141, v146
	v_div_scale_f32 v141, s[10:11], v144, v144, 1.0
	v_rcp_f32_e32 v143, v141
	v_div_fixup_f32 v131, v131, v145, 1.0
	v_fma_f32 v145, -v141, v143, 1.0
	v_fmac_f32_e32 v143, v145, v143
	v_div_scale_f32 v145, vcc, 1.0, v144, 1.0
	v_mul_f32_e32 v146, v145, v143
	v_fma_f32 v147, -v141, v146, v145
	v_fmac_f32_e32 v146, v147, v143
	v_fma_f32 v141, -v141, v146, v145
	v_div_fmas_f32 v141, v141, v143, v146
	v_div_fixup_f32 v141, v141, v144, 1.0
	v_cvt_pk_bf16_f32 v143, v141, v131
	v_mul_f32_e32 v131, 0xbfb8aa3b, v62
	global_store_dwordx2 v[134:135], v[142:143], off offset:3072
	v_exp_f32_e32 v142, v131
	v_mul_f32_e32 v131, 0xbfb8aa3b, v63
	v_exp_f32_e32 v143, v131
	s_nop 0
	v_pk_add_f32 v[142:143], v[142:143], 1.0 op_sel_hi:[1,0]
	s_nop 0
	v_div_scale_f32 v131, s[10:11], v143, v143, 1.0
	v_rcp_f32_e32 v141, v131
	s_nop 0
	v_fma_f32 v144, -v131, v141, 1.0
	v_fmac_f32_e32 v141, v144, v141
	v_div_scale_f32 v144, vcc, 1.0, v143, 1.0
	v_mul_f32_e32 v145, v144, v141
	v_fma_f32 v146, -v131, v145, v144
	v_fmac_f32_e32 v145, v146, v141
	v_fma_f32 v131, -v131, v145, v144
	v_div_fmas_f32 v131, v131, v141, v145
	v_div_scale_f32 v141, s[10:11], v142, v142, 1.0
	v_div_fixup_f32 v131, v131, v143, 1.0
	v_rcp_f32_e32 v143, v141
	s_nop 0
	v_fma_f32 v144, -v141, v143, 1.0
	v_fmac_f32_e32 v143, v144, v143
	v_div_scale_f32 v144, vcc, 1.0, v142, 1.0
	v_mul_f32_e32 v145, v144, v143
	v_fma_f32 v146, -v141, v145, v144
	v_fmac_f32_e32 v145, v146, v143
	v_fma_f32 v141, -v141, v145, v144
	v_div_fmas_f32 v141, v141, v143, v145
	v_div_fixup_f32 v141, v141, v142, 1.0
	v_cvt_pk_bf16_f32 v142, v141, v131
	v_mul_f32_e32 v131, 0xbfb8aa3b, v64
	v_exp_f32_e32 v144, v131
	v_mul_f32_e32 v131, 0xbfb8aa3b, v65
	v_exp_f32_e32 v145, v131
	s_nop 0
	v_pk_add_f32 v[144:145], v[144:145], 1.0 op_sel_hi:[1,0]
	s_nop 0
	v_div_scale_f32 v131, s[10:11], v145, v145, 1.0
	v_rcp_f32_e32 v141, v131
	s_nop 0
	v_fma_f32 v143, -v131, v141, 1.0
	v_fmac_f32_e32 v141, v143, v141
	v_div_scale_f32 v143, vcc, 1.0, v145, 1.0
	v_mul_f32_e32 v146, v143, v141
	v_fma_f32 v147, -v131, v146, v143
	v_fmac_f32_e32 v146, v147, v141
	v_fma_f32 v131, -v131, v146, v143
	v_div_fmas_f32 v131, v131, v141, v146
	v_div_scale_f32 v141, s[10:11], v144, v144, 1.0
	v_rcp_f32_e32 v143, v141
	v_div_fixup_f32 v131, v131, v145, 1.0
	v_fma_f32 v145, -v141, v143, 1.0
	v_fmac_f32_e32 v143, v145, v143
	v_div_scale_f32 v145, vcc, 1.0, v144, 1.0
	v_mul_f32_e32 v146, v145, v143
	v_fma_f32 v147, -v141, v146, v145
	v_fmac_f32_e32 v146, v147, v143
	v_fma_f32 v141, -v141, v146, v145
	v_div_fmas_f32 v141, v141, v143, v146
	v_div_fixup_f32 v141, v141, v144, 1.0
	v_cvt_pk_bf16_f32 v143, v141, v131
	global_store_dwordx2 v[134:135], v[142:143], off offset:3584
	v_mul_f32_e32 v134, 0xbfb8aa3b, v66
	v_mul_f32_e32 v135, 0xbfb8aa3b, v67
	v_exp_f32_e32 v134, v134
	v_exp_f32_e32 v135, v135
	v_ashrrev_i32_e32 v131, 31, v130
	v_lshl_add_u64 v[130:131], v[178:179], 0, v[130:131]
	v_lshlrev_b64 v[130:131], 13, v[130:131]
	v_pk_add_f32 v[134:135], v[134:135], 1.0 op_sel_hi:[1,0]
	v_lshl_add_u64 v[130:131], s[0:1], 0, v[130:131]
	v_div_scale_f32 v141, s[10:11], v135, v135, 1.0
	v_rcp_f32_e32 v142, v141
	v_lshl_add_u64 v[130:131], v[130:131], 0, v[132:133]
	v_mul_f32_e32 v132, 0xbfb8aa3b, v70
	v_mul_f32_e32 v133, 0xbfb8aa3b, v71
	v_fma_f32 v143, -v141, v142, 1.0
	v_fmac_f32_e32 v142, v143, v142
	v_div_scale_f32 v143, vcc, 1.0, v135, 1.0
	v_mul_f32_e32 v144, v143, v142
	v_fma_f32 v145, -v141, v144, v143
	v_fmac_f32_e32 v144, v145, v142
	v_fma_f32 v141, -v141, v144, v143
	v_div_fmas_f32 v141, v141, v142, v144
	v_div_fixup_f32 v135, v141, v135, 1.0
	v_div_scale_f32 v141, s[10:11], v134, v134, 1.0
	v_rcp_f32_e32 v142, v141
	v_exp_f32_e32 v132, v132
	v_exp_f32_e32 v133, v133
	v_fma_f32 v143, -v141, v142, 1.0
	v_fmac_f32_e32 v142, v143, v142
	v_div_scale_f32 v143, vcc, 1.0, v134, 1.0
	v_mul_f32_e32 v144, v143, v142
	v_fma_f32 v145, -v141, v144, v143
	v_fmac_f32_e32 v144, v145, v142
	v_fma_f32 v141, -v141, v144, v143
	v_div_fmas_f32 v141, v141, v142, v144
	v_div_fixup_f32 v134, v141, v134, 1.0
	v_cvt_pk_bf16_f32 v134, v134, v135
	v_mul_f32_e32 v135, 0xbfb8aa3b, v68
	v_exp_f32_e32 v142, v135
	v_mul_f32_e32 v135, 0xbfb8aa3b, v69
	v_exp_f32_e32 v143, v135
	v_pk_add_f32 v[132:133], v[132:133], 1.0 op_sel_hi:[1,0]
	v_pk_add_f32 v[142:143], v[142:143], 1.0 op_sel_hi:[1,0]
	s_nop 0
	v_div_scale_f32 v135, s[10:11], v143, v143, 1.0
	v_rcp_f32_e32 v141, v135
	s_nop 0
	v_fma_f32 v144, -v135, v141, 1.0
	v_fmac_f32_e32 v141, v144, v141
	v_div_scale_f32 v144, vcc, 1.0, v143, 1.0
	v_mul_f32_e32 v145, v144, v141
; DI unsigned pack2(float a, float b) { fl2_t f = {a, b}; bf2_t r = __builtin_convertvector(f, bf2_t); return __builtin_bit_cast(unsigned, r); }
; DI float sigmoidf_(float x) { return 1.f / (1.f + __expf(-x)); }
; DI void g1_phase(const P& p, int l, unsigned char* lds) {
;     ...
;       for (int mt = 0; mt < 4; ++mt) {
;         const int wave2 = (2 * wm + (mt >> 1)) * 2 + wn2, mt2 = mt & 1;
; #pragma unroll
;         for (int nt = 0; nt < 2; ++nt)
; #pragma unroll
;           for (int g4 = 0; g4 < 4; ++g4) {
;             size_t idx = ((((((size_t)tm_ * 8 + tn2) * 8 + wave2) * 2 + mt2) * 2 + nt) * 4 + g4) * 64 + lane;
;             *(uint2*)(gf + idx * 4) = make_uint2(pack2(sigmoidf_(acc[mt][nt][4 * g4]), sigmoidf_(acc[mt][nt][4 * g4 + 1])),
;                                                  pack2(sigmoidf_(acc[mt][nt][4 * g4 + 2]), sigmoidf_(acc[mt][nt][4 * g4 + 3])));
	v_fma_f32 v146, -v135, v145, v144
	v_fmac_f32_e32 v145, v146, v141
	v_fma_f32 v135, -v135, v145, v144
	v_div_fmas_f32 v135, v135, v141, v145
	v_div_scale_f32 v141, s[10:11], v142, v142, 1.0
	v_div_fixup_f32 v135, v135, v143, 1.0
	v_rcp_f32_e32 v143, v141
	s_nop 0
	v_fma_f32 v144, -v141, v143, 1.0
	v_fmac_f32_e32 v143, v144, v143
	v_div_scale_f32 v144, vcc, 1.0, v142, 1.0
	v_mul_f32_e32 v145, v144, v143
	v_fma_f32 v146, -v141, v145, v144
	v_fmac_f32_e32 v145, v146, v143
	v_fma_f32 v141, -v141, v145, v144
	v_div_fmas_f32 v141, v141, v143, v145
	v_div_fixup_f32 v141, v141, v142, 1.0
	v_cvt_pk_bf16_f32 v135, v141, v135
	global_store_dwordx2 v[130:131], v[134:135], off
	v_div_scale_f32 v134, s[0:1], v133, v133, 1.0
	v_rcp_f32_e32 v135, v134
	s_nop 0
	v_fma_f32 v141, -v134, v135, 1.0
	v_fmac_f32_e32 v135, v141, v135
	v_div_scale_f32 v141, vcc, 1.0, v133, 1.0
	v_mul_f32_e32 v142, v141, v135
	v_fma_f32 v143, -v134, v142, v141
	v_fmac_f32_e32 v142, v143, v135
	v_fma_f32 v134, -v134, v142, v141
	v_div_fmas_f32 v134, v134, v135, v142
	v_div_fixup_f32 v133, v134, v133, 1.0
	v_div_scale_f32 v134, s[0:1], v132, v132, 1.0
	v_rcp_f32_e32 v135, v134
	s_nop 0
	v_fma_f32 v141, -v134, v135, 1.0
	v_fmac_f32_e32 v135, v141, v135
	v_div_scale_f32 v141, vcc, 1.0, v132, 1.0
	v_mul_f32_e32 v142, v141, v135
	v_fma_f32 v143, -v134, v142, v141
	v_fmac_f32_e32 v142, v143, v135
	v_fma_f32 v134, -v134, v142, v141
	v_div_fmas_f32 v134, v134, v135, v142
	v_div_fixup_f32 v132, v134, v132, 1.0
	v_cvt_pk_bf16_f32 v132, v132, v133
	v_mul_f32_e32 v133, 0xbfb8aa3b, v72
	v_exp_f32_e32 v134, v133
	v_mul_f32_e32 v133, 0xbfb8aa3b, v73
	v_exp_f32_e32 v135, v133
	s_nop 0
	v_pk_add_f32 v[134:135], v[134:135], 1.0 op_sel_hi:[1,0]
	s_nop 0
	v_div_scale_f32 v133, s[0:1], v135, v135, 1.0
	v_rcp_f32_e32 v141, v133
	s_nop 0
	v_fma_f32 v142, -v133, v141, 1.0
	v_fmac_f32_e32 v141, v142, v141
	v_div_scale_f32 v142, vcc, 1.0, v135, 1.0
	v_mul_f32_e32 v143, v142, v141
	v_fma_f32 v144, -v133, v143, v142
	v_fmac_f32_e32 v143, v144, v141
	v_fma_f32 v133, -v133, v143, v142
	v_div_fmas_f32 v133, v133, v141, v143
	v_div_fixup_f32 v133, v133, v135, 1.0
	v_div_scale_f32 v135, s[0:1], v134, v134, 1.0
	v_rcp_f32_e32 v141, v135
	s_nop 0
	v_fma_f32 v142, -v135, v141, 1.0
	v_fmac_f32_e32 v141, v142, v141
	v_div_scale_f32 v142, vcc, 1.0, v134, 1.0
	v_mul_f32_e32 v143, v142, v141
	v_fma_f32 v144, -v135, v143, v142
	v_fmac_f32_e32 v143, v144, v141
	v_fma_f32 v135, -v135, v143, v142
	v_div_fmas_f32 v135, v135, v141, v143
	v_div_fixup_f32 v134, v135, v134, 1.0
	v_cvt_pk_bf16_f32 v133, v134, v133
	global_store_dwordx2 v[130:131], v[132:133], off offset:512
	v_mul_f32_e32 v132, 0xbfb8aa3b, v74
	v_mul_f32_e32 v133, 0xbfb8aa3b, v75
	v_exp_f32_e32 v132, v132
	v_exp_f32_e32 v133, v133
	s_nop 0
	v_pk_add_f32 v[132:133], v[132:133], 1.0 op_sel_hi:[1,0]
	s_nop 0
	v_div_scale_f32 v134, s[0:1], v133, v133, 1.0
	v_rcp_f32_e32 v135, v134
	s_nop 0
	v_fma_f32 v141, -v134, v135, 1.0
	v_fmac_f32_e32 v135, v141, v135
	v_div_scale_f32 v141, vcc, 1.0, v133, 1.0
	v_mul_f32_e32 v142, v141, v135
	v_fma_f32 v143, -v134, v142, v141
	v_fmac_f32_e32 v142, v143, v135
	v_fma_f32 v134, -v134, v142, v141
	v_div_fmas_f32 v134, v134, v135, v142
	v_div_fixup_f32 v133, v134, v133, 1.0
	v_div_scale_f32 v134, s[0:1], v132, v132, 1.0
	v_rcp_f32_e32 v135, v134
	s_nop 0
	v_fma_f32 v141, -v134, v135, 1.0
	v_fmac_f32_e32 v135, v141, v135
	v_div_scale_f32 v141, vcc, 1.0, v132, 1.0
	v_mul_f32_e32 v142, v141, v135
	v_fma_f32 v143, -v134, v142, v141
	v_fmac_f32_e32 v142, v143, v135
	v_fma_f32 v134, -v134, v142, v141
	v_div_fmas_f32 v134, v134, v135, v142
	v_div_fixup_f32 v132, v134, v132, 1.0
	v_cvt_pk_bf16_f32 v132, v132, v133
	v_mul_f32_e32 v133, 0xbfb8aa3b, v76
	v_exp_f32_e32 v134, v133
	v_mul_f32_e32 v133, 0xbfb8aa3b, v77
	v_exp_f32_e32 v135, v133
	s_nop 0
	v_pk_add_f32 v[134:135], v[134:135], 1.0 op_sel_hi:[1,0]
	s_nop 0
	v_div_scale_f32 v133, s[0:1], v135, v135, 1.0
	v_rcp_f32_e32 v141, v133
	s_nop 0
	v_fma_f32 v142, -v133, v141, 1.0
	v_fmac_f32_e32 v141, v142, v141
	v_div_scale_f32 v142, vcc, 1.0, v135, 1.0
	v_mul_f32_e32 v143, v142, v141
	v_fma_f32 v144, -v133, v143, v142
	v_fmac_f32_e32 v143, v144, v141
	v_fma_f32 v133, -v133, v143, v142
	v_div_fmas_f32 v133, v133, v141, v143
	v_div_fixup_f32 v133, v133, v135, 1.0
	v_div_scale_f32 v135, s[0:1], v134, v134, 1.0
	v_rcp_f32_e32 v141, v135
	s_nop 0
	v_fma_f32 v142, -v135, v141, 1.0
	v_fmac_f32_e32 v141, v142, v141
	v_div_scale_f32 v142, vcc, 1.0, v134, 1.0
	v_mul_f32_e32 v143, v142, v141
	v_fma_f32 v144, -v135, v143, v142
	v_fmac_f32_e32 v143, v144, v141
	v_fma_f32 v135, -v135, v143, v142
	v_div_fmas_f32 v135, v135, v141, v143
	v_div_fixup_f32 v134, v135, v134, 1.0
	v_cvt_pk_bf16_f32 v133, v134, v133
	global_store_dwordx2 v[130:131], v[132:133], off offset:1024
	v_mul_f32_e32 v132, 0xbfb8aa3b, v78
	v_mul_f32_e32 v133, 0xbfb8aa3b, v79
	v_exp_f32_e32 v132, v132
	v_exp_f32_e32 v133, v133
	s_nop 0
	v_pk_add_f32 v[132:133], v[132:133], 1.0 op_sel_hi:[1,0]
	s_nop 0
	v_div_scale_f32 v134, s[0:1], v133, v133, 1.0
	v_rcp_f32_e32 v135, v134
	s_nop 0
	v_fma_f32 v141, -v134, v135, 1.0
	v_fmac_f32_e32 v135, v141, v135
	v_div_scale_f32 v141, vcc, 1.0, v133, 1.0
	v_mul_f32_e32 v142, v141, v135
	v_fma_f32 v143, -v134, v142, v141
	v_fmac_f32_e32 v142, v143, v135
	v_fma_f32 v134, -v134, v142, v141
	v_div_fmas_f32 v134, v134, v135, v142
	v_div_fixup_f32 v133, v134, v133, 1.0
	v_div_scale_f32 v134, s[0:1], v132, v132, 1.0
	v_rcp_f32_e32 v135, v134
	s_nop 0
	v_fma_f32 v141, -v134, v135, 1.0
	v_fmac_f32_e32 v135, v141, v135
	v_div_scale_f32 v141, vcc, 1.0, v132, 1.0
	v_mul_f32_e32 v142, v141, v135
	v_fma_f32 v143, -v134, v142, v141
; DI unsigned pack2(float a, float b) { fl2_t f = {a, b}; bf2_t r = __builtin_convertvector(f, bf2_t); return __builtin_bit_cast(unsigned, r); }
; DI float sigmoidf_(float x) { return 1.f / (1.f + __expf(-x)); }
; DI void g1_phase(const P& p, int l, unsigned char* lds) {
;     ...
;       for (int mt = 0; mt < 4; ++mt) {
;         const int wave2 = (2 * wm + (mt >> 1)) * 2 + wn2, mt2 = mt & 1;
; #pragma unroll
;         for (int nt = 0; nt < 2; ++nt)
; #pragma unroll
;           for (int g4 = 0; g4 < 4; ++g4) {
;             size_t idx = ((((((size_t)tm_ * 8 + tn2) * 8 + wave2) * 2 + mt2) * 2 + nt) * 4 + g4) * 64 + lane;
;             *(uint2*)(gf + idx * 4) = make_uint2(pack2(sigmoidf_(acc[mt][nt][4 * g4]), sigmoidf_(acc[mt][nt][4 * g4 + 1])),
;                                                  pack2(sigmoidf_(acc[mt][nt][4 * g4 + 2]), sigmoidf_(acc[mt][nt][4 * g4 + 3])));
	v_fmac_f32_e32 v142, v143, v135
	v_fma_f32 v134, -v134, v142, v141
	v_div_fmas_f32 v134, v134, v135, v142
	v_div_fixup_f32 v132, v134, v132, 1.0
	v_cvt_pk_bf16_f32 v132, v132, v133
	v_mul_f32_e32 v133, 0xbfb8aa3b, v80
	v_exp_f32_e32 v134, v133
	v_mul_f32_e32 v133, 0xbfb8aa3b, v81
	v_exp_f32_e32 v135, v133
	s_nop 0
	v_pk_add_f32 v[134:135], v[134:135], 1.0 op_sel_hi:[1,0]
	s_nop 0
	v_div_scale_f32 v133, s[0:1], v135, v135, 1.0
	v_rcp_f32_e32 v141, v133
	s_nop 0
	v_fma_f32 v142, -v133, v141, 1.0
	v_fmac_f32_e32 v141, v142, v141
	v_div_scale_f32 v142, vcc, 1.0, v135, 1.0
	v_mul_f32_e32 v143, v142, v141
	v_fma_f32 v144, -v133, v143, v142
	v_fmac_f32_e32 v143, v144, v141
	v_fma_f32 v133, -v133, v143, v142
	v_div_fmas_f32 v133, v133, v141, v143
	v_div_fixup_f32 v133, v133, v135, 1.0
	v_div_scale_f32 v135, s[0:1], v134, v134, 1.0
	v_rcp_f32_e32 v141, v135
	s_nop 0
	v_fma_f32 v142, -v135, v141, 1.0
	v_fmac_f32_e32 v141, v142, v141
	v_div_scale_f32 v142, vcc, 1.0, v134, 1.0
	v_mul_f32_e32 v143, v142, v141
	v_fma_f32 v144, -v135, v143, v142
	v_fmac_f32_e32 v143, v144, v141
	v_fma_f32 v135, -v135, v143, v142
	v_div_fmas_f32 v135, v135, v141, v143
	v_div_fixup_f32 v134, v135, v134, 1.0
	v_cvt_pk_bf16_f32 v133, v134, v133
	global_store_dwordx2 v[130:131], v[132:133], off offset:1536
	v_mul_f32_e32 v132, 0xbfb8aa3b, v82
	v_mul_f32_e32 v133, 0xbfb8aa3b, v83
	v_exp_f32_e32 v132, v132
	v_exp_f32_e32 v133, v133
	s_nop 0
	v_pk_add_f32 v[132:133], v[132:133], 1.0 op_sel_hi:[1,0]
	s_nop 0
	v_div_scale_f32 v134, s[0:1], v133, v133, 1.0
	v_rcp_f32_e32 v135, v134
	s_nop 0
	v_fma_f32 v141, -v134, v135, 1.0
	v_fmac_f32_e32 v135, v141, v135
	v_div_scale_f32 v141, vcc, 1.0, v133, 1.0
	v_mul_f32_e32 v142, v141, v135
	v_fma_f32 v143, -v134, v142, v141
	v_fmac_f32_e32 v142, v143, v135
	v_fma_f32 v134, -v134, v142, v141
	v_div_fmas_f32 v134, v134, v135, v142
	v_div_fixup_f32 v133, v134, v133, 1.0
	v_div_scale_f32 v134, s[0:1], v132, v132, 1.0
	v_rcp_f32_e32 v135, v134
	s_nop 0
	v_fma_f32 v141, -v134, v135, 1.0
	v_fmac_f32_e32 v135, v141, v135
	v_div_scale_f32 v141, vcc, 1.0, v132, 1.0
	v_mul_f32_e32 v142, v141, v135
	v_fma_f32 v143, -v134, v142, v141
	v_fmac_f32_e32 v142, v143, v135
	v_fma_f32 v134, -v134, v142, v141
	v_div_fmas_f32 v134, v134, v135, v142
	v_div_fixup_f32 v132, v134, v132, 1.0
	v_cvt_pk_bf16_f32 v132, v132, v133
	v_mul_f32_e32 v133, 0xbfb8aa3b, v84
	v_exp_f32_e32 v134, v133
	v_mul_f32_e32 v133, 0xbfb8aa3b, v85
	v_exp_f32_e32 v135, v133
	s_nop 0
	v_pk_add_f32 v[134:135], v[134:135], 1.0 op_sel_hi:[1,0]
	s_nop 0
	v_div_scale_f32 v133, s[0:1], v135, v135, 1.0
	v_rcp_f32_e32 v141, v133
	s_nop 0
	v_fma_f32 v142, -v133, v141, 1.0
	v_fmac_f32_e32 v141, v142, v141
	v_div_scale_f32 v142, vcc, 1.0, v135, 1.0
	v_mul_f32_e32 v143, v142, v141
	v_fma_f32 v144, -v133, v143, v142
	v_fmac_f32_e32 v143, v144, v141
	v_fma_f32 v133, -v133, v143, v142
	v_div_fmas_f32 v133, v133, v141, v143
	v_div_fixup_f32 v133, v133, v135, 1.0
	v_div_scale_f32 v135, s[0:1], v134, v134, 1.0
	v_rcp_f32_e32 v141, v135
	s_nop 0
	v_fma_f32 v142, -v135, v141, 1.0
	v_fmac_f32_e32 v141, v142, v141
	v_div_scale_f32 v142, vcc, 1.0, v134, 1.0
	v_mul_f32_e32 v143, v142, v141
	v_fma_f32 v144, -v135, v143, v142
	v_fmac_f32_e32 v143, v144, v141
	v_fma_f32 v135, -v135, v143, v142
	v_div_fmas_f32 v135, v135, v141, v143
	v_div_fixup_f32 v134, v135, v134, 1.0
	v_cvt_pk_bf16_f32 v133, v134, v133
	global_store_dwordx2 v[130:131], v[132:133], off offset:2048
	v_mul_f32_e32 v132, 0xbfb8aa3b, v86
	v_mul_f32_e32 v133, 0xbfb8aa3b, v87
	v_exp_f32_e32 v132, v132
	v_exp_f32_e32 v133, v133
	s_nop 0
	v_pk_add_f32 v[132:133], v[132:133], 1.0 op_sel_hi:[1,0]
	s_nop 0
	v_div_scale_f32 v134, s[0:1], v133, v133, 1.0
	v_rcp_f32_e32 v135, v134
	s_nop 0
	v_fma_f32 v141, -v134, v135, 1.0
	v_fmac_f32_e32 v135, v141, v135
	v_div_scale_f32 v141, vcc, 1.0, v133, 1.0
	v_mul_f32_e32 v142, v141, v135
	v_fma_f32 v143, -v134, v142, v141
	v_fmac_f32_e32 v142, v143, v135
	v_fma_f32 v134, -v134, v142, v141
	v_div_fmas_f32 v134, v134, v135, v142
	v_div_fixup_f32 v133, v134, v133, 1.0
	v_div_scale_f32 v134, s[0:1], v132, v132, 1.0
	v_rcp_f32_e32 v135, v134
	s_nop 0
	v_fma_f32 v141, -v134, v135, 1.0
	v_fmac_f32_e32 v135, v141, v135
	v_div_scale_f32 v141, vcc, 1.0, v132, 1.0
	v_mul_f32_e32 v142, v141, v135
	v_fma_f32 v143, -v134, v142, v141
	v_fmac_f32_e32 v142, v143, v135
	v_fma_f32 v134, -v134, v142, v141
	v_div_fmas_f32 v134, v134, v135, v142
	v_div_fixup_f32 v132, v134, v132, 1.0
	v_cvt_pk_bf16_f32 v132, v132, v133
	v_mul_f32_e32 v133, 0xbfb8aa3b, v88
	v_exp_f32_e32 v134, v133
	v_mul_f32_e32 v133, 0xbfb8aa3b, v89
	v_exp_f32_e32 v135, v133
	s_nop 0
	v_pk_add_f32 v[134:135], v[134:135], 1.0 op_sel_hi:[1,0]
	s_nop 0
	v_div_scale_f32 v133, s[0:1], v135, v135, 1.0
	v_rcp_f32_e32 v141, v133
	s_nop 0
	v_fma_f32 v142, -v133, v141, 1.0
	v_fmac_f32_e32 v141, v142, v141
	v_div_scale_f32 v142, vcc, 1.0, v135, 1.0
	v_mul_f32_e32 v143, v142, v141
	v_fma_f32 v144, -v133, v143, v142
	v_fmac_f32_e32 v143, v144, v141
	v_fma_f32 v133, -v133, v143, v142
	v_div_fmas_f32 v133, v133, v141, v143
	v_div_fixup_f32 v133, v133, v135, 1.0
	v_div_scale_f32 v135, s[0:1], v134, v134, 1.0
	v_rcp_f32_e32 v141, v135
	s_nop 0
	v_fma_f32 v142, -v135, v141, 1.0
	v_fmac_f32_e32 v141, v142, v141
	v_div_scale_f32 v142, vcc, 1.0, v134, 1.0
	v_mul_f32_e32 v143, v142, v141
	v_fma_f32 v144, -v135, v143, v142
	v_fmac_f32_e32 v143, v144, v141
	v_fma_f32 v135, -v135, v143, v142
	v_div_fmas_f32 v135, v135, v141, v143
	v_div_fixup_f32 v134, v135, v134, 1.0
	v_cvt_pk_bf16_f32 v133, v134, v133
	global_store_dwordx2 v[130:131], v[132:133], off offset:2560
	v_mul_f32_e32 v132, 0xbfb8aa3b, v90
; DI unsigned pack2(float a, float b) { fl2_t f = {a, b}; bf2_t r = __builtin_convertvector(f, bf2_t); return __builtin_bit_cast(unsigned, r); }
; DI float sigmoidf_(float x) { return 1.f / (1.f + __expf(-x)); }
; DI void g1_phase(const P& p, int l, unsigned char* lds) {
;     ...
;       for (int mt = 0; mt < 4; ++mt) {
;         const int wave2 = (2 * wm + (mt >> 1)) * 2 + wn2, mt2 = mt & 1;
; #pragma unroll
;         for (int nt = 0; nt < 2; ++nt)
; #pragma unroll
;           for (int g4 = 0; g4 < 4; ++g4) {
;             size_t idx = ((((((size_t)tm_ * 8 + tn2) * 8 + wave2) * 2 + mt2) * 2 + nt) * 4 + g4) * 64 + lane;
;             *(uint2*)(gf + idx * 4) = make_uint2(pack2(sigmoidf_(acc[mt][nt][4 * g4]), sigmoidf_(acc[mt][nt][4 * g4 + 1])),
;                                                  pack2(sigmoidf_(acc[mt][nt][4 * g4 + 2]), sigmoidf_(acc[mt][nt][4 * g4 + 3])));
	v_mul_f32_e32 v133, 0xbfb8aa3b, v91
	v_exp_f32_e32 v132, v132
	v_exp_f32_e32 v133, v133
	s_nop 0
	v_pk_add_f32 v[132:133], v[132:133], 1.0 op_sel_hi:[1,0]
	s_nop 0
	v_div_scale_f32 v134, s[0:1], v133, v133, 1.0
	v_rcp_f32_e32 v135, v134
	s_nop 0
	v_fma_f32 v141, -v134, v135, 1.0
	v_fmac_f32_e32 v135, v141, v135
	v_div_scale_f32 v141, vcc, 1.0, v133, 1.0
	v_mul_f32_e32 v142, v141, v135
	v_fma_f32 v143, -v134, v142, v141
	v_fmac_f32_e32 v142, v143, v135
	v_fma_f32 v134, -v134, v142, v141
	v_div_fmas_f32 v134, v134, v135, v142
	v_div_fixup_f32 v133, v134, v133, 1.0
	v_div_scale_f32 v134, s[0:1], v132, v132, 1.0
	v_rcp_f32_e32 v135, v134
	s_nop 0
	v_fma_f32 v141, -v134, v135, 1.0
	v_fmac_f32_e32 v135, v141, v135
	v_div_scale_f32 v141, vcc, 1.0, v132, 1.0
	v_mul_f32_e32 v142, v141, v135
	v_fma_f32 v143, -v134, v142, v141
	v_fmac_f32_e32 v142, v143, v135
	v_fma_f32 v134, -v134, v142, v141
	v_div_fmas_f32 v134, v134, v135, v142
	v_div_fixup_f32 v132, v134, v132, 1.0
	v_cvt_pk_bf16_f32 v132, v132, v133
	v_mul_f32_e32 v133, 0xbfb8aa3b, v92
	v_exp_f32_e32 v134, v133
	v_mul_f32_e32 v133, 0xbfb8aa3b, v93
	v_exp_f32_e32 v135, v133
	s_nop 0
	v_pk_add_f32 v[134:135], v[134:135], 1.0 op_sel_hi:[1,0]
	s_nop 0
	v_div_scale_f32 v133, s[0:1], v135, v135, 1.0
	v_rcp_f32_e32 v141, v133
	s_nop 0
	v_fma_f32 v142, -v133, v141, 1.0
	v_fmac_f32_e32 v141, v142, v141
	v_div_scale_f32 v142, vcc, 1.0, v135, 1.0
	v_mul_f32_e32 v143, v142, v141
	v_fma_f32 v144, -v133, v143, v142
	v_fmac_f32_e32 v143, v144, v141
	v_fma_f32 v133, -v133, v143, v142
	v_div_fmas_f32 v133, v133, v141, v143
	v_div_fixup_f32 v133, v133, v135, 1.0
	v_div_scale_f32 v135, s[0:1], v134, v134, 1.0
	v_rcp_f32_e32 v141, v135
	s_nop 0
	v_fma_f32 v142, -v135, v141, 1.0
	v_fmac_f32_e32 v141, v142, v141
	v_div_scale_f32 v142, vcc, 1.0, v134, 1.0
	v_mul_f32_e32 v143, v142, v141
	v_fma_f32 v144, -v135, v143, v142
	v_fmac_f32_e32 v143, v144, v141
	v_fma_f32 v135, -v135, v143, v142
	v_div_fmas_f32 v135, v135, v141, v143
	v_div_fixup_f32 v134, v135, v134, 1.0
	v_cvt_pk_bf16_f32 v133, v134, v133
	global_store_dwordx2 v[130:131], v[132:133], off offset:3072
	v_mul_f32_e32 v132, 0xbfb8aa3b, v94
	v_mul_f32_e32 v133, 0xbfb8aa3b, v95
	v_exp_f32_e32 v132, v132
	v_exp_f32_e32 v133, v133
	s_nop 0
	v_pk_add_f32 v[132:133], v[132:133], 1.0 op_sel_hi:[1,0]
	s_nop 0
	v_div_scale_f32 v134, s[0:1], v133, v133, 1.0
	v_rcp_f32_e32 v135, v134
	s_nop 0
	v_fma_f32 v141, -v134, v135, 1.0
	v_fmac_f32_e32 v135, v141, v135
	v_div_scale_f32 v141, vcc, 1.0, v133, 1.0
	v_mul_f32_e32 v142, v141, v135
	v_fma_f32 v143, -v134, v142, v141
	v_fmac_f32_e32 v142, v143, v135
	v_fma_f32 v134, -v134, v142, v141
	v_div_fmas_f32 v134, v134, v135, v142
	v_div_fixup_f32 v133, v134, v133, 1.0
	v_div_scale_f32 v134, s[0:1], v132, v132, 1.0
	v_rcp_f32_e32 v135, v134
	s_nop 0
	v_fma_f32 v141, -v134, v135, 1.0
	v_fmac_f32_e32 v135, v141, v135
	v_div_scale_f32 v141, vcc, 1.0, v132, 1.0
	v_mul_f32_e32 v142, v141, v135
	v_fma_f32 v143, -v134, v142, v141
	v_fmac_f32_e32 v142, v143, v135
	v_fma_f32 v134, -v134, v142, v141
	v_div_fmas_f32 v134, v134, v135, v142
	v_div_fixup_f32 v132, v134, v132, 1.0
	v_cvt_pk_bf16_f32 v132, v132, v133
	v_mul_f32_e32 v133, 0xbfb8aa3b, v96
	v_exp_f32_e32 v134, v133
	v_mul_f32_e32 v133, 0xbfb8aa3b, v97
	v_exp_f32_e32 v135, v133
	s_nop 0
	v_pk_add_f32 v[134:135], v[134:135], 1.0 op_sel_hi:[1,0]
	s_nop 0
	v_div_scale_f32 v133, s[0:1], v135, v135, 1.0
	v_rcp_f32_e32 v141, v133
	s_nop 0
	v_fma_f32 v142, -v133, v141, 1.0
	v_fmac_f32_e32 v141, v142, v141
	v_div_scale_f32 v142, vcc, 1.0, v135, 1.0
	v_mul_f32_e32 v143, v142, v141
	v_fma_f32 v144, -v133, v143, v142
	v_fmac_f32_e32 v143, v144, v141
	v_fma_f32 v133, -v133, v143, v142
	v_div_fmas_f32 v133, v133, v141, v143
	v_div_fixup_f32 v133, v133, v135, 1.0
	v_div_scale_f32 v135, s[0:1], v134, v134, 1.0
	v_rcp_f32_e32 v141, v135
	s_nop 0
	v_fma_f32 v142, -v135, v141, 1.0
	v_fmac_f32_e32 v141, v142, v141
	v_div_scale_f32 v142, vcc, 1.0, v134, 1.0
	v_mul_f32_e32 v143, v142, v141
	v_fma_f32 v144, -v135, v143, v142
	v_fmac_f32_e32 v143, v144, v141
	v_fma_f32 v135, -v135, v143, v142
	v_div_fmas_f32 v135, v135, v141, v143
	v_div_fixup_f32 v134, v135, v134, 1.0
	v_cvt_pk_bf16_f32 v133, v134, v133
	global_store_dwordx2 v[130:131], v[132:133], off offset:3584
	v_mul_f32_e32 v132, 0xbfb8aa3b, v98
	v_mul_f32_e32 v133, 0xbfb8aa3b, v99
	v_exp_f32_e32 v132, v132
	v_exp_f32_e32 v133, v133
	s_nop 0
	v_pk_add_f32 v[132:133], v[132:133], 1.0 op_sel_hi:[1,0]
	s_nop 0
	v_div_scale_f32 v134, s[0:1], v133, v133, 1.0
	v_rcp_f32_e32 v135, v134
	s_nop 0
	v_fma_f32 v141, -v134, v135, 1.0
	v_fmac_f32_e32 v135, v141, v135
	v_div_scale_f32 v141, vcc, 1.0, v133, 1.0
	v_mul_f32_e32 v142, v141, v135
	v_fma_f32 v143, -v134, v142, v141
	v_fmac_f32_e32 v142, v143, v135
	v_fma_f32 v134, -v134, v142, v141
	v_div_fmas_f32 v134, v134, v135, v142
	v_div_fixup_f32 v133, v134, v133, 1.0
	v_div_scale_f32 v134, s[0:1], v132, v132, 1.0
	v_rcp_f32_e32 v135, v134
	s_nop 0
	v_fma_f32 v141, -v134, v135, 1.0
	v_fmac_f32_e32 v135, v141, v135
	v_div_scale_f32 v141, vcc, 1.0, v132, 1.0
	v_mul_f32_e32 v142, v141, v135
	v_fma_f32 v143, -v134, v142, v141
	v_fmac_f32_e32 v142, v143, v135
	v_fma_f32 v134, -v134, v142, v141
	v_div_fmas_f32 v134, v134, v135, v142
	v_div_fixup_f32 v132, v134, v132, 1.0
	v_cvt_pk_bf16_f32 v132, v132, v133
	v_mul_f32_e32 v133, 0xbfb8aa3b, v100
	v_exp_f32_e32 v134, v133
	v_mul_f32_e32 v133, 0xbfb8aa3b, v101
	v_exp_f32_e32 v135, v133
	s_nop 0
	v_pk_add_f32 v[134:135], v[134:135], 1.0 op_sel_hi:[1,0]
	s_nop 0
	v_div_scale_f32 v133, s[0:1], v135, v135, 1.0
	v_rcp_f32_e32 v141, v133
	s_nop 0
	v_fma_f32 v142, -v133, v141, 1.0
; DI unsigned pack2(float a, float b) { fl2_t f = {a, b}; bf2_t r = __builtin_convertvector(f, bf2_t); return __builtin_bit_cast(unsigned, r); }
; DI float sigmoidf_(float x) { return 1.f / (1.f + __expf(-x)); }
; DI void g1_phase(const P& p, int l, unsigned char* lds) {
;     ...
;       for (int mt = 0; mt < 4; ++mt) {
;         const int wave2 = (2 * wm + (mt >> 1)) * 2 + wn2, mt2 = mt & 1;
; #pragma unroll
;         for (int nt = 0; nt < 2; ++nt)
; #pragma unroll
;           for (int g4 = 0; g4 < 4; ++g4) {
;             size_t idx = ((((((size_t)tm_ * 8 + tn2) * 8 + wave2) * 2 + mt2) * 2 + nt) * 4 + g4) * 64 + lane;
;             *(uint2*)(gf + idx * 4) = make_uint2(pack2(sigmoidf_(acc[mt][nt][4 * g4]), sigmoidf_(acc[mt][nt][4 * g4 + 1])),
;                                                  pack2(sigmoidf_(acc[mt][nt][4 * g4 + 2]), sigmoidf_(acc[mt][nt][4 * g4 + 3])));
	v_fmac_f32_e32 v141, v142, v141
	v_div_scale_f32 v142, vcc, 1.0, v135, 1.0
	v_mul_f32_e32 v143, v142, v141
	v_fma_f32 v144, -v133, v143, v142
	v_fmac_f32_e32 v143, v144, v141
	v_fma_f32 v133, -v133, v143, v142
	v_div_fmas_f32 v133, v133, v141, v143
	v_div_fixup_f32 v133, v133, v135, 1.0
	v_div_scale_f32 v135, s[0:1], v134, v134, 1.0
	v_rcp_f32_e32 v141, v135
	s_nop 0
	v_fma_f32 v142, -v135, v141, 1.0
	v_fmac_f32_e32 v141, v142, v141
	v_div_scale_f32 v142, vcc, 1.0, v134, 1.0
	v_mul_f32_e32 v143, v142, v141
	v_fma_f32 v144, -v135, v143, v142
	v_fmac_f32_e32 v143, v144, v141
	v_fma_f32 v135, -v135, v143, v142
	v_div_fmas_f32 v135, v135, v141, v143
	v_div_fixup_f32 v134, v135, v134, 1.0
	v_add_co_u32_e32 v130, vcc, s46, v130
	v_cvt_pk_bf16_f32 v133, v134, v133
	s_nop 0
	v_addc_co_u32_e32 v131, vcc, 0, v131, vcc
	global_store_dwordx2 v[130:131], v[132:133], off
	v_mul_f32_e32 v132, 0xbfb8aa3b, v102
	v_mul_f32_e32 v133, 0xbfb8aa3b, v103
	v_exp_f32_e32 v132, v132
	v_exp_f32_e32 v133, v133
	s_nop 0
	v_pk_add_f32 v[132:133], v[132:133], 1.0 op_sel_hi:[1,0]
	s_nop 0
	v_div_scale_f32 v134, s[0:1], v133, v133, 1.0
	v_rcp_f32_e32 v135, v134
	s_nop 0
	v_fma_f32 v141, -v134, v135, 1.0
	v_fmac_f32_e32 v135, v141, v135
	v_div_scale_f32 v141, vcc, 1.0, v133, 1.0
	v_mul_f32_e32 v142, v141, v135
	v_fma_f32 v143, -v134, v142, v141
	v_fmac_f32_e32 v142, v143, v135
	v_fma_f32 v134, -v134, v142, v141
	v_div_fmas_f32 v134, v134, v135, v142
	v_div_fixup_f32 v133, v134, v133, 1.0
	v_div_scale_f32 v134, s[0:1], v132, v132, 1.0
	v_rcp_f32_e32 v135, v134
	s_nop 0
	v_fma_f32 v141, -v134, v135, 1.0
	v_fmac_f32_e32 v135, v141, v135
	v_div_scale_f32 v141, vcc, 1.0, v132, 1.0
	v_mul_f32_e32 v142, v141, v135
	v_fma_f32 v143, -v134, v142, v141
	v_fmac_f32_e32 v142, v143, v135
	v_fma_f32 v134, -v134, v142, v141
	v_div_fmas_f32 v134, v134, v135, v142
	v_div_fixup_f32 v132, v134, v132, 1.0
	v_cvt_pk_bf16_f32 v132, v132, v133
	v_mul_f32_e32 v133, 0xbfb8aa3b, v104
	v_exp_f32_e32 v134, v133
	v_mul_f32_e32 v133, 0xbfb8aa3b, v105
	v_exp_f32_e32 v135, v133
	s_nop 0
	v_pk_add_f32 v[134:135], v[134:135], 1.0 op_sel_hi:[1,0]
	s_nop 0
	v_div_scale_f32 v133, s[0:1], v135, v135, 1.0
	v_rcp_f32_e32 v141, v133
	s_nop 0
	v_fma_f32 v142, -v133, v141, 1.0
	v_fmac_f32_e32 v141, v142, v141
	v_div_scale_f32 v142, vcc, 1.0, v135, 1.0
	v_mul_f32_e32 v143, v142, v141
	v_fma_f32 v144, -v133, v143, v142
	v_fmac_f32_e32 v143, v144, v141
	v_fma_f32 v133, -v133, v143, v142
	v_div_fmas_f32 v133, v133, v141, v143
	v_div_fixup_f32 v133, v133, v135, 1.0
	v_div_scale_f32 v135, s[0:1], v134, v134, 1.0
	v_rcp_f32_e32 v141, v135
	s_nop 0
	v_fma_f32 v142, -v135, v141, 1.0
	v_fmac_f32_e32 v141, v142, v141
	v_div_scale_f32 v142, vcc, 1.0, v134, 1.0
	v_mul_f32_e32 v143, v142, v141
	v_fma_f32 v144, -v135, v143, v142
	v_fmac_f32_e32 v143, v144, v141
	v_fma_f32 v135, -v135, v143, v142
	v_div_fmas_f32 v135, v135, v141, v143
	v_div_fixup_f32 v134, v135, v134, 1.0
	v_cvt_pk_bf16_f32 v133, v134, v133
	global_store_dwordx2 v[130:131], v[132:133], off offset:512
	v_mul_f32_e32 v132, 0xbfb8aa3b, v106
	v_mul_f32_e32 v133, 0xbfb8aa3b, v107
	v_exp_f32_e32 v132, v132
	v_exp_f32_e32 v133, v133
	s_nop 0
	v_pk_add_f32 v[132:133], v[132:133], 1.0 op_sel_hi:[1,0]
	s_nop 0
	v_div_scale_f32 v134, s[0:1], v133, v133, 1.0
	v_rcp_f32_e32 v135, v134
	s_nop 0
	v_fma_f32 v141, -v134, v135, 1.0
	v_fmac_f32_e32 v135, v141, v135
	v_div_scale_f32 v141, vcc, 1.0, v133, 1.0
	v_mul_f32_e32 v142, v141, v135
	v_fma_f32 v143, -v134, v142, v141
	v_fmac_f32_e32 v142, v143, v135
	v_fma_f32 v134, -v134, v142, v141
	v_div_fmas_f32 v134, v134, v135, v142
	v_div_fixup_f32 v133, v134, v133, 1.0
	v_div_scale_f32 v134, s[0:1], v132, v132, 1.0
	v_rcp_f32_e32 v135, v134
	s_nop 0
	v_fma_f32 v141, -v134, v135, 1.0
	v_fmac_f32_e32 v135, v141, v135
	v_div_scale_f32 v141, vcc, 1.0, v132, 1.0
	v_mul_f32_e32 v142, v141, v135
	v_fma_f32 v143, -v134, v142, v141
	v_fmac_f32_e32 v142, v143, v135
	v_fma_f32 v134, -v134, v142, v141
	v_div_fmas_f32 v134, v134, v135, v142
	v_div_fixup_f32 v132, v134, v132, 1.0
	v_cvt_pk_bf16_f32 v132, v132, v133
	v_mul_f32_e32 v133, 0xbfb8aa3b, v108
	v_exp_f32_e32 v134, v133
	v_mul_f32_e32 v133, 0xbfb8aa3b, v109
	v_exp_f32_e32 v135, v133
	s_nop 0
	v_pk_add_f32 v[134:135], v[134:135], 1.0 op_sel_hi:[1,0]
	s_nop 0
	v_div_scale_f32 v133, s[0:1], v135, v135, 1.0
	v_rcp_f32_e32 v141, v133
	s_nop 0
	v_fma_f32 v142, -v133, v141, 1.0
	v_fmac_f32_e32 v141, v142, v141
	v_div_scale_f32 v142, vcc, 1.0, v135, 1.0
	v_mul_f32_e32 v143, v142, v141
	v_fma_f32 v144, -v133, v143, v142
	v_fmac_f32_e32 v143, v144, v141
	v_fma_f32 v133, -v133, v143, v142
	v_div_fmas_f32 v133, v133, v141, v143
	v_div_fixup_f32 v133, v133, v135, 1.0
	v_div_scale_f32 v135, s[0:1], v134, v134, 1.0
	v_rcp_f32_e32 v141, v135
	s_nop 0
	v_fma_f32 v142, -v135, v141, 1.0
	v_fmac_f32_e32 v141, v142, v141
	v_div_scale_f32 v142, vcc, 1.0, v134, 1.0
	v_mul_f32_e32 v143, v142, v141
	v_fma_f32 v144, -v135, v143, v142
	v_fmac_f32_e32 v143, v144, v141
	v_fma_f32 v135, -v135, v143, v142
	v_div_fmas_f32 v135, v135, v141, v143
	v_div_fixup_f32 v134, v135, v134, 1.0
	v_cvt_pk_bf16_f32 v133, v134, v133
	global_store_dwordx2 v[130:131], v[132:133], off offset:1024
	v_mul_f32_e32 v132, 0xbfb8aa3b, v110
	v_mul_f32_e32 v133, 0xbfb8aa3b, v111
	v_exp_f32_e32 v132, v132
	v_exp_f32_e32 v133, v133
	s_nop 0
	v_pk_add_f32 v[132:133], v[132:133], 1.0 op_sel_hi:[1,0]
	s_nop 0
	v_div_scale_f32 v134, s[0:1], v133, v133, 1.0
	v_rcp_f32_e32 v135, v134
	s_nop 0
	v_fma_f32 v141, -v134, v135, 1.0
	v_fmac_f32_e32 v135, v141, v135
	v_div_scale_f32 v141, vcc, 1.0, v133, 1.0
	v_mul_f32_e32 v142, v141, v135
	v_fma_f32 v143, -v134, v142, v141
; DI unsigned pack2(float a, float b) { fl2_t f = {a, b}; bf2_t r = __builtin_convertvector(f, bf2_t); return __builtin_bit_cast(unsigned, r); }
; DI float sigmoidf_(float x) { return 1.f / (1.f + __expf(-x)); }
; DI void g1_phase(const P& p, int l, unsigned char* lds) {
;     ...
;       for (int mt = 0; mt < 4; ++mt) {
;         const int wave2 = (2 * wm + (mt >> 1)) * 2 + wn2, mt2 = mt & 1;
; #pragma unroll
;         for (int nt = 0; nt < 2; ++nt)
; #pragma unroll
;           for (int g4 = 0; g4 < 4; ++g4) {
;             size_t idx = ((((((size_t)tm_ * 8 + tn2) * 8 + wave2) * 2 + mt2) * 2 + nt) * 4 + g4) * 64 + lane;
;             *(uint2*)(gf + idx * 4) = make_uint2(pack2(sigmoidf_(acc[mt][nt][4 * g4]), sigmoidf_(acc[mt][nt][4 * g4 + 1])),
;                                                  pack2(sigmoidf_(acc[mt][nt][4 * g4 + 2]), sigmoidf_(acc[mt][nt][4 * g4 + 3])));
	v_fmac_f32_e32 v142, v143, v135
	v_fma_f32 v134, -v134, v142, v141
	v_div_fmas_f32 v134, v134, v135, v142
	v_div_fixup_f32 v133, v134, v133, 1.0
	v_div_scale_f32 v134, s[0:1], v132, v132, 1.0
	v_rcp_f32_e32 v135, v134
	s_nop 0
	v_fma_f32 v141, -v134, v135, 1.0
	v_fmac_f32_e32 v135, v141, v135
	v_div_scale_f32 v141, vcc, 1.0, v132, 1.0
	v_mul_f32_e32 v142, v141, v135
	v_fma_f32 v143, -v134, v142, v141
	v_fmac_f32_e32 v142, v143, v135
	v_fma_f32 v134, -v134, v142, v141
	v_div_fmas_f32 v134, v134, v135, v142
	v_div_fixup_f32 v132, v134, v132, 1.0
	v_cvt_pk_bf16_f32 v132, v132, v133
	v_mul_f32_e32 v133, 0xbfb8aa3b, v112
	v_exp_f32_e32 v134, v133
	v_mul_f32_e32 v133, 0xbfb8aa3b, v113
	v_exp_f32_e32 v135, v133
	s_nop 0
	v_pk_add_f32 v[134:135], v[134:135], 1.0 op_sel_hi:[1,0]
	s_nop 0
	v_div_scale_f32 v133, s[0:1], v135, v135, 1.0
	v_rcp_f32_e32 v141, v133
	s_nop 0
	v_fma_f32 v142, -v133, v141, 1.0
	v_fmac_f32_e32 v141, v142, v141
	v_div_scale_f32 v142, vcc, 1.0, v135, 1.0
	v_mul_f32_e32 v143, v142, v141
	v_fma_f32 v144, -v133, v143, v142
	v_fmac_f32_e32 v143, v144, v141
	v_fma_f32 v133, -v133, v143, v142
	v_div_fmas_f32 v133, v133, v141, v143
	v_div_fixup_f32 v133, v133, v135, 1.0
	v_div_scale_f32 v135, s[0:1], v134, v134, 1.0
	v_rcp_f32_e32 v141, v135
	s_nop 0
	v_fma_f32 v142, -v135, v141, 1.0
	v_fmac_f32_e32 v141, v142, v141
	v_div_scale_f32 v142, vcc, 1.0, v134, 1.0
	v_mul_f32_e32 v143, v142, v141
	v_fma_f32 v144, -v135, v143, v142
	v_fmac_f32_e32 v143, v144, v141
	v_fma_f32 v135, -v135, v143, v142
	v_div_fmas_f32 v135, v135, v141, v143
	v_div_fixup_f32 v134, v135, v134, 1.0
	v_cvt_pk_bf16_f32 v133, v134, v133
	global_store_dwordx2 v[130:131], v[132:133], off offset:1536
	v_mul_f32_e32 v132, 0xbfb8aa3b, v114
	v_mul_f32_e32 v133, 0xbfb8aa3b, v115
	v_exp_f32_e32 v132, v132
	v_exp_f32_e32 v133, v133
	s_nop 0
	v_pk_add_f32 v[132:133], v[132:133], 1.0 op_sel_hi:[1,0]
	s_nop 0
	v_div_scale_f32 v134, s[0:1], v133, v133, 1.0
	v_rcp_f32_e32 v135, v134
	s_nop 0
	v_fma_f32 v141, -v134, v135, 1.0
	v_fmac_f32_e32 v135, v141, v135
	v_div_scale_f32 v141, vcc, 1.0, v133, 1.0
	v_mul_f32_e32 v142, v141, v135
	v_fma_f32 v143, -v134, v142, v141
	v_fmac_f32_e32 v142, v143, v135
	v_fma_f32 v134, -v134, v142, v141
	v_div_fmas_f32 v134, v134, v135, v142
	v_div_fixup_f32 v133, v134, v133, 1.0
	v_div_scale_f32 v134, s[0:1], v132, v132, 1.0
	v_rcp_f32_e32 v135, v134
	s_nop 0
	v_fma_f32 v141, -v134, v135, 1.0
	v_fmac_f32_e32 v135, v141, v135
	v_div_scale_f32 v141, vcc, 1.0, v132, 1.0
	v_mul_f32_e32 v142, v141, v135
	v_fma_f32 v143, -v134, v142, v141
	v_fmac_f32_e32 v142, v143, v135
	v_fma_f32 v134, -v134, v142, v141
	v_div_fmas_f32 v134, v134, v135, v142
	v_div_fixup_f32 v132, v134, v132, 1.0
	v_cvt_pk_bf16_f32 v132, v132, v133
	v_mul_f32_e32 v133, 0xbfb8aa3b, v116
	v_exp_f32_e32 v134, v133
	v_mul_f32_e32 v133, 0xbfb8aa3b, v117
	v_exp_f32_e32 v135, v133
	s_nop 0
	v_pk_add_f32 v[134:135], v[134:135], 1.0 op_sel_hi:[1,0]
	s_nop 0
	v_div_scale_f32 v133, s[0:1], v135, v135, 1.0
	v_rcp_f32_e32 v141, v133
	s_nop 0
	v_fma_f32 v142, -v133, v141, 1.0
	v_fmac_f32_e32 v141, v142, v141
	v_div_scale_f32 v142, vcc, 1.0, v135, 1.0
	v_mul_f32_e32 v143, v142, v141
	v_fma_f32 v144, -v133, v143, v142
	v_fmac_f32_e32 v143, v144, v141
	v_fma_f32 v133, -v133, v143, v142
	v_div_fmas_f32 v133, v133, v141, v143
	v_div_fixup_f32 v133, v133, v135, 1.0
	v_div_scale_f32 v135, s[0:1], v134, v134, 1.0
	v_rcp_f32_e32 v141, v135
	s_nop 0
	v_fma_f32 v142, -v135, v141, 1.0
	v_fmac_f32_e32 v141, v142, v141
	v_div_scale_f32 v142, vcc, 1.0, v134, 1.0
	v_mul_f32_e32 v143, v142, v141
	v_fma_f32 v144, -v135, v143, v142
	v_fmac_f32_e32 v143, v144, v141
	v_fma_f32 v135, -v135, v143, v142
	v_div_fmas_f32 v135, v135, v141, v143
	v_div_fixup_f32 v134, v135, v134, 1.0
	v_cvt_pk_bf16_f32 v133, v134, v133
	global_store_dwordx2 v[130:131], v[132:133], off offset:2048
	v_mul_f32_e32 v132, 0xbfb8aa3b, v118
	v_mul_f32_e32 v133, 0xbfb8aa3b, v119
	v_exp_f32_e32 v132, v132
	v_exp_f32_e32 v133, v133
	s_nop 0
	v_pk_add_f32 v[132:133], v[132:133], 1.0 op_sel_hi:[1,0]
	s_nop 0
	v_div_scale_f32 v134, s[0:1], v133, v133, 1.0
	v_rcp_f32_e32 v135, v134
	s_nop 0
	v_fma_f32 v141, -v134, v135, 1.0
	v_fmac_f32_e32 v135, v141, v135
	v_div_scale_f32 v141, vcc, 1.0, v133, 1.0
	v_mul_f32_e32 v142, v141, v135
	v_fma_f32 v143, -v134, v142, v141
	v_fmac_f32_e32 v142, v143, v135
	v_fma_f32 v134, -v134, v142, v141
	v_div_fmas_f32 v134, v134, v135, v142
	v_div_fixup_f32 v133, v134, v133, 1.0
	v_div_scale_f32 v134, s[0:1], v132, v132, 1.0
	v_rcp_f32_e32 v135, v134
	s_nop 0
	v_fma_f32 v141, -v134, v135, 1.0
	v_fmac_f32_e32 v135, v141, v135
	v_div_scale_f32 v141, vcc, 1.0, v132, 1.0
	v_mul_f32_e32 v142, v141, v135
	v_fma_f32 v143, -v134, v142, v141
	v_fmac_f32_e32 v142, v143, v135
	v_fma_f32 v134, -v134, v142, v141
	v_div_fmas_f32 v134, v134, v135, v142
	v_div_fixup_f32 v132, v134, v132, 1.0
	v_cvt_pk_bf16_f32 v132, v132, v133
	v_mul_f32_e32 v133, 0xbfb8aa3b, v120
	v_exp_f32_e32 v134, v133
	v_mul_f32_e32 v133, 0xbfb8aa3b, v121
	v_exp_f32_e32 v135, v133
	s_nop 0
	v_pk_add_f32 v[134:135], v[134:135], 1.0 op_sel_hi:[1,0]
	s_nop 0
	v_div_scale_f32 v133, s[0:1], v135, v135, 1.0
; DI unsigned pack2(float a, float b) { fl2_t f = {a, b}; bf2_t r = __builtin_convertvector(f, bf2_t); return __builtin_bit_cast(unsigned, r); }
; DI float sigmoidf_(float x) { return 1.f / (1.f + __expf(-x)); }
; DI void g1_phase(const P& p, int l, unsigned char* lds) {
;     ...
;       for (int mt = 0; mt < 4; ++mt) {
;         const int wave2 = (2 * wm + (mt >> 1)) * 2 + wn2, mt2 = mt & 1;
; #pragma unroll
;         for (int nt = 0; nt < 2; ++nt)
; #pragma unroll
;           for (int g4 = 0; g4 < 4; ++g4) {
;             size_t idx = ((((((size_t)tm_ * 8 + tn2) * 8 + wave2) * 2 + mt2) * 2 + nt) * 4 + g4) * 64 + lane;
;             *(uint2*)(gf + idx * 4) = make_uint2(pack2(sigmoidf_(acc[mt][nt][4 * g4]), sigmoidf_(acc[mt][nt][4 * g4 + 1])),
;                                                  pack2(sigmoidf_(acc[mt][nt][4 * g4 + 2]), sigmoidf_(acc[mt][nt][4 * g4 + 3])));
	v_rcp_f32_e32 v141, v133
	s_nop 0
	v_fma_f32 v142, -v133, v141, 1.0
	v_fmac_f32_e32 v141, v142, v141
	v_div_scale_f32 v142, vcc, 1.0, v135, 1.0
	v_mul_f32_e32 v143, v142, v141
	v_fma_f32 v144, -v133, v143, v142
	v_fmac_f32_e32 v143, v144, v141
	v_fma_f32 v133, -v133, v143, v142
	v_div_fmas_f32 v133, v133, v141, v143
	v_div_fixup_f32 v133, v133, v135, 1.0
	v_div_scale_f32 v135, s[0:1], v134, v134, 1.0
	v_rcp_f32_e32 v141, v135
	s_nop 0
	v_fma_f32 v142, -v135, v141, 1.0
	v_fmac_f32_e32 v141, v142, v141
	v_div_scale_f32 v142, vcc, 1.0, v134, 1.0
	v_mul_f32_e32 v143, v142, v141
	v_fma_f32 v144, -v135, v143, v142
	v_fmac_f32_e32 v143, v144, v141
	v_fma_f32 v135, -v135, v143, v142
	v_div_fmas_f32 v135, v135, v141, v143
	v_div_fixup_f32 v134, v135, v134, 1.0
	v_cvt_pk_bf16_f32 v133, v134, v133
	global_store_dwordx2 v[130:131], v[132:133], off offset:2560
	v_mul_f32_e32 v132, 0xbfb8aa3b, v122
	v_mul_f32_e32 v133, 0xbfb8aa3b, v123
	v_exp_f32_e32 v132, v132
	v_exp_f32_e32 v133, v133
	s_nop 0
	v_pk_add_f32 v[132:133], v[132:133], 1.0 op_sel_hi:[1,0]
	s_nop 0
	v_div_scale_f32 v134, s[0:1], v133, v133, 1.0
	v_rcp_f32_e32 v135, v134
	s_nop 0
	v_fma_f32 v141, -v134, v135, 1.0
	v_fmac_f32_e32 v135, v141, v135
	v_div_scale_f32 v141, vcc, 1.0, v133, 1.0
	v_mul_f32_e32 v142, v141, v135
	v_fma_f32 v143, -v134, v142, v141
	v_fmac_f32_e32 v142, v143, v135
	v_fma_f32 v134, -v134, v142, v141
	v_div_fmas_f32 v134, v134, v135, v142
	v_div_fixup_f32 v133, v134, v133, 1.0
	v_div_scale_f32 v134, s[0:1], v132, v132, 1.0
	v_rcp_f32_e32 v135, v134
	s_nop 0
	v_fma_f32 v141, -v134, v135, 1.0
	v_fmac_f32_e32 v135, v141, v135
	v_div_scale_f32 v141, vcc, 1.0, v132, 1.0
	v_mul_f32_e32 v142, v141, v135
	v_fma_f32 v143, -v134, v142, v141
	v_fmac_f32_e32 v142, v143, v135
	v_fma_f32 v134, -v134, v142, v141
	v_div_fmas_f32 v134, v134, v135, v142
	v_div_fixup_f32 v132, v134, v132, 1.0
	v_cvt_pk_bf16_f32 v132, v132, v133
	v_mul_f32_e32 v133, 0xbfb8aa3b, v124
	v_exp_f32_e32 v134, v133
	v_mul_f32_e32 v133, 0xbfb8aa3b, v125
	v_exp_f32_e32 v135, v133
	s_nop 0
	v_pk_add_f32 v[134:135], v[134:135], 1.0 op_sel_hi:[1,0]
	s_nop 0
	v_div_scale_f32 v133, s[0:1], v135, v135, 1.0
	v_rcp_f32_e32 v141, v133
	s_nop 0
	v_fma_f32 v142, -v133, v141, 1.0
	v_fmac_f32_e32 v141, v142, v141
	v_div_scale_f32 v142, vcc, 1.0, v135, 1.0
	v_mul_f32_e32 v143, v142, v141
	v_fma_f32 v144, -v133, v143, v142
	v_fmac_f32_e32 v143, v144, v141
	v_fma_f32 v133, -v133, v143, v142
	v_div_fmas_f32 v133, v133, v141, v143
	v_div_fixup_f32 v133, v133, v135, 1.0
	v_div_scale_f32 v135, s[0:1], v134, v134, 1.0
	v_rcp_f32_e32 v141, v135
	s_nop 0
	v_fma_f32 v142, -v135, v141, 1.0
	v_fmac_f32_e32 v141, v142, v141
	v_div_scale_f32 v142, vcc, 1.0, v134, 1.0
	v_mul_f32_e32 v143, v142, v141
	v_fma_f32 v144, -v135, v143, v142
	v_fmac_f32_e32 v143, v144, v141
	v_fma_f32 v135, -v135, v143, v142
	v_div_fmas_f32 v135, v135, v141, v143
	v_div_fixup_f32 v134, v135, v134, 1.0
	v_cvt_pk_bf16_f32 v133, v134, v133
	global_store_dwordx2 v[130:131], v[132:133], off offset:3072
	v_mul_f32_e32 v132, 0xbfb8aa3b, v126
	v_mul_f32_e32 v133, 0xbfb8aa3b, v127
	v_exp_f32_e32 v132, v132
	v_exp_f32_e32 v133, v133
	s_nop 0
	v_pk_add_f32 v[132:133], v[132:133], 1.0 op_sel_hi:[1,0]
	s_nop 0
	v_div_scale_f32 v134, s[0:1], v133, v133, 1.0
	v_rcp_f32_e32 v135, v134
	s_nop 0
	v_fma_f32 v141, -v134, v135, 1.0
	v_fmac_f32_e32 v135, v141, v135
	v_div_scale_f32 v141, vcc, 1.0, v133, 1.0
	v_mul_f32_e32 v142, v141, v135
	v_fma_f32 v143, -v134, v142, v141
	v_fmac_f32_e32 v142, v143, v135
	v_fma_f32 v134, -v134, v142, v141
	v_div_fmas_f32 v134, v134, v135, v142
	v_div_fixup_f32 v133, v134, v133, 1.0
	v_div_scale_f32 v134, s[0:1], v132, v132, 1.0
	v_rcp_f32_e32 v135, v134
	s_nop 0
	v_fma_f32 v141, -v134, v135, 1.0
	v_fmac_f32_e32 v135, v141, v135
	v_div_scale_f32 v141, vcc, 1.0, v132, 1.0
	v_mul_f32_e32 v142, v141, v135
	v_fma_f32 v143, -v134, v142, v141
	v_fmac_f32_e32 v142, v143, v135
	v_fma_f32 v134, -v134, v142, v141
	v_div_fmas_f32 v134, v134, v135, v142
	v_div_fixup_f32 v132, v134, v132, 1.0
	v_cvt_pk_bf16_f32 v132, v132, v133
	v_mul_f32_e32 v133, 0xbfb8aa3b, v128
	v_exp_f32_e32 v134, v133
	v_mul_f32_e32 v133, 0xbfb8aa3b, v129
	v_exp_f32_e32 v135, v133
	s_nop 0
	v_pk_add_f32 v[134:135], v[134:135], 1.0 op_sel_hi:[1,0]
	s_nop 0
	v_div_scale_f32 v133, s[0:1], v135, v135, 1.0
	v_rcp_f32_e32 v141, v133
	s_nop 0
	v_fma_f32 v142, -v133, v141, 1.0
	v_fmac_f32_e32 v141, v142, v141
	v_div_scale_f32 v142, vcc, 1.0, v135, 1.0
	v_mul_f32_e32 v143, v142, v141
	v_fma_f32 v144, -v133, v143, v142
	v_fmac_f32_e32 v143, v144, v141
	v_fma_f32 v133, -v133, v143, v142
	v_div_fmas_f32 v133, v133, v141, v143
	v_div_fixup_f32 v133, v133, v135, 1.0
	v_div_scale_f32 v135, s[0:1], v134, v134, 1.0
	v_rcp_f32_e32 v141, v135
	s_nop 0
	v_fma_f32 v142, -v135, v141, 1.0
	v_fmac_f32_e32 v141, v142, v141
	v_div_scale_f32 v142, vcc, 1.0, v134, 1.0
	v_mul_f32_e32 v143, v142, v141
	v_fma_f32 v144, -v135, v143, v142
	v_fmac_f32_e32 v143, v144, v141
	v_fma_f32 v135, -v135, v143, v142
	v_div_fmas_f32 v135, v135, v141, v143
	v_div_fixup_f32 v134, v135, v134, 1.0
	v_cvt_pk_bf16_f32 v133, v134, v133
	global_store_dwordx2 v[130:131], v[132:133], off offset:3584

; DI u16 f2bf(float a) { return (u16)(pack2(a, 0.f) & 0xffffu); }
; DI float sigmoidf_(float x) { return 1.f / (1.f + __expf(-x)); }
; DI size_t boff(int row, int k, int K) { return ((size_t)(row >> 8) * (K >> 6) + (k >> 6)) * 16384 + (row & 255) * 64 + (k & 63); }
; DI void moe1_phase(const P& p, int l, unsigned char* lds) {
;     ...
;     const int j = (n0 >> 1) + wn * 32 + r;
;     const float* b1 = p.in[I_BE1] + (size_t)(l * 32 + e) * 2048;
;     const float bg = b1[2 * j], bl = b1[2 * j + 1];
;     u16* abase = ACT + boff(m0 + wm * 128 + 4 * hh, j, 1024);
; #pragma unroll
;     for (int mt = 0; mt < 4; ++mt)
; #pragma unroll
;       for (int i = 0; i < 16; ++i) {
;         float ug = fminf(acc[mt][0][i] + bg, 7.f);
;         float ul = fminf(fmaxf(acc[mt][1][i] + bl, -7.f), 7.f);
;         float a = ug * sigmoidf_(1.702f * ug) * (ul + 1.f);
;         abase[(mt * 32 + 8 * (i >> 2) + (i & 3)) * 64] = f2bf(a);
;       }
.LBB0_1415:
	s_or_b64 exec, exec, s[0:1]
	s_waitcnt vmcnt(3)
	v_lshl_or_b32 v136, s6, 7, v196
	v_add_u32_e32 v130, s52, v174
	v_or_b32_e32 v132, v136, v194
	v_ashrrev_i32_e32 v131, 31, v130
	v_readlane_b32 s20, v252, 0
	v_lshlrev_b64 v[130:131], 13, v[130:131]
	v_readlane_b32 s21, v252, 1
	v_lshlrev_b32_e32 v132, 1, v132
	v_ashrrev_i32_e32 v133, 31, v132
	v_lshl_add_u64 v[130:131], s[20:21], 0, v[130:131]
	v_lshl_add_u64 v[130:131], v[132:133], 2, v[130:131]
	global_load_dwordx2 v[130:131], v[130:131], off
	v_add_u32_e32 v132, s17, v197
	v_ashrrev_i32_e32 v132, 8, v132
	v_ashrrev_i32_e32 v133, 31, v132
	v_ashrrev_i32_e32 v134, 6, v136
	v_readlane_b32 s0, v253, 1
	v_ashrrev_i32_e32 v135, 31, v134
	v_lshlrev_b64 v[132:133], 19, v[132:133]
	v_readlane_b32 s1, v253, 2
	v_lshlrev_b64 v[134:135], 15, v[134:135]
	v_bitop3_b32 v136, v136, 63, v194 bitop3:0xc8
	v_lshl_add_u64 v[132:133], s[0:1], 0, v[132:133]
	v_lshl_add_u64 v[132:133], v[132:133], 0, v[134:135]
	v_lshlrev_b32_e32 v178, 1, v136
	v_mov_b32_e32 v173, v179
	v_lshl_add_u64 v[132:133], v[132:133], 0, v[172:173]
	v_lshl_add_u64 v[132:133], v[132:133], 0, v[178:179]
	v_readlane_b32 s22, v252, 2
	v_readlane_b32 s23, v252, 3
	v_readlane_b32 s24, v252, 4
	v_readlane_b32 s25, v252, 5
	v_readlane_b32 s26, v252, 6
	v_readlane_b32 s27, v252, 7
	s_waitcnt vmcnt(0)
	v_min_f32_e32 v150, v18, v19
	v_min3_f32 v150, v150, v20, v21
	v_min3_f32 v150, v150, v22, v23
	v_min3_f32 v150, v150, v24, v25
	v_min3_f32 v150, v150, v26, v27
	v_min3_f32 v150, v150, v28, v29
	v_min3_f32 v150, v150, v30, v31
	v_min3_f32 v150, v150, v32, v33
	v_min3_f32 v150, v150, v50, v51
	v_min3_f32 v150, v150, v52, v53
	v_min3_f32 v150, v150, v54, v55
	v_min3_f32 v150, v150, v56, v57
	v_min3_f32 v150, v150, v58, v59
	v_min3_f32 v150, v150, v60, v61
	v_min3_f32 v150, v150, v62, v63
	v_min3_f32 v150, v150, v64, v65
	v_min3_f32 v150, v150, v82, v83
	v_min3_f32 v150, v150, v84, v85
	v_min3_f32 v150, v150, v86, v87
	v_min3_f32 v150, v150, v88, v89
	v_min3_f32 v150, v150, v90, v91
	v_min3_f32 v150, v150, v92, v93
	v_min3_f32 v150, v150, v94, v95
	v_min3_f32 v150, v150, v96, v97
	v_min3_f32 v150, v150, v114, v115
	v_min3_f32 v150, v150, v116, v117
	v_min3_f32 v150, v150, v118, v119
	v_min3_f32 v150, v150, v120, v121
	v_min3_f32 v150, v150, v122, v123
	v_min3_f32 v150, v150, v124, v125
	v_min3_f32 v150, v150, v126, v127
	v_min3_f32 v150, v150, v128, v129
	v_add_f32_e32 v150, v150, v130
	v_mov_b32_e32 v151, 0xc20c0000
	s_nop 0
	v_cmp_nlt_f32_e32 vcc, v151, v150
	s_cbranch_vccnz .Lmoe1_epi_slow
	v_add_f32_e32 v114, v114, v130
	v_min_f32_e32 v114, 0x40e00000, v114
	v_mul_f32_e32 v134, 0x3fd9db23, v114
	v_mul_f32_e32 v134, 0xbfb8aa3b, v134
	v_exp_f32_e32 v134, v134
	v_add_f32_e32 v98, v98, v131
	v_med3_f32 v98, v98, s36, v225
	v_add_f32_e32 v98, 1.0, v98
	v_add_f32_e32 v134, 1.0, v134
	v_rcp_f32_e32 v136, v134
	v_add_f32_e32 v99, v99, v131
	v_med3_f32 v99, v99, s36, v225
	v_add_f32_e32 v99, 1.0, v99
	v_fma_f32 v137, -v134, v136, 1.0
	v_fmac_f32_e32 v136, v137, v136
	v_fma_f32 v139, -v134, v136, 1.0
	v_fma_f32 v138, v139, v136, v136
	v_fma_f32 v135, -v134, v138, 1.0
	v_fma_f32 v135, v135, v136, v138
	v_mov_b32_e32 v134, v135
	v_mul_f32_e32 v114, v114, v134
	v_mul_f32_e32 v98, v98, v114
	v_cvt_pk_bf16_f32 v98, v98, s0
	global_store_short v[132:133], v98, off
	v_add_f32_e32 v98, v115, v130
	v_min_f32_e32 v98, 0x40e00000, v98
	v_mul_f32_e32 v114, 0x3fd9db23, v98
	v_mul_f32_e32 v114, 0xbfb8aa3b, v114
	v_exp_f32_e32 v114, v114
	v_add_f32_e32 v82, v82, v130
	v_min_f32_e32 v82, 0x40e00000, v82
	v_add_f32_e32 v66, v66, v131
	v_add_f32_e32 v114, 1.0, v114
	v_rcp_f32_e32 v134, v114
	v_med3_f32 v66, v66, s36, v225
	v_add_f32_e32 v66, 1.0, v66
	v_add_f32_e32 v67, v67, v131
	v_fma_f32 v135, -v114, v134, 1.0
	v_fmac_f32_e32 v134, v135, v134
	v_fma_f32 v137, -v114, v134, 1.0
	v_fma_f32 v136, v137, v134, v134
	v_fma_f32 v115, -v114, v136, 1.0
	v_fma_f32 v115, v115, v134, v136
	v_mov_b32_e32 v114, v115
	v_mul_f32_e32 v98, v98, v114
	v_mul_f32_e32 v98, v99, v98
	v_cvt_pk_bf16_f32 v98, v98, s0
	global_store_short v[132:133], v98, off offset:128
	v_add_f32_e32 v98, v116, v130
	v_min_f32_e32 v98, 0x40e00000, v98
	v_add_f32_e32 v99, v100, v131
	v_mul_f32_e32 v100, 0x3fd9db23, v98
	v_mul_f32_e32 v100, 0xbfb8aa3b, v100
	v_exp_f32_e32 v100, v100
	v_med3_f32 v99, v99, s36, v225
	v_add_f32_e32 v99, 1.0, v99
	v_med3_f32 v67, v67, s36, v225
	v_add_f32_e32 v100, 1.0, v100
	v_rcp_f32_e32 v115, v100
	v_add_f32_e32 v67, 1.0, v67
	v_add_f32_e32 v50, v50, v130
	v_min_f32_e32 v50, 0x40e00000, v50
	v_fma_f32 v116, -v100, v115, 1.0
	v_fmac_f32_e32 v115, v116, v115
	v_fma_f32 v135, -v100, v115, 1.0
	v_fma_f32 v134, v135, v115, v115
	v_fma_f32 v114, -v100, v134, 1.0
	v_fma_f32 v114, v114, v115, v134
	v_mov_b32_e32 v100, v114
	v_mul_f32_e32 v98, v98, v100
	v_mul_f32_e32 v98, v99, v98
	v_cvt_pk_bf16_f32 v98, v98, s0
	global_store_short v[132:133], v98, off offset:256
	v_add_f32_e32 v98, v117, v130
	v_min_f32_e32 v98, 0x40e00000, v98
	v_mul_f32_e32 v100, 0x3fd9db23, v98
	v_mul_f32_e32 v100, 0xbfb8aa3b, v100
	v_exp_f32_e32 v100, v100
	v_add_f32_e32 v99, v101, v131
	v_med3_f32 v99, v99, s36, v225
	v_add_f32_e32 v99, 1.0, v99
	v_add_f32_e32 v100, 1.0, v100
	v_rcp_f32_e32 v114, v100
	v_add_f32_e32 v34, v34, v131
	v_med3_f32 v34, v34, s36, v225
	v_add_f32_e32 v34, 1.0, v34
	v_fma_f32 v115, -v100, v114, 1.0
	v_fmac_f32_e32 v114, v115, v114
	v_fma_f32 v117, -v100, v114, 1.0
	v_fma_f32 v116, v117, v114, v114
	v_fma_f32 v101, -v100, v116, 1.0
	v_fma_f32 v101, v101, v114, v116
	v_mov_b32_e32 v100, v101
	v_mul_f32_e32 v98, v98, v100
	v_mul_f32_e32 v98, v99, v98
	v_cvt_pk_bf16_f32 v98, v98, s0
; DI u16 f2bf(float a) { return (u16)(pack2(a, 0.f) & 0xffffu); }
; DI float sigmoidf_(float x) { return 1.f / (1.f + __expf(-x)); }
; DI void moe1_phase(const P& p, int l, unsigned char* lds) {
;     ...
;     for (int mt = 0; mt < 4; ++mt)
; #pragma unroll
;       for (int i = 0; i < 16; ++i) {
;         float ug = fminf(acc[mt][0][i] + bg, 7.f);
;         float ul = fminf(fmaxf(acc[mt][1][i] + bl, -7.f), 7.f);
;         float a = ug * sigmoidf_(1.702f * ug) * (ul + 1.f);
;         abase[(mt * 32 + 8 * (i >> 2) + (i & 3)) * 64] = f2bf(a);
;       }
	global_store_short v[132:133], v98, off offset:384
	v_add_f32_e32 v98, v118, v130
	v_min_f32_e32 v98, 0x40e00000, v98
	v_mul_f32_e32 v100, 0x3fd9db23, v98
	v_mul_f32_e32 v100, 0xbfb8aa3b, v100
	v_exp_f32_e32 v100, v100
	v_add_f32_e32 v99, v102, v131
	v_med3_f32 v99, v99, s36, v225
	v_add_f32_e32 v99, 1.0, v99
	v_add_f32_e32 v100, 1.0, v100
	v_rcp_f32_e32 v102, v100
	v_add_f32_e32 v35, v35, v131
	v_med3_f32 v35, v35, s36, v225
	v_add_f32_e32 v35, 1.0, v35
	v_fma_f32 v114, -v100, v102, 1.0
	v_fmac_f32_e32 v102, v114, v102
	v_fma_f32 v116, -v100, v102, 1.0
	v_fma_f32 v115, v116, v102, v102
	v_fma_f32 v101, -v100, v115, 1.0
	v_fma_f32 v101, v101, v102, v115
	v_mov_b32_e32 v100, v101
	v_mul_f32_e32 v98, v98, v100
	v_mul_f32_e32 v98, v99, v98
	v_cvt_pk_bf16_f32 v98, v98, s0
	global_store_short v[132:133], v98, off offset:1024
	v_add_f32_e32 v98, v119, v130
	v_min_f32_e32 v98, 0x40e00000, v98
	v_mul_f32_e32 v100, 0x3fd9db23, v98
	v_mul_f32_e32 v100, 0xbfb8aa3b, v100
	v_exp_f32_e32 v100, v100
	v_add_f32_e32 v99, v103, v131
	v_med3_f32 v99, v99, s36, v225
	v_add_f32_e32 v99, 1.0, v99
	v_add_f32_e32 v100, 1.0, v100
	v_rcp_f32_e32 v102, v100
	v_add_f32_e32 v18, v18, v130
	v_min_f32_e32 v18, 0x40e00000, v18
	v_add_f32_e32 v2, v2, v131
	v_fma_f32 v103, -v100, v102, 1.0
	v_fmac_f32_e32 v102, v103, v102
	v_fma_f32 v115, -v100, v102, 1.0
	v_fma_f32 v114, v115, v102, v102
	v_fma_f32 v101, -v100, v114, 1.0
	v_fma_f32 v101, v101, v102, v114
	v_mov_b32_e32 v100, v101
	v_mul_f32_e32 v98, v98, v100
	v_mul_f32_e32 v98, v99, v98
	v_cvt_pk_bf16_f32 v98, v98, s0
	global_store_short v[132:133], v98, off offset:1152
	v_add_f32_e32 v98, v120, v130
	v_min_f32_e32 v98, 0x40e00000, v98
	v_mul_f32_e32 v100, 0x3fd9db23, v98
	v_mul_f32_e32 v100, 0xbfb8aa3b, v100
	v_exp_f32_e32 v100, v100
	v_add_f32_e32 v99, v104, v131
	v_med3_f32 v99, v99, s36, v225
	v_add_f32_e32 v99, 1.0, v99
	v_add_f32_e32 v100, 1.0, v100
	v_rcp_f32_e32 v102, v100
	v_med3_f32 v2, v2, s36, v225
	v_add_f32_e32 v2, 1.0, v2
	v_add_f32_e32 v3, v3, v131
	v_fma_f32 v103, -v100, v102, 1.0
	v_fmac_f32_e32 v102, v103, v102
	v_fma_f32 v114, -v100, v102, 1.0
	v_fma_f32 v104, v114, v102, v102
	v_fma_f32 v101, -v100, v104, 1.0
	v_fma_f32 v101, v101, v102, v104
	v_mov_b32_e32 v100, v101
	v_mul_f32_e32 v98, v98, v100
	v_mul_f32_e32 v98, v99, v98
	v_cvt_pk_bf16_f32 v98, v98, s0
	global_store_short v[132:133], v98, off offset:1280
	v_add_f32_e32 v98, v121, v130
	v_min_f32_e32 v98, 0x40e00000, v98
	v_mul_f32_e32 v100, 0x3fd9db23, v98
	v_mul_f32_e32 v100, 0xbfb8aa3b, v100
	v_exp_f32_e32 v100, v100
	v_add_f32_e32 v99, v105, v131
	v_med3_f32 v99, v99, s36, v225
	v_add_f32_e32 v99, 1.0, v99
	v_add_f32_e32 v100, 1.0, v100
	v_rcp_f32_e32 v102, v100
	v_med3_f32 v3, v3, s36, v225
	v_add_f32_e32 v3, 1.0, v3
	v_fma_f32 v103, -v100, v102, 1.0
	v_fmac_f32_e32 v102, v103, v102
	v_fma_f32 v105, -v100, v102, 1.0
	v_fma_f32 v104, v105, v102, v102
	v_fma_f32 v101, -v100, v104, 1.0
	v_fma_f32 v101, v101, v102, v104
	v_mov_b32_e32 v100, v101
	v_mul_f32_e32 v98, v98, v100
	v_mul_f32_e32 v98, v99, v98
	v_cvt_pk_bf16_f32 v98, v98, s0
	global_store_short v[132:133], v98, off offset:1408
	v_add_f32_e32 v98, v122, v130
	v_min_f32_e32 v98, 0x40e00000, v98
	v_mul_f32_e32 v100, 0x3fd9db23, v98
	v_mul_f32_e32 v100, 0xbfb8aa3b, v100
	v_exp_f32_e32 v100, v100
	v_add_f32_e32 v99, v106, v131
	v_med3_f32 v99, v99, s36, v225
	v_add_f32_e32 v99, 1.0, v99
	v_add_f32_e32 v100, 1.0, v100
	v_rcp_f32_e32 v102, v100
	s_nop 0
	v_fma_f32 v103, -v100, v102, 1.0
	v_fmac_f32_e32 v102, v103, v102
	v_fma_f32 v105, -v100, v102, 1.0
	v_fma_f32 v104, v105, v102, v102
	v_fma_f32 v101, -v100, v104, 1.0
	v_fma_f32 v101, v101, v102, v104
	v_mov_b32_e32 v100, v101
	v_mul_f32_e32 v98, v98, v100
	v_mul_f32_e32 v98, v99, v98
	v_cvt_pk_bf16_f32 v98, v98, s0
	global_store_short v[132:133], v98, off offset:2048
	v_add_f32_e32 v98, v123, v130
	v_min_f32_e32 v98, 0x40e00000, v98
	v_mul_f32_e32 v100, 0x3fd9db23, v98
	v_mul_f32_e32 v100, 0xbfb8aa3b, v100
	v_exp_f32_e32 v100, v100
	v_add_f32_e32 v99, v107, v131
	v_med3_f32 v99, v99, s36, v225
	v_add_f32_e32 v99, 1.0, v99
	v_add_f32_e32 v100, 1.0, v100
	v_rcp_f32_e32 v102, v100
	s_nop 0
	v_fma_f32 v103, -v100, v102, 1.0
	v_fmac_f32_e32 v102, v103, v102
	v_fma_f32 v105, -v100, v102, 1.0
	v_fma_f32 v104, v105, v102, v102
	v_fma_f32 v101, -v100, v104, 1.0
	v_fma_f32 v101, v101, v102, v104
	v_mov_b32_e32 v100, v101
	v_mul_f32_e32 v98, v98, v100
	v_mul_f32_e32 v98, v99, v98
	v_cvt_pk_bf16_f32 v98, v98, s0
	global_store_short v[132:133], v98, off offset:2176
	v_add_f32_e32 v98, v124, v130
	v_min_f32_e32 v98, 0x40e00000, v98
	v_mul_f32_e32 v100, 0x3fd9db23, v98
	v_mul_f32_e32 v100, 0xbfb8aa3b, v100
	v_exp_f32_e32 v100, v100
	v_add_f32_e32 v99, v108, v131
	v_med3_f32 v99, v99, s36, v225
	v_add_f32_e32 v99, 1.0, v99
	v_add_f32_e32 v100, 1.0, v100
	v_rcp_f32_e32 v102, v100
	s_nop 0
	v_fma_f32 v103, -v100, v102, 1.0
	v_fmac_f32_e32 v102, v103, v102
	v_fma_f32 v105, -v100, v102, 1.0
	v_fma_f32 v104, v105, v102, v102
	v_fma_f32 v101, -v100, v104, 1.0
	v_fma_f32 v101, v101, v102, v104
	v_mov_b32_e32 v100, v101
	v_mul_f32_e32 v98, v98, v100
	v_mul_f32_e32 v98, v99, v98
	v_cvt_pk_bf16_f32 v98, v98, s0
	global_store_short v[132:133], v98, off offset:2304
	v_add_f32_e32 v98, v125, v130
	v_min_f32_e32 v98, 0x40e00000, v98
	v_mul_f32_e32 v100, 0x3fd9db23, v98
	v_mul_f32_e32 v100, 0xbfb8aa3b, v100
	v_exp_f32_e32 v100, v100
	v_add_f32_e32 v99, v109, v131
	v_med3_f32 v99, v99, s36, v225
	v_add_f32_e32 v99, 1.0, v99
	v_add_f32_e32 v100, 1.0, v100
	v_rcp_f32_e32 v102, v100
	s_nop 0
	v_fma_f32 v103, -v100, v102, 1.0
	v_fmac_f32_e32 v102, v103, v102
; DI u16 f2bf(float a) { return (u16)(pack2(a, 0.f) & 0xffffu); }
; DI float sigmoidf_(float x) { return 1.f / (1.f + __expf(-x)); }
; DI void moe1_phase(const P& p, int l, unsigned char* lds) {
;     ...
;     for (int mt = 0; mt < 4; ++mt)
; #pragma unroll
;       for (int i = 0; i < 16; ++i) {
;         float ug = fminf(acc[mt][0][i] + bg, 7.f);
;         float ul = fminf(fmaxf(acc[mt][1][i] + bl, -7.f), 7.f);
;         float a = ug * sigmoidf_(1.702f * ug) * (ul + 1.f);
;         abase[(mt * 32 + 8 * (i >> 2) + (i & 3)) * 64] = f2bf(a);
;       }
	v_fma_f32 v105, -v100, v102, 1.0
	v_fma_f32 v104, v105, v102, v102
	v_fma_f32 v101, -v100, v104, 1.0
	v_fma_f32 v101, v101, v102, v104
	v_mov_b32_e32 v100, v101
	v_mul_f32_e32 v98, v98, v100
	v_mul_f32_e32 v98, v99, v98
	v_cvt_pk_bf16_f32 v98, v98, s0
	global_store_short v[132:133], v98, off offset:2432
	v_add_f32_e32 v98, v126, v130
	v_min_f32_e32 v98, 0x40e00000, v98
	v_mul_f32_e32 v100, 0x3fd9db23, v98
	v_mul_f32_e32 v100, 0xbfb8aa3b, v100
	v_exp_f32_e32 v100, v100
	v_add_f32_e32 v99, v110, v131
	v_med3_f32 v99, v99, s36, v225
	v_add_f32_e32 v99, 1.0, v99
	v_add_f32_e32 v100, 1.0, v100
	v_rcp_f32_e32 v102, v100
	s_nop 0
	v_fma_f32 v103, -v100, v102, 1.0
	v_fmac_f32_e32 v102, v103, v102
	v_fma_f32 v105, -v100, v102, 1.0
	v_fma_f32 v104, v105, v102, v102
	v_fma_f32 v101, -v100, v104, 1.0
	v_fma_f32 v101, v101, v102, v104
	v_mov_b32_e32 v100, v101
	v_mul_f32_e32 v98, v98, v100
	v_mul_f32_e32 v98, v99, v98
	v_cvt_pk_bf16_f32 v98, v98, s0
	global_store_short v[132:133], v98, off offset:3072
	v_add_f32_e32 v98, v127, v130
	v_min_f32_e32 v98, 0x40e00000, v98
	v_mul_f32_e32 v100, 0x3fd9db23, v98
	v_mul_f32_e32 v100, 0xbfb8aa3b, v100
	v_exp_f32_e32 v100, v100
	v_add_f32_e32 v99, v111, v131
	v_med3_f32 v99, v99, s36, v225
	v_add_f32_e32 v99, 1.0, v99
	v_add_f32_e32 v100, 1.0, v100
	v_rcp_f32_e32 v102, v100
	s_nop 0
	v_fma_f32 v103, -v100, v102, 1.0
	v_fmac_f32_e32 v102, v103, v102
	v_fma_f32 v105, -v100, v102, 1.0
	v_fma_f32 v104, v105, v102, v102
	v_fma_f32 v101, -v100, v104, 1.0
	v_fma_f32 v101, v101, v102, v104
	v_mov_b32_e32 v100, v101
	v_mul_f32_e32 v98, v98, v100
	v_mul_f32_e32 v98, v99, v98
	v_cvt_pk_bf16_f32 v98, v98, s0
	global_store_short v[132:133], v98, off offset:3200
	v_add_f32_e32 v98, v128, v130
	v_min_f32_e32 v98, 0x40e00000, v98
	v_mul_f32_e32 v100, 0x3fd9db23, v98
	v_mul_f32_e32 v100, 0xbfb8aa3b, v100
	v_exp_f32_e32 v100, v100
	v_add_f32_e32 v99, v112, v131
	v_med3_f32 v99, v99, s36, v225
	v_add_f32_e32 v99, 1.0, v99
	v_add_f32_e32 v100, 1.0, v100
	v_rcp_f32_e32 v102, v100
	s_nop 0
	v_fma_f32 v103, -v100, v102, 1.0
	v_fmac_f32_e32 v102, v103, v102
	v_fma_f32 v105, -v100, v102, 1.0
	v_fma_f32 v104, v105, v102, v102
	v_fma_f32 v101, -v100, v104, 1.0
	v_fma_f32 v101, v101, v102, v104
	v_mov_b32_e32 v100, v101
	v_mul_f32_e32 v98, v98, v100
	v_mul_f32_e32 v98, v99, v98
	v_cvt_pk_bf16_f32 v98, v98, s0
	global_store_short v[132:133], v98, off offset:3328
	v_add_f32_e32 v98, v129, v130
	v_min_f32_e32 v98, 0x40e00000, v98
	v_mul_f32_e32 v100, 0x3fd9db23, v98
	v_mul_f32_e32 v100, 0xbfb8aa3b, v100
	v_exp_f32_e32 v100, v100
	v_add_f32_e32 v99, v113, v131
	v_med3_f32 v99, v99, s36, v225
	v_add_f32_e32 v99, 1.0, v99
	v_add_f32_e32 v100, 1.0, v100
	v_rcp_f32_e32 v102, v100
	s_nop 0
	v_fma_f32 v103, -v100, v102, 1.0
	v_fmac_f32_e32 v102, v103, v102
	v_fma_f32 v105, -v100, v102, 1.0
	v_fma_f32 v104, v105, v102, v102
	v_fma_f32 v101, -v100, v104, 1.0
	v_fma_f32 v101, v101, v102, v104
	v_mov_b32_e32 v100, v101
	v_mul_f32_e32 v98, v98, v100
	v_mul_f32_e32 v98, v99, v98
	v_cvt_pk_bf16_f32 v98, v98, s0
	global_store_short v[132:133], v98, off offset:3456
	v_mul_f32_e32 v98, 0x3fd9db23, v82
	v_mul_f32_e32 v98, 0xbfb8aa3b, v98
	v_exp_f32_e32 v98, v98
	s_nop 0
	v_add_f32_e32 v98, 1.0, v98
	v_rcp_f32_e32 v100, v98
	s_nop 0
	v_fma_f32 v101, -v98, v100, 1.0
	v_fmac_f32_e32 v100, v101, v100
	v_fma_f32 v103, -v98, v100, 1.0
	v_fma_f32 v102, v103, v100, v100
	v_fma_f32 v99, -v98, v102, 1.0
	v_fma_f32 v99, v99, v100, v102
	v_mov_b32_e32 v98, v99
	v_add_co_u32_e32 v100, vcc, s46, v132
	v_mul_f32_e32 v82, v82, v98
	s_nop 0
	v_addc_co_u32_e32 v101, vcc, 0, v133, vcc
	v_mul_f32_e32 v66, v66, v82
	v_add_co_u32_e32 v98, vcc, s91, v132
	v_cvt_pk_bf16_f32 v66, v66, s0
	s_nop 0
	v_addc_co_u32_e32 v99, vcc, 0, v133, vcc
	global_store_short v[98:99], v66, off offset:-4096
	v_add_f32_e32 v66, v83, v130
	v_min_f32_e32 v66, 0x40e00000, v66
	v_mul_f32_e32 v82, 0x3fd9db23, v66
	v_mul_f32_e32 v82, 0xbfb8aa3b, v82
	v_exp_f32_e32 v82, v82
	s_nop 0
	v_add_f32_e32 v82, 1.0, v82
	v_rcp_f32_e32 v102, v82
	s_nop 0
	v_fma_f32 v103, -v82, v102, 1.0
	v_fmac_f32_e32 v102, v103, v102
	v_fma_f32 v105, -v82, v102, 1.0
	v_fma_f32 v104, v105, v102, v102
	v_fma_f32 v83, -v82, v104, 1.0
	v_fma_f32 v83, v83, v102, v104
	v_mov_b32_e32 v82, v83
	v_mul_f32_e32 v66, v66, v82
	v_mul_f32_e32 v66, v67, v66
	v_cvt_pk_bf16_f32 v66, v66, s0
	global_store_short v[100:101], v66, off offset:128
	v_add_f32_e32 v66, v84, v130
	v_min_f32_e32 v66, 0x40e00000, v66
	v_add_f32_e32 v67, v68, v131
	v_mul_f32_e32 v68, 0x3fd9db23, v66
	v_mul_f32_e32 v68, 0xbfb8aa3b, v68
	v_exp_f32_e32 v68, v68
	v_med3_f32 v67, v67, s36, v225
	v_add_f32_e32 v67, 1.0, v67
	v_add_f32_e32 v68, 1.0, v68
	v_rcp_f32_e32 v83, v68
	s_nop 0
	v_fma_f32 v84, -v68, v83, 1.0
	v_fmac_f32_e32 v83, v84, v83
	v_fma_f32 v103, -v68, v83, 1.0
	v_fma_f32 v102, v103, v83, v83
	v_fma_f32 v82, -v68, v102, 1.0
	v_fma_f32 v82, v82, v83, v102
	v_mov_b32_e32 v68, v82
	v_mul_f32_e32 v66, v66, v68
	v_mul_f32_e32 v66, v67, v66
	v_cvt_pk_bf16_f32 v66, v66, s0
	global_store_short v[100:101], v66, off offset:256
	v_add_f32_e32 v66, v85, v130
	v_min_f32_e32 v66, 0x40e00000, v66
	v_mul_f32_e32 v68, 0x3fd9db23, v66
	v_mul_f32_e32 v68, 0xbfb8aa3b, v68
	v_exp_f32_e32 v68, v68
	v_add_f32_e32 v67, v69, v131
	v_med3_f32 v67, v67, s36, v225
	v_add_f32_e32 v67, 1.0, v67
	v_add_f32_e32 v68, 1.0, v68
	v_rcp_f32_e32 v82, v68
	s_nop 0
	v_fma_f32 v83, -v68, v82, 1.0
	v_fmac_f32_e32 v82, v83, v82
	v_fma_f32 v85, -v68, v82, 1.0
	v_fma_f32 v84, v85, v82, v82
	v_fma_f32 v69, -v68, v84, 1.0
	v_fma_f32 v69, v69, v82, v84
	v_mov_b32_e32 v68, v69
	v_mul_f32_e32 v66, v66, v68
; DI u16 f2bf(float a) { return (u16)(pack2(a, 0.f) & 0xffffu); }
; DI float sigmoidf_(float x) { return 1.f / (1.f + __expf(-x)); }
; DI void moe1_phase(const P& p, int l, unsigned char* lds) {
;     ...
;     for (int mt = 0; mt < 4; ++mt)
; #pragma unroll
;       for (int i = 0; i < 16; ++i) {
;         float ug = fminf(acc[mt][0][i] + bg, 7.f);
;         float ul = fminf(fmaxf(acc[mt][1][i] + bl, -7.f), 7.f);
;         float a = ug * sigmoidf_(1.702f * ug) * (ul + 1.f);
;         abase[(mt * 32 + 8 * (i >> 2) + (i & 3)) * 64] = f2bf(a);
;       }
	v_mul_f32_e32 v66, v67, v66
	v_cvt_pk_bf16_f32 v66, v66, s0
	global_store_short v[100:101], v66, off offset:384
	v_add_f32_e32 v66, v86, v130
	v_min_f32_e32 v66, 0x40e00000, v66
	v_mul_f32_e32 v68, 0x3fd9db23, v66
	v_mul_f32_e32 v68, 0xbfb8aa3b, v68
	v_exp_f32_e32 v68, v68
	v_add_f32_e32 v67, v70, v131
	v_med3_f32 v67, v67, s36, v225
	v_add_f32_e32 v67, 1.0, v67
	v_add_f32_e32 v68, 1.0, v68
	v_rcp_f32_e32 v70, v68
	s_nop 0
	v_fma_f32 v82, -v68, v70, 1.0
	v_fmac_f32_e32 v70, v82, v70
	v_fma_f32 v84, -v68, v70, 1.0
	v_fma_f32 v83, v84, v70, v70
	v_fma_f32 v69, -v68, v83, 1.0
	v_fma_f32 v69, v69, v70, v83
	v_mov_b32_e32 v68, v69
	v_mul_f32_e32 v66, v66, v68
	v_mul_f32_e32 v66, v67, v66
	v_cvt_pk_bf16_f32 v66, v66, s0
	global_store_short v[100:101], v66, off offset:1024
	v_add_f32_e32 v66, v87, v130
	v_min_f32_e32 v66, 0x40e00000, v66
	v_mul_f32_e32 v68, 0x3fd9db23, v66
	v_mul_f32_e32 v68, 0xbfb8aa3b, v68
	v_exp_f32_e32 v68, v68
	v_add_f32_e32 v67, v71, v131
	v_med3_f32 v67, v67, s36, v225
	v_add_f32_e32 v67, 1.0, v67
	v_add_f32_e32 v68, 1.0, v68
	v_rcp_f32_e32 v70, v68
	s_nop 0
	v_fma_f32 v71, -v68, v70, 1.0
	v_fmac_f32_e32 v70, v71, v70
	v_fma_f32 v83, -v68, v70, 1.0
	v_fma_f32 v82, v83, v70, v70
	v_fma_f32 v69, -v68, v82, 1.0
	v_fma_f32 v69, v69, v70, v82
	v_mov_b32_e32 v68, v69
	v_mul_f32_e32 v66, v66, v68
	v_mul_f32_e32 v66, v67, v66
	v_cvt_pk_bf16_f32 v66, v66, s0
	global_store_short v[100:101], v66, off offset:1152
	v_add_f32_e32 v66, v88, v130
	v_min_f32_e32 v66, 0x40e00000, v66
	v_mul_f32_e32 v68, 0x3fd9db23, v66
	v_mul_f32_e32 v68, 0xbfb8aa3b, v68
	v_exp_f32_e32 v68, v68
	v_add_f32_e32 v67, v72, v131
	v_med3_f32 v67, v67, s36, v225
	v_add_f32_e32 v67, 1.0, v67
	v_add_f32_e32 v68, 1.0, v68
	v_rcp_f32_e32 v70, v68
	s_nop 0
	v_fma_f32 v71, -v68, v70, 1.0
	v_fmac_f32_e32 v70, v71, v70
	v_fma_f32 v82, -v68, v70, 1.0
	v_fma_f32 v72, v82, v70, v70
	v_fma_f32 v69, -v68, v72, 1.0
	v_fma_f32 v69, v69, v70, v72
	v_mov_b32_e32 v68, v69
	v_mul_f32_e32 v66, v66, v68
	v_mul_f32_e32 v66, v67, v66
	v_cvt_pk_bf16_f32 v66, v66, s0
	global_store_short v[100:101], v66, off offset:1280
	v_add_f32_e32 v66, v89, v130
	v_min_f32_e32 v66, 0x40e00000, v66
	v_mul_f32_e32 v68, 0x3fd9db23, v66
	v_mul_f32_e32 v68, 0xbfb8aa3b, v68
	v_exp_f32_e32 v68, v68
	v_add_f32_e32 v67, v73, v131
	v_med3_f32 v67, v67, s36, v225
	v_add_f32_e32 v67, 1.0, v67
	v_add_f32_e32 v68, 1.0, v68
	v_rcp_f32_e32 v70, v68
	s_nop 0
	v_fma_f32 v71, -v68, v70, 1.0
	v_fmac_f32_e32 v70, v71, v70
	v_fma_f32 v73, -v68, v70, 1.0
	v_fma_f32 v72, v73, v70, v70
	v_fma_f32 v69, -v68, v72, 1.0
	v_fma_f32 v69, v69, v70, v72
	v_mov_b32_e32 v68, v69
	v_mul_f32_e32 v66, v66, v68
	v_mul_f32_e32 v66, v67, v66
	v_cvt_pk_bf16_f32 v66, v66, s0
	global_store_short v[100:101], v66, off offset:1408
	v_add_f32_e32 v66, v90, v130
	v_min_f32_e32 v66, 0x40e00000, v66
	v_mul_f32_e32 v68, 0x3fd9db23, v66
	v_mul_f32_e32 v68, 0xbfb8aa3b, v68
	v_exp_f32_e32 v68, v68
	v_add_f32_e32 v67, v74, v131
	v_med3_f32 v67, v67, s36, v225
	v_add_f32_e32 v67, 1.0, v67
	v_add_f32_e32 v68, 1.0, v68
	v_rcp_f32_e32 v70, v68
	s_nop 0
	v_fma_f32 v71, -v68, v70, 1.0
	v_fmac_f32_e32 v70, v71, v70
	v_fma_f32 v73, -v68, v70, 1.0
	v_fma_f32 v72, v73, v70, v70
	v_fma_f32 v69, -v68, v72, 1.0
	v_fma_f32 v69, v69, v70, v72
	v_mov_b32_e32 v68, v69
	v_mul_f32_e32 v66, v66, v68
	v_mul_f32_e32 v66, v67, v66
	v_cvt_pk_bf16_f32 v66, v66, s0
	global_store_short v[100:101], v66, off offset:2048
	v_add_f32_e32 v66, v91, v130
	v_min_f32_e32 v66, 0x40e00000, v66
	v_mul_f32_e32 v68, 0x3fd9db23, v66
	v_mul_f32_e32 v68, 0xbfb8aa3b, v68
	v_exp_f32_e32 v68, v68
	v_add_f32_e32 v67, v75, v131
	v_med3_f32 v67, v67, s36, v225
	v_add_f32_e32 v67, 1.0, v67
	v_add_f32_e32 v68, 1.0, v68
	v_rcp_f32_e32 v70, v68
	s_nop 0
	v_fma_f32 v71, -v68, v70, 1.0
	v_fmac_f32_e32 v70, v71, v70
	v_fma_f32 v73, -v68, v70, 1.0
	v_fma_f32 v72, v73, v70, v70
	v_fma_f32 v69, -v68, v72, 1.0
	v_fma_f32 v69, v69, v70, v72
	v_mov_b32_e32 v68, v69
	v_mul_f32_e32 v66, v66, v68
	v_mul_f32_e32 v66, v67, v66
	v_cvt_pk_bf16_f32 v66, v66, s0
	global_store_short v[100:101], v66, off offset:2176
	v_add_f32_e32 v66, v92, v130
	v_min_f32_e32 v66, 0x40e00000, v66
	v_mul_f32_e32 v68, 0x3fd9db23, v66
	v_mul_f32_e32 v68, 0xbfb8aa3b, v68
	v_exp_f32_e32 v68, v68
	v_add_f32_e32 v67, v76, v131
	v_med3_f32 v67, v67, s36, v225
	v_add_f32_e32 v67, 1.0, v67
	v_add_f32_e32 v68, 1.0, v68
	v_rcp_f32_e32 v70, v68
	s_nop 0
	v_fma_f32 v71, -v68, v70, 1.0
	v_fmac_f32_e32 v70, v71, v70
	v_fma_f32 v73, -v68, v70, 1.0
	v_fma_f32 v72, v73, v70, v70
	v_fma_f32 v69, -v68, v72, 1.0
	v_fma_f32 v69, v69, v70, v72
	v_mov_b32_e32 v68, v69
	v_mul_f32_e32 v66, v66, v68
	v_mul_f32_e32 v66, v67, v66
	v_cvt_pk_bf16_f32 v66, v66, s0
	global_store_short v[100:101], v66, off offset:2304
	v_add_f32_e32 v66, v93, v130
	v_min_f32_e32 v66, 0x40e00000, v66
	v_mul_f32_e32 v68, 0x3fd9db23, v66
	v_mul_f32_e32 v68, 0xbfb8aa3b, v68
	v_exp_f32_e32 v68, v68
	v_add_f32_e32 v67, v77, v131
	v_med3_f32 v67, v67, s36, v225
	v_add_f32_e32 v67, 1.0, v67
	v_add_f32_e32 v68, 1.0, v68
	v_rcp_f32_e32 v70, v68
	s_nop 0
	v_fma_f32 v71, -v68, v70, 1.0
	v_fmac_f32_e32 v70, v71, v70
	v_fma_f32 v73, -v68, v70, 1.0
	v_fma_f32 v72, v73, v70, v70
	v_fma_f32 v69, -v68, v72, 1.0
	v_fma_f32 v69, v69, v70, v72
	v_mov_b32_e32 v68, v69
	v_mul_f32_e32 v66, v66, v68
	v_mul_f32_e32 v66, v67, v66
	v_cvt_pk_bf16_f32 v66, v66, s0
	global_store_short v[100:101], v66, off offset:2432
	v_add_f32_e32 v66, v94, v130
	v_min_f32_e32 v66, 0x40e00000, v66
	v_mul_f32_e32 v68, 0x3fd9db23, v66
	v_mul_f32_e32 v68, 0xbfb8aa3b, v68
	v_exp_f32_e32 v68, v68
	v_add_f32_e32 v67, v78, v131
; DI u16 f2bf(float a) { return (u16)(pack2(a, 0.f) & 0xffffu); }
; DI float sigmoidf_(float x) { return 1.f / (1.f + __expf(-x)); }
; DI void moe1_phase(const P& p, int l, unsigned char* lds) {
;     ...
;     for (int mt = 0; mt < 4; ++mt)
; #pragma unroll
;       for (int i = 0; i < 16; ++i) {
;         float ug = fminf(acc[mt][0][i] + bg, 7.f);
;         float ul = fminf(fmaxf(acc[mt][1][i] + bl, -7.f), 7.f);
;         float a = ug * sigmoidf_(1.702f * ug) * (ul + 1.f);
;         abase[(mt * 32 + 8 * (i >> 2) + (i & 3)) * 64] = f2bf(a);
;       }
	v_med3_f32 v67, v67, s36, v225
	v_add_f32_e32 v67, 1.0, v67
	v_add_f32_e32 v68, 1.0, v68
	v_rcp_f32_e32 v70, v68
	s_nop 0
	v_fma_f32 v71, -v68, v70, 1.0
	v_fmac_f32_e32 v70, v71, v70
	v_fma_f32 v73, -v68, v70, 1.0
	v_fma_f32 v72, v73, v70, v70
	v_fma_f32 v69, -v68, v72, 1.0
	v_fma_f32 v69, v69, v70, v72
	v_mov_b32_e32 v68, v69
	v_mul_f32_e32 v66, v66, v68
	v_mul_f32_e32 v66, v67, v66
	v_cvt_pk_bf16_f32 v66, v66, s0
	global_store_short v[100:101], v66, off offset:3072
	v_add_f32_e32 v66, v95, v130
	v_min_f32_e32 v66, 0x40e00000, v66
	v_mul_f32_e32 v68, 0x3fd9db23, v66
	v_mul_f32_e32 v68, 0xbfb8aa3b, v68
	v_exp_f32_e32 v68, v68
	v_add_f32_e32 v67, v79, v131
	v_med3_f32 v67, v67, s36, v225
	v_add_f32_e32 v67, 1.0, v67
	v_add_f32_e32 v68, 1.0, v68
	v_rcp_f32_e32 v70, v68
	s_nop 0
	v_fma_f32 v71, -v68, v70, 1.0
	v_fmac_f32_e32 v70, v71, v70
	v_fma_f32 v73, -v68, v70, 1.0
	v_fma_f32 v72, v73, v70, v70
	v_fma_f32 v69, -v68, v72, 1.0
	v_fma_f32 v69, v69, v70, v72
	v_mov_b32_e32 v68, v69
	v_mul_f32_e32 v66, v66, v68
	v_mul_f32_e32 v66, v67, v66
	v_cvt_pk_bf16_f32 v66, v66, s0
	global_store_short v[100:101], v66, off offset:3200
	v_add_f32_e32 v66, v96, v130
	v_min_f32_e32 v66, 0x40e00000, v66
	v_mul_f32_e32 v68, 0x3fd9db23, v66
	v_mul_f32_e32 v68, 0xbfb8aa3b, v68
	v_exp_f32_e32 v68, v68
	v_add_f32_e32 v67, v80, v131
	v_med3_f32 v67, v67, s36, v225
	v_add_f32_e32 v67, 1.0, v67
	v_add_f32_e32 v68, 1.0, v68
	v_rcp_f32_e32 v70, v68
	s_nop 0
	v_fma_f32 v71, -v68, v70, 1.0
	v_fmac_f32_e32 v70, v71, v70
	v_fma_f32 v73, -v68, v70, 1.0
	v_fma_f32 v72, v73, v70, v70
	v_fma_f32 v69, -v68, v72, 1.0
	v_fma_f32 v69, v69, v70, v72
	v_mov_b32_e32 v68, v69
	v_mul_f32_e32 v66, v66, v68
	v_mul_f32_e32 v66, v67, v66
	v_cvt_pk_bf16_f32 v66, v66, s0
	global_store_short v[100:101], v66, off offset:3328
	v_add_f32_e32 v66, v97, v130
	v_min_f32_e32 v66, 0x40e00000, v66
	v_mul_f32_e32 v68, 0x3fd9db23, v66
	v_mul_f32_e32 v68, 0xbfb8aa3b, v68
	v_exp_f32_e32 v68, v68
	v_add_f32_e32 v67, v81, v131
	v_med3_f32 v67, v67, s36, v225
	v_add_f32_e32 v67, 1.0, v67
	v_add_f32_e32 v68, 1.0, v68
	v_rcp_f32_e32 v70, v68
	s_nop 0
	v_fma_f32 v71, -v68, v70, 1.0
	v_fmac_f32_e32 v70, v71, v70
	v_fma_f32 v73, -v68, v70, 1.0
	v_fma_f32 v72, v73, v70, v70
	v_fma_f32 v69, -v68, v72, 1.0
	v_fma_f32 v69, v69, v70, v72
	v_mov_b32_e32 v68, v69
	v_mul_f32_e32 v66, v66, v68
	v_mul_f32_e32 v66, v67, v66
	v_cvt_pk_bf16_f32 v66, v66, s0
	global_store_short v[100:101], v66, off offset:3456
	v_mul_f32_e32 v66, 0x3fd9db23, v50
	v_mul_f32_e32 v66, 0xbfb8aa3b, v66
	v_exp_f32_e32 v66, v66
	s_nop 0
	v_add_f32_e32 v66, 1.0, v66
	v_rcp_f32_e32 v68, v66
	s_nop 0
	v_fma_f32 v69, -v66, v68, 1.0
	v_fmac_f32_e32 v68, v69, v68
	v_fma_f32 v71, -v66, v68, 1.0
	v_fma_f32 v70, v71, v68, v68
	v_fma_f32 v67, -v66, v70, 1.0
	v_fma_f32 v67, v67, v68, v70
	v_mov_b32_e32 v66, v67
	v_mul_f32_e32 v50, v50, v66
	v_mul_f32_e32 v34, v34, v50
	v_cvt_pk_bf16_f32 v34, v34, s0
	global_store_short v[98:99], v34, off
	v_add_f32_e32 v34, v51, v130
	v_min_f32_e32 v34, 0x40e00000, v34
	v_mul_f32_e32 v50, 0x3fd9db23, v34
	v_mul_f32_e32 v50, 0xbfb8aa3b, v50
	v_exp_f32_e32 v50, v50
	s_nop 0
	v_add_f32_e32 v50, 1.0, v50
	v_rcp_f32_e32 v66, v50
	s_nop 0
	v_fma_f32 v67, -v50, v66, 1.0
	v_fmac_f32_e32 v66, v67, v66
	v_fma_f32 v69, -v50, v66, 1.0
	v_fma_f32 v68, v69, v66, v66
	v_fma_f32 v51, -v50, v68, 1.0
	v_fma_f32 v51, v51, v66, v68
	v_mov_b32_e32 v50, v51
	v_mul_f32_e32 v34, v34, v50
	v_mul_f32_e32 v34, v35, v34
	v_cvt_pk_bf16_f32 v34, v34, s0
	global_store_short v[98:99], v34, off offset:128
	v_add_f32_e32 v34, v52, v130
	v_min_f32_e32 v34, 0x40e00000, v34
	v_add_f32_e32 v35, v36, v131
	v_mul_f32_e32 v36, 0x3fd9db23, v34
	v_mul_f32_e32 v36, 0xbfb8aa3b, v36
	v_exp_f32_e32 v36, v36
	v_med3_f32 v35, v35, s36, v225
	v_add_f32_e32 v35, 1.0, v35
	v_add_f32_e32 v36, 1.0, v36
	v_rcp_f32_e32 v51, v36
	s_nop 0
	v_fma_f32 v52, -v36, v51, 1.0
	v_fmac_f32_e32 v51, v52, v51
	v_fma_f32 v67, -v36, v51, 1.0
	v_fma_f32 v66, v67, v51, v51
	v_fma_f32 v50, -v36, v66, 1.0
	v_fma_f32 v50, v50, v51, v66
	v_mov_b32_e32 v36, v50
	v_mul_f32_e32 v34, v34, v36
	v_mul_f32_e32 v34, v35, v34
	v_cvt_pk_bf16_f32 v34, v34, s0
	global_store_short v[98:99], v34, off offset:256
	v_add_f32_e32 v34, v53, v130
	v_min_f32_e32 v34, 0x40e00000, v34
	v_mul_f32_e32 v36, 0x3fd9db23, v34
	v_mul_f32_e32 v36, 0xbfb8aa3b, v36
	v_exp_f32_e32 v36, v36
	v_add_f32_e32 v35, v37, v131
	v_med3_f32 v35, v35, s36, v225
	v_add_f32_e32 v35, 1.0, v35
	v_add_f32_e32 v36, 1.0, v36
	v_rcp_f32_e32 v50, v36
	s_nop 0
	v_fma_f32 v51, -v36, v50, 1.0
	v_fmac_f32_e32 v50, v51, v50
	v_fma_f32 v53, -v36, v50, 1.0
	v_fma_f32 v52, v53, v50, v50
	v_fma_f32 v37, -v36, v52, 1.0
	v_fma_f32 v37, v37, v50, v52
	v_mov_b32_e32 v36, v37
	v_mul_f32_e32 v34, v34, v36
	v_mul_f32_e32 v34, v35, v34
	v_cvt_pk_bf16_f32 v34, v34, s0
	global_store_short v[98:99], v34, off offset:384
	v_add_f32_e32 v34, v54, v130
	v_min_f32_e32 v34, 0x40e00000, v34
	v_mul_f32_e32 v36, 0x3fd9db23, v34
	v_mul_f32_e32 v36, 0xbfb8aa3b, v36
	v_exp_f32_e32 v36, v36
	v_add_f32_e32 v35, v38, v131
	v_med3_f32 v35, v35, s36, v225
	v_add_f32_e32 v35, 1.0, v35
	v_add_f32_e32 v36, 1.0, v36
	v_rcp_f32_e32 v38, v36
	s_nop 0
	v_fma_f32 v50, -v36, v38, 1.0
	v_fmac_f32_e32 v38, v50, v38
	v_fma_f32 v52, -v36, v38, 1.0
	v_fma_f32 v51, v52, v38, v38
	v_fma_f32 v37, -v36, v51, 1.0
	v_fma_f32 v37, v37, v38, v51
	v_mov_b32_e32 v36, v37
	v_mul_f32_e32 v34, v34, v36
	v_mul_f32_e32 v34, v35, v34
	v_cvt_pk_bf16_f32 v34, v34, s0
	global_store_short v[98:99], v34, off offset:1024
	v_add_f32_e32 v34, v55, v130
	v_min_f32_e32 v34, 0x40e00000, v34
	v_mul_f32_e32 v36, 0x3fd9db23, v34
; DI u16 f2bf(float a) { return (u16)(pack2(a, 0.f) & 0xffffu); }
; DI float sigmoidf_(float x) { return 1.f / (1.f + __expf(-x)); }
; DI void moe1_phase(const P& p, int l, unsigned char* lds) {
;     ...
;     for (int mt = 0; mt < 4; ++mt)
; #pragma unroll
;       for (int i = 0; i < 16; ++i) {
;         float ug = fminf(acc[mt][0][i] + bg, 7.f);
;         float ul = fminf(fmaxf(acc[mt][1][i] + bl, -7.f), 7.f);
;         float a = ug * sigmoidf_(1.702f * ug) * (ul + 1.f);
;         abase[(mt * 32 + 8 * (i >> 2) + (i & 3)) * 64] = f2bf(a);
;       }
	v_mul_f32_e32 v36, 0xbfb8aa3b, v36
	v_exp_f32_e32 v36, v36
	v_add_f32_e32 v35, v39, v131
	v_med3_f32 v35, v35, s36, v225
	v_add_f32_e32 v35, 1.0, v35
	v_add_f32_e32 v36, 1.0, v36
	v_rcp_f32_e32 v38, v36
	s_nop 0
	v_fma_f32 v39, -v36, v38, 1.0
	v_fmac_f32_e32 v38, v39, v38
	v_fma_f32 v51, -v36, v38, 1.0
	v_fma_f32 v50, v51, v38, v38
	v_fma_f32 v37, -v36, v50, 1.0
	v_fma_f32 v37, v37, v38, v50
	v_mov_b32_e32 v36, v37
	v_mul_f32_e32 v34, v34, v36
	v_mul_f32_e32 v34, v35, v34
	v_cvt_pk_bf16_f32 v34, v34, s0
	global_store_short v[98:99], v34, off offset:1152
	v_add_f32_e32 v34, v56, v130
	v_min_f32_e32 v34, 0x40e00000, v34
	v_mul_f32_e32 v36, 0x3fd9db23, v34
	v_mul_f32_e32 v36, 0xbfb8aa3b, v36
	v_exp_f32_e32 v36, v36
	v_add_f32_e32 v35, v40, v131
	v_med3_f32 v35, v35, s36, v225
	v_add_f32_e32 v35, 1.0, v35
	v_add_f32_e32 v36, 1.0, v36
	v_rcp_f32_e32 v38, v36
	s_nop 0
	v_fma_f32 v39, -v36, v38, 1.0
	v_fmac_f32_e32 v38, v39, v38
	v_fma_f32 v50, -v36, v38, 1.0
	v_fma_f32 v40, v50, v38, v38
	v_fma_f32 v37, -v36, v40, 1.0
	v_fma_f32 v37, v37, v38, v40
	v_mov_b32_e32 v36, v37
	v_mul_f32_e32 v34, v34, v36
	v_mul_f32_e32 v34, v35, v34
	v_cvt_pk_bf16_f32 v34, v34, s0
	global_store_short v[98:99], v34, off offset:1280
	v_add_f32_e32 v34, v57, v130
	v_min_f32_e32 v34, 0x40e00000, v34
	v_mul_f32_e32 v36, 0x3fd9db23, v34
	v_mul_f32_e32 v36, 0xbfb8aa3b, v36
	v_exp_f32_e32 v36, v36
	v_add_f32_e32 v35, v41, v131
	v_med3_f32 v35, v35, s36, v225
	v_add_f32_e32 v35, 1.0, v35
	v_add_f32_e32 v36, 1.0, v36
	v_rcp_f32_e32 v38, v36
	s_nop 0
	v_fma_f32 v39, -v36, v38, 1.0
	v_fmac_f32_e32 v38, v39, v38
	v_fma_f32 v41, -v36, v38, 1.0
	v_fma_f32 v40, v41, v38, v38
	v_fma_f32 v37, -v36, v40, 1.0
	v_fma_f32 v37, v37, v38, v40
	v_mov_b32_e32 v36, v37
	v_mul_f32_e32 v34, v34, v36
	v_mul_f32_e32 v34, v35, v34
	v_cvt_pk_bf16_f32 v34, v34, s0
	global_store_short v[98:99], v34, off offset:1408
	v_add_f32_e32 v34, v58, v130
	v_min_f32_e32 v34, 0x40e00000, v34
	v_mul_f32_e32 v36, 0x3fd9db23, v34
	v_mul_f32_e32 v36, 0xbfb8aa3b, v36
	v_exp_f32_e32 v36, v36
	v_add_f32_e32 v35, v42, v131
	v_med3_f32 v35, v35, s36, v225
	v_add_f32_e32 v35, 1.0, v35
	v_add_f32_e32 v36, 1.0, v36
	v_rcp_f32_e32 v38, v36
	s_nop 0
	v_fma_f32 v39, -v36, v38, 1.0
	v_fmac_f32_e32 v38, v39, v38
	v_fma_f32 v41, -v36, v38, 1.0
	v_fma_f32 v40, v41, v38, v38
	v_fma_f32 v37, -v36, v40, 1.0
	v_fma_f32 v37, v37, v38, v40
	v_mov_b32_e32 v36, v37
	v_mul_f32_e32 v34, v34, v36
	v_mul_f32_e32 v34, v35, v34
	v_cvt_pk_bf16_f32 v34, v34, s0
	global_store_short v[98:99], v34, off offset:2048
	v_add_f32_e32 v34, v59, v130
	v_min_f32_e32 v34, 0x40e00000, v34
	v_mul_f32_e32 v36, 0x3fd9db23, v34
	v_mul_f32_e32 v36, 0xbfb8aa3b, v36
	v_exp_f32_e32 v36, v36
	v_add_f32_e32 v35, v43, v131
	v_med3_f32 v35, v35, s36, v225
	v_add_f32_e32 v35, 1.0, v35
	v_add_f32_e32 v36, 1.0, v36
	v_rcp_f32_e32 v38, v36
	s_nop 0
	v_fma_f32 v39, -v36, v38, 1.0
	v_fmac_f32_e32 v38, v39, v38
	v_fma_f32 v41, -v36, v38, 1.0
	v_fma_f32 v40, v41, v38, v38
	v_fma_f32 v37, -v36, v40, 1.0
	v_fma_f32 v37, v37, v38, v40
	v_mov_b32_e32 v36, v37
	v_mul_f32_e32 v34, v34, v36
	v_mul_f32_e32 v34, v35, v34
	v_cvt_pk_bf16_f32 v34, v34, s0
	global_store_short v[98:99], v34, off offset:2176
	v_add_f32_e32 v34, v60, v130
	v_min_f32_e32 v34, 0x40e00000, v34
	v_mul_f32_e32 v36, 0x3fd9db23, v34
	v_mul_f32_e32 v36, 0xbfb8aa3b, v36
	v_exp_f32_e32 v36, v36
	v_add_f32_e32 v35, v44, v131
	v_med3_f32 v35, v35, s36, v225
	v_add_f32_e32 v35, 1.0, v35
	v_add_f32_e32 v36, 1.0, v36
	v_rcp_f32_e32 v38, v36
	s_nop 0
	v_fma_f32 v39, -v36, v38, 1.0
	v_fmac_f32_e32 v38, v39, v38
	v_fma_f32 v41, -v36, v38, 1.0
	v_fma_f32 v40, v41, v38, v38
	v_fma_f32 v37, -v36, v40, 1.0
	v_fma_f32 v37, v37, v38, v40
	v_mov_b32_e32 v36, v37
	v_mul_f32_e32 v34, v34, v36
	v_mul_f32_e32 v34, v35, v34
	v_cvt_pk_bf16_f32 v34, v34, s0
	global_store_short v[98:99], v34, off offset:2304
	v_add_f32_e32 v34, v61, v130
	v_min_f32_e32 v34, 0x40e00000, v34
	v_mul_f32_e32 v36, 0x3fd9db23, v34
	v_mul_f32_e32 v36, 0xbfb8aa3b, v36
	v_exp_f32_e32 v36, v36
	v_add_f32_e32 v35, v45, v131
	v_med3_f32 v35, v35, s36, v225
	v_add_f32_e32 v35, 1.0, v35
	v_add_f32_e32 v36, 1.0, v36
	v_rcp_f32_e32 v38, v36
	s_nop 0
	v_fma_f32 v39, -v36, v38, 1.0
	v_fmac_f32_e32 v38, v39, v38
	v_fma_f32 v41, -v36, v38, 1.0
	v_fma_f32 v40, v41, v38, v38
	v_fma_f32 v37, -v36, v40, 1.0
	v_fma_f32 v37, v37, v38, v40
	v_mov_b32_e32 v36, v37
	v_mul_f32_e32 v34, v34, v36
	v_mul_f32_e32 v34, v35, v34
	v_cvt_pk_bf16_f32 v34, v34, s0
	global_store_short v[98:99], v34, off offset:2432
	v_add_f32_e32 v34, v62, v130
	v_min_f32_e32 v34, 0x40e00000, v34
	v_mul_f32_e32 v36, 0x3fd9db23, v34
	v_mul_f32_e32 v36, 0xbfb8aa3b, v36
	v_exp_f32_e32 v36, v36
	v_add_f32_e32 v35, v46, v131
	v_med3_f32 v35, v35, s36, v225
	v_add_f32_e32 v35, 1.0, v35
	v_add_f32_e32 v36, 1.0, v36
	v_rcp_f32_e32 v38, v36
	s_nop 0
	v_fma_f32 v39, -v36, v38, 1.0
	v_fmac_f32_e32 v38, v39, v38
	v_fma_f32 v41, -v36, v38, 1.0
	v_fma_f32 v40, v41, v38, v38
	v_fma_f32 v37, -v36, v40, 1.0
	v_fma_f32 v37, v37, v38, v40
	v_mov_b32_e32 v36, v37
	v_mul_f32_e32 v34, v34, v36
	v_mul_f32_e32 v34, v35, v34
	v_cvt_pk_bf16_f32 v34, v34, s0
	global_store_short v[98:99], v34, off offset:3072
	v_add_f32_e32 v34, v63, v130
	v_min_f32_e32 v34, 0x40e00000, v34
	v_mul_f32_e32 v36, 0x3fd9db23, v34
	v_mul_f32_e32 v36, 0xbfb8aa3b, v36
	v_exp_f32_e32 v36, v36
	v_add_f32_e32 v35, v47, v131
	v_med3_f32 v35, v35, s36, v225
	v_add_f32_e32 v35, 1.0, v35
	v_add_f32_e32 v36, 1.0, v36
	v_rcp_f32_e32 v38, v36
	s_nop 0
	v_fma_f32 v39, -v36, v38, 1.0
	v_fmac_f32_e32 v38, v39, v38
	v_fma_f32 v41, -v36, v38, 1.0
	v_fma_f32 v40, v41, v38, v38
; DI u16 f2bf(float a) { return (u16)(pack2(a, 0.f) & 0xffffu); }
; DI float sigmoidf_(float x) { return 1.f / (1.f + __expf(-x)); }
; DI void moe1_phase(const P& p, int l, unsigned char* lds) {
;     ...
;     for (int mt = 0; mt < 4; ++mt)
; #pragma unroll
;       for (int i = 0; i < 16; ++i) {
;         float ug = fminf(acc[mt][0][i] + bg, 7.f);
;         float ul = fminf(fmaxf(acc[mt][1][i] + bl, -7.f), 7.f);
;         float a = ug * sigmoidf_(1.702f * ug) * (ul + 1.f);
;         abase[(mt * 32 + 8 * (i >> 2) + (i & 3)) * 64] = f2bf(a);
;       }
	v_fma_f32 v37, -v36, v40, 1.0
	v_fma_f32 v37, v37, v38, v40
	v_mov_b32_e32 v36, v37
	v_mul_f32_e32 v34, v34, v36
	v_mul_f32_e32 v34, v35, v34
	v_cvt_pk_bf16_f32 v34, v34, s0
	global_store_short v[98:99], v34, off offset:3200
	v_add_f32_e32 v34, v64, v130
	v_min_f32_e32 v34, 0x40e00000, v34
	v_mul_f32_e32 v36, 0x3fd9db23, v34
	v_mul_f32_e32 v36, 0xbfb8aa3b, v36
	v_exp_f32_e32 v36, v36
	v_add_f32_e32 v35, v48, v131
	v_med3_f32 v35, v35, s36, v225
	v_add_f32_e32 v35, 1.0, v35
	v_add_f32_e32 v36, 1.0, v36
	v_rcp_f32_e32 v38, v36
	s_nop 0
	v_fma_f32 v39, -v36, v38, 1.0
	v_fmac_f32_e32 v38, v39, v38
	v_fma_f32 v41, -v36, v38, 1.0
	v_fma_f32 v40, v41, v38, v38
	v_fma_f32 v37, -v36, v40, 1.0
	v_fma_f32 v37, v37, v38, v40
	v_mov_b32_e32 v36, v37
	v_mul_f32_e32 v34, v34, v36
	v_mul_f32_e32 v34, v35, v34
	v_cvt_pk_bf16_f32 v34, v34, s0
	global_store_short v[98:99], v34, off offset:3328
	v_add_f32_e32 v34, v65, v130
	v_min_f32_e32 v34, 0x40e00000, v34
	v_mul_f32_e32 v36, 0x3fd9db23, v34
	v_mul_f32_e32 v36, 0xbfb8aa3b, v36
	v_exp_f32_e32 v36, v36
	v_add_f32_e32 v35, v49, v131
	v_med3_f32 v35, v35, s36, v225
	v_add_f32_e32 v35, 1.0, v35
	v_add_f32_e32 v36, 1.0, v36
	v_rcp_f32_e32 v38, v36
	s_nop 0
	v_fma_f32 v39, -v36, v38, 1.0
	v_fmac_f32_e32 v38, v39, v38
	v_fma_f32 v41, -v36, v38, 1.0
	v_fma_f32 v40, v41, v38, v38
	v_fma_f32 v37, -v36, v40, 1.0
	v_fma_f32 v37, v37, v38, v40
	v_mov_b32_e32 v36, v37
	v_mul_f32_e32 v34, v34, v36
	v_mul_f32_e32 v34, v35, v34
	v_cvt_pk_bf16_f32 v34, v34, s0
	global_store_short v[98:99], v34, off offset:3456
	v_mul_f32_e32 v34, 0x3fd9db23, v18
	v_mul_f32_e32 v34, 0xbfb8aa3b, v34
	v_exp_f32_e32 v34, v34
	s_nop 0
	v_add_f32_e32 v34, 1.0, v34
	v_rcp_f32_e32 v36, v34
	s_nop 0
	v_fma_f32 v37, -v34, v36, 1.0
	v_fmac_f32_e32 v36, v37, v36
	v_fma_f32 v39, -v34, v36, 1.0
	v_fma_f32 v38, v39, v36, v36
	v_fma_f32 v35, -v34, v38, 1.0
	v_fma_f32 v35, v35, v36, v38
	v_mov_b32_e32 v34, v35
	v_mul_f32_e32 v18, v18, v34
	v_mul_f32_e32 v2, v2, v18
	v_cvt_pk_bf16_f32 v2, v2, s0
	s_movk_i32 s0, 0x3000
	v_add_co_u32_e32 v34, vcc, s0, v132
	s_nop 1
	v_addc_co_u32_e32 v35, vcc, 0, v133, vcc
	global_store_short v[34:35], v2, off
	v_add_f32_e32 v2, v19, v130
	v_min_f32_e32 v2, 0x40e00000, v2
	v_mul_f32_e32 v18, 0x3fd9db23, v2
	v_mul_f32_e32 v18, 0xbfb8aa3b, v18
	v_exp_f32_e32 v18, v18
	s_nop 0
	v_add_f32_e32 v18, 1.0, v18
	v_rcp_f32_e32 v36, v18
	s_nop 0
	v_fma_f32 v37, -v18, v36, 1.0
	v_fmac_f32_e32 v36, v37, v36
	v_fma_f32 v39, -v18, v36, 1.0
	v_fma_f32 v38, v39, v36, v36
	v_fma_f32 v19, -v18, v38, 1.0
	v_fma_f32 v19, v19, v36, v38
	v_mov_b32_e32 v18, v19
	v_mul_f32_e32 v2, v2, v18
	v_mul_f32_e32 v2, v3, v2
	v_cvt_pk_bf16_f32 v2, v2, s0
	global_store_short v[34:35], v2, off offset:128
	v_add_f32_e32 v2, v20, v130
	v_min_f32_e32 v2, 0x40e00000, v2
	v_add_f32_e32 v3, v4, v131
	v_mul_f32_e32 v4, 0x3fd9db23, v2
	v_mul_f32_e32 v4, 0xbfb8aa3b, v4
	v_exp_f32_e32 v4, v4
	v_med3_f32 v3, v3, s36, v225
	v_add_f32_e32 v3, 1.0, v3
	v_add_f32_e32 v4, 1.0, v4
	v_rcp_f32_e32 v19, v4
	s_nop 0
	v_fma_f32 v20, -v4, v19, 1.0
	v_fmac_f32_e32 v19, v20, v19
	v_fma_f32 v37, -v4, v19, 1.0
	v_fma_f32 v36, v37, v19, v19
	v_fma_f32 v18, -v4, v36, 1.0
	v_fma_f32 v18, v18, v19, v36
	v_mov_b32_e32 v4, v18
	v_mul_f32_e32 v2, v2, v4
	v_mul_f32_e32 v2, v3, v2
	v_cvt_pk_bf16_f32 v2, v2, s0
	global_store_short v[34:35], v2, off offset:256
	v_add_f32_e32 v2, v21, v130
	v_min_f32_e32 v2, 0x40e00000, v2
	v_mul_f32_e32 v4, 0x3fd9db23, v2
	v_mul_f32_e32 v4, 0xbfb8aa3b, v4
	v_exp_f32_e32 v4, v4
	v_add_f32_e32 v3, v5, v131
	v_med3_f32 v3, v3, s36, v225
	v_add_f32_e32 v3, 1.0, v3
	v_add_f32_e32 v4, 1.0, v4
	v_rcp_f32_e32 v18, v4
	s_nop 0
	v_fma_f32 v19, -v4, v18, 1.0
	v_fmac_f32_e32 v18, v19, v18
	v_fma_f32 v21, -v4, v18, 1.0
	v_fma_f32 v20, v21, v18, v18
	v_fma_f32 v5, -v4, v20, 1.0
	v_fma_f32 v5, v5, v18, v20
	v_mov_b32_e32 v4, v5
	v_mul_f32_e32 v2, v2, v4
	v_mul_f32_e32 v2, v3, v2
	v_cvt_pk_bf16_f32 v2, v2, s0
	global_store_short v[34:35], v2, off offset:384
	v_add_f32_e32 v2, v22, v130
	v_min_f32_e32 v2, 0x40e00000, v2
	v_mul_f32_e32 v4, 0x3fd9db23, v2
	v_mul_f32_e32 v4, 0xbfb8aa3b, v4
	v_exp_f32_e32 v4, v4
	v_add_f32_e32 v3, v6, v131
	v_med3_f32 v3, v3, s36, v225
	v_add_f32_e32 v3, 1.0, v3
	v_add_f32_e32 v4, 1.0, v4
	v_rcp_f32_e32 v6, v4
	s_nop 0
	v_fma_f32 v18, -v4, v6, 1.0
	v_fmac_f32_e32 v6, v18, v6
	v_fma_f32 v20, -v4, v6, 1.0
	v_fma_f32 v19, v20, v6, v6
	v_fma_f32 v5, -v4, v19, 1.0
	v_fma_f32 v5, v5, v6, v19
	v_mov_b32_e32 v4, v5
	v_mul_f32_e32 v2, v2, v4
	v_mul_f32_e32 v2, v3, v2
	v_cvt_pk_bf16_f32 v2, v2, s0
	global_store_short v[34:35], v2, off offset:1024
	v_add_f32_e32 v2, v23, v130
	v_min_f32_e32 v2, 0x40e00000, v2
	v_mul_f32_e32 v4, 0x3fd9db23, v2
	v_mul_f32_e32 v4, 0xbfb8aa3b, v4
	v_exp_f32_e32 v4, v4
	v_add_f32_e32 v3, v7, v131
	v_med3_f32 v3, v3, s36, v225
	v_add_f32_e32 v3, 1.0, v3
	v_add_f32_e32 v4, 1.0, v4
	v_rcp_f32_e32 v6, v4
	s_nop 0
	v_fma_f32 v7, -v4, v6, 1.0
	v_fmac_f32_e32 v6, v7, v6
	v_fma_f32 v19, -v4, v6, 1.0
	v_fma_f32 v18, v19, v6, v6
	v_fma_f32 v5, -v4, v18, 1.0
	v_fma_f32 v5, v5, v6, v18
	v_mov_b32_e32 v4, v5
	v_mul_f32_e32 v2, v2, v4
	v_mul_f32_e32 v2, v3, v2
	v_cvt_pk_bf16_f32 v2, v2, s0
	global_store_short v[34:35], v2, off offset:1152
	v_add_f32_e32 v2, v24, v130
	v_min_f32_e32 v2, 0x40e00000, v2
	v_mul_f32_e32 v4, 0x3fd9db23, v2
	v_mul_f32_e32 v4, 0xbfb8aa3b, v4
	v_exp_f32_e32 v4, v4
	v_add_f32_e32 v3, v8, v131
	v_med3_f32 v3, v3, s36, v225
	v_add_f32_e32 v3, 1.0, v3
	v_add_f32_e32 v4, 1.0, v4
	v_rcp_f32_e32 v6, v4
	s_nop 0
	v_fma_f32 v7, -v4, v6, 1.0
	v_fmac_f32_e32 v6, v7, v6
	v_fma_f32 v18, -v4, v6, 1.0
	v_fma_f32 v8, v18, v6, v6
; DI u16 f2bf(float a) { return (u16)(pack2(a, 0.f) & 0xffffu); }
; DI float sigmoidf_(float x) { return 1.f / (1.f + __expf(-x)); }
; DI void moe1_phase(const P& p, int l, unsigned char* lds) {
;     ...
;     for (int mt = 0; mt < 4; ++mt)
; #pragma unroll
;       for (int i = 0; i < 16; ++i) {
;         float ug = fminf(acc[mt][0][i] + bg, 7.f);
;         float ul = fminf(fmaxf(acc[mt][1][i] + bl, -7.f), 7.f);
;         float a = ug * sigmoidf_(1.702f * ug) * (ul + 1.f);
;         abase[(mt * 32 + 8 * (i >> 2) + (i & 3)) * 64] = f2bf(a);
;       }
	v_fma_f32 v5, -v4, v8, 1.0
	v_fma_f32 v5, v5, v6, v8
	v_mov_b32_e32 v4, v5
	v_mul_f32_e32 v2, v2, v4
	v_mul_f32_e32 v2, v3, v2
	v_cvt_pk_bf16_f32 v2, v2, s0
	global_store_short v[34:35], v2, off offset:1280
	v_add_f32_e32 v2, v25, v130
	v_min_f32_e32 v2, 0x40e00000, v2
	v_mul_f32_e32 v4, 0x3fd9db23, v2
	v_mul_f32_e32 v4, 0xbfb8aa3b, v4
	v_exp_f32_e32 v4, v4
	v_add_f32_e32 v3, v9, v131
	v_med3_f32 v3, v3, s36, v225
	v_add_f32_e32 v3, 1.0, v3
	v_add_f32_e32 v4, 1.0, v4
	v_rcp_f32_e32 v6, v4
	s_nop 0
	v_fma_f32 v7, -v4, v6, 1.0
	v_fmac_f32_e32 v6, v7, v6
	v_fma_f32 v9, -v4, v6, 1.0
	v_fma_f32 v8, v9, v6, v6
	v_fma_f32 v5, -v4, v8, 1.0
	v_fma_f32 v5, v5, v6, v8
	v_mov_b32_e32 v4, v5
	v_mul_f32_e32 v2, v2, v4
	v_mul_f32_e32 v2, v3, v2
	v_cvt_pk_bf16_f32 v2, v2, s0
	global_store_short v[34:35], v2, off offset:1408
	v_add_f32_e32 v2, v26, v130
	v_min_f32_e32 v2, 0x40e00000, v2
	v_mul_f32_e32 v4, 0x3fd9db23, v2
	v_mul_f32_e32 v4, 0xbfb8aa3b, v4
	v_exp_f32_e32 v4, v4
	v_add_f32_e32 v3, v10, v131
	v_med3_f32 v3, v3, s36, v225
	v_add_f32_e32 v3, 1.0, v3
	v_add_f32_e32 v4, 1.0, v4
	v_rcp_f32_e32 v6, v4
	s_nop 0
	v_fma_f32 v7, -v4, v6, 1.0
	v_fmac_f32_e32 v6, v7, v6
	v_fma_f32 v9, -v4, v6, 1.0
	v_fma_f32 v8, v9, v6, v6
	v_fma_f32 v5, -v4, v8, 1.0
	v_fma_f32 v5, v5, v6, v8
	v_mov_b32_e32 v4, v5
	v_mul_f32_e32 v2, v2, v4
	v_mul_f32_e32 v2, v3, v2
	v_cvt_pk_bf16_f32 v2, v2, s0
	global_store_short v[34:35], v2, off offset:2048
	v_add_f32_e32 v2, v27, v130
	v_min_f32_e32 v2, 0x40e00000, v2
	v_mul_f32_e32 v4, 0x3fd9db23, v2
	v_mul_f32_e32 v4, 0xbfb8aa3b, v4
	v_exp_f32_e32 v4, v4
	v_add_f32_e32 v3, v11, v131
	v_med3_f32 v3, v3, s36, v225
	v_add_f32_e32 v3, 1.0, v3
	v_add_f32_e32 v4, 1.0, v4
	v_rcp_f32_e32 v6, v4
	s_nop 0
	v_fma_f32 v7, -v4, v6, 1.0
	v_fmac_f32_e32 v6, v7, v6
	v_fma_f32 v9, -v4, v6, 1.0
	v_fma_f32 v8, v9, v6, v6
	v_fma_f32 v5, -v4, v8, 1.0
	v_fma_f32 v5, v5, v6, v8
	v_mov_b32_e32 v4, v5
	v_mul_f32_e32 v2, v2, v4
	v_mul_f32_e32 v2, v3, v2
	v_cvt_pk_bf16_f32 v2, v2, s0
	global_store_short v[34:35], v2, off offset:2176
	v_add_f32_e32 v2, v28, v130
	v_min_f32_e32 v2, 0x40e00000, v2
	v_mul_f32_e32 v4, 0x3fd9db23, v2
	v_mul_f32_e32 v4, 0xbfb8aa3b, v4
	v_exp_f32_e32 v4, v4
	v_add_f32_e32 v3, v12, v131
	v_med3_f32 v3, v3, s36, v225
	v_add_f32_e32 v3, 1.0, v3
	v_add_f32_e32 v4, 1.0, v4
	v_rcp_f32_e32 v6, v4
	s_nop 0
	v_fma_f32 v7, -v4, v6, 1.0
	v_fmac_f32_e32 v6, v7, v6
	v_fma_f32 v9, -v4, v6, 1.0
	v_fma_f32 v8, v9, v6, v6
	v_fma_f32 v5, -v4, v8, 1.0
	v_fma_f32 v5, v5, v6, v8
	v_mov_b32_e32 v4, v5
	v_mul_f32_e32 v2, v2, v4
	v_mul_f32_e32 v2, v3, v2
	v_cvt_pk_bf16_f32 v2, v2, s0
	global_store_short v[34:35], v2, off offset:2304
	v_add_f32_e32 v2, v29, v130
	v_min_f32_e32 v2, 0x40e00000, v2
	v_mul_f32_e32 v4, 0x3fd9db23, v2
	v_mul_f32_e32 v4, 0xbfb8aa3b, v4
	v_exp_f32_e32 v4, v4
	v_add_f32_e32 v3, v13, v131
	v_med3_f32 v3, v3, s36, v225
	v_add_f32_e32 v3, 1.0, v3
	v_add_f32_e32 v4, 1.0, v4
	v_rcp_f32_e32 v6, v4
	s_nop 0
	v_fma_f32 v7, -v4, v6, 1.0
	v_fmac_f32_e32 v6, v7, v6
	v_fma_f32 v9, -v4, v6, 1.0
	v_fma_f32 v8, v9, v6, v6
	v_fma_f32 v5, -v4, v8, 1.0
	v_fma_f32 v5, v5, v6, v8
	v_mov_b32_e32 v4, v5
	v_mul_f32_e32 v2, v2, v4
	v_mul_f32_e32 v2, v3, v2
	v_cvt_pk_bf16_f32 v2, v2, s0
	global_store_short v[34:35], v2, off offset:2432
	v_add_f32_e32 v2, v30, v130
	v_min_f32_e32 v2, 0x40e00000, v2
	v_mul_f32_e32 v4, 0x3fd9db23, v2
	v_mul_f32_e32 v4, 0xbfb8aa3b, v4
	v_exp_f32_e32 v4, v4
	v_add_f32_e32 v3, v14, v131
	v_med3_f32 v3, v3, s36, v225
	v_add_f32_e32 v3, 1.0, v3
	v_add_f32_e32 v4, 1.0, v4
	v_rcp_f32_e32 v6, v4
	s_nop 0
	v_fma_f32 v7, -v4, v6, 1.0
	v_fmac_f32_e32 v6, v7, v6
	v_fma_f32 v9, -v4, v6, 1.0
	v_fma_f32 v8, v9, v6, v6
	v_fma_f32 v5, -v4, v8, 1.0
	v_fma_f32 v5, v5, v6, v8
	v_mov_b32_e32 v4, v5
	v_mul_f32_e32 v2, v2, v4
	v_mul_f32_e32 v2, v3, v2
	v_cvt_pk_bf16_f32 v2, v2, s0
	global_store_short v[34:35], v2, off offset:3072
	v_add_f32_e32 v2, v31, v130
	v_min_f32_e32 v2, 0x40e00000, v2
	v_mul_f32_e32 v4, 0x3fd9db23, v2
	v_mul_f32_e32 v4, 0xbfb8aa3b, v4
	v_exp_f32_e32 v4, v4
	v_add_f32_e32 v3, v15, v131
	v_med3_f32 v3, v3, s36, v225
	v_add_f32_e32 v3, 1.0, v3
	v_add_f32_e32 v4, 1.0, v4
	v_rcp_f32_e32 v6, v4
	s_nop 0
	v_fma_f32 v7, -v4, v6, 1.0
	v_fmac_f32_e32 v6, v7, v6
	v_fma_f32 v9, -v4, v6, 1.0
	v_fma_f32 v8, v9, v6, v6
	v_fma_f32 v5, -v4, v8, 1.0
	v_fma_f32 v5, v5, v6, v8
	v_mov_b32_e32 v4, v5
	v_mul_f32_e32 v2, v2, v4
	v_mul_f32_e32 v2, v3, v2
	v_cvt_pk_bf16_f32 v2, v2, s0
	global_store_short v[34:35], v2, off offset:3200
	v_add_f32_e32 v2, v32, v130
	v_min_f32_e32 v2, 0x40e00000, v2
	v_mul_f32_e32 v4, 0x3fd9db23, v2
	v_mul_f32_e32 v4, 0xbfb8aa3b, v4
	v_exp_f32_e32 v4, v4
	v_add_f32_e32 v3, v16, v131
	v_med3_f32 v3, v3, s36, v225
	v_add_f32_e32 v3, 1.0, v3
	v_add_f32_e32 v4, 1.0, v4
	v_rcp_f32_e32 v6, v4
	s_nop 0
	v_fma_f32 v7, -v4, v6, 1.0
	v_fmac_f32_e32 v6, v7, v6
	v_fma_f32 v9, -v4, v6, 1.0
	v_fma_f32 v8, v9, v6, v6
	v_fma_f32 v5, -v4, v8, 1.0
	v_fma_f32 v5, v5, v6, v8
	v_mov_b32_e32 v4, v5
	v_mul_f32_e32 v2, v2, v4
	v_mul_f32_e32 v2, v3, v2
	v_cvt_pk_bf16_f32 v2, v2, s0
	global_store_short v[34:35], v2, off offset:3328
	v_add_f32_e32 v2, v33, v130
	v_min_f32_e32 v2, 0x40e00000, v2
	v_mul_f32_e32 v4, 0x3fd9db23, v2
	v_mul_f32_e32 v4, 0xbfb8aa3b, v4
	v_exp_f32_e32 v4, v4
	v_add_f32_e32 v3, v17, v131
	v_med3_f32 v3, v3, s36, v225
	v_add_f32_e32 v3, 1.0, v3
	v_add_f32_e32 v4, 1.0, v4
	v_rcp_f32_e32 v6, v4
	s_nop 0
	v_fma_f32 v7, -v4, v6, 1.0
	v_fmac_f32_e32 v6, v7, v6
	v_fma_f32 v9, -v4, v6, 1.0
	v_fma_f32 v8, v9, v6, v6
	v_fma_f32 v5, -v4, v8, 1.0
	v_fma_f32 v5, v5, v6, v8
	v_mov_b32_e32 v4, v5
	v_mul_f32_e32 v2, v2, v4
	v_mul_f32_e32 v2, v3, v2
	v_cvt_pk_bf16_f32 v2, v2, s0
	global_store_short v[34:35], v2, off offset:3456
	s_branch .LBB0_1416
; DI u16 f2bf(float a) { return (u16)(pack2(a, 0.f) & 0xffffu); }
; DI float sigmoidf_(float x) { return 1.f / (1.f + __expf(-x)); }
; DI void moe1_phase(const P& p, int l, unsigned char* lds) {
;     ...
;     for (int mt = 0; mt < 4; ++mt)
; #pragma unroll
;       for (int i = 0; i < 16; ++i) {
;         float ug = fminf(acc[mt][0][i] + bg, 7.f);
;         float ul = fminf(fmaxf(acc[mt][1][i] + bl, -7.f), 7.f);
;         float a = ug * sigmoidf_(1.702f * ug) * (ul + 1.f);
;         abase[(mt * 32 + 8 * (i >> 2) + (i & 3)) * 64] = f2bf(a);
;       }
.Lmoe1_epi_slow:
	v_add_f32_e32 v114, v114, v130
	v_min_f32_e32 v114, 0x40e00000, v114
	v_mul_f32_e32 v134, 0x3fd9db23, v114
	v_mul_f32_e32 v134, 0xbfb8aa3b, v134
	v_exp_f32_e32 v134, v134
	v_add_f32_e32 v98, v98, v131
	v_med3_f32 v98, v98, s36, v225
	v_add_f32_e32 v98, 1.0, v98
	v_add_f32_e32 v134, 1.0, v134
	v_div_scale_f32 v135, s[0:1], v134, v134, 1.0
	v_rcp_f32_e32 v136, v135
	v_add_f32_e32 v99, v99, v131
	v_med3_f32 v99, v99, s36, v225
	v_add_f32_e32 v99, 1.0, v99
	v_fma_f32 v137, -v135, v136, 1.0
	v_fmac_f32_e32 v136, v137, v136
	v_div_scale_f32 v137, vcc, 1.0, v134, 1.0
	v_mul_f32_e32 v138, v137, v136
	v_fma_f32 v139, -v135, v138, v137
	v_fmac_f32_e32 v138, v139, v136
	v_fma_f32 v135, -v135, v138, v137
	v_div_fmas_f32 v135, v135, v136, v138
	v_div_fixup_f32 v134, v135, v134, 1.0
	v_mul_f32_e32 v114, v114, v134
	v_mul_f32_e32 v98, v98, v114
	v_cvt_pk_bf16_f32 v98, v98, s0
	global_store_short v[132:133], v98, off
	v_add_f32_e32 v98, v115, v130
	v_min_f32_e32 v98, 0x40e00000, v98
	v_mul_f32_e32 v114, 0x3fd9db23, v98
	v_mul_f32_e32 v114, 0xbfb8aa3b, v114
	v_exp_f32_e32 v114, v114
	v_add_f32_e32 v82, v82, v130
	v_min_f32_e32 v82, 0x40e00000, v82
	v_add_f32_e32 v66, v66, v131
	v_add_f32_e32 v114, 1.0, v114
	v_div_scale_f32 v115, s[0:1], v114, v114, 1.0
	v_rcp_f32_e32 v134, v115
	v_med3_f32 v66, v66, s36, v225
	v_add_f32_e32 v66, 1.0, v66
	v_add_f32_e32 v67, v67, v131
	v_fma_f32 v135, -v115, v134, 1.0
	v_fmac_f32_e32 v134, v135, v134
	v_div_scale_f32 v135, vcc, 1.0, v114, 1.0
	v_mul_f32_e32 v136, v135, v134
	v_fma_f32 v137, -v115, v136, v135
	v_fmac_f32_e32 v136, v137, v134
	v_fma_f32 v115, -v115, v136, v135
	v_div_fmas_f32 v115, v115, v134, v136
	v_div_fixup_f32 v114, v115, v114, 1.0
	v_mul_f32_e32 v98, v98, v114
	v_mul_f32_e32 v98, v99, v98
	v_cvt_pk_bf16_f32 v98, v98, s0
	global_store_short v[132:133], v98, off offset:128
	v_add_f32_e32 v98, v116, v130
	v_min_f32_e32 v98, 0x40e00000, v98
	v_add_f32_e32 v99, v100, v131
	v_mul_f32_e32 v100, 0x3fd9db23, v98
	v_mul_f32_e32 v100, 0xbfb8aa3b, v100
	v_exp_f32_e32 v100, v100
	v_med3_f32 v99, v99, s36, v225
	v_add_f32_e32 v99, 1.0, v99
	v_med3_f32 v67, v67, s36, v225
	v_add_f32_e32 v100, 1.0, v100
	v_div_scale_f32 v114, s[0:1], v100, v100, 1.0
	v_rcp_f32_e32 v115, v114
	v_add_f32_e32 v67, 1.0, v67
	v_add_f32_e32 v50, v50, v130
	v_min_f32_e32 v50, 0x40e00000, v50
	v_fma_f32 v116, -v114, v115, 1.0
	v_fmac_f32_e32 v115, v116, v115
	v_div_scale_f32 v116, vcc, 1.0, v100, 1.0
	v_mul_f32_e32 v134, v116, v115
	v_fma_f32 v135, -v114, v134, v116
	v_fmac_f32_e32 v134, v135, v115
	v_fma_f32 v114, -v114, v134, v116
	v_div_fmas_f32 v114, v114, v115, v134
	v_div_fixup_f32 v100, v114, v100, 1.0
	v_mul_f32_e32 v98, v98, v100
	v_mul_f32_e32 v98, v99, v98
	v_cvt_pk_bf16_f32 v98, v98, s0
	global_store_short v[132:133], v98, off offset:256
	v_add_f32_e32 v98, v117, v130
	v_min_f32_e32 v98, 0x40e00000, v98
	v_mul_f32_e32 v100, 0x3fd9db23, v98
	v_mul_f32_e32 v100, 0xbfb8aa3b, v100
	v_exp_f32_e32 v100, v100
	v_add_f32_e32 v99, v101, v131
	v_med3_f32 v99, v99, s36, v225
	v_add_f32_e32 v99, 1.0, v99
	v_add_f32_e32 v100, 1.0, v100
	v_div_scale_f32 v101, s[0:1], v100, v100, 1.0
	v_rcp_f32_e32 v114, v101
	v_add_f32_e32 v34, v34, v131
	v_med3_f32 v34, v34, s36, v225
	v_add_f32_e32 v34, 1.0, v34
	v_fma_f32 v115, -v101, v114, 1.0
	v_fmac_f32_e32 v114, v115, v114
	v_div_scale_f32 v115, vcc, 1.0, v100, 1.0
	v_mul_f32_e32 v116, v115, v114
	v_fma_f32 v117, -v101, v116, v115
	v_fmac_f32_e32 v116, v117, v114
	v_fma_f32 v101, -v101, v116, v115
	v_div_fmas_f32 v101, v101, v114, v116
	v_div_fixup_f32 v100, v101, v100, 1.0
	v_mul_f32_e32 v98, v98, v100
	v_mul_f32_e32 v98, v99, v98
	v_cvt_pk_bf16_f32 v98, v98, s0
	global_store_short v[132:133], v98, off offset:384
	v_add_f32_e32 v98, v118, v130
	v_min_f32_e32 v98, 0x40e00000, v98
	v_mul_f32_e32 v100, 0x3fd9db23, v98
	v_mul_f32_e32 v100, 0xbfb8aa3b, v100
	v_exp_f32_e32 v100, v100
	v_add_f32_e32 v99, v102, v131
	v_med3_f32 v99, v99, s36, v225
	v_add_f32_e32 v99, 1.0, v99
	v_add_f32_e32 v100, 1.0, v100
	v_div_scale_f32 v101, s[0:1], v100, v100, 1.0
	v_rcp_f32_e32 v102, v101
	v_add_f32_e32 v35, v35, v131
	v_med3_f32 v35, v35, s36, v225
	v_add_f32_e32 v35, 1.0, v35
	v_fma_f32 v114, -v101, v102, 1.0
	v_fmac_f32_e32 v102, v114, v102
	v_div_scale_f32 v114, vcc, 1.0, v100, 1.0
	v_mul_f32_e32 v115, v114, v102
	v_fma_f32 v116, -v101, v115, v114
	v_fmac_f32_e32 v115, v116, v102
	v_fma_f32 v101, -v101, v115, v114
	v_div_fmas_f32 v101, v101, v102, v115
	v_div_fixup_f32 v100, v101, v100, 1.0
	v_mul_f32_e32 v98, v98, v100
	v_mul_f32_e32 v98, v99, v98
	v_cvt_pk_bf16_f32 v98, v98, s0
	global_store_short v[132:133], v98, off offset:1024
	v_add_f32_e32 v98, v119, v130
	v_min_f32_e32 v98, 0x40e00000, v98
	v_mul_f32_e32 v100, 0x3fd9db23, v98
	v_mul_f32_e32 v100, 0xbfb8aa3b, v100
	v_exp_f32_e32 v100, v100
	v_add_f32_e32 v99, v103, v131
	v_med3_f32 v99, v99, s36, v225
	v_add_f32_e32 v99, 1.0, v99
	v_add_f32_e32 v100, 1.0, v100
	v_div_scale_f32 v101, s[0:1], v100, v100, 1.0
	v_rcp_f32_e32 v102, v101
	v_add_f32_e32 v18, v18, v130
	v_min_f32_e32 v18, 0x40e00000, v18
	v_add_f32_e32 v2, v2, v131
	v_fma_f32 v103, -v101, v102, 1.0
	v_fmac_f32_e32 v102, v103, v102
	v_div_scale_f32 v103, vcc, 1.0, v100, 1.0
	v_mul_f32_e32 v114, v103, v102
	v_fma_f32 v115, -v101, v114, v103
	v_fmac_f32_e32 v114, v115, v102
	v_fma_f32 v101, -v101, v114, v103
	v_div_fmas_f32 v101, v101, v102, v114
	v_div_fixup_f32 v100, v101, v100, 1.0
	v_mul_f32_e32 v98, v98, v100
	v_mul_f32_e32 v98, v99, v98
	v_cvt_pk_bf16_f32 v98, v98, s0
	global_store_short v[132:133], v98, off offset:1152
	v_add_f32_e32 v98, v120, v130
	v_min_f32_e32 v98, 0x40e00000, v98
; DI u16 f2bf(float a) { return (u16)(pack2(a, 0.f) & 0xffffu); }
; DI float sigmoidf_(float x) { return 1.f / (1.f + __expf(-x)); }
; DI void moe1_phase(const P& p, int l, unsigned char* lds) {
;     ...
;     for (int mt = 0; mt < 4; ++mt)
; #pragma unroll
;       for (int i = 0; i < 16; ++i) {
;         float ug = fminf(acc[mt][0][i] + bg, 7.f);
;         float ul = fminf(fmaxf(acc[mt][1][i] + bl, -7.f), 7.f);
;         float a = ug * sigmoidf_(1.702f * ug) * (ul + 1.f);
;         abase[(mt * 32 + 8 * (i >> 2) + (i & 3)) * 64] = f2bf(a);
;       }
	v_mul_f32_e32 v100, 0x3fd9db23, v98
	v_mul_f32_e32 v100, 0xbfb8aa3b, v100
	v_exp_f32_e32 v100, v100
	v_add_f32_e32 v99, v104, v131
	v_med3_f32 v99, v99, s36, v225
	v_add_f32_e32 v99, 1.0, v99
	v_add_f32_e32 v100, 1.0, v100
	v_div_scale_f32 v101, s[0:1], v100, v100, 1.0
	v_rcp_f32_e32 v102, v101
	v_med3_f32 v2, v2, s36, v225
	v_add_f32_e32 v2, 1.0, v2
	v_add_f32_e32 v3, v3, v131
	v_fma_f32 v103, -v101, v102, 1.0
	v_fmac_f32_e32 v102, v103, v102
	v_div_scale_f32 v103, vcc, 1.0, v100, 1.0
	v_mul_f32_e32 v104, v103, v102
	v_fma_f32 v114, -v101, v104, v103
	v_fmac_f32_e32 v104, v114, v102
	v_fma_f32 v101, -v101, v104, v103
	v_div_fmas_f32 v101, v101, v102, v104
	v_div_fixup_f32 v100, v101, v100, 1.0
	v_mul_f32_e32 v98, v98, v100
	v_mul_f32_e32 v98, v99, v98
	v_cvt_pk_bf16_f32 v98, v98, s0
	global_store_short v[132:133], v98, off offset:1280
	v_add_f32_e32 v98, v121, v130
	v_min_f32_e32 v98, 0x40e00000, v98
	v_mul_f32_e32 v100, 0x3fd9db23, v98
	v_mul_f32_e32 v100, 0xbfb8aa3b, v100
	v_exp_f32_e32 v100, v100
	v_add_f32_e32 v99, v105, v131
	v_med3_f32 v99, v99, s36, v225
	v_add_f32_e32 v99, 1.0, v99
	v_add_f32_e32 v100, 1.0, v100
	v_div_scale_f32 v101, s[0:1], v100, v100, 1.0
	v_rcp_f32_e32 v102, v101
	v_med3_f32 v3, v3, s36, v225
	v_add_f32_e32 v3, 1.0, v3
	v_fma_f32 v103, -v101, v102, 1.0
	v_fmac_f32_e32 v102, v103, v102
	v_div_scale_f32 v103, vcc, 1.0, v100, 1.0
	v_mul_f32_e32 v104, v103, v102
	v_fma_f32 v105, -v101, v104, v103
	v_fmac_f32_e32 v104, v105, v102
	v_fma_f32 v101, -v101, v104, v103
	v_div_fmas_f32 v101, v101, v102, v104
	v_div_fixup_f32 v100, v101, v100, 1.0
	v_mul_f32_e32 v98, v98, v100
	v_mul_f32_e32 v98, v99, v98
	v_cvt_pk_bf16_f32 v98, v98, s0
	global_store_short v[132:133], v98, off offset:1408
	v_add_f32_e32 v98, v122, v130
	v_min_f32_e32 v98, 0x40e00000, v98
	v_mul_f32_e32 v100, 0x3fd9db23, v98
	v_mul_f32_e32 v100, 0xbfb8aa3b, v100
	v_exp_f32_e32 v100, v100
	v_add_f32_e32 v99, v106, v131
	v_med3_f32 v99, v99, s36, v225
	v_add_f32_e32 v99, 1.0, v99
	v_add_f32_e32 v100, 1.0, v100
	v_div_scale_f32 v101, s[0:1], v100, v100, 1.0
	v_rcp_f32_e32 v102, v101
	s_nop 0
	v_fma_f32 v103, -v101, v102, 1.0
	v_fmac_f32_e32 v102, v103, v102
	v_div_scale_f32 v103, vcc, 1.0, v100, 1.0
	v_mul_f32_e32 v104, v103, v102
	v_fma_f32 v105, -v101, v104, v103
	v_fmac_f32_e32 v104, v105, v102
	v_fma_f32 v101, -v101, v104, v103
	v_div_fmas_f32 v101, v101, v102, v104
	v_div_fixup_f32 v100, v101, v100, 1.0
	v_mul_f32_e32 v98, v98, v100
	v_mul_f32_e32 v98, v99, v98
	v_cvt_pk_bf16_f32 v98, v98, s0
	global_store_short v[132:133], v98, off offset:2048
	v_add_f32_e32 v98, v123, v130
	v_min_f32_e32 v98, 0x40e00000, v98
	v_mul_f32_e32 v100, 0x3fd9db23, v98
	v_mul_f32_e32 v100, 0xbfb8aa3b, v100
	v_exp_f32_e32 v100, v100
	v_add_f32_e32 v99, v107, v131
	v_med3_f32 v99, v99, s36, v225
	v_add_f32_e32 v99, 1.0, v99
	v_add_f32_e32 v100, 1.0, v100
	v_div_scale_f32 v101, s[0:1], v100, v100, 1.0
	v_rcp_f32_e32 v102, v101
	s_nop 0
	v_fma_f32 v103, -v101, v102, 1.0
	v_fmac_f32_e32 v102, v103, v102
	v_div_scale_f32 v103, vcc, 1.0, v100, 1.0
	v_mul_f32_e32 v104, v103, v102
	v_fma_f32 v105, -v101, v104, v103
	v_fmac_f32_e32 v104, v105, v102
	v_fma_f32 v101, -v101, v104, v103
	v_div_fmas_f32 v101, v101, v102, v104
	v_div_fixup_f32 v100, v101, v100, 1.0
	v_mul_f32_e32 v98, v98, v100
	v_mul_f32_e32 v98, v99, v98
	v_cvt_pk_bf16_f32 v98, v98, s0
	global_store_short v[132:133], v98, off offset:2176
	v_add_f32_e32 v98, v124, v130
	v_min_f32_e32 v98, 0x40e00000, v98
	v_mul_f32_e32 v100, 0x3fd9db23, v98
	v_mul_f32_e32 v100, 0xbfb8aa3b, v100
	v_exp_f32_e32 v100, v100
	v_add_f32_e32 v99, v108, v131
	v_med3_f32 v99, v99, s36, v225
	v_add_f32_e32 v99, 1.0, v99
	v_add_f32_e32 v100, 1.0, v100
	v_div_scale_f32 v101, s[0:1], v100, v100, 1.0
	v_rcp_f32_e32 v102, v101
	s_nop 0
	v_fma_f32 v103, -v101, v102, 1.0
	v_fmac_f32_e32 v102, v103, v102
	v_div_scale_f32 v103, vcc, 1.0, v100, 1.0
	v_mul_f32_e32 v104, v103, v102
	v_fma_f32 v105, -v101, v104, v103
	v_fmac_f32_e32 v104, v105, v102
	v_fma_f32 v101, -v101, v104, v103
	v_div_fmas_f32 v101, v101, v102, v104
	v_div_fixup_f32 v100, v101, v100, 1.0
	v_mul_f32_e32 v98, v98, v100
	v_mul_f32_e32 v98, v99, v98
	v_cvt_pk_bf16_f32 v98, v98, s0
	global_store_short v[132:133], v98, off offset:2304
	v_add_f32_e32 v98, v125, v130
	v_min_f32_e32 v98, 0x40e00000, v98
	v_mul_f32_e32 v100, 0x3fd9db23, v98
	v_mul_f32_e32 v100, 0xbfb8aa3b, v100
	v_exp_f32_e32 v100, v100
	v_add_f32_e32 v99, v109, v131
	v_med3_f32 v99, v99, s36, v225
	v_add_f32_e32 v99, 1.0, v99
	v_add_f32_e32 v100, 1.0, v100
	v_div_scale_f32 v101, s[0:1], v100, v100, 1.0
	v_rcp_f32_e32 v102, v101
	s_nop 0
	v_fma_f32 v103, -v101, v102, 1.0
	v_fmac_f32_e32 v102, v103, v102
	v_div_scale_f32 v103, vcc, 1.0, v100, 1.0
	v_mul_f32_e32 v104, v103, v102
	v_fma_f32 v105, -v101, v104, v103
	v_fmac_f32_e32 v104, v105, v102
	v_fma_f32 v101, -v101, v104, v103
	v_div_fmas_f32 v101, v101, v102, v104
	v_div_fixup_f32 v100, v101, v100, 1.0
	v_mul_f32_e32 v98, v98, v100
	v_mul_f32_e32 v98, v99, v98
	v_cvt_pk_bf16_f32 v98, v98, s0
	global_store_short v[132:133], v98, off offset:2432
	v_add_f32_e32 v98, v126, v130
	v_min_f32_e32 v98, 0x40e00000, v98
	v_mul_f32_e32 v100, 0x3fd9db23, v98
	v_mul_f32_e32 v100, 0xbfb8aa3b, v100
	v_exp_f32_e32 v100, v100
	v_add_f32_e32 v99, v110, v131
	v_med3_f32 v99, v99, s36, v225
	v_add_f32_e32 v99, 1.0, v99
	v_add_f32_e32 v100, 1.0, v100
	v_div_scale_f32 v101, s[0:1], v100, v100, 1.0
	v_rcp_f32_e32 v102, v101
	s_nop 0
	v_fma_f32 v103, -v101, v102, 1.0
	v_fmac_f32_e32 v102, v103, v102
	v_div_scale_f32 v103, vcc, 1.0, v100, 1.0
	v_mul_f32_e32 v104, v103, v102
	v_fma_f32 v105, -v101, v104, v103
; DI u16 f2bf(float a) { return (u16)(pack2(a, 0.f) & 0xffffu); }
; DI float sigmoidf_(float x) { return 1.f / (1.f + __expf(-x)); }
; DI void moe1_phase(const P& p, int l, unsigned char* lds) {
;     ...
;     for (int mt = 0; mt < 4; ++mt)
; #pragma unroll
;       for (int i = 0; i < 16; ++i) {
;         float ug = fminf(acc[mt][0][i] + bg, 7.f);
;         float ul = fminf(fmaxf(acc[mt][1][i] + bl, -7.f), 7.f);
;         float a = ug * sigmoidf_(1.702f * ug) * (ul + 1.f);
;         abase[(mt * 32 + 8 * (i >> 2) + (i & 3)) * 64] = f2bf(a);
;       }
	v_fmac_f32_e32 v104, v105, v102
	v_fma_f32 v101, -v101, v104, v103
	v_div_fmas_f32 v101, v101, v102, v104
	v_div_fixup_f32 v100, v101, v100, 1.0
	v_mul_f32_e32 v98, v98, v100
	v_mul_f32_e32 v98, v99, v98
	v_cvt_pk_bf16_f32 v98, v98, s0
	global_store_short v[132:133], v98, off offset:3072
	v_add_f32_e32 v98, v127, v130
	v_min_f32_e32 v98, 0x40e00000, v98
	v_mul_f32_e32 v100, 0x3fd9db23, v98
	v_mul_f32_e32 v100, 0xbfb8aa3b, v100
	v_exp_f32_e32 v100, v100
	v_add_f32_e32 v99, v111, v131
	v_med3_f32 v99, v99, s36, v225
	v_add_f32_e32 v99, 1.0, v99
	v_add_f32_e32 v100, 1.0, v100
	v_div_scale_f32 v101, s[0:1], v100, v100, 1.0
	v_rcp_f32_e32 v102, v101
	s_nop 0
	v_fma_f32 v103, -v101, v102, 1.0
	v_fmac_f32_e32 v102, v103, v102
	v_div_scale_f32 v103, vcc, 1.0, v100, 1.0
	v_mul_f32_e32 v104, v103, v102
	v_fma_f32 v105, -v101, v104, v103
	v_fmac_f32_e32 v104, v105, v102
	v_fma_f32 v101, -v101, v104, v103
	v_div_fmas_f32 v101, v101, v102, v104
	v_div_fixup_f32 v100, v101, v100, 1.0
	v_mul_f32_e32 v98, v98, v100
	v_mul_f32_e32 v98, v99, v98
	v_cvt_pk_bf16_f32 v98, v98, s0
	global_store_short v[132:133], v98, off offset:3200
	v_add_f32_e32 v98, v128, v130
	v_min_f32_e32 v98, 0x40e00000, v98
	v_mul_f32_e32 v100, 0x3fd9db23, v98
	v_mul_f32_e32 v100, 0xbfb8aa3b, v100
	v_exp_f32_e32 v100, v100
	v_add_f32_e32 v99, v112, v131
	v_med3_f32 v99, v99, s36, v225
	v_add_f32_e32 v99, 1.0, v99
	v_add_f32_e32 v100, 1.0, v100
	v_div_scale_f32 v101, s[0:1], v100, v100, 1.0
	v_rcp_f32_e32 v102, v101
	s_nop 0
	v_fma_f32 v103, -v101, v102, 1.0
	v_fmac_f32_e32 v102, v103, v102
	v_div_scale_f32 v103, vcc, 1.0, v100, 1.0
	v_mul_f32_e32 v104, v103, v102
	v_fma_f32 v105, -v101, v104, v103
	v_fmac_f32_e32 v104, v105, v102
	v_fma_f32 v101, -v101, v104, v103
	v_div_fmas_f32 v101, v101, v102, v104
	v_div_fixup_f32 v100, v101, v100, 1.0
	v_mul_f32_e32 v98, v98, v100
	v_mul_f32_e32 v98, v99, v98
	v_cvt_pk_bf16_f32 v98, v98, s0
	global_store_short v[132:133], v98, off offset:3328
	v_add_f32_e32 v98, v129, v130
	v_min_f32_e32 v98, 0x40e00000, v98
	v_mul_f32_e32 v100, 0x3fd9db23, v98
	v_mul_f32_e32 v100, 0xbfb8aa3b, v100
	v_exp_f32_e32 v100, v100
	v_add_f32_e32 v99, v113, v131
	v_med3_f32 v99, v99, s36, v225
	v_add_f32_e32 v99, 1.0, v99
	v_add_f32_e32 v100, 1.0, v100
	v_div_scale_f32 v101, s[0:1], v100, v100, 1.0
	v_rcp_f32_e32 v102, v101
	s_nop 0
	v_fma_f32 v103, -v101, v102, 1.0
	v_fmac_f32_e32 v102, v103, v102
	v_div_scale_f32 v103, vcc, 1.0, v100, 1.0
	v_mul_f32_e32 v104, v103, v102
	v_fma_f32 v105, -v101, v104, v103
	v_fmac_f32_e32 v104, v105, v102
	v_fma_f32 v101, -v101, v104, v103
	v_div_fmas_f32 v101, v101, v102, v104
	v_div_fixup_f32 v100, v101, v100, 1.0
	v_mul_f32_e32 v98, v98, v100
	v_mul_f32_e32 v98, v99, v98
	v_cvt_pk_bf16_f32 v98, v98, s0
	global_store_short v[132:133], v98, off offset:3456
	v_mul_f32_e32 v98, 0x3fd9db23, v82
	v_mul_f32_e32 v98, 0xbfb8aa3b, v98
	v_exp_f32_e32 v98, v98
	s_nop 0
	v_add_f32_e32 v98, 1.0, v98
	v_div_scale_f32 v99, s[0:1], v98, v98, 1.0
	v_rcp_f32_e32 v100, v99
	s_nop 0
	v_fma_f32 v101, -v99, v100, 1.0
	v_fmac_f32_e32 v100, v101, v100
	v_div_scale_f32 v101, vcc, 1.0, v98, 1.0
	v_mul_f32_e32 v102, v101, v100
	v_fma_f32 v103, -v99, v102, v101
	v_fmac_f32_e32 v102, v103, v100
	v_fma_f32 v99, -v99, v102, v101
	v_div_fmas_f32 v99, v99, v100, v102
	v_div_fixup_f32 v98, v99, v98, 1.0
	v_add_co_u32_e32 v100, vcc, s46, v132
	v_mul_f32_e32 v82, v82, v98
	s_nop 0
	v_addc_co_u32_e32 v101, vcc, 0, v133, vcc
	v_mul_f32_e32 v66, v66, v82
	v_add_co_u32_e32 v98, vcc, s91, v132
	v_cvt_pk_bf16_f32 v66, v66, s0
	s_nop 0
	v_addc_co_u32_e32 v99, vcc, 0, v133, vcc
	global_store_short v[98:99], v66, off offset:-4096
	v_add_f32_e32 v66, v83, v130
	v_min_f32_e32 v66, 0x40e00000, v66
	v_mul_f32_e32 v82, 0x3fd9db23, v66
	v_mul_f32_e32 v82, 0xbfb8aa3b, v82
	v_exp_f32_e32 v82, v82
	s_nop 0
	v_add_f32_e32 v82, 1.0, v82
	v_div_scale_f32 v83, s[0:1], v82, v82, 1.0
	v_rcp_f32_e32 v102, v83
	s_nop 0
	v_fma_f32 v103, -v83, v102, 1.0
	v_fmac_f32_e32 v102, v103, v102
	v_div_scale_f32 v103, vcc, 1.0, v82, 1.0
	v_mul_f32_e32 v104, v103, v102
	v_fma_f32 v105, -v83, v104, v103
	v_fmac_f32_e32 v104, v105, v102
	v_fma_f32 v83, -v83, v104, v103
	v_div_fmas_f32 v83, v83, v102, v104
	v_div_fixup_f32 v82, v83, v82, 1.0
	v_mul_f32_e32 v66, v66, v82
	v_mul_f32_e32 v66, v67, v66
	v_cvt_pk_bf16_f32 v66, v66, s0
	global_store_short v[100:101], v66, off offset:128
	v_add_f32_e32 v66, v84, v130
	v_min_f32_e32 v66, 0x40e00000, v66
	v_add_f32_e32 v67, v68, v131
	v_mul_f32_e32 v68, 0x3fd9db23, v66
	v_mul_f32_e32 v68, 0xbfb8aa3b, v68
	v_exp_f32_e32 v68, v68
	v_med3_f32 v67, v67, s36, v225
	v_add_f32_e32 v67, 1.0, v67
	v_add_f32_e32 v68, 1.0, v68
	v_div_scale_f32 v82, s[0:1], v68, v68, 1.0
	v_rcp_f32_e32 v83, v82
	s_nop 0
	v_fma_f32 v84, -v82, v83, 1.0
	v_fmac_f32_e32 v83, v84, v83
	v_div_scale_f32 v84, vcc, 1.0, v68, 1.0
	v_mul_f32_e32 v102, v84, v83
	v_fma_f32 v103, -v82, v102, v84
	v_fmac_f32_e32 v102, v103, v83
	v_fma_f32 v82, -v82, v102, v84
	v_div_fmas_f32 v82, v82, v83, v102
	v_div_fixup_f32 v68, v82, v68, 1.0
	v_mul_f32_e32 v66, v66, v68
	v_mul_f32_e32 v66, v67, v66
	v_cvt_pk_bf16_f32 v66, v66, s0
	global_store_short v[100:101], v66, off offset:256
	v_add_f32_e32 v66, v85, v130
	v_min_f32_e32 v66, 0x40e00000, v66
	v_mul_f32_e32 v68, 0x3fd9db23, v66
	v_mul_f32_e32 v68, 0xbfb8aa3b, v68
	v_exp_f32_e32 v68, v68
	v_add_f32_e32 v67, v69, v131
	v_med3_f32 v67, v67, s36, v225
	v_add_f32_e32 v67, 1.0, v67
	v_add_f32_e32 v68, 1.0, v68
	v_div_scale_f32 v69, s[0:1], v68, v68, 1.0
	v_rcp_f32_e32 v82, v69
	s_nop 0
	v_fma_f32 v83, -v69, v82, 1.0
	v_fmac_f32_e32 v82, v83, v82
	v_div_scale_f32 v83, vcc, 1.0, v68, 1.0
; DI u16 f2bf(float a) { return (u16)(pack2(a, 0.f) & 0xffffu); }
; DI float sigmoidf_(float x) { return 1.f / (1.f + __expf(-x)); }
; DI void moe1_phase(const P& p, int l, unsigned char* lds) {
;     ...
;     for (int mt = 0; mt < 4; ++mt)
; #pragma unroll
;       for (int i = 0; i < 16; ++i) {
;         float ug = fminf(acc[mt][0][i] + bg, 7.f);
;         float ul = fminf(fmaxf(acc[mt][1][i] + bl, -7.f), 7.f);
;         float a = ug * sigmoidf_(1.702f * ug) * (ul + 1.f);
;         abase[(mt * 32 + 8 * (i >> 2) + (i & 3)) * 64] = f2bf(a);
;       }
	v_mul_f32_e32 v84, v83, v82
	v_fma_f32 v85, -v69, v84, v83
	v_fmac_f32_e32 v84, v85, v82
	v_fma_f32 v69, -v69, v84, v83
	v_div_fmas_f32 v69, v69, v82, v84
	v_div_fixup_f32 v68, v69, v68, 1.0
	v_mul_f32_e32 v66, v66, v68
	v_mul_f32_e32 v66, v67, v66
	v_cvt_pk_bf16_f32 v66, v66, s0
	global_store_short v[100:101], v66, off offset:384
	v_add_f32_e32 v66, v86, v130
	v_min_f32_e32 v66, 0x40e00000, v66
	v_mul_f32_e32 v68, 0x3fd9db23, v66
	v_mul_f32_e32 v68, 0xbfb8aa3b, v68
	v_exp_f32_e32 v68, v68
	v_add_f32_e32 v67, v70, v131
	v_med3_f32 v67, v67, s36, v225
	v_add_f32_e32 v67, 1.0, v67
	v_add_f32_e32 v68, 1.0, v68
	v_div_scale_f32 v69, s[0:1], v68, v68, 1.0
	v_rcp_f32_e32 v70, v69
	s_nop 0
	v_fma_f32 v82, -v69, v70, 1.0
	v_fmac_f32_e32 v70, v82, v70
	v_div_scale_f32 v82, vcc, 1.0, v68, 1.0
	v_mul_f32_e32 v83, v82, v70
	v_fma_f32 v84, -v69, v83, v82
	v_fmac_f32_e32 v83, v84, v70
	v_fma_f32 v69, -v69, v83, v82
	v_div_fmas_f32 v69, v69, v70, v83
	v_div_fixup_f32 v68, v69, v68, 1.0
	v_mul_f32_e32 v66, v66, v68
	v_mul_f32_e32 v66, v67, v66
	v_cvt_pk_bf16_f32 v66, v66, s0
	global_store_short v[100:101], v66, off offset:1024
	v_add_f32_e32 v66, v87, v130
	v_min_f32_e32 v66, 0x40e00000, v66
	v_mul_f32_e32 v68, 0x3fd9db23, v66
	v_mul_f32_e32 v68, 0xbfb8aa3b, v68
	v_exp_f32_e32 v68, v68
	v_add_f32_e32 v67, v71, v131
	v_med3_f32 v67, v67, s36, v225
	v_add_f32_e32 v67, 1.0, v67
	v_add_f32_e32 v68, 1.0, v68
	v_div_scale_f32 v69, s[0:1], v68, v68, 1.0
	v_rcp_f32_e32 v70, v69
	s_nop 0
	v_fma_f32 v71, -v69, v70, 1.0
	v_fmac_f32_e32 v70, v71, v70
	v_div_scale_f32 v71, vcc, 1.0, v68, 1.0
	v_mul_f32_e32 v82, v71, v70
	v_fma_f32 v83, -v69, v82, v71
	v_fmac_f32_e32 v82, v83, v70
	v_fma_f32 v69, -v69, v82, v71
	v_div_fmas_f32 v69, v69, v70, v82
	v_div_fixup_f32 v68, v69, v68, 1.0
	v_mul_f32_e32 v66, v66, v68
	v_mul_f32_e32 v66, v67, v66
	v_cvt_pk_bf16_f32 v66, v66, s0
	global_store_short v[100:101], v66, off offset:1152
	v_add_f32_e32 v66, v88, v130
	v_min_f32_e32 v66, 0x40e00000, v66
	v_mul_f32_e32 v68, 0x3fd9db23, v66
	v_mul_f32_e32 v68, 0xbfb8aa3b, v68
	v_exp_f32_e32 v68, v68
	v_add_f32_e32 v67, v72, v131
	v_med3_f32 v67, v67, s36, v225
	v_add_f32_e32 v67, 1.0, v67
	v_add_f32_e32 v68, 1.0, v68
	v_div_scale_f32 v69, s[0:1], v68, v68, 1.0
	v_rcp_f32_e32 v70, v69
	s_nop 0
	v_fma_f32 v71, -v69, v70, 1.0
	v_fmac_f32_e32 v70, v71, v70
	v_div_scale_f32 v71, vcc, 1.0, v68, 1.0
	v_mul_f32_e32 v72, v71, v70
	v_fma_f32 v82, -v69, v72, v71
	v_fmac_f32_e32 v72, v82, v70
	v_fma_f32 v69, -v69, v72, v71
	v_div_fmas_f32 v69, v69, v70, v72
	v_div_fixup_f32 v68, v69, v68, 1.0
	v_mul_f32_e32 v66, v66, v68
	v_mul_f32_e32 v66, v67, v66
	v_cvt_pk_bf16_f32 v66, v66, s0
	global_store_short v[100:101], v66, off offset:1280
	v_add_f32_e32 v66, v89, v130
	v_min_f32_e32 v66, 0x40e00000, v66
	v_mul_f32_e32 v68, 0x3fd9db23, v66
	v_mul_f32_e32 v68, 0xbfb8aa3b, v68
	v_exp_f32_e32 v68, v68
	v_add_f32_e32 v67, v73, v131
	v_med3_f32 v67, v67, s36, v225
	v_add_f32_e32 v67, 1.0, v67
	v_add_f32_e32 v68, 1.0, v68
	v_div_scale_f32 v69, s[0:1], v68, v68, 1.0
	v_rcp_f32_e32 v70, v69
	s_nop 0
	v_fma_f32 v71, -v69, v70, 1.0
	v_fmac_f32_e32 v70, v71, v70
	v_div_scale_f32 v71, vcc, 1.0, v68, 1.0
	v_mul_f32_e32 v72, v71, v70
	v_fma_f32 v73, -v69, v72, v71
	v_fmac_f32_e32 v72, v73, v70
	v_fma_f32 v69, -v69, v72, v71
	v_div_fmas_f32 v69, v69, v70, v72
	v_div_fixup_f32 v68, v69, v68, 1.0
	v_mul_f32_e32 v66, v66, v68
	v_mul_f32_e32 v66, v67, v66
	v_cvt_pk_bf16_f32 v66, v66, s0
	global_store_short v[100:101], v66, off offset:1408
	v_add_f32_e32 v66, v90, v130
	v_min_f32_e32 v66, 0x40e00000, v66
	v_mul_f32_e32 v68, 0x3fd9db23, v66
	v_mul_f32_e32 v68, 0xbfb8aa3b, v68
	v_exp_f32_e32 v68, v68
	v_add_f32_e32 v67, v74, v131
	v_med3_f32 v67, v67, s36, v225
	v_add_f32_e32 v67, 1.0, v67
	v_add_f32_e32 v68, 1.0, v68
	v_div_scale_f32 v69, s[0:1], v68, v68, 1.0
	v_rcp_f32_e32 v70, v69
	s_nop 0
	v_fma_f32 v71, -v69, v70, 1.0
	v_fmac_f32_e32 v70, v71, v70
	v_div_scale_f32 v71, vcc, 1.0, v68, 1.0
	v_mul_f32_e32 v72, v71, v70
	v_fma_f32 v73, -v69, v72, v71
	v_fmac_f32_e32 v72, v73, v70
	v_fma_f32 v69, -v69, v72, v71
	v_div_fmas_f32 v69, v69, v70, v72
	v_div_fixup_f32 v68, v69, v68, 1.0
	v_mul_f32_e32 v66, v66, v68
	v_mul_f32_e32 v66, v67, v66
	v_cvt_pk_bf16_f32 v66, v66, s0
	global_store_short v[100:101], v66, off offset:2048
	v_add_f32_e32 v66, v91, v130
	v_min_f32_e32 v66, 0x40e00000, v66
	v_mul_f32_e32 v68, 0x3fd9db23, v66
	v_mul_f32_e32 v68, 0xbfb8aa3b, v68
	v_exp_f32_e32 v68, v68
	v_add_f32_e32 v67, v75, v131
	v_med3_f32 v67, v67, s36, v225
	v_add_f32_e32 v67, 1.0, v67
	v_add_f32_e32 v68, 1.0, v68
	v_div_scale_f32 v69, s[0:1], v68, v68, 1.0
	v_rcp_f32_e32 v70, v69
	s_nop 0
	v_fma_f32 v71, -v69, v70, 1.0
	v_fmac_f32_e32 v70, v71, v70
	v_div_scale_f32 v71, vcc, 1.0, v68, 1.0
	v_mul_f32_e32 v72, v71, v70
	v_fma_f32 v73, -v69, v72, v71
	v_fmac_f32_e32 v72, v73, v70
	v_fma_f32 v69, -v69, v72, v71
	v_div_fmas_f32 v69, v69, v70, v72
	v_div_fixup_f32 v68, v69, v68, 1.0
	v_mul_f32_e32 v66, v66, v68
	v_mul_f32_e32 v66, v67, v66
	v_cvt_pk_bf16_f32 v66, v66, s0
	global_store_short v[100:101], v66, off offset:2176
	v_add_f32_e32 v66, v92, v130
	v_min_f32_e32 v66, 0x40e00000, v66
	v_mul_f32_e32 v68, 0x3fd9db23, v66
	v_mul_f32_e32 v68, 0xbfb8aa3b, v68
	v_exp_f32_e32 v68, v68
	v_add_f32_e32 v67, v76, v131
	v_med3_f32 v67, v67, s36, v225
	v_add_f32_e32 v67, 1.0, v67
	v_add_f32_e32 v68, 1.0, v68
	v_div_scale_f32 v69, s[0:1], v68, v68, 1.0
	v_rcp_f32_e32 v70, v69
	s_nop 0
	v_fma_f32 v71, -v69, v70, 1.0
	v_fmac_f32_e32 v70, v71, v70
	v_div_scale_f32 v71, vcc, 1.0, v68, 1.0
	v_mul_f32_e32 v72, v71, v70
	v_fma_f32 v73, -v69, v72, v71
; DI u16 f2bf(float a) { return (u16)(pack2(a, 0.f) & 0xffffu); }
; DI float sigmoidf_(float x) { return 1.f / (1.f + __expf(-x)); }
; DI void moe1_phase(const P& p, int l, unsigned char* lds) {
;     ...
;     for (int mt = 0; mt < 4; ++mt)
; #pragma unroll
;       for (int i = 0; i < 16; ++i) {
;         float ug = fminf(acc[mt][0][i] + bg, 7.f);
;         float ul = fminf(fmaxf(acc[mt][1][i] + bl, -7.f), 7.f);
;         float a = ug * sigmoidf_(1.702f * ug) * (ul + 1.f);
;         abase[(mt * 32 + 8 * (i >> 2) + (i & 3)) * 64] = f2bf(a);
;       }
	v_fmac_f32_e32 v72, v73, v70
	v_fma_f32 v69, -v69, v72, v71
	v_div_fmas_f32 v69, v69, v70, v72
	v_div_fixup_f32 v68, v69, v68, 1.0
	v_mul_f32_e32 v66, v66, v68
	v_mul_f32_e32 v66, v67, v66
	v_cvt_pk_bf16_f32 v66, v66, s0
	global_store_short v[100:101], v66, off offset:2304
	v_add_f32_e32 v66, v93, v130
	v_min_f32_e32 v66, 0x40e00000, v66
	v_mul_f32_e32 v68, 0x3fd9db23, v66
	v_mul_f32_e32 v68, 0xbfb8aa3b, v68
	v_exp_f32_e32 v68, v68
	v_add_f32_e32 v67, v77, v131
	v_med3_f32 v67, v67, s36, v225
	v_add_f32_e32 v67, 1.0, v67
	v_add_f32_e32 v68, 1.0, v68
	v_div_scale_f32 v69, s[0:1], v68, v68, 1.0
	v_rcp_f32_e32 v70, v69
	s_nop 0
	v_fma_f32 v71, -v69, v70, 1.0
	v_fmac_f32_e32 v70, v71, v70
	v_div_scale_f32 v71, vcc, 1.0, v68, 1.0
	v_mul_f32_e32 v72, v71, v70
	v_fma_f32 v73, -v69, v72, v71
	v_fmac_f32_e32 v72, v73, v70
	v_fma_f32 v69, -v69, v72, v71
	v_div_fmas_f32 v69, v69, v70, v72
	v_div_fixup_f32 v68, v69, v68, 1.0
	v_mul_f32_e32 v66, v66, v68
	v_mul_f32_e32 v66, v67, v66
	v_cvt_pk_bf16_f32 v66, v66, s0
	global_store_short v[100:101], v66, off offset:2432
	v_add_f32_e32 v66, v94, v130
	v_min_f32_e32 v66, 0x40e00000, v66
	v_mul_f32_e32 v68, 0x3fd9db23, v66
	v_mul_f32_e32 v68, 0xbfb8aa3b, v68
	v_exp_f32_e32 v68, v68
	v_add_f32_e32 v67, v78, v131
	v_med3_f32 v67, v67, s36, v225
	v_add_f32_e32 v67, 1.0, v67
	v_add_f32_e32 v68, 1.0, v68
	v_div_scale_f32 v69, s[0:1], v68, v68, 1.0
	v_rcp_f32_e32 v70, v69
	s_nop 0
	v_fma_f32 v71, -v69, v70, 1.0
	v_fmac_f32_e32 v70, v71, v70
	v_div_scale_f32 v71, vcc, 1.0, v68, 1.0
	v_mul_f32_e32 v72, v71, v70
	v_fma_f32 v73, -v69, v72, v71
	v_fmac_f32_e32 v72, v73, v70
	v_fma_f32 v69, -v69, v72, v71
	v_div_fmas_f32 v69, v69, v70, v72
	v_div_fixup_f32 v68, v69, v68, 1.0
	v_mul_f32_e32 v66, v66, v68
	v_mul_f32_e32 v66, v67, v66
	v_cvt_pk_bf16_f32 v66, v66, s0
	global_store_short v[100:101], v66, off offset:3072
	v_add_f32_e32 v66, v95, v130
	v_min_f32_e32 v66, 0x40e00000, v66
	v_mul_f32_e32 v68, 0x3fd9db23, v66
	v_mul_f32_e32 v68, 0xbfb8aa3b, v68
	v_exp_f32_e32 v68, v68
	v_add_f32_e32 v67, v79, v131
	v_med3_f32 v67, v67, s36, v225
	v_add_f32_e32 v67, 1.0, v67
	v_add_f32_e32 v68, 1.0, v68
	v_div_scale_f32 v69, s[0:1], v68, v68, 1.0
	v_rcp_f32_e32 v70, v69
	s_nop 0
	v_fma_f32 v71, -v69, v70, 1.0
	v_fmac_f32_e32 v70, v71, v70
	v_div_scale_f32 v71, vcc, 1.0, v68, 1.0
	v_mul_f32_e32 v72, v71, v70
	v_fma_f32 v73, -v69, v72, v71
	v_fmac_f32_e32 v72, v73, v70
	v_fma_f32 v69, -v69, v72, v71
	v_div_fmas_f32 v69, v69, v70, v72
	v_div_fixup_f32 v68, v69, v68, 1.0
	v_mul_f32_e32 v66, v66, v68
	v_mul_f32_e32 v66, v67, v66
	v_cvt_pk_bf16_f32 v66, v66, s0
	global_store_short v[100:101], v66, off offset:3200
	v_add_f32_e32 v66, v96, v130
	v_min_f32_e32 v66, 0x40e00000, v66
	v_mul_f32_e32 v68, 0x3fd9db23, v66
	v_mul_f32_e32 v68, 0xbfb8aa3b, v68
	v_exp_f32_e32 v68, v68
	v_add_f32_e32 v67, v80, v131
	v_med3_f32 v67, v67, s36, v225
	v_add_f32_e32 v67, 1.0, v67
	v_add_f32_e32 v68, 1.0, v68
	v_div_scale_f32 v69, s[0:1], v68, v68, 1.0
	v_rcp_f32_e32 v70, v69
	s_nop 0
	v_fma_f32 v71, -v69, v70, 1.0
	v_fmac_f32_e32 v70, v71, v70
	v_div_scale_f32 v71, vcc, 1.0, v68, 1.0
	v_mul_f32_e32 v72, v71, v70
	v_fma_f32 v73, -v69, v72, v71
	v_fmac_f32_e32 v72, v73, v70
	v_fma_f32 v69, -v69, v72, v71
	v_div_fmas_f32 v69, v69, v70, v72
	v_div_fixup_f32 v68, v69, v68, 1.0
	v_mul_f32_e32 v66, v66, v68
	v_mul_f32_e32 v66, v67, v66
	v_cvt_pk_bf16_f32 v66, v66, s0
	global_store_short v[100:101], v66, off offset:3328
	v_add_f32_e32 v66, v97, v130
	v_min_f32_e32 v66, 0x40e00000, v66
	v_mul_f32_e32 v68, 0x3fd9db23, v66
	v_mul_f32_e32 v68, 0xbfb8aa3b, v68
	v_exp_f32_e32 v68, v68
	v_add_f32_e32 v67, v81, v131
	v_med3_f32 v67, v67, s36, v225
	v_add_f32_e32 v67, 1.0, v67
	v_add_f32_e32 v68, 1.0, v68
	v_div_scale_f32 v69, s[0:1], v68, v68, 1.0
	v_rcp_f32_e32 v70, v69
	s_nop 0
	v_fma_f32 v71, -v69, v70, 1.0
	v_fmac_f32_e32 v70, v71, v70
	v_div_scale_f32 v71, vcc, 1.0, v68, 1.0
	v_mul_f32_e32 v72, v71, v70
	v_fma_f32 v73, -v69, v72, v71
	v_fmac_f32_e32 v72, v73, v70
	v_fma_f32 v69, -v69, v72, v71
	v_div_fmas_f32 v69, v69, v70, v72
	v_div_fixup_f32 v68, v69, v68, 1.0
	v_mul_f32_e32 v66, v66, v68
	v_mul_f32_e32 v66, v67, v66
	v_cvt_pk_bf16_f32 v66, v66, s0
	global_store_short v[100:101], v66, off offset:3456
	v_mul_f32_e32 v66, 0x3fd9db23, v50
	v_mul_f32_e32 v66, 0xbfb8aa3b, v66
	v_exp_f32_e32 v66, v66
	s_nop 0
	v_add_f32_e32 v66, 1.0, v66
	v_div_scale_f32 v67, s[0:1], v66, v66, 1.0
	v_rcp_f32_e32 v68, v67
	s_nop 0
	v_fma_f32 v69, -v67, v68, 1.0
	v_fmac_f32_e32 v68, v69, v68
	v_div_scale_f32 v69, vcc, 1.0, v66, 1.0
	v_mul_f32_e32 v70, v69, v68
	v_fma_f32 v71, -v67, v70, v69
	v_fmac_f32_e32 v70, v71, v68
	v_fma_f32 v67, -v67, v70, v69
	v_div_fmas_f32 v67, v67, v68, v70
	v_div_fixup_f32 v66, v67, v66, 1.0
	v_mul_f32_e32 v50, v50, v66
	v_mul_f32_e32 v34, v34, v50
	v_cvt_pk_bf16_f32 v34, v34, s0
	global_store_short v[98:99], v34, off
	v_add_f32_e32 v34, v51, v130
	v_min_f32_e32 v34, 0x40e00000, v34
	v_mul_f32_e32 v50, 0x3fd9db23, v34
	v_mul_f32_e32 v50, 0xbfb8aa3b, v50
	v_exp_f32_e32 v50, v50
	s_nop 0
	v_add_f32_e32 v50, 1.0, v50
	v_div_scale_f32 v51, s[0:1], v50, v50, 1.0
	v_rcp_f32_e32 v66, v51
	s_nop 0
	v_fma_f32 v67, -v51, v66, 1.0
	v_fmac_f32_e32 v66, v67, v66
	v_div_scale_f32 v67, vcc, 1.0, v50, 1.0
	v_mul_f32_e32 v68, v67, v66
	v_fma_f32 v69, -v51, v68, v67
	v_fmac_f32_e32 v68, v69, v66
	v_fma_f32 v51, -v51, v68, v67
	v_div_fmas_f32 v51, v51, v66, v68
	v_div_fixup_f32 v50, v51, v50, 1.0
	v_mul_f32_e32 v34, v34, v50
	v_mul_f32_e32 v34, v35, v34
	v_cvt_pk_bf16_f32 v34, v34, s0
	global_store_short v[98:99], v34, off offset:128
	v_add_f32_e32 v34, v52, v130
; DI u16 f2bf(float a) { return (u16)(pack2(a, 0.f) & 0xffffu); }
; DI float sigmoidf_(float x) { return 1.f / (1.f + __expf(-x)); }
; DI void moe1_phase(const P& p, int l, unsigned char* lds) {
;     ...
;     for (int mt = 0; mt < 4; ++mt)
; #pragma unroll
;       for (int i = 0; i < 16; ++i) {
;         float ug = fminf(acc[mt][0][i] + bg, 7.f);
;         float ul = fminf(fmaxf(acc[mt][1][i] + bl, -7.f), 7.f);
;         float a = ug * sigmoidf_(1.702f * ug) * (ul + 1.f);
;         abase[(mt * 32 + 8 * (i >> 2) + (i & 3)) * 64] = f2bf(a);
;       }
	v_min_f32_e32 v34, 0x40e00000, v34
	v_add_f32_e32 v35, v36, v131
	v_mul_f32_e32 v36, 0x3fd9db23, v34
	v_mul_f32_e32 v36, 0xbfb8aa3b, v36
	v_exp_f32_e32 v36, v36
	v_med3_f32 v35, v35, s36, v225
	v_add_f32_e32 v35, 1.0, v35
	v_add_f32_e32 v36, 1.0, v36
	v_div_scale_f32 v50, s[0:1], v36, v36, 1.0
	v_rcp_f32_e32 v51, v50
	s_nop 0
	v_fma_f32 v52, -v50, v51, 1.0
	v_fmac_f32_e32 v51, v52, v51
	v_div_scale_f32 v52, vcc, 1.0, v36, 1.0
	v_mul_f32_e32 v66, v52, v51
	v_fma_f32 v67, -v50, v66, v52
	v_fmac_f32_e32 v66, v67, v51
	v_fma_f32 v50, -v50, v66, v52
	v_div_fmas_f32 v50, v50, v51, v66
	v_div_fixup_f32 v36, v50, v36, 1.0
	v_mul_f32_e32 v34, v34, v36
	v_mul_f32_e32 v34, v35, v34
	v_cvt_pk_bf16_f32 v34, v34, s0
	global_store_short v[98:99], v34, off offset:256
	v_add_f32_e32 v34, v53, v130
	v_min_f32_e32 v34, 0x40e00000, v34
	v_mul_f32_e32 v36, 0x3fd9db23, v34
	v_mul_f32_e32 v36, 0xbfb8aa3b, v36
	v_exp_f32_e32 v36, v36
	v_add_f32_e32 v35, v37, v131
	v_med3_f32 v35, v35, s36, v225
	v_add_f32_e32 v35, 1.0, v35
	v_add_f32_e32 v36, 1.0, v36
	v_div_scale_f32 v37, s[0:1], v36, v36, 1.0
	v_rcp_f32_e32 v50, v37
	s_nop 0
	v_fma_f32 v51, -v37, v50, 1.0
	v_fmac_f32_e32 v50, v51, v50
	v_div_scale_f32 v51, vcc, 1.0, v36, 1.0
	v_mul_f32_e32 v52, v51, v50
	v_fma_f32 v53, -v37, v52, v51
	v_fmac_f32_e32 v52, v53, v50
	v_fma_f32 v37, -v37, v52, v51
	v_div_fmas_f32 v37, v37, v50, v52
	v_div_fixup_f32 v36, v37, v36, 1.0
	v_mul_f32_e32 v34, v34, v36
	v_mul_f32_e32 v34, v35, v34
	v_cvt_pk_bf16_f32 v34, v34, s0
	global_store_short v[98:99], v34, off offset:384
	v_add_f32_e32 v34, v54, v130
	v_min_f32_e32 v34, 0x40e00000, v34
	v_mul_f32_e32 v36, 0x3fd9db23, v34
	v_mul_f32_e32 v36, 0xbfb8aa3b, v36
	v_exp_f32_e32 v36, v36
	v_add_f32_e32 v35, v38, v131
	v_med3_f32 v35, v35, s36, v225
	v_add_f32_e32 v35, 1.0, v35
	v_add_f32_e32 v36, 1.0, v36
	v_div_scale_f32 v37, s[0:1], v36, v36, 1.0
	v_rcp_f32_e32 v38, v37
	s_nop 0
	v_fma_f32 v50, -v37, v38, 1.0
	v_fmac_f32_e32 v38, v50, v38
	v_div_scale_f32 v50, vcc, 1.0, v36, 1.0
	v_mul_f32_e32 v51, v50, v38
	v_fma_f32 v52, -v37, v51, v50
	v_fmac_f32_e32 v51, v52, v38
	v_fma_f32 v37, -v37, v51, v50
	v_div_fmas_f32 v37, v37, v38, v51
	v_div_fixup_f32 v36, v37, v36, 1.0
	v_mul_f32_e32 v34, v34, v36
	v_mul_f32_e32 v34, v35, v34
	v_cvt_pk_bf16_f32 v34, v34, s0
	global_store_short v[98:99], v34, off offset:1024
	v_add_f32_e32 v34, v55, v130
	v_min_f32_e32 v34, 0x40e00000, v34
	v_mul_f32_e32 v36, 0x3fd9db23, v34
	v_mul_f32_e32 v36, 0xbfb8aa3b, v36
	v_exp_f32_e32 v36, v36
	v_add_f32_e32 v35, v39, v131
	v_med3_f32 v35, v35, s36, v225
	v_add_f32_e32 v35, 1.0, v35
	v_add_f32_e32 v36, 1.0, v36
	v_div_scale_f32 v37, s[0:1], v36, v36, 1.0
	v_rcp_f32_e32 v38, v37
	s_nop 0
	v_fma_f32 v39, -v37, v38, 1.0
	v_fmac_f32_e32 v38, v39, v38
	v_div_scale_f32 v39, vcc, 1.0, v36, 1.0
	v_mul_f32_e32 v50, v39, v38
	v_fma_f32 v51, -v37, v50, v39
	v_fmac_f32_e32 v50, v51, v38
	v_fma_f32 v37, -v37, v50, v39
	v_div_fmas_f32 v37, v37, v38, v50
	v_div_fixup_f32 v36, v37, v36, 1.0
	v_mul_f32_e32 v34, v34, v36
	v_mul_f32_e32 v34, v35, v34
	v_cvt_pk_bf16_f32 v34, v34, s0
	global_store_short v[98:99], v34, off offset:1152
	v_add_f32_e32 v34, v56, v130
	v_min_f32_e32 v34, 0x40e00000, v34
	v_mul_f32_e32 v36, 0x3fd9db23, v34
	v_mul_f32_e32 v36, 0xbfb8aa3b, v36
	v_exp_f32_e32 v36, v36
	v_add_f32_e32 v35, v40, v131
	v_med3_f32 v35, v35, s36, v225
	v_add_f32_e32 v35, 1.0, v35
	v_add_f32_e32 v36, 1.0, v36
	v_div_scale_f32 v37, s[0:1], v36, v36, 1.0
	v_rcp_f32_e32 v38, v37
	s_nop 0
	v_fma_f32 v39, -v37, v38, 1.0
	v_fmac_f32_e32 v38, v39, v38
	v_div_scale_f32 v39, vcc, 1.0, v36, 1.0
	v_mul_f32_e32 v40, v39, v38
	v_fma_f32 v50, -v37, v40, v39
	v_fmac_f32_e32 v40, v50, v38
	v_fma_f32 v37, -v37, v40, v39
	v_div_fmas_f32 v37, v37, v38, v40
	v_div_fixup_f32 v36, v37, v36, 1.0
	v_mul_f32_e32 v34, v34, v36
	v_mul_f32_e32 v34, v35, v34
	v_cvt_pk_bf16_f32 v34, v34, s0
	global_store_short v[98:99], v34, off offset:1280
	v_add_f32_e32 v34, v57, v130
	v_min_f32_e32 v34, 0x40e00000, v34
	v_mul_f32_e32 v36, 0x3fd9db23, v34
	v_mul_f32_e32 v36, 0xbfb8aa3b, v36
	v_exp_f32_e32 v36, v36
	v_add_f32_e32 v35, v41, v131
	v_med3_f32 v35, v35, s36, v225
	v_add_f32_e32 v35, 1.0, v35
	v_add_f32_e32 v36, 1.0, v36
	v_div_scale_f32 v37, s[0:1], v36, v36, 1.0
	v_rcp_f32_e32 v38, v37
	s_nop 0
	v_fma_f32 v39, -v37, v38, 1.0
	v_fmac_f32_e32 v38, v39, v38
	v_div_scale_f32 v39, vcc, 1.0, v36, 1.0
	v_mul_f32_e32 v40, v39, v38
	v_fma_f32 v41, -v37, v40, v39
	v_fmac_f32_e32 v40, v41, v38
	v_fma_f32 v37, -v37, v40, v39
	v_div_fmas_f32 v37, v37, v38, v40
	v_div_fixup_f32 v36, v37, v36, 1.0
	v_mul_f32_e32 v34, v34, v36
	v_mul_f32_e32 v34, v35, v34
	v_cvt_pk_bf16_f32 v34, v34, s0
	global_store_short v[98:99], v34, off offset:1408
	v_add_f32_e32 v34, v58, v130
	v_min_f32_e32 v34, 0x40e00000, v34
	v_mul_f32_e32 v36, 0x3fd9db23, v34
	v_mul_f32_e32 v36, 0xbfb8aa3b, v36
	v_exp_f32_e32 v36, v36
	v_add_f32_e32 v35, v42, v131
	v_med3_f32 v35, v35, s36, v225
	v_add_f32_e32 v35, 1.0, v35
	v_add_f32_e32 v36, 1.0, v36
	v_div_scale_f32 v37, s[0:1], v36, v36, 1.0
	v_rcp_f32_e32 v38, v37
	s_nop 0
	v_fma_f32 v39, -v37, v38, 1.0
	v_fmac_f32_e32 v38, v39, v38
	v_div_scale_f32 v39, vcc, 1.0, v36, 1.0
	v_mul_f32_e32 v40, v39, v38
	v_fma_f32 v41, -v37, v40, v39
	v_fmac_f32_e32 v40, v41, v38
	v_fma_f32 v37, -v37, v40, v39
	v_div_fmas_f32 v37, v37, v38, v40
	v_div_fixup_f32 v36, v37, v36, 1.0
	v_mul_f32_e32 v34, v34, v36
	v_mul_f32_e32 v34, v35, v34
	v_cvt_pk_bf16_f32 v34, v34, s0
	global_store_short v[98:99], v34, off offset:2048
	v_add_f32_e32 v34, v59, v130
	v_min_f32_e32 v34, 0x40e00000, v34
	v_mul_f32_e32 v36, 0x3fd9db23, v34
; DI u16 f2bf(float a) { return (u16)(pack2(a, 0.f) & 0xffffu); }
; DI float sigmoidf_(float x) { return 1.f / (1.f + __expf(-x)); }
; DI void moe1_phase(const P& p, int l, unsigned char* lds) {
;     ...
;     for (int mt = 0; mt < 4; ++mt)
; #pragma unroll
;       for (int i = 0; i < 16; ++i) {
;         float ug = fminf(acc[mt][0][i] + bg, 7.f);
;         float ul = fminf(fmaxf(acc[mt][1][i] + bl, -7.f), 7.f);
;         float a = ug * sigmoidf_(1.702f * ug) * (ul + 1.f);
;         abase[(mt * 32 + 8 * (i >> 2) + (i & 3)) * 64] = f2bf(a);
;       }
	v_mul_f32_e32 v36, 0xbfb8aa3b, v36
	v_exp_f32_e32 v36, v36
	v_add_f32_e32 v35, v43, v131
	v_med3_f32 v35, v35, s36, v225
	v_add_f32_e32 v35, 1.0, v35
	v_add_f32_e32 v36, 1.0, v36
	v_div_scale_f32 v37, s[0:1], v36, v36, 1.0
	v_rcp_f32_e32 v38, v37
	s_nop 0
	v_fma_f32 v39, -v37, v38, 1.0
	v_fmac_f32_e32 v38, v39, v38
	v_div_scale_f32 v39, vcc, 1.0, v36, 1.0
	v_mul_f32_e32 v40, v39, v38
	v_fma_f32 v41, -v37, v40, v39
	v_fmac_f32_e32 v40, v41, v38
	v_fma_f32 v37, -v37, v40, v39
	v_div_fmas_f32 v37, v37, v38, v40
	v_div_fixup_f32 v36, v37, v36, 1.0
	v_mul_f32_e32 v34, v34, v36
	v_mul_f32_e32 v34, v35, v34
	v_cvt_pk_bf16_f32 v34, v34, s0
	global_store_short v[98:99], v34, off offset:2176
	v_add_f32_e32 v34, v60, v130
	v_min_f32_e32 v34, 0x40e00000, v34
	v_mul_f32_e32 v36, 0x3fd9db23, v34
	v_mul_f32_e32 v36, 0xbfb8aa3b, v36
	v_exp_f32_e32 v36, v36
	v_add_f32_e32 v35, v44, v131
	v_med3_f32 v35, v35, s36, v225
	v_add_f32_e32 v35, 1.0, v35
	v_add_f32_e32 v36, 1.0, v36
	v_div_scale_f32 v37, s[0:1], v36, v36, 1.0
	v_rcp_f32_e32 v38, v37
	s_nop 0
	v_fma_f32 v39, -v37, v38, 1.0
	v_fmac_f32_e32 v38, v39, v38
	v_div_scale_f32 v39, vcc, 1.0, v36, 1.0
	v_mul_f32_e32 v40, v39, v38
	v_fma_f32 v41, -v37, v40, v39
	v_fmac_f32_e32 v40, v41, v38
	v_fma_f32 v37, -v37, v40, v39
	v_div_fmas_f32 v37, v37, v38, v40
	v_div_fixup_f32 v36, v37, v36, 1.0
	v_mul_f32_e32 v34, v34, v36
	v_mul_f32_e32 v34, v35, v34
	v_cvt_pk_bf16_f32 v34, v34, s0
	global_store_short v[98:99], v34, off offset:2304
	v_add_f32_e32 v34, v61, v130
	v_min_f32_e32 v34, 0x40e00000, v34
	v_mul_f32_e32 v36, 0x3fd9db23, v34
	v_mul_f32_e32 v36, 0xbfb8aa3b, v36
	v_exp_f32_e32 v36, v36
	v_add_f32_e32 v35, v45, v131
	v_med3_f32 v35, v35, s36, v225
	v_add_f32_e32 v35, 1.0, v35
	v_add_f32_e32 v36, 1.0, v36
	v_div_scale_f32 v37, s[0:1], v36, v36, 1.0
	v_rcp_f32_e32 v38, v37
	s_nop 0
	v_fma_f32 v39, -v37, v38, 1.0
	v_fmac_f32_e32 v38, v39, v38
	v_div_scale_f32 v39, vcc, 1.0, v36, 1.0
	v_mul_f32_e32 v40, v39, v38
	v_fma_f32 v41, -v37, v40, v39
	v_fmac_f32_e32 v40, v41, v38
	v_fma_f32 v37, -v37, v40, v39
	v_div_fmas_f32 v37, v37, v38, v40
	v_div_fixup_f32 v36, v37, v36, 1.0
	v_mul_f32_e32 v34, v34, v36
	v_mul_f32_e32 v34, v35, v34
	v_cvt_pk_bf16_f32 v34, v34, s0
	global_store_short v[98:99], v34, off offset:2432
	v_add_f32_e32 v34, v62, v130
	v_min_f32_e32 v34, 0x40e00000, v34
	v_mul_f32_e32 v36, 0x3fd9db23, v34
	v_mul_f32_e32 v36, 0xbfb8aa3b, v36
	v_exp_f32_e32 v36, v36
	v_add_f32_e32 v35, v46, v131
	v_med3_f32 v35, v35, s36, v225
	v_add_f32_e32 v35, 1.0, v35
	v_add_f32_e32 v36, 1.0, v36
	v_div_scale_f32 v37, s[0:1], v36, v36, 1.0
	v_rcp_f32_e32 v38, v37
	s_nop 0
	v_fma_f32 v39, -v37, v38, 1.0
	v_fmac_f32_e32 v38, v39, v38
	v_div_scale_f32 v39, vcc, 1.0, v36, 1.0
	v_mul_f32_e32 v40, v39, v38
	v_fma_f32 v41, -v37, v40, v39
	v_fmac_f32_e32 v40, v41, v38
	v_fma_f32 v37, -v37, v40, v39
	v_div_fmas_f32 v37, v37, v38, v40
	v_div_fixup_f32 v36, v37, v36, 1.0
	v_mul_f32_e32 v34, v34, v36
	v_mul_f32_e32 v34, v35, v34
	v_cvt_pk_bf16_f32 v34, v34, s0
	global_store_short v[98:99], v34, off offset:3072
	v_add_f32_e32 v34, v63, v130
	v_min_f32_e32 v34, 0x40e00000, v34
	v_mul_f32_e32 v36, 0x3fd9db23, v34
	v_mul_f32_e32 v36, 0xbfb8aa3b, v36
	v_exp_f32_e32 v36, v36
	v_add_f32_e32 v35, v47, v131
	v_med3_f32 v35, v35, s36, v225
	v_add_f32_e32 v35, 1.0, v35
	v_add_f32_e32 v36, 1.0, v36
	v_div_scale_f32 v37, s[0:1], v36, v36, 1.0
	v_rcp_f32_e32 v38, v37
	s_nop 0
	v_fma_f32 v39, -v37, v38, 1.0
	v_fmac_f32_e32 v38, v39, v38
	v_div_scale_f32 v39, vcc, 1.0, v36, 1.0
	v_mul_f32_e32 v40, v39, v38
	v_fma_f32 v41, -v37, v40, v39
	v_fmac_f32_e32 v40, v41, v38
	v_fma_f32 v37, -v37, v40, v39
	v_div_fmas_f32 v37, v37, v38, v40
	v_div_fixup_f32 v36, v37, v36, 1.0
	v_mul_f32_e32 v34, v34, v36
	v_mul_f32_e32 v34, v35, v34
	v_cvt_pk_bf16_f32 v34, v34, s0
	global_store_short v[98:99], v34, off offset:3200
	v_add_f32_e32 v34, v64, v130
	v_min_f32_e32 v34, 0x40e00000, v34
	v_mul_f32_e32 v36, 0x3fd9db23, v34
	v_mul_f32_e32 v36, 0xbfb8aa3b, v36
	v_exp_f32_e32 v36, v36
	v_add_f32_e32 v35, v48, v131
	v_med3_f32 v35, v35, s36, v225
	v_add_f32_e32 v35, 1.0, v35
	v_add_f32_e32 v36, 1.0, v36
	v_div_scale_f32 v37, s[0:1], v36, v36, 1.0
	v_rcp_f32_e32 v38, v37
	s_nop 0
	v_fma_f32 v39, -v37, v38, 1.0
	v_fmac_f32_e32 v38, v39, v38
	v_div_scale_f32 v39, vcc, 1.0, v36, 1.0
	v_mul_f32_e32 v40, v39, v38
	v_fma_f32 v41, -v37, v40, v39
	v_fmac_f32_e32 v40, v41, v38
	v_fma_f32 v37, -v37, v40, v39
	v_div_fmas_f32 v37, v37, v38, v40
	v_div_fixup_f32 v36, v37, v36, 1.0
	v_mul_f32_e32 v34, v34, v36
	v_mul_f32_e32 v34, v35, v34
	v_cvt_pk_bf16_f32 v34, v34, s0
	global_store_short v[98:99], v34, off offset:3328
	v_add_f32_e32 v34, v65, v130
	v_min_f32_e32 v34, 0x40e00000, v34
	v_mul_f32_e32 v36, 0x3fd9db23, v34
	v_mul_f32_e32 v36, 0xbfb8aa3b, v36
	v_exp_f32_e32 v36, v36
	v_add_f32_e32 v35, v49, v131
	v_med3_f32 v35, v35, s36, v225
	v_add_f32_e32 v35, 1.0, v35
	v_add_f32_e32 v36, 1.0, v36
	v_div_scale_f32 v37, s[0:1], v36, v36, 1.0
	v_rcp_f32_e32 v38, v37
	s_nop 0
	v_fma_f32 v39, -v37, v38, 1.0
	v_fmac_f32_e32 v38, v39, v38
	v_div_scale_f32 v39, vcc, 1.0, v36, 1.0
	v_mul_f32_e32 v40, v39, v38
	v_fma_f32 v41, -v37, v40, v39
	v_fmac_f32_e32 v40, v41, v38
	v_fma_f32 v37, -v37, v40, v39
	v_div_fmas_f32 v37, v37, v38, v40
	v_div_fixup_f32 v36, v37, v36, 1.0
	v_mul_f32_e32 v34, v34, v36
	v_mul_f32_e32 v34, v35, v34
	v_cvt_pk_bf16_f32 v34, v34, s0
	global_store_short v[98:99], v34, off offset:3456
	v_mul_f32_e32 v34, 0x3fd9db23, v18
	v_mul_f32_e32 v34, 0xbfb8aa3b, v34
	v_exp_f32_e32 v34, v34
	s_nop 0
	v_add_f32_e32 v34, 1.0, v34
	v_div_scale_f32 v35, s[0:1], v34, v34, 1.0
; DI u16 f2bf(float a) { return (u16)(pack2(a, 0.f) & 0xffffu); }
; DI float sigmoidf_(float x) { return 1.f / (1.f + __expf(-x)); }
; DI void moe1_phase(const P& p, int l, unsigned char* lds) {
;     ...
;     for (int mt = 0; mt < 4; ++mt)
; #pragma unroll
;       for (int i = 0; i < 16; ++i) {
;         float ug = fminf(acc[mt][0][i] + bg, 7.f);
;         float ul = fminf(fmaxf(acc[mt][1][i] + bl, -7.f), 7.f);
;         float a = ug * sigmoidf_(1.702f * ug) * (ul + 1.f);
;         abase[(mt * 32 + 8 * (i >> 2) + (i & 3)) * 64] = f2bf(a);
;       }
	v_rcp_f32_e32 v36, v35
	s_nop 0
	v_fma_f32 v37, -v35, v36, 1.0
	v_fmac_f32_e32 v36, v37, v36
	v_div_scale_f32 v37, vcc, 1.0, v34, 1.0
	v_mul_f32_e32 v38, v37, v36
	v_fma_f32 v39, -v35, v38, v37
	v_fmac_f32_e32 v38, v39, v36
	v_fma_f32 v35, -v35, v38, v37
	v_div_fmas_f32 v35, v35, v36, v38
	v_div_fixup_f32 v34, v35, v34, 1.0
	v_mul_f32_e32 v18, v18, v34
	v_mul_f32_e32 v2, v2, v18
	v_cvt_pk_bf16_f32 v2, v2, s0
	s_movk_i32 s0, 0x3000
	v_add_co_u32_e32 v34, vcc, s0, v132
	s_nop 1
	v_addc_co_u32_e32 v35, vcc, 0, v133, vcc
	global_store_short v[34:35], v2, off
	v_add_f32_e32 v2, v19, v130
	v_min_f32_e32 v2, 0x40e00000, v2
	v_mul_f32_e32 v18, 0x3fd9db23, v2
	v_mul_f32_e32 v18, 0xbfb8aa3b, v18
	v_exp_f32_e32 v18, v18
	s_nop 0
	v_add_f32_e32 v18, 1.0, v18
	v_div_scale_f32 v19, s[0:1], v18, v18, 1.0
	v_rcp_f32_e32 v36, v19
	s_nop 0
	v_fma_f32 v37, -v19, v36, 1.0
	v_fmac_f32_e32 v36, v37, v36
	v_div_scale_f32 v37, vcc, 1.0, v18, 1.0
	v_mul_f32_e32 v38, v37, v36
	v_fma_f32 v39, -v19, v38, v37
	v_fmac_f32_e32 v38, v39, v36
	v_fma_f32 v19, -v19, v38, v37
	v_div_fmas_f32 v19, v19, v36, v38
	v_div_fixup_f32 v18, v19, v18, 1.0
	v_mul_f32_e32 v2, v2, v18
	v_mul_f32_e32 v2, v3, v2
	v_cvt_pk_bf16_f32 v2, v2, s0
	global_store_short v[34:35], v2, off offset:128
	v_add_f32_e32 v2, v20, v130
	v_min_f32_e32 v2, 0x40e00000, v2
	v_add_f32_e32 v3, v4, v131
	v_mul_f32_e32 v4, 0x3fd9db23, v2
	v_mul_f32_e32 v4, 0xbfb8aa3b, v4
	v_exp_f32_e32 v4, v4
	v_med3_f32 v3, v3, s36, v225
	v_add_f32_e32 v3, 1.0, v3
	v_add_f32_e32 v4, 1.0, v4
	v_div_scale_f32 v18, s[0:1], v4, v4, 1.0
	v_rcp_f32_e32 v19, v18
	s_nop 0
	v_fma_f32 v20, -v18, v19, 1.0
	v_fmac_f32_e32 v19, v20, v19
	v_div_scale_f32 v20, vcc, 1.0, v4, 1.0
	v_mul_f32_e32 v36, v20, v19
	v_fma_f32 v37, -v18, v36, v20
	v_fmac_f32_e32 v36, v37, v19
	v_fma_f32 v18, -v18, v36, v20
	v_div_fmas_f32 v18, v18, v19, v36
	v_div_fixup_f32 v4, v18, v4, 1.0
	v_mul_f32_e32 v2, v2, v4
	v_mul_f32_e32 v2, v3, v2
	v_cvt_pk_bf16_f32 v2, v2, s0
	global_store_short v[34:35], v2, off offset:256
	v_add_f32_e32 v2, v21, v130
	v_min_f32_e32 v2, 0x40e00000, v2
	v_mul_f32_e32 v4, 0x3fd9db23, v2
	v_mul_f32_e32 v4, 0xbfb8aa3b, v4
	v_exp_f32_e32 v4, v4
	v_add_f32_e32 v3, v5, v131
	v_med3_f32 v3, v3, s36, v225
	v_add_f32_e32 v3, 1.0, v3
	v_add_f32_e32 v4, 1.0, v4
	v_div_scale_f32 v5, s[0:1], v4, v4, 1.0
	v_rcp_f32_e32 v18, v5
	s_nop 0
	v_fma_f32 v19, -v5, v18, 1.0
	v_fmac_f32_e32 v18, v19, v18
	v_div_scale_f32 v19, vcc, 1.0, v4, 1.0
	v_mul_f32_e32 v20, v19, v18
	v_fma_f32 v21, -v5, v20, v19
	v_fmac_f32_e32 v20, v21, v18
	v_fma_f32 v5, -v5, v20, v19
	v_div_fmas_f32 v5, v5, v18, v20
	v_div_fixup_f32 v4, v5, v4, 1.0
	v_mul_f32_e32 v2, v2, v4
	v_mul_f32_e32 v2, v3, v2
	v_cvt_pk_bf16_f32 v2, v2, s0
	global_store_short v[34:35], v2, off offset:384
	v_add_f32_e32 v2, v22, v130
	v_min_f32_e32 v2, 0x40e00000, v2
	v_mul_f32_e32 v4, 0x3fd9db23, v2
	v_mul_f32_e32 v4, 0xbfb8aa3b, v4
	v_exp_f32_e32 v4, v4
	v_add_f32_e32 v3, v6, v131
	v_med3_f32 v3, v3, s36, v225
	v_add_f32_e32 v3, 1.0, v3
	v_add_f32_e32 v4, 1.0, v4
	v_div_scale_f32 v5, s[0:1], v4, v4, 1.0
	v_rcp_f32_e32 v6, v5
	s_nop 0
	v_fma_f32 v18, -v5, v6, 1.0
	v_fmac_f32_e32 v6, v18, v6
	v_div_scale_f32 v18, vcc, 1.0, v4, 1.0
	v_mul_f32_e32 v19, v18, v6
	v_fma_f32 v20, -v5, v19, v18
	v_fmac_f32_e32 v19, v20, v6
	v_fma_f32 v5, -v5, v19, v18
	v_div_fmas_f32 v5, v5, v6, v19
	v_div_fixup_f32 v4, v5, v4, 1.0
	v_mul_f32_e32 v2, v2, v4
	v_mul_f32_e32 v2, v3, v2
	v_cvt_pk_bf16_f32 v2, v2, s0
	global_store_short v[34:35], v2, off offset:1024
	v_add_f32_e32 v2, v23, v130
	v_min_f32_e32 v2, 0x40e00000, v2
	v_mul_f32_e32 v4, 0x3fd9db23, v2
	v_mul_f32_e32 v4, 0xbfb8aa3b, v4
	v_exp_f32_e32 v4, v4
	v_add_f32_e32 v3, v7, v131
	v_med3_f32 v3, v3, s36, v225
	v_add_f32_e32 v3, 1.0, v3
	v_add_f32_e32 v4, 1.0, v4
	v_div_scale_f32 v5, s[0:1], v4, v4, 1.0
	v_rcp_f32_e32 v6, v5
	s_nop 0
	v_fma_f32 v7, -v5, v6, 1.0
	v_fmac_f32_e32 v6, v7, v6
	v_div_scale_f32 v7, vcc, 1.0, v4, 1.0
	v_mul_f32_e32 v18, v7, v6
	v_fma_f32 v19, -v5, v18, v7
	v_fmac_f32_e32 v18, v19, v6
	v_fma_f32 v5, -v5, v18, v7
	v_div_fmas_f32 v5, v5, v6, v18
	v_div_fixup_f32 v4, v5, v4, 1.0
	v_mul_f32_e32 v2, v2, v4
	v_mul_f32_e32 v2, v3, v2
	v_cvt_pk_bf16_f32 v2, v2, s0
	global_store_short v[34:35], v2, off offset:1152
	v_add_f32_e32 v2, v24, v130
	v_min_f32_e32 v2, 0x40e00000, v2
	v_mul_f32_e32 v4, 0x3fd9db23, v2
	v_mul_f32_e32 v4, 0xbfb8aa3b, v4
	v_exp_f32_e32 v4, v4
	v_add_f32_e32 v3, v8, v131
	v_med3_f32 v3, v3, s36, v225
	v_add_f32_e32 v3, 1.0, v3
	v_add_f32_e32 v4, 1.0, v4
	v_div_scale_f32 v5, s[0:1], v4, v4, 1.0
	v_rcp_f32_e32 v6, v5
	s_nop 0
	v_fma_f32 v7, -v5, v6, 1.0
	v_fmac_f32_e32 v6, v7, v6
	v_div_scale_f32 v7, vcc, 1.0, v4, 1.0
	v_mul_f32_e32 v8, v7, v6
	v_fma_f32 v18, -v5, v8, v7
	v_fmac_f32_e32 v8, v18, v6
	v_fma_f32 v5, -v5, v8, v7
	v_div_fmas_f32 v5, v5, v6, v8
	v_div_fixup_f32 v4, v5, v4, 1.0
	v_mul_f32_e32 v2, v2, v4
	v_mul_f32_e32 v2, v3, v2
	v_cvt_pk_bf16_f32 v2, v2, s0
	global_store_short v[34:35], v2, off offset:1280
	v_add_f32_e32 v2, v25, v130
	v_min_f32_e32 v2, 0x40e00000, v2
	v_mul_f32_e32 v4, 0x3fd9db23, v2
	v_mul_f32_e32 v4, 0xbfb8aa3b, v4
	v_exp_f32_e32 v4, v4
	v_add_f32_e32 v3, v9, v131
	v_med3_f32 v3, v3, s36, v225
	v_add_f32_e32 v3, 1.0, v3
	v_add_f32_e32 v4, 1.0, v4
	v_div_scale_f32 v5, s[0:1], v4, v4, 1.0
	v_rcp_f32_e32 v6, v5
	s_nop 0
	v_fma_f32 v7, -v5, v6, 1.0
	v_fmac_f32_e32 v6, v7, v6
	v_div_scale_f32 v7, vcc, 1.0, v4, 1.0
	v_mul_f32_e32 v8, v7, v6
	v_fma_f32 v9, -v5, v8, v7
	v_fmac_f32_e32 v8, v9, v6
	v_fma_f32 v5, -v5, v8, v7
	v_div_fmas_f32 v5, v5, v6, v8
	v_div_fixup_f32 v4, v5, v4, 1.0
	v_mul_f32_e32 v2, v2, v4
; DI u16 f2bf(float a) { return (u16)(pack2(a, 0.f) & 0xffffu); }
; DI float sigmoidf_(float x) { return 1.f / (1.f + __expf(-x)); }
; DI void moe1_phase(const P& p, int l, unsigned char* lds) {
;     ...
;     for (int mt = 0; mt < 4; ++mt)
; #pragma unroll
;       for (int i = 0; i < 16; ++i) {
;         float ug = fminf(acc[mt][0][i] + bg, 7.f);
;         float ul = fminf(fmaxf(acc[mt][1][i] + bl, -7.f), 7.f);
;         float a = ug * sigmoidf_(1.702f * ug) * (ul + 1.f);
;         abase[(mt * 32 + 8 * (i >> 2) + (i & 3)) * 64] = f2bf(a);
;       }
	v_mul_f32_e32 v2, v3, v2
	v_cvt_pk_bf16_f32 v2, v2, s0
	global_store_short v[34:35], v2, off offset:1408
	v_add_f32_e32 v2, v26, v130
	v_min_f32_e32 v2, 0x40e00000, v2
	v_mul_f32_e32 v4, 0x3fd9db23, v2
	v_mul_f32_e32 v4, 0xbfb8aa3b, v4
	v_exp_f32_e32 v4, v4
	v_add_f32_e32 v3, v10, v131
	v_med3_f32 v3, v3, s36, v225
	v_add_f32_e32 v3, 1.0, v3
	v_add_f32_e32 v4, 1.0, v4
	v_div_scale_f32 v5, s[0:1], v4, v4, 1.0
	v_rcp_f32_e32 v6, v5
	s_nop 0
	v_fma_f32 v7, -v5, v6, 1.0
	v_fmac_f32_e32 v6, v7, v6
	v_div_scale_f32 v7, vcc, 1.0, v4, 1.0
	v_mul_f32_e32 v8, v7, v6
	v_fma_f32 v9, -v5, v8, v7
	v_fmac_f32_e32 v8, v9, v6
	v_fma_f32 v5, -v5, v8, v7
	v_div_fmas_f32 v5, v5, v6, v8
	v_div_fixup_f32 v4, v5, v4, 1.0
	v_mul_f32_e32 v2, v2, v4
	v_mul_f32_e32 v2, v3, v2
	v_cvt_pk_bf16_f32 v2, v2, s0
	global_store_short v[34:35], v2, off offset:2048
	v_add_f32_e32 v2, v27, v130
	v_min_f32_e32 v2, 0x40e00000, v2
	v_mul_f32_e32 v4, 0x3fd9db23, v2
	v_mul_f32_e32 v4, 0xbfb8aa3b, v4
	v_exp_f32_e32 v4, v4
	v_add_f32_e32 v3, v11, v131
	v_med3_f32 v3, v3, s36, v225
	v_add_f32_e32 v3, 1.0, v3
	v_add_f32_e32 v4, 1.0, v4
	v_div_scale_f32 v5, s[0:1], v4, v4, 1.0
	v_rcp_f32_e32 v6, v5
	s_nop 0
	v_fma_f32 v7, -v5, v6, 1.0
	v_fmac_f32_e32 v6, v7, v6
	v_div_scale_f32 v7, vcc, 1.0, v4, 1.0
	v_mul_f32_e32 v8, v7, v6
	v_fma_f32 v9, -v5, v8, v7
	v_fmac_f32_e32 v8, v9, v6
	v_fma_f32 v5, -v5, v8, v7
	v_div_fmas_f32 v5, v5, v6, v8
	v_div_fixup_f32 v4, v5, v4, 1.0
	v_mul_f32_e32 v2, v2, v4
	v_mul_f32_e32 v2, v3, v2
	v_cvt_pk_bf16_f32 v2, v2, s0
	global_store_short v[34:35], v2, off offset:2176
	v_add_f32_e32 v2, v28, v130
	v_min_f32_e32 v2, 0x40e00000, v2
	v_mul_f32_e32 v4, 0x3fd9db23, v2
	v_mul_f32_e32 v4, 0xbfb8aa3b, v4
	v_exp_f32_e32 v4, v4
	v_add_f32_e32 v3, v12, v131
	v_med3_f32 v3, v3, s36, v225
	v_add_f32_e32 v3, 1.0, v3
	v_add_f32_e32 v4, 1.0, v4
	v_div_scale_f32 v5, s[0:1], v4, v4, 1.0
	v_rcp_f32_e32 v6, v5
	s_nop 0
	v_fma_f32 v7, -v5, v6, 1.0
	v_fmac_f32_e32 v6, v7, v6
	v_div_scale_f32 v7, vcc, 1.0, v4, 1.0
	v_mul_f32_e32 v8, v7, v6
	v_fma_f32 v9, -v5, v8, v7
	v_fmac_f32_e32 v8, v9, v6
	v_fma_f32 v5, -v5, v8, v7
	v_div_fmas_f32 v5, v5, v6, v8
	v_div_fixup_f32 v4, v5, v4, 1.0
	v_mul_f32_e32 v2, v2, v4
	v_mul_f32_e32 v2, v3, v2
	v_cvt_pk_bf16_f32 v2, v2, s0
	global_store_short v[34:35], v2, off offset:2304
	v_add_f32_e32 v2, v29, v130
	v_min_f32_e32 v2, 0x40e00000, v2
	v_mul_f32_e32 v4, 0x3fd9db23, v2
	v_mul_f32_e32 v4, 0xbfb8aa3b, v4
	v_exp_f32_e32 v4, v4
	v_add_f32_e32 v3, v13, v131
	v_med3_f32 v3, v3, s36, v225
	v_add_f32_e32 v3, 1.0, v3
	v_add_f32_e32 v4, 1.0, v4
	v_div_scale_f32 v5, s[0:1], v4, v4, 1.0
	v_rcp_f32_e32 v6, v5
	s_nop 0
	v_fma_f32 v7, -v5, v6, 1.0
	v_fmac_f32_e32 v6, v7, v6
	v_div_scale_f32 v7, vcc, 1.0, v4, 1.0
	v_mul_f32_e32 v8, v7, v6
	v_fma_f32 v9, -v5, v8, v7
	v_fmac_f32_e32 v8, v9, v6
	v_fma_f32 v5, -v5, v8, v7
	v_div_fmas_f32 v5, v5, v6, v8
	v_div_fixup_f32 v4, v5, v4, 1.0
	v_mul_f32_e32 v2, v2, v4
	v_mul_f32_e32 v2, v3, v2
	v_cvt_pk_bf16_f32 v2, v2, s0
	global_store_short v[34:35], v2, off offset:2432
	v_add_f32_e32 v2, v30, v130
	v_min_f32_e32 v2, 0x40e00000, v2
	v_mul_f32_e32 v4, 0x3fd9db23, v2
	v_mul_f32_e32 v4, 0xbfb8aa3b, v4
	v_exp_f32_e32 v4, v4
	v_add_f32_e32 v3, v14, v131
	v_med3_f32 v3, v3, s36, v225
	v_add_f32_e32 v3, 1.0, v3
	v_add_f32_e32 v4, 1.0, v4
	v_div_scale_f32 v5, s[0:1], v4, v4, 1.0
	v_rcp_f32_e32 v6, v5
	s_nop 0
	v_fma_f32 v7, -v5, v6, 1.0
	v_fmac_f32_e32 v6, v7, v6
	v_div_scale_f32 v7, vcc, 1.0, v4, 1.0
	v_mul_f32_e32 v8, v7, v6
	v_fma_f32 v9, -v5, v8, v7
	v_fmac_f32_e32 v8, v9, v6
	v_fma_f32 v5, -v5, v8, v7
	v_div_fmas_f32 v5, v5, v6, v8
	v_div_fixup_f32 v4, v5, v4, 1.0
	v_mul_f32_e32 v2, v2, v4
	v_mul_f32_e32 v2, v3, v2
	v_cvt_pk_bf16_f32 v2, v2, s0
	global_store_short v[34:35], v2, off offset:3072
	v_add_f32_e32 v2, v31, v130
	v_min_f32_e32 v2, 0x40e00000, v2
	v_mul_f32_e32 v4, 0x3fd9db23, v2
	v_mul_f32_e32 v4, 0xbfb8aa3b, v4
	v_exp_f32_e32 v4, v4
	v_add_f32_e32 v3, v15, v131
	v_med3_f32 v3, v3, s36, v225
	v_add_f32_e32 v3, 1.0, v3
	v_add_f32_e32 v4, 1.0, v4
	v_div_scale_f32 v5, s[0:1], v4, v4, 1.0
	v_rcp_f32_e32 v6, v5
	s_nop 0
	v_fma_f32 v7, -v5, v6, 1.0
	v_fmac_f32_e32 v6, v7, v6
	v_div_scale_f32 v7, vcc, 1.0, v4, 1.0
	v_mul_f32_e32 v8, v7, v6
	v_fma_f32 v9, -v5, v8, v7
	v_fmac_f32_e32 v8, v9, v6
	v_fma_f32 v5, -v5, v8, v7
	v_div_fmas_f32 v5, v5, v6, v8
	v_div_fixup_f32 v4, v5, v4, 1.0
	v_mul_f32_e32 v2, v2, v4
	v_mul_f32_e32 v2, v3, v2
	v_cvt_pk_bf16_f32 v2, v2, s0
	global_store_short v[34:35], v2, off offset:3200
	v_add_f32_e32 v2, v32, v130
	v_min_f32_e32 v2, 0x40e00000, v2
	v_mul_f32_e32 v4, 0x3fd9db23, v2
	v_mul_f32_e32 v4, 0xbfb8aa3b, v4
	v_exp_f32_e32 v4, v4
	v_add_f32_e32 v3, v16, v131
	v_med3_f32 v3, v3, s36, v225
	v_add_f32_e32 v3, 1.0, v3
	v_add_f32_e32 v4, 1.0, v4
	v_div_scale_f32 v5, s[0:1], v4, v4, 1.0
	v_rcp_f32_e32 v6, v5
	s_nop 0
	v_fma_f32 v7, -v5, v6, 1.0
	v_fmac_f32_e32 v6, v7, v6
	v_div_scale_f32 v7, vcc, 1.0, v4, 1.0
	v_mul_f32_e32 v8, v7, v6
	v_fma_f32 v9, -v5, v8, v7
	v_fmac_f32_e32 v8, v9, v6
	v_fma_f32 v5, -v5, v8, v7
	v_div_fmas_f32 v5, v5, v6, v8
	v_div_fixup_f32 v4, v5, v4, 1.0
	v_mul_f32_e32 v2, v2, v4
	v_mul_f32_e32 v2, v3, v2
	v_cvt_pk_bf16_f32 v2, v2, s0
	global_store_short v[34:35], v2, off offset:3328
	v_add_f32_e32 v2, v33, v130
	v_min_f32_e32 v2, 0x40e00000, v2
	v_mul_f32_e32 v4, 0x3fd9db23, v2
	v_mul_f32_e32 v4, 0xbfb8aa3b, v4
	v_exp_f32_e32 v4, v4
	v_add_f32_e32 v3, v17, v131
	v_med3_f32 v3, v3, s36, v225
	v_add_f32_e32 v3, 1.0, v3
	v_add_f32_e32 v4, 1.0, v4
	v_div_scale_f32 v5, s[0:1], v4, v4, 1.0
	v_rcp_f32_e32 v6, v5
	s_nop 0
	v_fma_f32 v7, -v5, v6, 1.0
	v_fmac_f32_e32 v6, v7, v6
	v_div_scale_f32 v7, vcc, 1.0, v4, 1.0
	v_mul_f32_e32 v8, v7, v6
	v_fma_f32 v9, -v5, v8, v7
	v_fmac_f32_e32 v8, v9, v6
	v_fma_f32 v5, -v5, v8, v7
	v_div_fmas_f32 v5, v5, v6, v8
	v_div_fixup_f32 v4, v5, v4, 1.0
	v_mul_f32_e32 v2, v2, v4
	v_mul_f32_e32 v2, v3, v2
	v_cvt_pk_bf16_f32 v2, v2, s0
	global_store_short v[34:35], v2, off offset:3456
